# GEMM K-loops: first lgkmcnt wait of each MFMA block hoisted before the pre-MFMA barrier (merged with the existing pre-barrier wait), so the first MFMA issues right at barrier release
# speedup vs baseline: 1.0077x; 1.0000x over previous
; #define PG8_STAGE(bufoff, gbase, voff) do { _Pragma("unroll") for (int _i = 0; _i < 2; ++_i) \
;         __builtin_amdgcn_global_load_lds((const unsigned*)((const char*)(gbase) + (voff)[_i]), (LAS unsigned*)(lds + (bufoff) + ldsw + _i * 8192), 16, 0, 0); } while (0)
; #define PG8_LDA(dst, b, h) do { _Pragma("unroll") for (int m = 0; m < 4; ++m) _Pragma("unroll") for (int k = 0; k < 2; ++k) dst[m][k] = *(const LAS bf16x8*)(lds + PG8_SA(b, h) + aoff + m * 2048 + k * 1024); } while (0)
; #define PG8_LDB(dst, b, h) do { _Pragma("unroll") for (int n = 0; n < 2; ++n) _Pragma("unroll") for (int k = 0; k < 2; ++k) dst[n][k] = *(const LAS bf16x8*)(lds + PG8_SB(b, h) + boff + n * 2048 + k * 1024); } while (0)
; #define PG8_WAIT_V(n) asm volatile("s_waitcnt vmcnt(" #n ")" ::: "memory")
; #define PG8_WAIT_L(n) asm volatile("s_waitcnt lgkmcnt(" #n ")" ::: "memory")
; #define PG8_BAR __builtin_amdgcn_s_barrier()
; #define PG8_SCHED __builtin_amdgcn_sched_barrier(0)
; template <class Map, class Epi>
; DI void gemm_phase(LAS unsigned char* lds, const Map& MP, const Epi& E, const int nM, const int nN, const int K, const int lda, const int ldb) {
;     ...
;             const bool last = (t == nt - 2);
;             const char* a1 = cA + (size_t)(t + 1) * kstep;
;             const char* a2 = last ? nA : cA + (size_t)(t + 2) * kstep; const char* b2 = last ? nB : cB + (size_t)(t + 2) * kstep;
;             const char* a3 = a2 + kstep; const char* b3 = b2 + kstep;
;             PG8_LDB(B0, 0, 0); PG8_SCHED; PG8_LDA(At, 0, 0); PG8_STAGE(PG8_SA(1, 1), a1 + hstepA, voffA);
;             PG8_WAIT_L(8); PG8_BAR; PG8_WAIT_L(0); PG8_MMA(0, 0, At, B0); PG8_BAR; PG8_SCHED;
;             PG8_LDB(B1, 0, 1); PG8_STAGE(PG8_SB(0, 0), b2, voffB);
;             PG8_BAR; PG8_WAIT_L(0); PG8_MMA(0, 1, At, B1); PG8_BAR;
;             PG8_LDA(At, 0, 1); PG8_STAGE(PG8_SA(0, 0), a2, voffA);
;             PG8_BAR; PG8_WAIT_L(0); PG8_MMA(1, 0, At, B0); PG8_BAR; PG8_SCHED;
;             PG8_STAGE(PG8_SB(0, 1), b2 + hstepB, voffB);
;             PG8_WAIT_V(6); PG8_BAR; PG8_MMA(1, 1, At, B1); PG8_BAR;
;             PG8_LDB(B0, 1, 0); PG8_SCHED; PG8_LDA(At, 1, 0); PG8_STAGE(PG8_SA(0, 1), a2 + hstepA, voffA);
;             PG8_WAIT_L(8); PG8_BAR; PG8_WAIT_L(0); PG8_MMA(0, 0, At, B0); PG8_BAR; PG8_SCHED;
.LBB1_229:
	s_add_u32 s26, s24, 0xfff80080
	s_addc_u32 s27, s25, -1
	s_cmp_eq_u32 s57, 4
	s_cselect_b32 s29, s17, s27
	s_cselect_b32 s28, s43, s26
	s_cselect_b32 s27, s53, s56
	s_cselect_b32 s26, s54, s55
	s_add_i32 m0, s2, 0xc000
	ds_read_b128 v[160:163], v168
	ds_read_b128 v[170:173], v168 offset:1024
	ds_read_b128 v[174:177], v168 offset:2048
	ds_read_b128 v[178:181], v168 offset:3072
	ds_read_b128 v[182:185], v168 offset:4096
	ds_read_b128 v[186:189], v168 offset:5120
	ds_read_b128 v[190:193], v168 offset:6144
	ds_read_b128 v[198:201], v168 offset:7168
	global_load_lds_dwordx4 v154, s[24:25]
	s_add_i32 m0, s2, 0xe000
	s_nop 0
	global_load_lds_dwordx4 v152, s[24:25]
	s_waitcnt lgkmcnt(7)
	s_setprio 1
	s_barrier
	v_mfma_f32_16x16x32_bf16 v[140:143], v[72:75], v[160:163], v[140:143]
	v_mfma_f32_16x16x32_bf16 v[136:139], v[80:83], v[160:163], v[136:139]
	s_waitcnt lgkmcnt(5)
	v_mfma_f32_16x16x32_bf16 v[124:127], v[72:75], v[174:177], v[124:127]
	v_mfma_f32_16x16x32_bf16 v[120:123], v[80:83], v[174:177], v[120:123]
	s_waitcnt lgkmcnt(3)
	v_mfma_f32_16x16x32_bf16 v[108:111], v[72:75], v[182:185], v[108:111]
	v_mfma_f32_16x16x32_bf16 v[104:107], v[80:83], v[182:185], v[104:107]
	s_waitcnt lgkmcnt(1)
	v_mfma_f32_16x16x32_bf16 v[92:95], v[72:75], v[190:193], v[92:95]
	v_mfma_f32_16x16x32_bf16 v[88:91], v[80:83], v[190:193], v[88:91]
	v_mfma_f32_16x16x32_bf16 v[140:143], v[76:79], v[170:173], v[140:143]
	v_mfma_f32_16x16x32_bf16 v[136:139], v[84:87], v[170:173], v[136:139]
	v_mfma_f32_16x16x32_bf16 v[124:127], v[76:79], v[178:181], v[124:127]
	v_mfma_f32_16x16x32_bf16 v[120:123], v[84:87], v[178:181], v[120:123]
	v_mfma_f32_16x16x32_bf16 v[108:111], v[76:79], v[186:189], v[108:111]
	v_mfma_f32_16x16x32_bf16 v[104:107], v[84:87], v[186:189], v[104:107]
	s_waitcnt lgkmcnt(0)
	v_mfma_f32_16x16x32_bf16 v[92:95], v[76:79], v[198:201], v[92:95]
	v_mfma_f32_16x16x32_bf16 v[88:91], v[84:87], v[198:201], v[88:91]
	s_barrier
	s_setprio 0
	s_add_i32 s58, s48, s34
	v_lshl_add_u64 v[194:195], s[26:27], 0, v[148:149]
	s_mov_b32 m0, s58
	ds_read_b128 v[202:205], v169
	ds_read_b128 v[206:209], v169 offset:1024
	ds_read_b128 v[210:213], v169 offset:2048
	ds_read_b128 v[214:217], v169 offset:3072
	global_load_lds_dwordx4 v[194:195], off
	v_lshl_add_u64 v[218:219], s[26:27], 0, v[144:145]
	s_add_i32 m0, s58, 0x2000
	s_nop 0
	global_load_lds_dwordx4 v[218:219], off
	s_waitcnt lgkmcnt(3)
	s_setprio 1
	s_barrier
	v_mfma_f32_16x16x32_bf16 v[132:135], v[202:205], v[160:163], v[132:135]
	s_waitcnt lgkmcnt(1)
	v_mfma_f32_16x16x32_bf16 v[128:131], v[210:213], v[160:163], v[128:131]
	v_mfma_f32_16x16x32_bf16 v[116:119], v[202:205], v[174:177], v[116:119]
	v_mfma_f32_16x16x32_bf16 v[112:115], v[210:213], v[174:177], v[112:115]
	v_mfma_f32_16x16x32_bf16 v[100:103], v[202:205], v[182:185], v[100:103]
	v_mfma_f32_16x16x32_bf16 v[96:99], v[210:213], v[182:185], v[96:99]
	v_mfma_f32_16x16x32_bf16 v[68:71], v[202:205], v[190:193], v[68:71]
	v_mfma_f32_16x16x32_bf16 v[64:67], v[210:213], v[190:193], v[64:67]
	v_mfma_f32_16x16x32_bf16 v[132:135], v[206:209], v[170:173], v[132:135]
	s_mov_b32 m0, s2
	s_waitcnt lgkmcnt(0)
	v_mfma_f32_16x16x32_bf16 v[128:131], v[214:217], v[170:173], v[128:131]
	v_lshl_add_u64 v[220:221], s[28:29], 0, v[150:151]
	v_mfma_f32_16x16x32_bf16 v[116:119], v[206:209], v[178:181], v[116:119]
	v_mfma_f32_16x16x32_bf16 v[112:115], v[214:217], v[178:181], v[112:115]
	v_mfma_f32_16x16x32_bf16 v[100:103], v[206:209], v[186:189], v[100:103]
	v_mfma_f32_16x16x32_bf16 v[96:99], v[214:217], v[186:189], v[96:99]
	v_mfma_f32_16x16x32_bf16 v[68:71], v[206:209], v[198:201], v[68:71]
	v_mfma_f32_16x16x32_bf16 v[64:67], v[214:217], v[198:201], v[64:67]
	s_barrier
	s_setprio 0
	ds_read_b128 v[160:163], v168 offset:16384
	ds_read_b128 v[170:173], v168 offset:17408
	ds_read_b128 v[174:177], v168 offset:18432
	ds_read_b128 v[178:181], v168 offset:19456
	ds_read_b128 v[182:185], v168 offset:20480
	ds_read_b128 v[186:189], v168 offset:21504
	ds_read_b128 v[190:193], v168 offset:22528
	ds_read_b128 v[198:201], v168 offset:23552
	global_load_lds_dwordx4 v[220:221], off
	v_lshl_add_u64 v[222:223], s[28:29], 0, v[146:147]
	s_mov_b32 m0, s4
	s_nop 0
	global_load_lds_dwordx4 v[222:223], off
	s_waitcnt vmcnt(10) lgkmcnt(7)
	s_setprio 1
	s_barrier
	v_mfma_f32_16x16x32_bf16 v[60:63], v[72:75], v[160:163], v[60:63]
	v_mfma_f32_16x16x32_bf16 v[56:59], v[80:83], v[160:163], v[56:59]
	s_waitcnt lgkmcnt(5)
	v_mfma_f32_16x16x32_bf16 v[44:47], v[72:75], v[174:177], v[44:47]
	v_mfma_f32_16x16x32_bf16 v[40:43], v[80:83], v[174:177], v[40:43]
	s_waitcnt lgkmcnt(3)
	v_mfma_f32_16x16x32_bf16 v[28:31], v[72:75], v[182:185], v[28:31]
	v_mfma_f32_16x16x32_bf16 v[24:27], v[80:83], v[182:185], v[24:27]
	s_waitcnt lgkmcnt(1)
	v_mfma_f32_16x16x32_bf16 v[12:15], v[72:75], v[190:193], v[12:15]
	v_mfma_f32_16x16x32_bf16 v[8:11], v[80:83], v[190:193], v[8:11]
	v_mfma_f32_16x16x32_bf16 v[60:63], v[76:79], v[170:173], v[60:63]
	v_mfma_f32_16x16x32_bf16 v[56:59], v[84:87], v[170:173], v[56:59]
	v_mfma_f32_16x16x32_bf16 v[44:47], v[76:79], v[178:181], v[44:47]
	v_mfma_f32_16x16x32_bf16 v[40:43], v[84:87], v[178:181], v[40:43]
	v_mfma_f32_16x16x32_bf16 v[28:31], v[76:79], v[186:189], v[28:31]
	v_mfma_f32_16x16x32_bf16 v[24:27], v[84:87], v[186:189], v[24:27]
	s_waitcnt lgkmcnt(0)
	v_mfma_f32_16x16x32_bf16 v[12:15], v[76:79], v[198:201], v[12:15]
	v_mfma_f32_16x16x32_bf16 v[8:11], v[84:87], v[198:201], v[8:11]
	s_barrier
	s_setprio 0
	s_add_u32 s58, s26, 0x20000
	s_addc_u32 s59, s27, 0
	s_add_i32 s60, s49, s34
	s_mov_b32 m0, s60
	s_nop 0
	global_load_lds_dwordx4 v148, s[58:59]
	s_add_i32 m0, s60, 0x2000
	s_nop 0
	global_load_lds_dwordx4 v144, s[58:59]
	s_waitcnt vmcnt(6)
	s_setprio 1
	s_barrier
; #define PG8_STAGE(bufoff, gbase, voff) do { _Pragma("unroll") for (int _i = 0; _i < 2; ++_i) \
;         __builtin_amdgcn_global_load_lds((const unsigned*)((const char*)(gbase) + (voff)[_i]), (LAS unsigned*)(lds + (bufoff) + ldsw + _i * 8192), 16, 0, 0); } while (0)
; #define PG8_LDA(dst, b, h) do { _Pragma("unroll") for (int m = 0; m < 4; ++m) _Pragma("unroll") for (int k = 0; k < 2; ++k) dst[m][k] = *(const LAS bf16x8*)(lds + PG8_SA(b, h) + aoff + m * 2048 + k * 1024); } while (0)
; #define PG8_LDB(dst, b, h) do { _Pragma("unroll") for (int n = 0; n < 2; ++n) _Pragma("unroll") for (int k = 0; k < 2; ++k) dst[n][k] = *(const LAS bf16x8*)(lds + PG8_SB(b, h) + boff + n * 2048 + k * 1024); } while (0)
; #define PG8_MMA(ai, bj, At, Bt) do { __builtin_amdgcn_s_setprio(1); _Pragma("unroll") for (int m = 0; m < 4; ++m) _Pragma("unroll") for (int n = 0; n < 2; ++n) _Pragma("unroll") for (int k = 0; k < 2; ++k) \
;         acc[ai][bj][m][n] = __builtin_amdgcn_mfma_f32_16x16x32_bf16(Bt[n][k], At[m][k], acc[ai][bj][m][n], 0, 0, 0); __builtin_amdgcn_s_setprio(0); } while (0)
; #define PG8_WAIT_V(n) asm volatile("s_waitcnt vmcnt(" #n ")" ::: "memory")
; #define PG8_WAIT_L(n) asm volatile("s_waitcnt lgkmcnt(" #n ")" ::: "memory")
; #define PG8_BAR __builtin_amdgcn_s_barrier()
; #define PG8_SCHED __builtin_amdgcn_sched_barrier(0)
; template <class Map, class Epi>
; DI void gemm_phase(LAS unsigned char* lds, const Map& MP, const Epi& E, const int nM, const int nN, const int K, const int lda, const int ldb) {
;     ...
;             PG8_WAIT_V(6); PG8_BAR; PG8_MMA(1, 1, At, B1); PG8_BAR;
;             PG8_LDB(B0, 1, 0); PG8_SCHED; PG8_LDA(At, 1, 0); PG8_STAGE(PG8_SA(0, 1), a2 + hstepA, voffA);
;             PG8_WAIT_L(8); PG8_BAR; PG8_WAIT_L(0); PG8_MMA(0, 0, At, B0); PG8_BAR; PG8_SCHED;
;             PG8_LDB(B1, 1, 1); PG8_STAGE(PG8_SB(1, 0), b3, voffB);
;             PG8_BAR; PG8_WAIT_L(0); PG8_MMA(0, 1, At, B1); PG8_BAR;
;             PG8_LDA(At, 1, 1); PG8_STAGE(PG8_SA(1, 0), a3, voffA);
;             PG8_BAR; PG8_WAIT_L(0); PG8_MMA(1, 0, At, B0); PG8_BAR; PG8_SCHED;
	v_mfma_f32_16x16x32_bf16 v[52:55], v[202:205], v[160:163], v[52:55]
	v_mfma_f32_16x16x32_bf16 v[48:51], v[210:213], v[160:163], v[48:51]
	s_add_i32 s58, 0, 0x18000
	v_add_u32_e32 v84, s58, v166
	ds_read_b128 v[72:75], v84
	v_mfma_f32_16x16x32_bf16 v[36:39], v[202:205], v[174:177], v[36:39]
	v_mfma_f32_16x16x32_bf16 v[32:35], v[210:213], v[174:177], v[32:35]
	ds_read_b128 v[76:79], v84 offset:1024
	v_mfma_f32_16x16x32_bf16 v[20:23], v[202:205], v[182:185], v[20:23]
	v_mfma_f32_16x16x32_bf16 v[16:19], v[210:213], v[182:185], v[16:19]
	ds_read_b128 v[80:83], v84 offset:2048
	v_mfma_f32_16x16x32_bf16 v[4:7], v[202:205], v[190:193], v[4:7]
	v_mfma_f32_16x16x32_bf16 v[0:3], v[210:213], v[190:193], v[0:3]
	ds_read_b128 v[84:87], v84 offset:3072
	v_mfma_f32_16x16x32_bf16 v[52:55], v[206:209], v[170:173], v[52:55]
	v_mfma_f32_16x16x32_bf16 v[48:51], v[214:217], v[170:173], v[48:51]
	v_mfma_f32_16x16x32_bf16 v[36:39], v[206:209], v[178:181], v[36:39]
	v_mfma_f32_16x16x32_bf16 v[32:35], v[214:217], v[178:181], v[32:35]
	v_mfma_f32_16x16x32_bf16 v[20:23], v[206:209], v[186:189], v[20:23]
	v_mfma_f32_16x16x32_bf16 v[16:19], v[214:217], v[186:189], v[16:19]
	v_mfma_f32_16x16x32_bf16 v[4:7], v[206:209], v[198:201], v[4:7]
	v_mfma_f32_16x16x32_bf16 v[0:3], v[214:217], v[198:201], v[0:3]
	s_barrier
	s_setprio 0
	s_add_u32 s28, s28, 0x80000
	s_addc_u32 s29, s29, 0
	s_mov_b32 m0, s5
	ds_read_b128 v[160:163], v168 offset:32768
	ds_read_b128 v[170:173], v168 offset:33792
	ds_read_b128 v[174:177], v168 offset:34816
	ds_read_b128 v[178:181], v168 offset:35840
	ds_read_b128 v[182:185], v168 offset:36864
	ds_read_b128 v[186:189], v168 offset:37888
	ds_read_b128 v[190:193], v168 offset:38912
	ds_read_b128 v[198:201], v168 offset:39936
	global_load_lds_dwordx4 v150, s[28:29]
	s_mov_b32 m0, s23
	s_nop 0
	global_load_lds_dwordx4 v146, s[28:29]
	s_waitcnt lgkmcnt(7)
	s_setprio 1
	s_barrier
	v_mfma_f32_16x16x32_bf16 v[140:143], v[72:75], v[160:163], v[140:143]
	v_mfma_f32_16x16x32_bf16 v[136:139], v[80:83], v[160:163], v[136:139]
	s_waitcnt lgkmcnt(5)
	v_mfma_f32_16x16x32_bf16 v[124:127], v[72:75], v[174:177], v[124:127]
	v_mfma_f32_16x16x32_bf16 v[120:123], v[80:83], v[174:177], v[120:123]
	s_waitcnt lgkmcnt(3)
	v_mfma_f32_16x16x32_bf16 v[108:111], v[72:75], v[182:185], v[108:111]
	v_mfma_f32_16x16x32_bf16 v[104:107], v[80:83], v[182:185], v[104:107]
	s_waitcnt lgkmcnt(1)
	v_mfma_f32_16x16x32_bf16 v[92:95], v[72:75], v[190:193], v[92:95]
	v_mfma_f32_16x16x32_bf16 v[88:91], v[80:83], v[190:193], v[88:91]
	v_mfma_f32_16x16x32_bf16 v[140:143], v[76:79], v[170:173], v[140:143]
	v_mfma_f32_16x16x32_bf16 v[136:139], v[84:87], v[170:173], v[136:139]
	v_mfma_f32_16x16x32_bf16 v[124:127], v[76:79], v[178:181], v[124:127]
	v_mfma_f32_16x16x32_bf16 v[120:123], v[84:87], v[178:181], v[120:123]
	v_mfma_f32_16x16x32_bf16 v[108:111], v[76:79], v[186:189], v[108:111]
	v_mfma_f32_16x16x32_bf16 v[104:107], v[84:87], v[186:189], v[104:107]
	s_waitcnt lgkmcnt(0)
	v_mfma_f32_16x16x32_bf16 v[92:95], v[76:79], v[198:201], v[92:95]
	v_mfma_f32_16x16x32_bf16 v[88:91], v[84:87], v[198:201], v[88:91]
	s_barrier
	s_setprio 0
	s_add_i32 s28, 0, 0x1c000
	s_add_i32 s29, s58, s34
	v_add_u32_e32 v196, s28, v166
	v_lshl_add_u64 v[194:195], v[194:195], 0, s[12:13]
	s_mov_b32 m0, s29
	ds_read_b128 v[202:205], v196
	ds_read_b128 v[206:209], v196 offset:1024
	ds_read_b128 v[210:213], v196 offset:2048
	ds_read_b128 v[214:217], v196 offset:3072
	global_load_lds_dwordx4 v[194:195], off
	v_lshl_add_u64 v[194:195], v[218:219], 0, s[12:13]
	s_add_i32 m0, s29, 0x2000
	s_nop 0
	global_load_lds_dwordx4 v[194:195], off
	s_waitcnt lgkmcnt(3)
	s_setprio 1
	s_barrier
	v_mfma_f32_16x16x32_bf16 v[132:135], v[202:205], v[160:163], v[132:135]
	s_waitcnt lgkmcnt(1)
	v_mfma_f32_16x16x32_bf16 v[128:131], v[210:213], v[160:163], v[128:131]
	v_mfma_f32_16x16x32_bf16 v[116:119], v[202:205], v[174:177], v[116:119]
	v_mfma_f32_16x16x32_bf16 v[112:115], v[210:213], v[174:177], v[112:115]
	v_mfma_f32_16x16x32_bf16 v[100:103], v[202:205], v[182:185], v[100:103]
	v_mfma_f32_16x16x32_bf16 v[96:99], v[210:213], v[182:185], v[96:99]
	v_mfma_f32_16x16x32_bf16 v[68:71], v[202:205], v[190:193], v[68:71]
	v_mfma_f32_16x16x32_bf16 v[64:67], v[210:213], v[190:193], v[64:67]
	v_mfma_f32_16x16x32_bf16 v[132:135], v[206:209], v[170:173], v[132:135]
	s_mov_b32 m0, s39
	s_waitcnt lgkmcnt(0)
	v_mfma_f32_16x16x32_bf16 v[128:131], v[214:217], v[170:173], v[128:131]
	v_lshl_add_u64 v[194:195], v[220:221], 0, s[12:13]
	v_mfma_f32_16x16x32_bf16 v[116:119], v[206:209], v[178:181], v[116:119]
	v_mfma_f32_16x16x32_bf16 v[112:115], v[214:217], v[178:181], v[112:115]
	v_mfma_f32_16x16x32_bf16 v[100:103], v[206:209], v[186:189], v[100:103]
	v_mfma_f32_16x16x32_bf16 v[96:99], v[214:217], v[186:189], v[96:99]
	v_mfma_f32_16x16x32_bf16 v[68:71], v[206:209], v[198:201], v[68:71]
	v_mfma_f32_16x16x32_bf16 v[64:67], v[214:217], v[198:201], v[64:67]
	s_barrier
; #define PG8_STAGE(bufoff, gbase, voff) do { _Pragma("unroll") for (int _i = 0; _i < 2; ++_i) \
;         __builtin_amdgcn_global_load_lds((const unsigned*)((const char*)(gbase) + (voff)[_i]), (LAS unsigned*)(lds + (bufoff) + ldsw + _i * 8192), 16, 0, 0); } while (0)
; #define PG8_LDA(dst, b, h) do { _Pragma("unroll") for (int m = 0; m < 4; ++m) _Pragma("unroll") for (int k = 0; k < 2; ++k) dst[m][k] = *(const LAS bf16x8*)(lds + PG8_SA(b, h) + aoff + m * 2048 + k * 1024); } while (0)
; #define PG8_MMA(ai, bj, At, Bt) do { __builtin_amdgcn_s_setprio(1); _Pragma("unroll") for (int m = 0; m < 4; ++m) _Pragma("unroll") for (int n = 0; n < 2; ++n) _Pragma("unroll") for (int k = 0; k < 2; ++k) \
;         acc[ai][bj][m][n] = __builtin_amdgcn_mfma_f32_16x16x32_bf16(Bt[n][k], At[m][k], acc[ai][bj][m][n], 0, 0, 0); __builtin_amdgcn_s_setprio(0); } while (0)
; #define PG8_WAIT_V(n) asm volatile("s_waitcnt vmcnt(" #n ")" ::: "memory")
; #define PG8_WAIT_L(n) asm volatile("s_waitcnt lgkmcnt(" #n ")" ::: "memory")
; #define PG8_BAR __builtin_amdgcn_s_barrier()
; #define PG8_SCHED __builtin_amdgcn_sched_barrier(0)
;     DI void operator()(const f32x4 (&acc)[2][2][4][2], const Unit& u, int wr, int wc, int fr, int fq) const {
;         const int row0 = u.pm * BM + wr * 64 + fr, col0 = u.pn * BM + wc * 32 + 8 * fq;
;         f32x4 sc[2][2];
; #pragma unroll
;         for (int bj = 0; bj < 2; ++bj)
; #pragma unroll
;             for (int n = 0; n < 2; ++n) sc[bj][n] = scale ? *(const f32x4*)(scale + col0 + bj * HALF + 4 * n) : (f32x4){1.f, 1.f, 1.f, 1.f};
; #pragma unroll
; template <class Map, class Epi>
; DI void gemm_phase(LAS unsigned char* lds, const Map& MP, const Epi& E, const int nM, const int nN, const int K, const int lda, const int ldb) {
;     ...
;             PG8_LDA(At, 1, 1); PG8_STAGE(PG8_SA(1, 0), a3, voffA);
;             PG8_BAR; PG8_WAIT_L(0); PG8_MMA(1, 0, At, B0); PG8_BAR; PG8_SCHED;
;             PG8_STAGE(PG8_SB(1, 1), b3 + hstepB, voffB);
;             PG8_WAIT_V(6); PG8_BAR; PG8_MMA(1, 1, At, B1); PG8_BAR;
	s_setprio 0
	ds_read_b128 v[160:163], v168 offset:49152
	ds_read_b128 v[170:173], v168 offset:50176
	ds_read_b128 v[174:177], v168 offset:51200
	ds_read_b128 v[178:181], v168 offset:52224
	ds_read_b128 v[182:185], v168 offset:53248
	ds_read_b128 v[186:189], v168 offset:54272
	ds_read_b128 v[190:193], v168 offset:55296
	ds_read_b128 v[198:201], v168 offset:56320
	global_load_lds_dwordx4 v[194:195], off
	v_lshl_add_u64 v[194:195], v[222:223], 0, s[12:13]
	s_mov_b32 m0, s46
	s_nop 0
	global_load_lds_dwordx4 v[194:195], off
	s_waitcnt vmcnt(10) lgkmcnt(7)
	s_setprio 1
	s_barrier
	v_mfma_f32_16x16x32_bf16 v[60:63], v[72:75], v[160:163], v[60:63]
	v_mfma_f32_16x16x32_bf16 v[56:59], v[80:83], v[160:163], v[56:59]
	s_waitcnt lgkmcnt(5)
	v_mfma_f32_16x16x32_bf16 v[44:47], v[72:75], v[174:177], v[44:47]
	v_mfma_f32_16x16x32_bf16 v[40:43], v[80:83], v[174:177], v[40:43]
	s_waitcnt lgkmcnt(3)
	v_mfma_f32_16x16x32_bf16 v[28:31], v[72:75], v[182:185], v[28:31]
	v_mfma_f32_16x16x32_bf16 v[24:27], v[80:83], v[182:185], v[24:27]
	s_waitcnt lgkmcnt(1)
	v_mfma_f32_16x16x32_bf16 v[12:15], v[72:75], v[190:193], v[12:15]
	v_mfma_f32_16x16x32_bf16 v[8:11], v[80:83], v[190:193], v[8:11]
	v_mfma_f32_16x16x32_bf16 v[60:63], v[76:79], v[170:173], v[60:63]
	v_mfma_f32_16x16x32_bf16 v[56:59], v[84:87], v[170:173], v[56:59]
	v_mfma_f32_16x16x32_bf16 v[44:47], v[76:79], v[178:181], v[44:47]
	v_mfma_f32_16x16x32_bf16 v[40:43], v[84:87], v[178:181], v[40:43]
	v_mfma_f32_16x16x32_bf16 v[28:31], v[76:79], v[186:189], v[28:31]
	v_mfma_f32_16x16x32_bf16 v[24:27], v[84:87], v[186:189], v[24:27]
	s_waitcnt lgkmcnt(0)
	v_mfma_f32_16x16x32_bf16 v[12:15], v[76:79], v[198:201], v[12:15]
	v_mfma_f32_16x16x32_bf16 v[8:11], v[84:87], v[198:201], v[8:11]
	s_barrier
	s_setprio 0
	s_add_u32 s26, s26, 0x20080
	s_addc_u32 s27, s27, 0
	s_add_i32 s28, s28, s34
	s_mov_b32 m0, s28
	s_nop 0
	global_load_lds_dwordx4 v148, s[26:27]
	s_add_i32 m0, s28, 0x2000
	s_nop 0
	global_load_lds_dwordx4 v144, s[26:27]
	s_waitcnt vmcnt(6)
	s_setprio 1
	s_barrier
	v_mfma_f32_16x16x32_bf16 v[52:55], v[202:205], v[160:163], v[52:55]
	v_mfma_f32_16x16x32_bf16 v[48:51], v[210:213], v[160:163], v[48:51]
	ds_read_b128 v[72:75], v167
	v_mfma_f32_16x16x32_bf16 v[36:39], v[202:205], v[174:177], v[36:39]
	v_mfma_f32_16x16x32_bf16 v[32:35], v[210:213], v[174:177], v[32:35]
	ds_read_b128 v[76:79], v167 offset:1024
	v_mfma_f32_16x16x32_bf16 v[20:23], v[202:205], v[182:185], v[20:23]
	v_mfma_f32_16x16x32_bf16 v[16:19], v[210:213], v[182:185], v[16:19]
	ds_read_b128 v[80:83], v167 offset:2048
	v_mfma_f32_16x16x32_bf16 v[4:7], v[202:205], v[190:193], v[4:7]
	v_mfma_f32_16x16x32_bf16 v[0:3], v[210:213], v[190:193], v[0:3]
	ds_read_b128 v[84:87], v167 offset:3072
	v_mfma_f32_16x16x32_bf16 v[52:55], v[206:209], v[170:173], v[52:55]
	s_add_i32 s57, s57, 2
	v_mfma_f32_16x16x32_bf16 v[48:51], v[214:217], v[170:173], v[48:51]
	s_add_u32 s55, s55, 0x100
	s_addc_u32 s56, s56, 0
	v_mfma_f32_16x16x32_bf16 v[36:39], v[206:209], v[178:181], v[36:39]
	s_add_u32 s24, s24, 0x100
	s_addc_u32 s25, s25, 0
	v_mfma_f32_16x16x32_bf16 v[32:35], v[214:217], v[178:181], v[32:35]
	s_cmp_gt_u32 s57, 5
	v_mfma_f32_16x16x32_bf16 v[20:23], v[206:209], v[186:189], v[20:23]
	v_mfma_f32_16x16x32_bf16 v[16:19], v[214:217], v[186:189], v[16:19]
	v_mfma_f32_16x16x32_bf16 v[4:7], v[206:209], v[198:201], v[4:7]
	v_mfma_f32_16x16x32_bf16 v[0:3], v[214:217], v[198:201], v[0:3]
	s_barrier
	s_setprio 0
	s_cbranch_scc0 .LBB1_229
	s_waitcnt lgkmcnt(0)
	s_lshl_b32 s17, s42, 8
	v_mov_b32_e32 v170, v164
	v_mov_b32_e32 v72, v165
	s_or_b32 s17, s17, s38
	v_mov_b32_e32 v80, 1.0
	v_lshl_add_u32 v160, v72, 3, s17
	v_ashrrev_i32_e32 v161, 31, v160
	v_cndmask_b32_e64 v72, 0, 1, s[14:15]
	v_lshl_add_u64 v[162:163], v[160:161], 2, s[8:9]
	v_cmp_ne_u32_e64 s[42:43], 1, v72
	s_andn2_b64 vcc, exec, s[14:15]
	v_mov_b32_e32 v84, 1.0
	v_mov_b32_e32 v85, 1.0
	v_mov_b32_e32 v86, 1.0
	v_mov_b32_e32 v87, 1.0
	s_cbranch_vccnz .LBB1_232
	global_load_dwordx4 v[84:87], v[162:163], off

; #define PG8_STAGE(bufoff, gbase, voff) do { _Pragma("unroll") for (int _i = 0; _i < 2; ++_i) \
;         __builtin_amdgcn_global_load_lds((const unsigned*)((const char*)(gbase) + (voff)[_i]), (LAS unsigned*)(lds + (bufoff) + ldsw + _i * 8192), 16, 0, 0); } while (0)
; #define PG8_LDA(dst, b, h) do { _Pragma("unroll") for (int m = 0; m < 4; ++m) _Pragma("unroll") for (int k = 0; k < 2; ++k) dst[m][k] = *(const LAS bf16x8*)(lds + PG8_SA(b, h) + aoff + m * 2048 + k * 1024); } while (0)
; #define PG8_LDB(dst, b, h) do { _Pragma("unroll") for (int n = 0; n < 2; ++n) _Pragma("unroll") for (int k = 0; k < 2; ++k) dst[n][k] = *(const LAS bf16x8*)(lds + PG8_SB(b, h) + boff + n * 2048 + k * 1024); } while (0)
; #define PG8_MMA(ai, bj, At, Bt) do { __builtin_amdgcn_s_setprio(1); _Pragma("unroll") for (int m = 0; m < 4; ++m) _Pragma("unroll") for (int n = 0; n < 2; ++n) _Pragma("unroll") for (int k = 0; k < 2; ++k) \
;         acc[ai][bj][m][n] = __builtin_amdgcn_mfma_f32_16x16x32_bf16(Bt[n][k], At[m][k], acc[ai][bj][m][n], 0, 0, 0); __builtin_amdgcn_s_setprio(0); } while (0)
; #define PG8_WAIT_V(n) asm volatile("s_waitcnt vmcnt(" #n ")" ::: "memory")
; #define PG8_WAIT_L(n) asm volatile("s_waitcnt lgkmcnt(" #n ")" ::: "memory")
; template <class Map, class Epi>
; DI void gemm_phase(LAS unsigned char* lds, const Map& MP, const Epi& E, const int nM, const int nN, const int K, const int lda, const int ldb) {
;     ...
;             const bool last = (t == nt - 2);
;             const char* a1 = cA + (size_t)(t + 1) * kstep;
;             const char* a2 = last ? nA : cA + (size_t)(t + 2) * kstep; const char* b2 = last ? nB : cB + (size_t)(t + 2) * kstep;
;             const char* a3 = a2 + kstep; const char* b3 = b2 + kstep;
;             PG8_LDB(B0, 0, 0); PG8_SCHED; PG8_LDA(At, 0, 0); PG8_STAGE(PG8_SA(1, 1), a1 + hstepA, voffA);
;             PG8_WAIT_L(8); PG8_BAR; PG8_WAIT_L(0); PG8_MMA(0, 0, At, B0); PG8_BAR; PG8_SCHED;
;             PG8_LDB(B1, 0, 1); PG8_STAGE(PG8_SB(0, 0), b2, voffB);
;             PG8_BAR; PG8_WAIT_L(0); PG8_MMA(0, 1, At, B1); PG8_BAR;
;             PG8_LDA(At, 0, 1); PG8_STAGE(PG8_SA(0, 0), a2, voffA);
;             PG8_BAR; PG8_WAIT_L(0); PG8_MMA(1, 0, At, B0); PG8_BAR; PG8_SCHED;
;             PG8_STAGE(PG8_SB(0, 1), b2 + hstepB, voffB);
;             PG8_WAIT_V(6); PG8_BAR; PG8_MMA(1, 1, At, B1); PG8_BAR;
.LBB1_380:
	s_add_u32 s28, s44, 0xfff80080
	s_addc_u32 s29, s45, -1
	s_cmp_eq_u32 vcc_hi, 28
	s_cselect_b32 s47, s23, s29
	s_cselect_b32 s46, s61, s28
	s_cselect_b32 s29, s21, vcc_lo
	s_cselect_b32 s28, s58, s59
	s_add_i32 m0, s38, 0xc000
	ds_read_b128 v[96:99], v190
	ds_read_b128 v[100:103], v190 offset:1024
	ds_read_b128 v[108:111], v190 offset:2048
	ds_read_b128 v[112:115], v190 offset:3072
	ds_read_b128 v[160:163], v190 offset:4096
	ds_read_b128 v[164:167], v190 offset:5120
	ds_read_b128 v[198:201], v190 offset:6144
	ds_read_b128 v[202:205], v190 offset:7168
	global_load_lds_dwordx4 v178, s[44:45]
	s_add_i32 m0, s38, 0xe000
	s_nop 0
	global_load_lds_dwordx4 v176, s[44:45]
	s_waitcnt lgkmcnt(7)
	s_setprio 1
	s_barrier
	v_mfma_f32_16x16x32_bf16 v[148:151], v[80:83], v[96:99], v[148:151]
	v_mfma_f32_16x16x32_bf16 v[144:147], v[88:91], v[96:99], v[144:147]
	s_waitcnt lgkmcnt(5)
	v_mfma_f32_16x16x32_bf16 v[136:139], v[80:83], v[108:111], v[136:139]
	v_mfma_f32_16x16x32_bf16 v[128:131], v[88:91], v[108:111], v[128:131]
	s_waitcnt lgkmcnt(3)
	v_mfma_f32_16x16x32_bf16 v[120:123], v[80:83], v[160:163], v[120:123]
	v_mfma_f32_16x16x32_bf16 v[104:107], v[88:91], v[160:163], v[104:107]
	s_waitcnt lgkmcnt(1)
	v_mfma_f32_16x16x32_bf16 v[76:79], v[80:83], v[198:201], v[76:79]
	v_mfma_f32_16x16x32_bf16 v[72:75], v[88:91], v[198:201], v[72:75]
	v_mfma_f32_16x16x32_bf16 v[148:151], v[84:87], v[100:103], v[148:151]
	v_mfma_f32_16x16x32_bf16 v[144:147], v[92:95], v[100:103], v[144:147]
	v_mfma_f32_16x16x32_bf16 v[136:139], v[84:87], v[112:115], v[136:139]
	v_mfma_f32_16x16x32_bf16 v[128:131], v[92:95], v[112:115], v[128:131]
	v_mfma_f32_16x16x32_bf16 v[120:123], v[84:87], v[164:167], v[120:123]
	v_mfma_f32_16x16x32_bf16 v[104:107], v[92:95], v[164:167], v[104:107]
	s_waitcnt lgkmcnt(0)
	v_mfma_f32_16x16x32_bf16 v[76:79], v[84:87], v[202:205], v[76:79]
	v_mfma_f32_16x16x32_bf16 v[72:75], v[92:95], v[202:205], v[72:75]
	s_barrier
	s_setprio 0
	s_add_i32 s68, s5, s37
	v_lshl_add_u64 v[184:185], s[28:29], 0, v[172:173]
	s_mov_b32 m0, s68
	ds_read_b128 v[206:209], v191
	ds_read_b128 v[210:213], v191 offset:1024
	ds_read_b128 v[214:217], v191 offset:2048
	ds_read_b128 v[218:221], v191 offset:3072
	global_load_lds_dwordx4 v[184:185], off
	v_lshl_add_u64 v[194:195], s[28:29], 0, v[168:169]
	s_add_i32 m0, s68, 0x2000
	s_nop 0
	global_load_lds_dwordx4 v[194:195], off
	s_waitcnt lgkmcnt(3)
	s_setprio 1
	s_barrier
	v_mfma_f32_16x16x32_bf16 v[156:159], v[206:209], v[96:99], v[156:159]
	s_waitcnt lgkmcnt(1)
	v_mfma_f32_16x16x32_bf16 v[96:99], v[214:217], v[96:99], v[152:155]
	v_mfma_f32_16x16x32_bf16 v[156:159], v[210:213], v[100:103], v[156:159]
	s_waitcnt lgkmcnt(0)
	v_mfma_f32_16x16x32_bf16 v[96:99], v[218:221], v[100:103], v[96:99]
	v_mfma_f32_16x16x32_bf16 v[100:103], v[206:209], v[108:111], v[140:143]
	v_mfma_f32_16x16x32_bf16 v[108:111], v[214:217], v[108:111], v[132:135]
	v_mfma_f32_16x16x32_bf16 v[116:119], v[214:217], v[160:163], v[116:119]
	v_mfma_f32_16x16x32_bf16 v[68:71], v[206:209], v[198:201], v[68:71]
	v_mfma_f32_16x16x32_bf16 v[64:67], v[214:217], v[198:201], v[64:67]
	s_mov_b32 m0, s38
	v_mfma_f32_16x16x32_bf16 v[100:103], v[210:213], v[112:115], v[100:103]
	v_lshl_add_u64 v[226:227], s[46:47], 0, v[174:175]
	v_mfma_f32_16x16x32_bf16 v[108:111], v[218:221], v[112:115], v[108:111]
	v_mfma_f32_16x16x32_bf16 v[112:115], v[206:209], v[160:163], v[124:127]
	v_mfma_f32_16x16x32_bf16 v[116:119], v[218:221], v[164:167], v[116:119]
	v_mfma_f32_16x16x32_bf16 v[68:71], v[210:213], v[202:205], v[68:71]
	v_mfma_f32_16x16x32_bf16 v[64:67], v[218:221], v[202:205], v[64:67]
	v_mfma_f32_16x16x32_bf16 v[112:115], v[210:213], v[164:167], v[112:115]
	s_barrier
	s_setprio 0
	ds_read_b128 v[124:127], v190 offset:16384
	ds_read_b128 v[132:135], v190 offset:17408
	ds_read_b128 v[140:143], v190 offset:18432
	ds_read_b128 v[152:155], v190 offset:19456
	ds_read_b128 v[160:163], v190 offset:20480
	ds_read_b128 v[164:167], v190 offset:21504
	ds_read_b128 v[198:201], v190 offset:22528
	ds_read_b128 v[202:205], v190 offset:23552
	global_load_lds_dwordx4 v[226:227], off
	v_lshl_add_u64 v[234:235], s[46:47], 0, v[170:171]
	s_mov_b32 m0, s39
	s_nop 0
	global_load_lds_dwordx4 v[234:235], off
	s_waitcnt vmcnt(10) lgkmcnt(7)
	s_setprio 1
	s_barrier
	v_mfma_f32_16x16x32_bf16 v[60:63], v[80:83], v[124:127], v[60:63]
	v_mfma_f32_16x16x32_bf16 v[48:51], v[88:91], v[124:127], v[48:51]
	s_waitcnt lgkmcnt(5)
	v_mfma_f32_16x16x32_bf16 v[40:43], v[80:83], v[140:143], v[40:43]
	v_mfma_f32_16x16x32_bf16 v[32:35], v[88:91], v[140:143], v[32:35]
	s_waitcnt lgkmcnt(3)
	v_mfma_f32_16x16x32_bf16 v[24:27], v[80:83], v[160:163], v[24:27]
	v_mfma_f32_16x16x32_bf16 v[16:19], v[88:91], v[160:163], v[16:19]
	s_waitcnt lgkmcnt(1)
	v_mfma_f32_16x16x32_bf16 v[12:15], v[80:83], v[198:201], v[12:15]
	v_mfma_f32_16x16x32_bf16 v[8:11], v[88:91], v[198:201], v[8:11]
	v_mfma_f32_16x16x32_bf16 v[60:63], v[84:87], v[132:135], v[60:63]
	v_mfma_f32_16x16x32_bf16 v[48:51], v[92:95], v[132:135], v[48:51]
	v_mfma_f32_16x16x32_bf16 v[40:43], v[84:87], v[152:155], v[40:43]
	v_mfma_f32_16x16x32_bf16 v[32:35], v[92:95], v[152:155], v[32:35]
	v_mfma_f32_16x16x32_bf16 v[24:27], v[84:87], v[164:167], v[24:27]
	v_mfma_f32_16x16x32_bf16 v[16:19], v[92:95], v[164:167], v[16:19]
	s_waitcnt lgkmcnt(0)
	v_mfma_f32_16x16x32_bf16 v[12:15], v[84:87], v[202:205], v[12:15]
	v_mfma_f32_16x16x32_bf16 v[8:11], v[92:95], v[202:205], v[8:11]
	s_barrier
	s_setprio 0
	s_add_u32 s68, s28, 0x80000
	s_addc_u32 s69, s29, 0
	s_add_i32 s70, s2, s37
	s_mov_b32 m0, s70
	s_nop 0
	global_load_lds_dwordx4 v172, s[68:69]
	s_add_i32 m0, s70, 0x2000
	s_nop 0
	global_load_lds_dwordx4 v168, s[68:69]
	s_waitcnt vmcnt(6)
	s_setprio 1
	s_barrier
; #define PG8_STAGE(bufoff, gbase, voff) do { _Pragma("unroll") for (int _i = 0; _i < 2; ++_i) \
;         __builtin_amdgcn_global_load_lds((const unsigned*)((const char*)(gbase) + (voff)[_i]), (LAS unsigned*)(lds + (bufoff) + ldsw + _i * 8192), 16, 0, 0); } while (0)
; #define PG8_LDA(dst, b, h) do { _Pragma("unroll") for (int m = 0; m < 4; ++m) _Pragma("unroll") for (int k = 0; k < 2; ++k) dst[m][k] = *(const LAS bf16x8*)(lds + PG8_SA(b, h) + aoff + m * 2048 + k * 1024); } while (0)
; #define PG8_LDB(dst, b, h) do { _Pragma("unroll") for (int n = 0; n < 2; ++n) _Pragma("unroll") for (int k = 0; k < 2; ++k) dst[n][k] = *(const LAS bf16x8*)(lds + PG8_SB(b, h) + boff + n * 2048 + k * 1024); } while (0)
; #define PG8_MMA(ai, bj, At, Bt) do { __builtin_amdgcn_s_setprio(1); _Pragma("unroll") for (int m = 0; m < 4; ++m) _Pragma("unroll") for (int n = 0; n < 2; ++n) _Pragma("unroll") for (int k = 0; k < 2; ++k) \
;         acc[ai][bj][m][n] = __builtin_amdgcn_mfma_f32_16x16x32_bf16(Bt[n][k], At[m][k], acc[ai][bj][m][n], 0, 0, 0); __builtin_amdgcn_s_setprio(0); } while (0)
; #define PG8_WAIT_V(n) asm volatile("s_waitcnt vmcnt(" #n ")" ::: "memory")
; #define PG8_WAIT_L(n) asm volatile("s_waitcnt lgkmcnt(" #n ")" ::: "memory")
; #define PG8_BAR __builtin_amdgcn_s_barrier()
; #define PG8_SCHED __builtin_amdgcn_sched_barrier(0)
; template <class Map, class Epi>
; DI void gemm_phase(LAS unsigned char* lds, const Map& MP, const Epi& E, const int nM, const int nN, const int K, const int lda, const int ldb) {
;     ...
;             PG8_BAR; PG8_WAIT_L(0); PG8_MMA(1, 0, At, B0); PG8_BAR; PG8_SCHED;
;             PG8_STAGE(PG8_SB(0, 1), b2 + hstepB, voffB);
;             PG8_WAIT_V(6); PG8_BAR; PG8_MMA(1, 1, At, B1); PG8_BAR;
;             PG8_LDB(B0, 1, 0); PG8_SCHED; PG8_LDA(At, 1, 0); PG8_STAGE(PG8_SA(0, 1), a2 + hstepA, voffA);
;             PG8_WAIT_L(8); PG8_BAR; PG8_WAIT_L(0); PG8_MMA(0, 0, At, B0); PG8_BAR; PG8_SCHED;
	v_mfma_f32_16x16x32_bf16 v[56:59], v[206:209], v[124:127], v[56:59]
	v_mfma_f32_16x16x32_bf16 v[52:55], v[214:217], v[124:127], v[52:55]
	s_add_i32 s68, 0, 0x18000
	v_add_u32_e32 v92, s68, v188
	ds_read_b128 v[80:83], v92
	v_mfma_f32_16x16x32_bf16 v[44:47], v[206:209], v[140:143], v[44:47]
	v_mfma_f32_16x16x32_bf16 v[36:39], v[214:217], v[140:143], v[36:39]
	ds_read_b128 v[84:87], v92 offset:1024
	v_mfma_f32_16x16x32_bf16 v[28:31], v[206:209], v[160:163], v[28:31]
	v_mfma_f32_16x16x32_bf16 v[20:23], v[214:217], v[160:163], v[20:23]
	ds_read_b128 v[88:91], v92 offset:2048
	v_mfma_f32_16x16x32_bf16 v[4:7], v[206:209], v[198:201], v[4:7]
	v_mfma_f32_16x16x32_bf16 v[0:3], v[214:217], v[198:201], v[0:3]
	ds_read_b128 v[92:95], v92 offset:3072
	v_mfma_f32_16x16x32_bf16 v[56:59], v[210:213], v[132:135], v[56:59]
	v_mfma_f32_16x16x32_bf16 v[52:55], v[218:221], v[132:135], v[52:55]
	v_mfma_f32_16x16x32_bf16 v[44:47], v[210:213], v[152:155], v[44:47]
	v_mfma_f32_16x16x32_bf16 v[36:39], v[218:221], v[152:155], v[36:39]
	v_mfma_f32_16x16x32_bf16 v[28:31], v[210:213], v[164:167], v[28:31]
	v_mfma_f32_16x16x32_bf16 v[20:23], v[218:221], v[164:167], v[20:23]
	v_mfma_f32_16x16x32_bf16 v[4:7], v[210:213], v[202:205], v[4:7]
	v_mfma_f32_16x16x32_bf16 v[0:3], v[218:221], v[202:205], v[0:3]
	s_barrier
	s_setprio 0
	s_add_u32 s46, s46, 0x80000
	s_addc_u32 s47, s47, 0
	s_mov_b32 m0, s56
	ds_read_b128 v[124:127], v190 offset:32768
	ds_read_b128 v[132:135], v190 offset:33792
	ds_read_b128 v[160:163], v190 offset:34816
	ds_read_b128 v[164:167], v190 offset:35840
	ds_read_b128 v[198:201], v190 offset:36864
	ds_read_b128 v[202:205], v190 offset:37888
	ds_read_b128 v[206:209], v190 offset:38912
	ds_read_b128 v[210:213], v190 offset:39936
	global_load_lds_dwordx4 v174, s[46:47]
	s_mov_b32 m0, s57
	s_nop 0
	global_load_lds_dwordx4 v170, s[46:47]
	s_waitcnt lgkmcnt(7)
	s_setprio 1
	s_barrier
	v_mfma_f32_16x16x32_bf16 v[140:143], v[80:83], v[124:127], v[148:151]
	s_waitcnt lgkmcnt(6)
	v_mfma_f32_16x16x32_bf16 v[148:151], v[84:87], v[132:135], v[140:143]
	v_mfma_f32_16x16x32_bf16 v[140:143], v[88:91], v[124:127], v[144:147]
	s_waitcnt lgkmcnt(5)
	v_mfma_f32_16x16x32_bf16 v[136:139], v[80:83], v[160:163], v[136:139]
	v_mfma_f32_16x16x32_bf16 v[128:131], v[88:91], v[160:163], v[128:131]
	s_waitcnt lgkmcnt(3)
	v_mfma_f32_16x16x32_bf16 v[120:123], v[80:83], v[198:201], v[120:123]
	v_mfma_f32_16x16x32_bf16 v[104:107], v[88:91], v[198:201], v[104:107]
	s_waitcnt lgkmcnt(1)
	v_mfma_f32_16x16x32_bf16 v[76:79], v[80:83], v[206:209], v[76:79]
	v_mfma_f32_16x16x32_bf16 v[72:75], v[88:91], v[206:209], v[72:75]
	v_mfma_f32_16x16x32_bf16 v[144:147], v[92:95], v[132:135], v[140:143]
	v_mfma_f32_16x16x32_bf16 v[136:139], v[84:87], v[164:167], v[136:139]
	v_mfma_f32_16x16x32_bf16 v[128:131], v[92:95], v[164:167], v[128:131]
	v_mfma_f32_16x16x32_bf16 v[120:123], v[84:87], v[202:205], v[120:123]
	v_mfma_f32_16x16x32_bf16 v[104:107], v[92:95], v[202:205], v[104:107]
	s_waitcnt lgkmcnt(0)
	v_mfma_f32_16x16x32_bf16 v[76:79], v[84:87], v[210:213], v[76:79]
	v_mfma_f32_16x16x32_bf16 v[72:75], v[92:95], v[210:213], v[72:75]
	s_barrier
	s_setprio 0
	s_add_i32 s46, 0, 0x1c000
	v_add_u32_e32 v140, s46, v188
	s_add_i32 s47, s68, s37
	ds_read_b128 v[214:217], v140
	ds_read_b128 v[218:221], v140 offset:1024
	ds_read_b128 v[222:225], v140 offset:2048
	ds_read_b128 v[230:233], v140 offset:3072
	v_lshl_add_u64 v[140:141], v[184:185], 0, s[14:15]
	s_mov_b32 m0, s47
	s_nop 0
	global_load_lds_dwordx4 v[140:141], off
	v_lshl_add_u64 v[140:141], v[194:195], 0, s[14:15]
	s_add_i32 m0, s47, 0x2000
	s_nop 0
	global_load_lds_dwordx4 v[140:141], off
	s_waitcnt lgkmcnt(1)
	s_setprio 1
	s_barrier
	v_mfma_f32_16x16x32_bf16 v[96:99], v[222:225], v[124:127], v[96:99]
	v_mfma_f32_16x16x32_bf16 v[140:143], v[214:217], v[124:127], v[156:159]
	s_waitcnt lgkmcnt(0)
	v_mfma_f32_16x16x32_bf16 v[152:155], v[230:233], v[132:135], v[96:99]
	v_mfma_f32_16x16x32_bf16 v[96:99], v[214:217], v[160:163], v[100:103]
	v_mfma_f32_16x16x32_bf16 v[156:159], v[218:221], v[132:135], v[140:143]
	v_mfma_f32_16x16x32_bf16 v[140:143], v[218:221], v[164:167], v[96:99]
	v_mfma_f32_16x16x32_bf16 v[96:99], v[222:225], v[160:163], v[108:111]
	v_mfma_f32_16x16x32_bf16 v[132:135], v[230:233], v[164:167], v[96:99]
	v_mfma_f32_16x16x32_bf16 v[96:99], v[214:217], v[198:201], v[112:115]
	s_mov_b32 m0, s62
	v_mfma_f32_16x16x32_bf16 v[124:127], v[218:221], v[202:205], v[96:99]
	v_lshl_add_u64 v[184:185], v[226:227], 0, s[14:15]
	v_mfma_f32_16x16x32_bf16 v[96:99], v[222:225], v[198:201], v[116:119]
	v_mfma_f32_16x16x32_bf16 v[68:71], v[214:217], v[206:209], v[68:71]
	v_mfma_f32_16x16x32_bf16 v[64:67], v[222:225], v[206:209], v[64:67]
	v_mfma_f32_16x16x32_bf16 v[116:119], v[230:233], v[202:205], v[96:99]
	v_mfma_f32_16x16x32_bf16 v[68:71], v[218:221], v[210:213], v[68:71]
	v_mfma_f32_16x16x32_bf16 v[64:67], v[230:233], v[210:213], v[64:67]
	s_barrier
	s_setprio 0
	ds_read_b128 v[96:99], v190 offset:49152
	ds_read_b128 v[100:103], v190 offset:50176
	ds_read_b128 v[108:111], v190 offset:51200
	ds_read_b128 v[112:115], v190 offset:52224
	ds_read_b128 v[160:163], v190 offset:53248
	ds_read_b128 v[164:167], v190 offset:54272
	ds_read_b128 v[198:201], v190 offset:55296
	ds_read_b128 v[202:205], v190 offset:56320
	global_load_lds_dwordx4 v[184:185], off
	v_lshl_add_u64 v[184:185], v[234:235], 0, s[14:15]
	s_mov_b32 m0, s63
	s_nop 0
	global_load_lds_dwordx4 v[184:185], off
	s_waitcnt vmcnt(10) lgkmcnt(7)
	s_setprio 1
	s_barrier
; #define PG8_STAGE(bufoff, gbase, voff) do { _Pragma("unroll") for (int _i = 0; _i < 2; ++_i) \
;         __builtin_amdgcn_global_load_lds((const unsigned*)((const char*)(gbase) + (voff)[_i]), (LAS unsigned*)(lds + (bufoff) + ldsw + _i * 8192), 16, 0, 0); } while (0)
; #define PG8_MMA(ai, bj, At, Bt) do { __builtin_amdgcn_s_setprio(1); _Pragma("unroll") for (int m = 0; m < 4; ++m) _Pragma("unroll") for (int n = 0; n < 2; ++n) _Pragma("unroll") for (int k = 0; k < 2; ++k) \
;         acc[ai][bj][m][n] = __builtin_amdgcn_mfma_f32_16x16x32_bf16(Bt[n][k], At[m][k], acc[ai][bj][m][n], 0, 0, 0); __builtin_amdgcn_s_setprio(0); } while (0)
; #define PG8_WAIT_V(n) asm volatile("s_waitcnt vmcnt(" #n ")" ::: "memory")
; #define PG8_WAIT_L(n) asm volatile("s_waitcnt lgkmcnt(" #n ")" ::: "memory")
; #define PG8_BAR __builtin_amdgcn_s_barrier()
; #define PG8_SCHED __builtin_amdgcn_sched_barrier(0)
; template <class Map, class Epi>
; DI void gemm_phase(LAS unsigned char* lds, const Map& MP, const Epi& E, const int nM, const int nN, const int K, const int lda, const int ldb) {
;     ...
;             PG8_BAR; PG8_WAIT_L(0); PG8_MMA(1, 0, At, B0); PG8_BAR; PG8_SCHED;
;             PG8_STAGE(PG8_SB(1, 1), b3 + hstepB, voffB);
;             PG8_WAIT_V(6); PG8_BAR; PG8_MMA(1, 1, At, B1); PG8_BAR;
;         }
	v_mfma_f32_16x16x32_bf16 v[60:63], v[80:83], v[96:99], v[60:63]
	v_mfma_f32_16x16x32_bf16 v[48:51], v[88:91], v[96:99], v[48:51]
	s_waitcnt lgkmcnt(5)
	v_mfma_f32_16x16x32_bf16 v[40:43], v[80:83], v[108:111], v[40:43]
	v_mfma_f32_16x16x32_bf16 v[32:35], v[88:91], v[108:111], v[32:35]
	s_waitcnt lgkmcnt(3)
	v_mfma_f32_16x16x32_bf16 v[24:27], v[80:83], v[160:163], v[24:27]
	v_mfma_f32_16x16x32_bf16 v[16:19], v[88:91], v[160:163], v[16:19]
	s_waitcnt lgkmcnt(1)
	v_mfma_f32_16x16x32_bf16 v[12:15], v[80:83], v[198:201], v[12:15]
	v_mfma_f32_16x16x32_bf16 v[8:11], v[88:91], v[198:201], v[8:11]
	v_mfma_f32_16x16x32_bf16 v[60:63], v[84:87], v[100:103], v[60:63]
	v_mfma_f32_16x16x32_bf16 v[48:51], v[92:95], v[100:103], v[48:51]
	v_mfma_f32_16x16x32_bf16 v[40:43], v[84:87], v[112:115], v[40:43]
	v_mfma_f32_16x16x32_bf16 v[32:35], v[92:95], v[112:115], v[32:35]
	v_mfma_f32_16x16x32_bf16 v[24:27], v[84:87], v[164:167], v[24:27]
	v_mfma_f32_16x16x32_bf16 v[16:19], v[92:95], v[164:167], v[16:19]
	s_waitcnt lgkmcnt(0)
	v_mfma_f32_16x16x32_bf16 v[12:15], v[84:87], v[202:205], v[12:15]
	v_mfma_f32_16x16x32_bf16 v[8:11], v[92:95], v[202:205], v[8:11]
	s_barrier
	s_setprio 0
	s_add_u32 s28, s28, 0x80080
	s_addc_u32 s29, s29, 0
	s_add_i32 s46, s46, s37
	s_mov_b32 m0, s46
	s_nop 0
	global_load_lds_dwordx4 v172, s[28:29]
	s_add_i32 m0, s46, 0x2000
	s_nop 0
	global_load_lds_dwordx4 v168, s[28:29]
	s_waitcnt vmcnt(6)
	s_setprio 1
	s_barrier
	v_mfma_f32_16x16x32_bf16 v[56:59], v[214:217], v[96:99], v[56:59]
	v_mfma_f32_16x16x32_bf16 v[52:55], v[222:225], v[96:99], v[52:55]
	ds_read_b128 v[80:83], v189
	v_mfma_f32_16x16x32_bf16 v[44:47], v[214:217], v[108:111], v[44:47]
	v_mfma_f32_16x16x32_bf16 v[36:39], v[222:225], v[108:111], v[36:39]
	ds_read_b128 v[84:87], v189 offset:1024
	v_mfma_f32_16x16x32_bf16 v[28:31], v[214:217], v[160:163], v[28:31]
	v_mfma_f32_16x16x32_bf16 v[20:23], v[222:225], v[160:163], v[20:23]
	ds_read_b128 v[88:91], v189 offset:2048
	v_mfma_f32_16x16x32_bf16 v[4:7], v[214:217], v[198:201], v[4:7]
	v_mfma_f32_16x16x32_bf16 v[0:3], v[222:225], v[198:201], v[0:3]
	ds_read_b128 v[92:95], v189 offset:3072
	v_mfma_f32_16x16x32_bf16 v[56:59], v[218:221], v[100:103], v[56:59]
	s_add_i32 vcc_hi, vcc_hi, 2
	v_mfma_f32_16x16x32_bf16 v[52:55], v[230:233], v[100:103], v[52:55]
	s_add_u32 s59, s59, 0x100
	s_addc_u32 vcc_lo, vcc_lo, 0
	v_mfma_f32_16x16x32_bf16 v[44:47], v[218:221], v[112:115], v[44:47]
	s_add_u32 s44, s44, 0x100
	s_addc_u32 s45, s45, 0
	v_mfma_f32_16x16x32_bf16 v[36:39], v[230:233], v[112:115], v[36:39]
	s_cmp_gt_u32 vcc_hi, 29
	v_mfma_f32_16x16x32_bf16 v[28:31], v[218:221], v[164:167], v[28:31]
	v_mfma_f32_16x16x32_bf16 v[20:23], v[230:233], v[164:167], v[20:23]
	v_mfma_f32_16x16x32_bf16 v[4:7], v[218:221], v[202:205], v[4:7]
	v_mfma_f32_16x16x32_bf16 v[0:3], v[230:233], v[202:205], v[0:3]
	s_barrier
	s_setprio 0
	s_cbranch_scc0 .LBB1_380
; DI float silu_mul(float g, float v) { return g * v * __builtin_amdgcn_rcpf(1.0f + __builtin_amdgcn_exp2f(-LOG2E * g)); }
;     DI void operator()(const f32x4 (&acc)[2][2][4][2], const Unit& u, int wr, int wc, int fr, int fq) const {
;         const int row0 = u.pm * BM + wr * 64 + fr, ch0 = u.pn * 128 + wc * 32 + 8 * fq;
;         f32x4 w0[2], w1[2], w2[2], bb[2];
; #pragma unroll
;         for (int n = 0; n < 2; ++n) { w0[n] = *(const f32x4*)(cw + ch0 + 4 * n); w1[n] = *(const f32x4*)(cw + DFF + ch0 + 4 * n); w2[n] = *(const f32x4*)(cw + 2 * DFF + ch0 + 4 * n); bb[n] = *(const f32x4*)(cb + ch0 + 4 * n); }
; #pragma unroll
;         for (int ai = 0; ai < 2; ++ai)
; #pragma unroll
;             for (int m = 0; m < 4; ++m) {
;                 const bool efirst = (m == 0) && (fr == 0), elast = (m == 3) && (fr == 15);
;                 const int row = row0 + ai * HALF + m * 16;
;                 f32x4 gc[2];
; #pragma unroll
;                 for (int n = 0; n < 2; ++n) {
;                     const f32x4 g = acc[ai][0][m][n];
;                     const f32x4 gprev = acc[ai][0][m > 0 ? m - 1 : 0][n], gnext = acc[ai][0][m < 3 ? m + 1 : 3][n];
;                     f32x4 up, dn;
; #pragma unroll
;                     for (int e = 0; e < 4; ++e) {
;                         const float pu = (m > 0 && fr == 15) ? gprev[e] : g[e];
;                         const float pd = (m < 3 && fr == 0) ? gnext[e] : g[e];
;                         up[e] = dpp_ror1(pu); dn[e] = dpp_ror15(pd);
;                     }
;                     if (efirst) up = (f32x4){0.f, 0.f, 0.f, 0.f};
;                     if (elast) dn = (f32x4){0.f, 0.f, 0.f, 0.f};
;                     gc[n] = w0[n] * up + w1[n] * g + w2[n] * dn + bb[n];
;                 }
;                 if (efirst || elast) {
;                     const size_t eo = (size_t)((row >> 6) * 2 + (elast ? 1 : 0)) * DFF + ch0;
; #pragma unroll
;                     for (int n = 0; n < 2; ++n) { *(f32x4*)(EP + eo + 4 * n) = gc[n]; *(f32x4*)(ER + eo + 4 * n) = acc[ai][0][m][n]; *(f32x4*)(EV + eo + 4 * n) = acc[ai][1][m][n]; }
;                 } else {
;                     const f32x4 v0 = acc[ai][1][m][0], v1 = acc[ai][1][m][1];
;                     u32x4 o;
;                     o[0] = pack2(silu_mul(gc[0][0], v0[0]), silu_mul(gc[0][1], v0[1])); o[1] = pack2(silu_mul(gc[0][2], v0[2]), silu_mul(gc[0][3], v0[3]));
	s_waitcnt lgkmcnt(0)
	s_lshl_b32 s23, s43, 7
	v_mov_b32_e32 v194, v186
	v_mov_b32_e32 v80, v187
	s_or_b32 s23, s23, s67
	v_mov_b32_e32 v160, 0
	v_lshl_add_u32 v184, v80, 3, s23
	v_ashrrev_i32_e32 v185, 31, v184
	v_lshlrev_b64 v[80:81], 2, v[184:185]
	v_lshl_add_u64 v[84:85], s[52:53], 0, v[80:81]
	v_lshl_add_u64 v[88:89], s[16:17], 0, v[80:81]
	v_lshl_add_u64 v[92:93], s[18:19], 0, v[80:81]
	v_lshl_add_u64 v[112:113], s[54:55], 0, v[80:81]
	global_load_dwordx4 v[80:83], v[84:85], off offset:16
	global_load_dwordx4 v[96:99], v[84:85], off
	s_nop 0
	global_load_dwordx4 v[84:87], v[88:89], off offset:16
	global_load_dwordx4 v[100:103], v[88:89], off
	s_nop 0
	global_load_dwordx4 v[88:91], v[92:93], off offset:16
	global_load_dwordx4 v[108:111], v[92:93], off
	s_nop 0
	global_load_dwordx4 v[92:95], v[112:113], off offset:16
	s_nop 0
	global_load_dwordx4 v[112:115], v[112:113], off
	v_cmp_eq_u32_e32 vcc, 0, v194
	v_mov_b32_e32 v164, 0
	v_mov_b32_e32 v195, 0
	v_cndmask_b32_e32 v161, v148, v136, vcc
	v_cndmask_b32_e32 v162, v149, v137, vcc
	v_cndmask_b32_e32 v163, v150, v138, vcc
	v_mov_b32_dpp v160, v161 row_ror:15 row_mask:0xf bank_mask:0xf
	v_mov_b32_e32 v161, 0
	v_mov_b32_e32 v166, 0
	v_mov_b32_e32 v167, 0
	v_mov_b32_dpp v161, v162 row_ror:15 row_mask:0xf bank_mask:0xf
	v_mov_b32_e32 v162, 0
	v_mov_b32_dpp v164, v150 row_ror:1 row_mask:0xf bank_mask:0xf
	v_cndmask_b32_e32 v165, v151, v139, vcc
	v_mov_b32_dpp v162, v163 row_ror:15 row_mask:0xf bank_mask:0xf
	v_mov_b32_dpp v195, v151 row_ror:1 row_mask:0xf bank_mask:0xf
	v_mov_b32_e32 v163, 0
	v_mov_b32_dpp v166, v148 row_ror:1 row_mask:0xf bank_mask:0xf
	v_mov_b32_dpp v167, v149 row_ror:1 row_mask:0xf bank_mask:0xf
	v_mov_b32_dpp v163, v165 row_ror:15 row_mask:0xf bank_mask:0xf
	v_cndmask_b32_e64 v165, v195, 0, vcc
	v_cndmask_b32_e64 v164, v164, 0, vcc
	v_cndmask_b32_e64 v167, v167, 0, vcc
	v_cndmask_b32_e64 v166, v166, 0, vcc
	v_mov_b32_e32 v195, 0
	v_mov_b32_e32 v196, 0
	v_mov_b32_e32 v198, 0
	v_mov_b32_e32 v200, 0
	v_mov_b32_dpp v195, v144 row_ror:1 row_mask:0xf bank_mask:0xf
	v_mov_b32_dpp v196, v145 row_ror:1 row_mask:0xf bank_mask:0xf
	v_mov_b32_dpp v198, v146 row_ror:1 row_mask:0xf bank_mask:0xf
	v_cndmask_b32_e32 v199, v147, v131, vcc
	v_mov_b32_dpp v200, v147 row_ror:1 row_mask:0xf bank_mask:0xf
	v_cndmask_b32_e64 v198, v198, 0, vcc
	v_cndmask_b32_e64 v201, v196, 0, vcc
	s_lshl_b32 s21, s42, 8
	s_add_i32 s21, s21, s49
	v_add_u32_e32 v193, s21, v194
	v_cmp_ne_u32_e64 s[46:47], 0, v194
	s_waitcnt vmcnt(0)
	v_pk_mul_f32 v[164:165], v[98:99], v[164:165]
	v_pk_mul_f32 v[166:167], v[96:97], v[166:167]
	v_pk_fma_f32 v[164:165], v[150:151], v[102:103], v[164:165]
	v_pk_fma_f32 v[166:167], v[148:149], v[100:101], v[166:167]
	v_pk_fma_f32 v[162:163], v[110:111], v[162:163], v[164:165]
	v_cndmask_b32_e32 v165, v144, v128, vcc
	v_mov_b32_e32 v164, 0
	v_pk_fma_f32 v[160:161], v[108:109], v[160:161], v[166:167]
	v_cndmask_b32_e32 v166, v145, v129, vcc
	v_mov_b32_dpp v164, v165 row_ror:15 row_mask:0xf bank_mask:0xf
	v_mov_b32_e32 v165, 0
	v_cndmask_b32_e32 v167, v146, v130, vcc
	v_pk_add_f32 v[162:163], v[114:115], v[162:163]
	v_mov_b32_dpp v165, v166 row_ror:15 row_mask:0xf bank_mask:0xf
	v_mov_b32_e32 v166, 0
	v_pk_add_f32 v[160:161], v[112:113], v[160:161]
	s_nop 0
	v_mov_b32_dpp v166, v167 row_ror:15 row_mask:0xf bank_mask:0xf
	v_mov_b32_e32 v167, 0
	s_nop 1
	v_mov_b32_dpp v167, v199 row_ror:15 row_mask:0xf bank_mask:0xf
	v_cndmask_b32_e64 v199, v200, 0, vcc
	v_cndmask_b32_e64 v200, v195, 0, vcc
	v_pk_mul_f32 v[200:201], v[80:81], v[200:201]
	v_pk_mul_f32 v[198:199], v[82:83], v[198:199]
	v_pk_fma_f32 v[200:201], v[144:145], v[84:85], v[200:201]
	v_pk_fma_f32 v[198:199], v[146:147], v[86:87], v[198:199]
	v_pk_fma_f32 v[164:165], v[88:89], v[164:165], v[200:201]
	v_pk_fma_f32 v[166:167], v[90:91], v[166:167], v[198:199]
	v_pk_add_f32 v[164:165], v[92:93], v[164:165]
	v_pk_add_f32 v[166:167], v[94:95], v[166:167]
	s_and_saveexec_b64 s[28:29], s[46:47]
	s_xor_b64 s[28:29], exec, s[28:29]
	s_cbranch_execz .LBB1_383
	v_mul_f32_e32 v195, 0xbfb8aa3b, v160
	v_exp_f32_e32 v195, v195
	v_mul_f32_e32 v196, 0xbfb8aa3b, v161
	v_exp_f32_e32 v196, v196
	v_pk_mul_f32 v[160:161], v[156:157], v[160:161]
	v_add_f32_e32 v195, 1.0, v195
	v_rcp_f32_e32 v198, v195
	v_add_f32_e32 v196, 1.0, v196
	v_mul_f32_e32 v195, 0xbfb8aa3b, v162
	v_rcp_f32_e32 v199, v196
	v_exp_f32_e32 v195, v195
	v_mul_f32_e32 v196, 0xbfb8aa3b, v163
	v_exp_f32_e32 v196, v196
	v_pk_mul_f32 v[160:161], v[160:161], v[198:199]
	v_add_f32_e32 v195, 1.0, v195
	v_rcp_f32_e32 v200, v195
	v_add_f32_e32 v195, 1.0, v196
	v_rcp_f32_e32 v201, v195
	v_cvt_pk_bf16_f32 v160, v160, v161
	v_mul_f32_e32 v161, 0xbfb8aa3b, v164
	v_exp_f32_e32 v195, v161
	v_mul_f32_e32 v161, 0xbfb8aa3b, v165
	v_exp_f32_e32 v196, v161
	v_pk_mul_f32 v[162:163], v[158:159], v[162:163]
	v_pk_mul_f32 v[164:165], v[152:153], v[164:165]
	v_pk_mul_f32 v[162:163], v[162:163], v[200:201]
	s_nop 0
	v_cvt_pk_bf16_f32 v161, v162, v163
	v_add_f32_e32 v162, 1.0, v195
	v_mul_f32_e32 v195, 0xbfb8aa3b, v166
	v_add_f32_e32 v163, 1.0, v196
	v_exp_f32_e32 v195, v195
	v_mul_f32_e32 v196, 0xbfb8aa3b, v167
	v_exp_f32_e32 v196, v196
	v_rcp_f32_e32 v162, v162
	v_add_f32_e32 v195, 1.0, v195
	v_rcp_f32_e32 v198, v195
	v_add_f32_e32 v195, 1.0, v196
	v_rcp_f32_e32 v163, v163
	v_rcp_f32_e32 v199, v195
	v_pk_mul_f32 v[166:167], v[154:155], v[166:167]
	v_pk_mul_f32 v[162:163], v[164:165], v[162:163]
	v_pk_mul_f32 v[164:165], v[166:167], v[198:199]
	v_cvt_pk_bf16_f32 v162, v162, v163
	v_cvt_pk_bf16_f32 v163, v164, v165
	v_mov_b64_e32 v[164:165], s[6:7]
	v_mad_i64_i32 v[164:165], s[42:43], v193, s30, v[164:165]
	v_lshl_add_u64 v[164:165], v[184:185], 1, v[164:165]
	global_store_dwordx4 v[164:165], v[160:163], off

; #define PG8_STAGE(bufoff, gbase, voff) do { _Pragma("unroll") for (int _i = 0; _i < 2; ++_i) \
;         __builtin_amdgcn_global_load_lds((const unsigned*)((const char*)(gbase) + (voff)[_i]), (LAS unsigned*)(lds + (bufoff) + ldsw + _i * 8192), 16, 0, 0); } while (0)
; #define PG8_LDA(dst, b, h) do { _Pragma("unroll") for (int m = 0; m < 4; ++m) _Pragma("unroll") for (int k = 0; k < 2; ++k) dst[m][k] = *(const LAS bf16x8*)(lds + PG8_SA(b, h) + aoff + m * 2048 + k * 1024); } while (0)
; #define PG8_LDB(dst, b, h) do { _Pragma("unroll") for (int n = 0; n < 2; ++n) _Pragma("unroll") for (int k = 0; k < 2; ++k) dst[n][k] = *(const LAS bf16x8*)(lds + PG8_SB(b, h) + boff + n * 2048 + k * 1024); } while (0)
; #define PG8_MMA(ai, bj, At, Bt) do { __builtin_amdgcn_s_setprio(1); _Pragma("unroll") for (int m = 0; m < 4; ++m) _Pragma("unroll") for (int n = 0; n < 2; ++n) _Pragma("unroll") for (int k = 0; k < 2; ++k) \
;         acc[ai][bj][m][n] = __builtin_amdgcn_mfma_f32_16x16x32_bf16(Bt[n][k], At[m][k], acc[ai][bj][m][n], 0, 0, 0); __builtin_amdgcn_s_setprio(0); } while (0)
; #define PG8_WAIT_V(n) asm volatile("s_waitcnt vmcnt(" #n ")" ::: "memory")
; #define PG8_WAIT_L(n) asm volatile("s_waitcnt lgkmcnt(" #n ")" ::: "memory")
; template <class Map, class Epi>
; DI void gemm_phase(LAS unsigned char* lds, const Map& MP, const Epi& E, const int nM, const int nN, const int K, const int lda, const int ldb) {
;     ...
;             const bool last = (t == nt - 2);
;             const char* a1 = cA + (size_t)(t + 1) * kstep;
;             const char* a2 = last ? nA : cA + (size_t)(t + 2) * kstep; const char* b2 = last ? nB : cB + (size_t)(t + 2) * kstep;
;             const char* a3 = a2 + kstep; const char* b3 = b2 + kstep;
;             PG8_LDB(B0, 0, 0); PG8_SCHED; PG8_LDA(At, 0, 0); PG8_STAGE(PG8_SA(1, 1), a1 + hstepA, voffA);
;             PG8_WAIT_L(8); PG8_BAR; PG8_WAIT_L(0); PG8_MMA(0, 0, At, B0); PG8_BAR; PG8_SCHED;
;             PG8_LDB(B1, 0, 1); PG8_STAGE(PG8_SB(0, 0), b2, voffB);
;             PG8_BAR; PG8_WAIT_L(0); PG8_MMA(0, 1, At, B1); PG8_BAR;
;             PG8_LDA(At, 0, 1); PG8_STAGE(PG8_SA(0, 0), a2, voffA);
;             PG8_BAR; PG8_WAIT_L(0); PG8_MMA(1, 0, At, B0); PG8_BAR; PG8_SCHED;
;             PG8_STAGE(PG8_SB(0, 1), b2 + hstepB, voffB);
;             PG8_WAIT_V(6); PG8_BAR; PG8_MMA(1, 1, At, B1); PG8_BAR;
.LBB1_550:
	s_add_u32 s10, s8, 0x100
	s_addc_u32 s11, s9, 0
	s_cmpk_eq_i32 s3, 0x54
	s_cselect_b32 s15, s43, s11
	s_cselect_b32 s14, s42, s10
	s_cselect_b32 s13, s7, s38
	s_cselect_b32 s12, s6, s5
	s_add_i32 m0, s24, 0xc000
	ds_read_b128 v[168:171], v150
	ds_read_b128 v[172:175], v150 offset:1024
	ds_read_b128 v[176:179], v150 offset:2048
	ds_read_b128 v[180:183], v150 offset:3072
	ds_read_b128 v[184:187], v150 offset:4096
	ds_read_b128 v[188:191], v150 offset:5120
	ds_read_b128 v[192:195], v150 offset:6144
	ds_read_b128 v[198:201], v150 offset:7168
	global_load_lds_dwordx4 v138, s[8:9]
	s_add_i32 m0, s24, 0xe000
	s_nop 0
	global_load_lds_dwordx4 v136, s[8:9]
	s_waitcnt lgkmcnt(7)
	s_setprio 1
	s_barrier
	v_mfma_f32_16x16x32_bf16 v[124:127], v[152:155], v[168:171], v[124:127]
	v_mfma_f32_16x16x32_bf16 v[120:123], v[160:163], v[168:171], v[120:123]
	s_waitcnt lgkmcnt(5)
	v_mfma_f32_16x16x32_bf16 v[108:111], v[152:155], v[176:179], v[108:111]
	v_mfma_f32_16x16x32_bf16 v[104:107], v[160:163], v[176:179], v[104:107]
	s_waitcnt lgkmcnt(3)
	v_mfma_f32_16x16x32_bf16 v[92:95], v[152:155], v[184:187], v[92:95]
	v_mfma_f32_16x16x32_bf16 v[88:91], v[160:163], v[184:187], v[88:91]
	s_waitcnt lgkmcnt(1)
	v_mfma_f32_16x16x32_bf16 v[76:79], v[152:155], v[192:195], v[76:79]
	v_mfma_f32_16x16x32_bf16 v[72:75], v[160:163], v[192:195], v[72:75]
	v_mfma_f32_16x16x32_bf16 v[124:127], v[156:159], v[172:175], v[124:127]
	v_mfma_f32_16x16x32_bf16 v[120:123], v[164:167], v[172:175], v[120:123]
	v_mfma_f32_16x16x32_bf16 v[108:111], v[156:159], v[180:183], v[108:111]
	v_mfma_f32_16x16x32_bf16 v[104:107], v[164:167], v[180:183], v[104:107]
	v_mfma_f32_16x16x32_bf16 v[92:95], v[156:159], v[188:191], v[92:95]
	v_mfma_f32_16x16x32_bf16 v[88:91], v[164:167], v[188:191], v[88:91]
	s_waitcnt lgkmcnt(0)
	v_mfma_f32_16x16x32_bf16 v[76:79], v[156:159], v[198:201], v[76:79]
	v_mfma_f32_16x16x32_bf16 v[72:75], v[164:167], v[198:201], v[72:75]
	s_barrier
	s_setprio 0
	s_add_i32 s8, s35, s22
	v_lshl_add_u64 v[144:145], s[12:13], 0, v[132:133]
	s_mov_b32 m0, s8
	ds_read_b128 v[202:205], v151
	ds_read_b128 v[206:209], v151 offset:1024
	ds_read_b128 v[210:213], v151 offset:2048
	ds_read_b128 v[214:217], v151 offset:3072
	global_load_lds_dwordx4 v[144:145], off
	v_lshl_add_u64 v[218:219], s[12:13], 0, v[128:129]
	s_add_i32 m0, s8, 0x2000
	s_nop 0
	global_load_lds_dwordx4 v[218:219], off
	s_waitcnt lgkmcnt(3)
	s_setprio 1
	s_barrier
	v_mfma_f32_16x16x32_bf16 v[116:119], v[202:205], v[168:171], v[116:119]
	s_waitcnt lgkmcnt(1)
	v_mfma_f32_16x16x32_bf16 v[112:115], v[210:213], v[168:171], v[112:115]
	v_mfma_f32_16x16x32_bf16 v[100:103], v[202:205], v[176:179], v[100:103]
	v_mfma_f32_16x16x32_bf16 v[96:99], v[210:213], v[176:179], v[96:99]
	v_mfma_f32_16x16x32_bf16 v[84:87], v[202:205], v[184:187], v[84:87]
	v_mfma_f32_16x16x32_bf16 v[80:83], v[210:213], v[184:187], v[80:83]
	v_mfma_f32_16x16x32_bf16 v[68:71], v[202:205], v[192:195], v[68:71]
	v_mfma_f32_16x16x32_bf16 v[64:67], v[210:213], v[192:195], v[64:67]
	v_mfma_f32_16x16x32_bf16 v[116:119], v[206:209], v[172:175], v[116:119]
	s_mov_b32 m0, s24
	s_waitcnt lgkmcnt(0)
	v_mfma_f32_16x16x32_bf16 v[112:115], v[214:217], v[172:175], v[112:115]
	v_lshl_add_u64 v[220:221], s[14:15], 0, v[134:135]
	v_mfma_f32_16x16x32_bf16 v[100:103], v[206:209], v[180:183], v[100:103]
	v_mfma_f32_16x16x32_bf16 v[96:99], v[214:217], v[180:183], v[96:99]
	v_mfma_f32_16x16x32_bf16 v[84:87], v[206:209], v[188:191], v[84:87]
	v_mfma_f32_16x16x32_bf16 v[80:83], v[214:217], v[188:191], v[80:83]
	v_mfma_f32_16x16x32_bf16 v[68:71], v[206:209], v[198:201], v[68:71]
	v_mfma_f32_16x16x32_bf16 v[64:67], v[214:217], v[198:201], v[64:67]
	s_barrier
	s_setprio 0
	ds_read_b128 v[168:171], v150 offset:16384
	ds_read_b128 v[172:175], v150 offset:17408
	ds_read_b128 v[176:179], v150 offset:18432
	ds_read_b128 v[180:183], v150 offset:19456
	ds_read_b128 v[184:187], v150 offset:20480
	ds_read_b128 v[188:191], v150 offset:21504
	ds_read_b128 v[192:195], v150 offset:22528
	ds_read_b128 v[198:201], v150 offset:23552
	global_load_lds_dwordx4 v[220:221], off
	v_lshl_add_u64 v[222:223], s[14:15], 0, v[130:131]
	s_mov_b32 m0, s25
	s_nop 0
	global_load_lds_dwordx4 v[222:223], off
	s_waitcnt vmcnt(10) lgkmcnt(7)
	s_setprio 1
	s_barrier
	v_mfma_f32_16x16x32_bf16 v[60:63], v[152:155], v[168:171], v[60:63]
	v_mfma_f32_16x16x32_bf16 v[56:59], v[160:163], v[168:171], v[56:59]
	s_waitcnt lgkmcnt(5)
	v_mfma_f32_16x16x32_bf16 v[44:47], v[152:155], v[176:179], v[44:47]
	v_mfma_f32_16x16x32_bf16 v[40:43], v[160:163], v[176:179], v[40:43]
	s_waitcnt lgkmcnt(3)
	v_mfma_f32_16x16x32_bf16 v[28:31], v[152:155], v[184:187], v[28:31]
	v_mfma_f32_16x16x32_bf16 v[24:27], v[160:163], v[184:187], v[24:27]
	s_waitcnt lgkmcnt(1)
	v_mfma_f32_16x16x32_bf16 v[12:15], v[152:155], v[192:195], v[12:15]
	v_mfma_f32_16x16x32_bf16 v[8:11], v[160:163], v[192:195], v[8:11]
	v_mfma_f32_16x16x32_bf16 v[60:63], v[156:159], v[172:175], v[60:63]
	v_mfma_f32_16x16x32_bf16 v[56:59], v[164:167], v[172:175], v[56:59]
	v_mfma_f32_16x16x32_bf16 v[44:47], v[156:159], v[180:183], v[44:47]
	v_mfma_f32_16x16x32_bf16 v[40:43], v[164:167], v[180:183], v[40:43]
	v_mfma_f32_16x16x32_bf16 v[28:31], v[156:159], v[188:191], v[28:31]
	v_mfma_f32_16x16x32_bf16 v[24:27], v[164:167], v[188:191], v[24:27]
	s_waitcnt lgkmcnt(0)
	v_mfma_f32_16x16x32_bf16 v[12:15], v[156:159], v[198:201], v[12:15]
	v_mfma_f32_16x16x32_bf16 v[8:11], v[164:167], v[198:201], v[8:11]
	s_barrier
	s_setprio 0
	s_add_u32 s8, s12, 0x160000
	s_addc_u32 s9, s13, 0
	s_add_i32 s39, s36, s22
	s_mov_b32 m0, s39
	s_nop 0
	global_load_lds_dwordx4 v132, s[8:9]
	s_add_i32 m0, s39, 0x2000
	s_nop 0
	global_load_lds_dwordx4 v128, s[8:9]
	s_waitcnt vmcnt(6)
	s_setprio 1
	s_barrier
; #define PG8_STAGE(bufoff, gbase, voff) do { _Pragma("unroll") for (int _i = 0; _i < 2; ++_i) \
;         __builtin_amdgcn_global_load_lds((const unsigned*)((const char*)(gbase) + (voff)[_i]), (LAS unsigned*)(lds + (bufoff) + ldsw + _i * 8192), 16, 0, 0); } while (0)
; #define PG8_LDA(dst, b, h) do { _Pragma("unroll") for (int m = 0; m < 4; ++m) _Pragma("unroll") for (int k = 0; k < 2; ++k) dst[m][k] = *(const LAS bf16x8*)(lds + PG8_SA(b, h) + aoff + m * 2048 + k * 1024); } while (0)
; #define PG8_LDB(dst, b, h) do { _Pragma("unroll") for (int n = 0; n < 2; ++n) _Pragma("unroll") for (int k = 0; k < 2; ++k) dst[n][k] = *(const LAS bf16x8*)(lds + PG8_SB(b, h) + boff + n * 2048 + k * 1024); } while (0)
; #define PG8_MMA(ai, bj, At, Bt) do { __builtin_amdgcn_s_setprio(1); _Pragma("unroll") for (int m = 0; m < 4; ++m) _Pragma("unroll") for (int n = 0; n < 2; ++n) _Pragma("unroll") for (int k = 0; k < 2; ++k) \
;         acc[ai][bj][m][n] = __builtin_amdgcn_mfma_f32_16x16x32_bf16(Bt[n][k], At[m][k], acc[ai][bj][m][n], 0, 0, 0); __builtin_amdgcn_s_setprio(0); } while (0)
; #define PG8_WAIT_V(n) asm volatile("s_waitcnt vmcnt(" #n ")" ::: "memory")
; #define PG8_WAIT_L(n) asm volatile("s_waitcnt lgkmcnt(" #n ")" ::: "memory")
; #define PG8_BAR __builtin_amdgcn_s_barrier()
; #define PG8_SCHED __builtin_amdgcn_sched_barrier(0)
; template <class Map, class Epi>
; DI void gemm_phase(LAS unsigned char* lds, const Map& MP, const Epi& E, const int nM, const int nN, const int K, const int lda, const int ldb) {
;     ...
;             PG8_WAIT_V(6); PG8_BAR; PG8_MMA(1, 1, At, B1); PG8_BAR;
;             PG8_LDB(B0, 1, 0); PG8_SCHED; PG8_LDA(At, 1, 0); PG8_STAGE(PG8_SA(0, 1), a2 + hstepA, voffA);
;             PG8_WAIT_L(8); PG8_BAR; PG8_WAIT_L(0); PG8_MMA(0, 0, At, B0); PG8_BAR; PG8_SCHED;
;             PG8_LDB(B1, 1, 1); PG8_STAGE(PG8_SB(1, 0), b3, voffB);
;             PG8_BAR; PG8_WAIT_L(0); PG8_MMA(0, 1, At, B1); PG8_BAR;
;             PG8_LDA(At, 1, 1); PG8_STAGE(PG8_SA(1, 0), a3, voffA);
;             PG8_BAR; PG8_WAIT_L(0); PG8_MMA(1, 0, At, B0); PG8_BAR; PG8_SCHED;
	v_mfma_f32_16x16x32_bf16 v[52:55], v[202:205], v[168:171], v[52:55]
	v_mfma_f32_16x16x32_bf16 v[48:51], v[210:213], v[168:171], v[48:51]
	s_add_i32 s39, 0, 0x18000
	v_add_u32_e32 v164, s39, v148
	ds_read_b128 v[152:155], v164
	v_mfma_f32_16x16x32_bf16 v[36:39], v[202:205], v[176:179], v[36:39]
	v_mfma_f32_16x16x32_bf16 v[32:35], v[210:213], v[176:179], v[32:35]
	ds_read_b128 v[156:159], v164 offset:1024
	v_mfma_f32_16x16x32_bf16 v[20:23], v[202:205], v[184:187], v[20:23]
	v_mfma_f32_16x16x32_bf16 v[16:19], v[210:213], v[184:187], v[16:19]
	ds_read_b128 v[160:163], v164 offset:2048
	v_mfma_f32_16x16x32_bf16 v[4:7], v[202:205], v[192:195], v[4:7]
	v_mfma_f32_16x16x32_bf16 v[0:3], v[210:213], v[192:195], v[0:3]
	ds_read_b128 v[164:167], v164 offset:3072
	v_mfma_f32_16x16x32_bf16 v[52:55], v[206:209], v[172:175], v[52:55]
	v_mfma_f32_16x16x32_bf16 v[48:51], v[214:217], v[172:175], v[48:51]
	v_mfma_f32_16x16x32_bf16 v[36:39], v[206:209], v[180:183], v[36:39]
	v_mfma_f32_16x16x32_bf16 v[32:35], v[214:217], v[180:183], v[32:35]
	v_mfma_f32_16x16x32_bf16 v[20:23], v[206:209], v[188:191], v[20:23]
	v_mfma_f32_16x16x32_bf16 v[16:19], v[214:217], v[188:191], v[16:19]
	v_mfma_f32_16x16x32_bf16 v[4:7], v[206:209], v[198:201], v[4:7]
	v_mfma_f32_16x16x32_bf16 v[0:3], v[214:217], v[198:201], v[0:3]
	s_barrier
	s_setprio 0
	s_add_u32 s8, s14, 0x160000
	s_addc_u32 s9, s15, 0
	s_mov_b32 m0, s26
	ds_read_b128 v[168:171], v150 offset:32768
	ds_read_b128 v[172:175], v150 offset:33792
	ds_read_b128 v[176:179], v150 offset:34816
	ds_read_b128 v[180:183], v150 offset:35840
	ds_read_b128 v[184:187], v150 offset:36864
	ds_read_b128 v[188:191], v150 offset:37888
	ds_read_b128 v[192:195], v150 offset:38912
	ds_read_b128 v[198:201], v150 offset:39936
	global_load_lds_dwordx4 v134, s[8:9]
	s_mov_b32 m0, s27
	s_nop 0
	global_load_lds_dwordx4 v130, s[8:9]
	s_waitcnt lgkmcnt(7)
	s_setprio 1
	s_barrier
	v_mfma_f32_16x16x32_bf16 v[124:127], v[152:155], v[168:171], v[124:127]
	v_mfma_f32_16x16x32_bf16 v[120:123], v[160:163], v[168:171], v[120:123]
	s_waitcnt lgkmcnt(5)
	v_mfma_f32_16x16x32_bf16 v[108:111], v[152:155], v[176:179], v[108:111]
	v_mfma_f32_16x16x32_bf16 v[104:107], v[160:163], v[176:179], v[104:107]
	s_waitcnt lgkmcnt(3)
	v_mfma_f32_16x16x32_bf16 v[92:95], v[152:155], v[184:187], v[92:95]
	v_mfma_f32_16x16x32_bf16 v[88:91], v[160:163], v[184:187], v[88:91]
	s_waitcnt lgkmcnt(1)
	v_mfma_f32_16x16x32_bf16 v[76:79], v[152:155], v[192:195], v[76:79]
	v_mfma_f32_16x16x32_bf16 v[72:75], v[160:163], v[192:195], v[72:75]
	v_mfma_f32_16x16x32_bf16 v[124:127], v[156:159], v[172:175], v[124:127]
	v_mfma_f32_16x16x32_bf16 v[120:123], v[164:167], v[172:175], v[120:123]
	v_mfma_f32_16x16x32_bf16 v[108:111], v[156:159], v[180:183], v[108:111]
	v_mfma_f32_16x16x32_bf16 v[104:107], v[164:167], v[180:183], v[104:107]
	v_mfma_f32_16x16x32_bf16 v[92:95], v[156:159], v[188:191], v[92:95]
	v_mfma_f32_16x16x32_bf16 v[88:91], v[164:167], v[188:191], v[88:91]
	s_waitcnt lgkmcnt(0)
	v_mfma_f32_16x16x32_bf16 v[76:79], v[156:159], v[198:201], v[76:79]
	v_mfma_f32_16x16x32_bf16 v[72:75], v[164:167], v[198:201], v[72:75]
	s_barrier
	s_setprio 0
	s_add_i32 s14, 0, 0x1c000
	s_add_i32 s8, s39, s22
	v_add_u32_e32 v196, s14, v148
	v_lshl_add_u64 v[144:145], v[144:145], 0, s[52:53]
	s_mov_b32 m0, s8
	ds_read_b128 v[202:205], v196
	ds_read_b128 v[206:209], v196 offset:1024
	ds_read_b128 v[210:213], v196 offset:2048
	ds_read_b128 v[214:217], v196 offset:3072
	global_load_lds_dwordx4 v[144:145], off
	v_lshl_add_u64 v[144:145], v[218:219], 0, s[52:53]
	s_add_i32 m0, s8, 0x2000
	s_nop 0
	global_load_lds_dwordx4 v[144:145], off
	s_waitcnt lgkmcnt(3)
	s_setprio 1
	s_barrier
	v_mfma_f32_16x16x32_bf16 v[116:119], v[202:205], v[168:171], v[116:119]
	s_waitcnt lgkmcnt(1)
	v_mfma_f32_16x16x32_bf16 v[112:115], v[210:213], v[168:171], v[112:115]
	v_mfma_f32_16x16x32_bf16 v[100:103], v[202:205], v[176:179], v[100:103]
	v_mfma_f32_16x16x32_bf16 v[96:99], v[210:213], v[176:179], v[96:99]
	v_mfma_f32_16x16x32_bf16 v[84:87], v[202:205], v[184:187], v[84:87]
	v_mfma_f32_16x16x32_bf16 v[80:83], v[210:213], v[184:187], v[80:83]
	v_mfma_f32_16x16x32_bf16 v[68:71], v[202:205], v[192:195], v[68:71]
	v_mfma_f32_16x16x32_bf16 v[64:67], v[210:213], v[192:195], v[64:67]
	v_mfma_f32_16x16x32_bf16 v[116:119], v[206:209], v[172:175], v[116:119]
	s_mov_b32 m0, s30
	s_waitcnt lgkmcnt(0)
	v_mfma_f32_16x16x32_bf16 v[112:115], v[214:217], v[172:175], v[112:115]
	v_lshl_add_u64 v[144:145], v[220:221], 0, s[52:53]
	v_mfma_f32_16x16x32_bf16 v[100:103], v[206:209], v[180:183], v[100:103]
	v_mfma_f32_16x16x32_bf16 v[96:99], v[214:217], v[180:183], v[96:99]
	v_mfma_f32_16x16x32_bf16 v[84:87], v[206:209], v[188:191], v[84:87]
	v_mfma_f32_16x16x32_bf16 v[80:83], v[214:217], v[188:191], v[80:83]
	v_mfma_f32_16x16x32_bf16 v[68:71], v[206:209], v[198:201], v[68:71]
	v_mfma_f32_16x16x32_bf16 v[64:67], v[214:217], v[198:201], v[64:67]
	s_barrier
	s_setprio 0
	ds_read_b128 v[168:171], v150 offset:49152
	ds_read_b128 v[172:175], v150 offset:50176
	ds_read_b128 v[176:179], v150 offset:51200
	ds_read_b128 v[180:183], v150 offset:52224
	ds_read_b128 v[184:187], v150 offset:53248
	ds_read_b128 v[188:191], v150 offset:54272
	ds_read_b128 v[192:195], v150 offset:55296
	ds_read_b128 v[198:201], v150 offset:56320
	global_load_lds_dwordx4 v[144:145], off
	v_lshl_add_u64 v[144:145], v[222:223], 0, s[52:53]
	s_mov_b32 m0, s31
	s_nop 0
	global_load_lds_dwordx4 v[144:145], off
	s_waitcnt vmcnt(10) lgkmcnt(7)
	s_setprio 1
	s_barrier
; DI unsigned pack2(float a, float b) { f32x2 v = {a, b}; hwbf16x2 r = __builtin_convertvector(v, hwbf16x2); return __builtin_bit_cast(unsigned, r); }
; DI float bflo(unsigned w) { return __uint_as_float(w << 16); }
; DI float bfhi(unsigned w) { return __uint_as_float(w & 0xffff0000u); }
; #define PG8_STAGE(bufoff, gbase, voff) do { _Pragma("unroll") for (int _i = 0; _i < 2; ++_i) \
;         __builtin_amdgcn_global_load_lds((const unsigned*)((const char*)(gbase) + (voff)[_i]), (LAS unsigned*)(lds + (bufoff) + ldsw + _i * 8192), 16, 0, 0); } while (0)
; #define PG8_WAIT_V(n) asm volatile("s_waitcnt vmcnt(" #n ")" ::: "memory")
; #define PG8_WAIT_L(n) asm volatile("s_waitcnt lgkmcnt(" #n ")" ::: "memory")
; #define PG8_BAR __builtin_amdgcn_s_barrier()
;     DI void operator()(const f32x4 (&acc)[2][2][4][2], const Unit& u, int wr, int wc, int fr, int fq) const {
;     ...
;             for (int m = 0; m < 4; ++m) { const size_t ro = (size_t)(row0 + ai * HALF + m * 16) * D + col0;
; #pragma unroll
;                 for (int bj = 0; bj < 2; ++bj) {
;                     f32x4 x0, x1;
;                     if constexpr (IB) { const u32x4 w = *(const u32x4*)((const bf16_t*)Xin + ro + bj * HALF);
;                         x0 = (f32x4){bflo(w[0]), bfhi(w[0]), bflo(w[1]), bfhi(w[1])}; x1 = (f32x4){bflo(w[2]), bfhi(w[2]), bflo(w[3]), bfhi(w[3])}; }
;                     else { x0 = *(const f32x4*)((const float*)Xin + ro + bj * HALF); x1 = *(const f32x4*)((const float*)Xin + ro + bj * HALF + 4); }
;                     x0 += acc[ai][bj][m][0] * sc[bj][0]; x1 += acc[ai][bj][m][1] * sc[bj][1];
;                     if constexpr (OB) { u32x4 o; o[0] = pack2(x0[0], x0[1]); o[1] = pack2(x0[2], x0[3]); o[2] = pack2(x1[0], x1[1]); o[3] = pack2(x1[2], x1[3]);
;                         *(u32x4*)((bf16_t*)Xout + ro + bj * HALF) = o; }
;                     else { *(f32x4*)((float*)Xout + ro + bj * HALF) = x0; *(f32x4*)((float*)Xout + ro + bj * HALF + 4) = x1; } } }
; template <class Map, class Epi>
; DI void gemm_phase(LAS unsigned char* lds, const Map& MP, const Epi& E, const int nM, const int nN, const int K, const int lda, const int ldb) {
;     ...
;             PG8_BAR; PG8_WAIT_L(0); PG8_MMA(1, 0, At, B0); PG8_BAR; PG8_SCHED;
;             PG8_STAGE(PG8_SB(1, 1), b3 + hstepB, voffB);
;             PG8_WAIT_V(6); PG8_BAR; PG8_MMA(1, 1, At, B1); PG8_BAR;
;         }
	v_mfma_f32_16x16x32_bf16 v[60:63], v[152:155], v[168:171], v[60:63]
	v_mfma_f32_16x16x32_bf16 v[56:59], v[160:163], v[168:171], v[56:59]
	s_waitcnt lgkmcnt(5)
	v_mfma_f32_16x16x32_bf16 v[44:47], v[152:155], v[176:179], v[44:47]
	v_mfma_f32_16x16x32_bf16 v[40:43], v[160:163], v[176:179], v[40:43]
	s_waitcnt lgkmcnt(3)
	v_mfma_f32_16x16x32_bf16 v[28:31], v[152:155], v[184:187], v[28:31]
	v_mfma_f32_16x16x32_bf16 v[24:27], v[160:163], v[184:187], v[24:27]
	s_waitcnt lgkmcnt(1)
	v_mfma_f32_16x16x32_bf16 v[12:15], v[152:155], v[192:195], v[12:15]
	v_mfma_f32_16x16x32_bf16 v[8:11], v[160:163], v[192:195], v[8:11]
	v_mfma_f32_16x16x32_bf16 v[60:63], v[156:159], v[172:175], v[60:63]
	v_mfma_f32_16x16x32_bf16 v[56:59], v[164:167], v[172:175], v[56:59]
	v_mfma_f32_16x16x32_bf16 v[44:47], v[156:159], v[180:183], v[44:47]
	v_mfma_f32_16x16x32_bf16 v[40:43], v[164:167], v[180:183], v[40:43]
	v_mfma_f32_16x16x32_bf16 v[28:31], v[156:159], v[188:191], v[28:31]
	v_mfma_f32_16x16x32_bf16 v[24:27], v[164:167], v[188:191], v[24:27]
	s_waitcnt lgkmcnt(0)
	v_mfma_f32_16x16x32_bf16 v[12:15], v[156:159], v[198:201], v[12:15]
	v_mfma_f32_16x16x32_bf16 v[8:11], v[164:167], v[198:201], v[8:11]
	s_barrier
	s_setprio 0
	s_add_u32 s8, s12, 0x160080
	s_addc_u32 s9, s13, 0
	s_add_i32 s12, s14, s22
	s_mov_b32 m0, s12
	s_nop 0
	global_load_lds_dwordx4 v132, s[8:9]
	s_add_i32 m0, s12, 0x2000
	s_nop 0
	global_load_lds_dwordx4 v128, s[8:9]
	s_waitcnt vmcnt(6)
	s_setprio 1
	s_barrier
	v_mfma_f32_16x16x32_bf16 v[52:55], v[202:205], v[168:171], v[52:55]
	v_mfma_f32_16x16x32_bf16 v[48:51], v[210:213], v[168:171], v[48:51]
	ds_read_b128 v[152:155], v149
	v_mfma_f32_16x16x32_bf16 v[36:39], v[202:205], v[176:179], v[36:39]
	v_mfma_f32_16x16x32_bf16 v[32:35], v[210:213], v[176:179], v[32:35]
	ds_read_b128 v[156:159], v149 offset:1024
	v_mfma_f32_16x16x32_bf16 v[20:23], v[202:205], v[184:187], v[20:23]
	v_mfma_f32_16x16x32_bf16 v[16:19], v[210:213], v[184:187], v[16:19]
	ds_read_b128 v[160:163], v149 offset:2048
	v_mfma_f32_16x16x32_bf16 v[4:7], v[202:205], v[192:195], v[4:7]
	v_mfma_f32_16x16x32_bf16 v[0:3], v[210:213], v[192:195], v[0:3]
	ds_read_b128 v[164:167], v149 offset:3072
	v_mfma_f32_16x16x32_bf16 v[52:55], v[206:209], v[172:175], v[52:55]
	s_add_i32 s3, s3, 2
	v_mfma_f32_16x16x32_bf16 v[48:51], v[214:217], v[172:175], v[48:51]
	s_add_u32 s5, s5, 0x100
	s_addc_u32 s38, s38, 0
	v_mfma_f32_16x16x32_bf16 v[36:39], v[206:209], v[180:183], v[36:39]
	s_cmpk_gt_u32 s3, 0x55
	v_mfma_f32_16x16x32_bf16 v[32:35], v[214:217], v[180:183], v[32:35]
	s_mov_b64 s[8:9], s[10:11]
	v_mfma_f32_16x16x32_bf16 v[20:23], v[206:209], v[188:191], v[20:23]
	v_mfma_f32_16x16x32_bf16 v[16:19], v[214:217], v[188:191], v[16:19]
	v_mfma_f32_16x16x32_bf16 v[4:7], v[206:209], v[198:201], v[4:7]
	v_mfma_f32_16x16x32_bf16 v[0:3], v[214:217], v[198:201], v[0:3]
	s_barrier
	s_setprio 0
	s_cbranch_scc0 .LBB1_550
	s_waitcnt lgkmcnt(0)
	v_mov_b32_e32 v144, v146
	v_mov_b32_e32 v152, v147
	s_lshl_b32 s2, s2, 8
	s_add_i32 s2, s2, s29
	s_lshl_b32 s3, s4, 8
	v_add_u32_e32 v152, s2, v152
	s_or_b32 s3, s3, s54
	v_ashrrev_i32_e32 v153, 31, v152
	v_lshl_add_u32 v144, v144, 3, s3
	v_lshlrev_b64 v[152:153], 12, v[152:153]
	v_ashrrev_i32_e32 v145, 31, v144
	v_lshl_add_u64 v[152:153], s[46:47], 0, v[152:153]
	v_lshl_add_u64 v[144:145], v[144:145], 1, v[152:153]
	global_load_dwordx4 v[160:163], v[144:145], off
	global_load_dwordx4 v[164:167], v[144:145], off offset:256
	s_mov_b64 s[98:99], 0x10000
	v_lshl_add_u64 v[154:155], v[144:145], 0, s[98:99]
	global_load_dwordx4 v[168:171], v[154:155], off
	global_load_dwordx4 v[172:175], v[154:155], off offset:256
	s_mov_b64 s[98:99], 0x20000
	v_lshl_add_u64 v[154:155], v[144:145], 0, s[98:99]
	global_load_dwordx4 v[176:179], v[154:155], off
	global_load_dwordx4 v[180:183], v[154:155], off offset:256
	s_mov_b64 s[98:99], 0x30000
	v_lshl_add_u64 v[154:155], v[144:145], 0, s[98:99]
	global_load_dwordx4 v[184:187], v[154:155], off
	global_load_dwordx4 v[188:191], v[154:155], off offset:256
	s_mov_b64 s[98:99], 0x80000
	v_lshl_add_u64 v[154:155], v[144:145], 0, s[98:99]
	global_load_dwordx4 v[192:195], v[154:155], off
	global_load_dwordx4 v[198:201], v[154:155], off offset:256
	s_mov_b64 s[98:99], 0x90000
	v_lshl_add_u64 v[154:155], v[144:145], 0, s[98:99]
	global_load_dwordx4 v[202:205], v[154:155], off
	global_load_dwordx4 v[206:209], v[154:155], off offset:256
	s_mov_b64 s[98:99], 0xa0000
	v_lshl_add_u64 v[154:155], v[144:145], 0, s[98:99]
	global_load_dwordx4 v[210:213], v[154:155], off
	global_load_dwordx4 v[214:217], v[154:155], off offset:256
	s_mov_b64 s[98:99], 0xb0000
	v_lshl_add_u64 v[154:155], v[144:145], 0, s[98:99]
	global_load_dwordx4 v[248:251], v[154:155], off
	global_load_dwordx4 v[252:255], v[154:155], off offset:256
	s_waitcnt vmcnt(15)
	s_nop 1
	v_mov_b32_e32 v152, v160
	v_mov_b32_e32 v153, v161
	v_mov_b32_e32 v154, v162
	v_mov_b32_e32 v155, v163
	s_mov_b64 s[2:3], 0x10000
	s_mov_b32 s4, s37
	s_mov_b64 s[10:11], s[6:7]
	s_mov_b64 s[8:9], s[42:43]
	s_waitcnt lgkmcnt(0)
	v_lshlrev_b32_e32 v156, 16, v152
	v_and_b32_e32 v157, 0xffff0000, v152
	v_lshlrev_b32_e32 v152, 16, v153
	v_and_b32_e32 v153, 0xffff0000, v153
	v_lshlrev_b32_e32 v158, 16, v154
	v_and_b32_e32 v159, 0xffff0000, v154
	v_lshlrev_b32_e32 v154, 16, v155
	v_and_b32_e32 v155, 0xffff0000, v155
	v_pk_add_f32 v[126:127], v[126:127], v[152:153]
	v_pk_add_f32 v[124:125], v[124:125], v[156:157]
	v_pk_add_f32 v[152:153], v[122:123], v[154:155]
	v_pk_add_f32 v[122:123], v[120:121], v[158:159]
	v_cvt_pk_bf16_f32 v120, v124, v125
	v_cvt_pk_bf16_f32 v121, v126, v127
	v_cvt_pk_bf16_f32 v122, v122, v123
	v_cvt_pk_bf16_f32 v123, v152, v153
	global_store_dwordx4 v[144:145], v[120:123], off
	s_waitcnt vmcnt(15)
; DI unsigned pack2(float a, float b) { f32x2 v = {a, b}; hwbf16x2 r = __builtin_convertvector(v, hwbf16x2); return __builtin_bit_cast(unsigned, r); }
; DI float bflo(unsigned w) { return __uint_as_float(w << 16); }
; DI float bfhi(unsigned w) { return __uint_as_float(w & 0xffff0000u); }
;     DI void operator()(const f32x4 (&acc)[2][2][4][2], const Unit& u, int wr, int wc, int fr, int fq) const {
;     ...
;             for (int m = 0; m < 4; ++m) { const size_t ro = (size_t)(row0 + ai * HALF + m * 16) * D + col0;
; #pragma unroll
;                 for (int bj = 0; bj < 2; ++bj) {
;                     f32x4 x0, x1;
;                     if constexpr (IB) { const u32x4 w = *(const u32x4*)((const bf16_t*)Xin + ro + bj * HALF);
;                         x0 = (f32x4){bflo(w[0]), bfhi(w[0]), bflo(w[1]), bfhi(w[1])}; x1 = (f32x4){bflo(w[2]), bfhi(w[2]), bflo(w[3]), bfhi(w[3])}; }
;                     else { x0 = *(const f32x4*)((const float*)Xin + ro + bj * HALF); x1 = *(const f32x4*)((const float*)Xin + ro + bj * HALF + 4); }
;                     x0 += acc[ai][bj][m][0] * sc[bj][0]; x1 += acc[ai][bj][m][1] * sc[bj][1];
;                     if constexpr (OB) { u32x4 o; o[0] = pack2(x0[0], x0[1]); o[1] = pack2(x0[2], x0[3]); o[2] = pack2(x1[0], x1[1]); o[3] = pack2(x1[2], x1[3]);
;                         *(u32x4*)((bf16_t*)Xout + ro + bj * HALF) = o; }
;                     else { *(f32x4*)((float*)Xout + ro + bj * HALF) = x0; *(f32x4*)((float*)Xout + ro + bj * HALF + 4) = x1; } } }
	s_nop 1
	v_mov_b32_e32 v120, v164
	v_mov_b32_e32 v121, v165
	v_mov_b32_e32 v122, v166
	v_mov_b32_e32 v123, v167
	s_waitcnt lgkmcnt(0)
	v_lshlrev_b32_e32 v124, 16, v120
	v_and_b32_e32 v125, 0xffff0000, v120
	v_lshlrev_b32_e32 v120, 16, v121
	v_and_b32_e32 v121, 0xffff0000, v121
	v_lshlrev_b32_e32 v126, 16, v122
	v_and_b32_e32 v127, 0xffff0000, v122
	v_lshlrev_b32_e32 v122, 16, v123
	v_and_b32_e32 v123, 0xffff0000, v123
	v_pk_add_f32 v[116:117], v[116:117], v[124:125]
	v_pk_add_f32 v[118:119], v[118:119], v[120:121]
	v_pk_add_f32 v[120:121], v[114:115], v[122:123]
	v_pk_add_f32 v[114:115], v[112:113], v[126:127]
	v_cvt_pk_bf16_f32 v112, v116, v117
	v_lshl_add_u64 v[116:117], v[144:145], 0, s[2:3]
	s_mov_b32 s2, 0x10000
	v_cvt_pk_bf16_f32 v113, v118, v119
	v_add_co_u32_e32 v118, vcc, s2, v144
	v_cvt_pk_bf16_f32 v114, v114, v115
	v_cvt_pk_bf16_f32 v115, v120, v121
	v_addc_co_u32_e32 v119, vcc, 0, v145, vcc
	global_store_dwordx4 v[144:145], v[112:115], off offset:256
	s_waitcnt vmcnt(15)
	s_nop 1
	v_mov_b32_e32 v112, v168
	v_mov_b32_e32 v113, v169
	v_mov_b32_e32 v114, v170
	v_mov_b32_e32 v115, v171
	s_mov_b64 s[2:3], 0x20000
	s_waitcnt lgkmcnt(0)
	v_lshlrev_b32_e32 v120, 16, v112
	v_and_b32_e32 v121, 0xffff0000, v112
	v_lshlrev_b32_e32 v112, 16, v113
	v_and_b32_e32 v113, 0xffff0000, v113
	v_lshlrev_b32_e32 v122, 16, v114
	v_and_b32_e32 v123, 0xffff0000, v114
	v_lshlrev_b32_e32 v114, 16, v115
	v_and_b32_e32 v115, 0xffff0000, v115
	v_pk_add_f32 v[110:111], v[110:111], v[112:113]
	v_pk_add_f32 v[108:109], v[108:109], v[120:121]
	v_pk_add_f32 v[112:113], v[106:107], v[114:115]
	v_pk_add_f32 v[106:107], v[104:105], v[122:123]
	v_cvt_pk_bf16_f32 v104, v108, v109
	v_cvt_pk_bf16_f32 v105, v110, v111
	v_cvt_pk_bf16_f32 v106, v106, v107
	v_cvt_pk_bf16_f32 v107, v112, v113
	global_store_dwordx4 v[118:119], v[104:107], off
	s_waitcnt vmcnt(15)
	s_nop 1
	v_mov_b32_e32 v104, v172
	v_mov_b32_e32 v105, v173
	v_mov_b32_e32 v106, v174
	v_mov_b32_e32 v107, v175
	s_waitcnt lgkmcnt(0)
	v_lshlrev_b32_e32 v108, 16, v104
	v_and_b32_e32 v109, 0xffff0000, v104
	v_lshlrev_b32_e32 v104, 16, v105
	v_and_b32_e32 v105, 0xffff0000, v105
	v_lshlrev_b32_e32 v110, 16, v106
	v_and_b32_e32 v111, 0xffff0000, v106
	v_lshlrev_b32_e32 v106, 16, v107
	v_and_b32_e32 v107, 0xffff0000, v107
	v_pk_add_f32 v[100:101], v[100:101], v[108:109]
	v_pk_add_f32 v[102:103], v[102:103], v[104:105]
	v_pk_add_f32 v[104:105], v[98:99], v[106:107]
	v_pk_add_f32 v[98:99], v[96:97], v[110:111]
	v_cvt_pk_bf16_f32 v96, v100, v101
	v_lshl_add_u64 v[100:101], v[144:145], 0, s[2:3]
	s_mov_b32 s2, 0x20000
	v_cvt_pk_bf16_f32 v97, v102, v103
	v_add_co_u32_e32 v102, vcc, s2, v144
	v_cvt_pk_bf16_f32 v98, v98, v99
	v_cvt_pk_bf16_f32 v99, v104, v105
	v_addc_co_u32_e32 v103, vcc, 0, v145, vcc
	global_store_dwordx4 v[116:117], v[96:99], off offset:256
	s_waitcnt vmcnt(15)
	s_nop 1
	v_mov_b32_e32 v96, v176
	v_mov_b32_e32 v97, v177
	v_mov_b32_e32 v98, v178
	v_mov_b32_e32 v99, v179
	s_mov_b64 s[2:3], 0x30000
	s_waitcnt lgkmcnt(0)
	v_lshlrev_b32_e32 v104, 16, v96
	v_and_b32_e32 v105, 0xffff0000, v96
	v_lshlrev_b32_e32 v96, 16, v97
	v_and_b32_e32 v97, 0xffff0000, v97
	v_lshlrev_b32_e32 v106, 16, v98
	v_and_b32_e32 v107, 0xffff0000, v98
	v_lshlrev_b32_e32 v98, 16, v99
	v_and_b32_e32 v99, 0xffff0000, v99
	v_pk_add_f32 v[94:95], v[94:95], v[96:97]
	v_pk_add_f32 v[92:93], v[92:93], v[104:105]
	v_pk_add_f32 v[96:97], v[90:91], v[98:99]
	v_pk_add_f32 v[90:91], v[88:89], v[106:107]
	v_cvt_pk_bf16_f32 v88, v92, v93
	v_cvt_pk_bf16_f32 v89, v94, v95
	v_cvt_pk_bf16_f32 v90, v90, v91
	v_cvt_pk_bf16_f32 v91, v96, v97
	global_store_dwordx4 v[102:103], v[88:91], off
	s_waitcnt vmcnt(15)
	s_nop 1
	v_mov_b32_e32 v88, v180
	v_mov_b32_e32 v89, v181
	v_mov_b32_e32 v90, v182
	v_mov_b32_e32 v91, v183
	s_waitcnt lgkmcnt(0)
	v_lshlrev_b32_e32 v92, 16, v88
	v_and_b32_e32 v93, 0xffff0000, v88
	v_lshlrev_b32_e32 v88, 16, v89
	v_and_b32_e32 v89, 0xffff0000, v89
	v_lshlrev_b32_e32 v94, 16, v90
	v_and_b32_e32 v95, 0xffff0000, v90
	v_lshlrev_b32_e32 v90, 16, v91
	v_and_b32_e32 v91, 0xffff0000, v91
	v_pk_add_f32 v[86:87], v[86:87], v[88:89]
	v_pk_add_f32 v[84:85], v[84:85], v[92:93]
	v_pk_add_f32 v[88:89], v[82:83], v[90:91]
	v_pk_add_f32 v[82:83], v[80:81], v[94:95]
	v_cvt_pk_bf16_f32 v80, v84, v85
	v_cvt_pk_bf16_f32 v81, v86, v87
	v_cvt_pk_bf16_f32 v82, v82, v83
	v_cvt_pk_bf16_f32 v83, v88, v89
	global_store_dwordx4 v[100:101], v[80:83], off offset:256
	s_nop 1
	v_lshl_add_u64 v[80:81], v[144:145], 0, s[2:3]
	s_mov_b32 s2, 0x30000
	v_add_co_u32_e32 v86, vcc, s2, v144
	s_mov_b64 s[2:3], 0x80000
	s_nop 0
	v_addc_co_u32_e32 v87, vcc, 0, v145, vcc
	s_waitcnt vmcnt(15)
	s_nop 1
	v_mov_b32_e32 v82, v184
	v_mov_b32_e32 v83, v185
	v_mov_b32_e32 v84, v186
	v_mov_b32_e32 v85, v187
	s_waitcnt lgkmcnt(0)
	v_lshlrev_b32_e32 v88, 16, v82
	v_and_b32_e32 v89, 0xffff0000, v82
	v_lshlrev_b32_e32 v82, 16, v83
	v_and_b32_e32 v83, 0xffff0000, v83
	v_lshlrev_b32_e32 v90, 16, v84
	v_and_b32_e32 v91, 0xffff0000, v84
	v_lshlrev_b32_e32 v84, 16, v85
	v_and_b32_e32 v85, 0xffff0000, v85
	v_pk_add_f32 v[78:79], v[78:79], v[82:83]
	v_pk_add_f32 v[76:77], v[76:77], v[88:89]
	v_pk_add_f32 v[82:83], v[74:75], v[84:85]
	v_pk_add_f32 v[74:75], v[72:73], v[90:91]
	v_cvt_pk_bf16_f32 v72, v76, v77
	v_cvt_pk_bf16_f32 v73, v78, v79
	v_cvt_pk_bf16_f32 v74, v74, v75
	v_cvt_pk_bf16_f32 v75, v82, v83
	global_store_dwordx4 v[86:87], v[72:75], off
	s_waitcnt vmcnt(15)
	s_nop 1
	v_mov_b32_e32 v72, v188
	v_mov_b32_e32 v73, v189
	v_mov_b32_e32 v74, v190
	v_mov_b32_e32 v75, v191
	s_waitcnt lgkmcnt(0)
; DI unsigned pack2(float a, float b) { f32x2 v = {a, b}; hwbf16x2 r = __builtin_convertvector(v, hwbf16x2); return __builtin_bit_cast(unsigned, r); }
; DI float bflo(unsigned w) { return __uint_as_float(w << 16); }
; DI float bfhi(unsigned w) { return __uint_as_float(w & 0xffff0000u); }
;     DI void operator()(const f32x4 (&acc)[2][2][4][2], const Unit& u, int wr, int wc, int fr, int fq) const {
;     ...
;             for (int m = 0; m < 4; ++m) { const size_t ro = (size_t)(row0 + ai * HALF + m * 16) * D + col0;
; #pragma unroll
;                 for (int bj = 0; bj < 2; ++bj) {
;                     f32x4 x0, x1;
;                     if constexpr (IB) { const u32x4 w = *(const u32x4*)((const bf16_t*)Xin + ro + bj * HALF);
;                         x0 = (f32x4){bflo(w[0]), bfhi(w[0]), bflo(w[1]), bfhi(w[1])}; x1 = (f32x4){bflo(w[2]), bfhi(w[2]), bflo(w[3]), bfhi(w[3])}; }
;                     else { x0 = *(const f32x4*)((const float*)Xin + ro + bj * HALF); x1 = *(const f32x4*)((const float*)Xin + ro + bj * HALF + 4); }
;                     x0 += acc[ai][bj][m][0] * sc[bj][0]; x1 += acc[ai][bj][m][1] * sc[bj][1];
;                     if constexpr (OB) { u32x4 o; o[0] = pack2(x0[0], x0[1]); o[1] = pack2(x0[2], x0[3]); o[2] = pack2(x1[0], x1[1]); o[3] = pack2(x1[2], x1[3]);
;                         *(u32x4*)((bf16_t*)Xout + ro + bj * HALF) = o; }
;                     else { *(f32x4*)((float*)Xout + ro + bj * HALF) = x0; *(f32x4*)((float*)Xout + ro + bj * HALF + 4) = x1; } } }
	v_lshlrev_b32_e32 v76, 16, v72
	v_and_b32_e32 v77, 0xffff0000, v72
	v_lshlrev_b32_e32 v72, 16, v73
	v_and_b32_e32 v73, 0xffff0000, v73
	v_lshlrev_b32_e32 v78, 16, v74
	v_and_b32_e32 v79, 0xffff0000, v74
	v_lshlrev_b32_e32 v74, 16, v75
	v_and_b32_e32 v75, 0xffff0000, v75
	v_pk_add_f32 v[70:71], v[70:71], v[72:73]
	v_pk_add_f32 v[68:69], v[68:69], v[76:77]
	v_pk_add_f32 v[72:73], v[66:67], v[74:75]
	v_pk_add_f32 v[66:67], v[64:65], v[78:79]
	v_cvt_pk_bf16_f32 v64, v68, v69
	v_cvt_pk_bf16_f32 v65, v70, v71
	v_cvt_pk_bf16_f32 v66, v66, v67
	v_cvt_pk_bf16_f32 v67, v72, v73
	global_store_dwordx4 v[80:81], v[64:67], off offset:256
	s_nop 1
	v_lshl_add_u64 v[64:65], v[144:145], 0, s[2:3]
	s_mov_b32 s2, 0x80000
	v_add_co_u32_e32 v70, vcc, s2, v144
	s_mov_b64 s[2:3], 0x90000
	s_nop 0
	v_addc_co_u32_e32 v71, vcc, 0, v145, vcc
	s_waitcnt vmcnt(15)
	s_nop 1
	v_mov_b32_e32 v66, v192
	v_mov_b32_e32 v67, v193
	v_mov_b32_e32 v68, v194
	v_mov_b32_e32 v69, v195
	s_waitcnt lgkmcnt(0)
	v_lshlrev_b32_e32 v72, 16, v66
	v_and_b32_e32 v73, 0xffff0000, v66
	v_lshlrev_b32_e32 v66, 16, v67
	v_and_b32_e32 v67, 0xffff0000, v67
	v_lshlrev_b32_e32 v74, 16, v68
	v_and_b32_e32 v75, 0xffff0000, v68
	v_lshlrev_b32_e32 v68, 16, v69
	v_and_b32_e32 v69, 0xffff0000, v69
	v_pk_add_f32 v[62:63], v[62:63], v[66:67]
	v_pk_add_f32 v[60:61], v[60:61], v[72:73]
	v_pk_add_f32 v[66:67], v[58:59], v[68:69]
	v_pk_add_f32 v[58:59], v[56:57], v[74:75]
	v_cvt_pk_bf16_f32 v56, v60, v61
	v_cvt_pk_bf16_f32 v57, v62, v63
	v_cvt_pk_bf16_f32 v58, v58, v59
	v_cvt_pk_bf16_f32 v59, v66, v67
	global_store_dwordx4 v[70:71], v[56:59], off
	s_waitcnt vmcnt(15)
	s_nop 1
	v_mov_b32_e32 v56, v198
	v_mov_b32_e32 v57, v199
	v_mov_b32_e32 v58, v200
	v_mov_b32_e32 v59, v201
	s_waitcnt lgkmcnt(0)
	v_lshlrev_b32_e32 v60, 16, v56
	v_and_b32_e32 v61, 0xffff0000, v56
	v_lshlrev_b32_e32 v56, 16, v57
	v_and_b32_e32 v57, 0xffff0000, v57
	v_lshlrev_b32_e32 v62, 16, v58
	v_and_b32_e32 v63, 0xffff0000, v58
	v_lshlrev_b32_e32 v58, 16, v59
	v_and_b32_e32 v59, 0xffff0000, v59
	v_pk_add_f32 v[54:55], v[54:55], v[56:57]
	v_pk_add_f32 v[52:53], v[52:53], v[60:61]
	v_pk_add_f32 v[56:57], v[50:51], v[58:59]
	v_pk_add_f32 v[50:51], v[48:49], v[62:63]
	v_cvt_pk_bf16_f32 v48, v52, v53
	v_cvt_pk_bf16_f32 v49, v54, v55
	v_cvt_pk_bf16_f32 v50, v50, v51
	v_cvt_pk_bf16_f32 v51, v56, v57
	global_store_dwordx4 v[64:65], v[48:51], off offset:256
	s_nop 1
	v_lshl_add_u64 v[48:49], v[144:145], 0, s[2:3]
	s_mov_b32 s2, 0x90000
	v_add_co_u32_e32 v54, vcc, s2, v144
	s_mov_b64 s[2:3], 0xa0000
	s_nop 0
	v_addc_co_u32_e32 v55, vcc, 0, v145, vcc
	s_waitcnt vmcnt(15)
	s_nop 1
	v_mov_b32_e32 v50, v202
	v_mov_b32_e32 v51, v203
	v_mov_b32_e32 v52, v204
	v_mov_b32_e32 v53, v205
	s_waitcnt lgkmcnt(0)
	v_lshlrev_b32_e32 v56, 16, v50
	v_and_b32_e32 v57, 0xffff0000, v50
	v_lshlrev_b32_e32 v50, 16, v51
	v_and_b32_e32 v51, 0xffff0000, v51
	v_lshlrev_b32_e32 v58, 16, v52
	v_and_b32_e32 v59, 0xffff0000, v52
	v_lshlrev_b32_e32 v52, 16, v53
	v_and_b32_e32 v53, 0xffff0000, v53
	v_pk_add_f32 v[46:47], v[46:47], v[50:51]
	v_pk_add_f32 v[44:45], v[44:45], v[56:57]
	v_pk_add_f32 v[50:51], v[42:43], v[52:53]
	v_pk_add_f32 v[42:43], v[40:41], v[58:59]
	v_cvt_pk_bf16_f32 v40, v44, v45
	v_cvt_pk_bf16_f32 v41, v46, v47
	v_cvt_pk_bf16_f32 v42, v42, v43
	v_cvt_pk_bf16_f32 v43, v50, v51
	global_store_dwordx4 v[54:55], v[40:43], off
	s_waitcnt vmcnt(15)
	s_nop 1
	v_mov_b32_e32 v40, v206
	v_mov_b32_e32 v41, v207
	v_mov_b32_e32 v42, v208
	v_mov_b32_e32 v43, v209
	s_waitcnt lgkmcnt(0)
; DI unsigned pack2(float a, float b) { f32x2 v = {a, b}; hwbf16x2 r = __builtin_convertvector(v, hwbf16x2); return __builtin_bit_cast(unsigned, r); }
; DI float bflo(unsigned w) { return __uint_as_float(w << 16); }
; DI float bfhi(unsigned w) { return __uint_as_float(w & 0xffff0000u); }
;     DI const char* a(const Unit& u) const { return (const char*)(A + (size_t)u.pm * BM * lda); }
;     DI const char* a(const Unit& u) const { return (const char*)(A + (size_t)u.pm * BM * 2048 + (u.pn >> 1) * 512); }
; #define PG8_BAR __builtin_amdgcn_s_barrier()
;     DI void operator()(const f32x4 (&acc)[2][2][4][2], const Unit& u, int wr, int wc, int fr, int fq) const {
;     ...
;             for (int m = 0; m < 4; ++m) { const size_t ro = (size_t)(row0 + ai * HALF + m * 16) * D + col0;
; #pragma unroll
;                 for (int bj = 0; bj < 2; ++bj) {
;                     f32x4 x0, x1;
;                     if constexpr (IB) { const u32x4 w = *(const u32x4*)((const bf16_t*)Xin + ro + bj * HALF);
;                         x0 = (f32x4){bflo(w[0]), bfhi(w[0]), bflo(w[1]), bfhi(w[1])}; x1 = (f32x4){bflo(w[2]), bfhi(w[2]), bflo(w[3]), bfhi(w[3])}; }
;                     else { x0 = *(const f32x4*)((const float*)Xin + ro + bj * HALF); x1 = *(const f32x4*)((const float*)Xin + ro + bj * HALF + 4); }
;                     x0 += acc[ai][bj][m][0] * sc[bj][0]; x1 += acc[ai][bj][m][1] * sc[bj][1];
;                     if constexpr (OB) { u32x4 o; o[0] = pack2(x0[0], x0[1]); o[1] = pack2(x0[2], x0[3]); o[2] = pack2(x1[0], x1[1]); o[3] = pack2(x1[2], x1[3]);
;                         *(u32x4*)((bf16_t*)Xout + ro + bj * HALF) = o; }
;                     else { *(f32x4*)((float*)Xout + ro + bj * HALF) = x0; *(f32x4*)((float*)Xout + ro + bj * HALF + 4) = x1; } } }
; template <class Map, class Epi>
; DI void gemm_phase(LAS unsigned char* lds, const Map& MP, const Epi& E, const int nM, const int nN, const int K, const int lda, const int ldb) {
;     ...
;         if (!has_next) break;
; #pragma unroll
;         for (int a = 0; a < 2; ++a)
; #pragma unroll
;             for (int b = 0; b < 2; ++b)
; #pragma unroll
;                 for (int m = 0; m < 4; ++m)
; #pragma unroll
;                     for (int n = 0; n < 2; ++n) acc[a][b][m][n] = (f32x4){0.f, 0.f, 0.f, 0.f};
;         cur = nxt; cA = nA; cB = nB; ++ui;
;     }
;     PG8_WAIT_V(0);
;     if (wr == 0) PG8_BAR;
;     PG8_BAR;
	v_lshlrev_b32_e32 v44, 16, v40
	v_and_b32_e32 v45, 0xffff0000, v40
	v_lshlrev_b32_e32 v40, 16, v41
	v_and_b32_e32 v41, 0xffff0000, v41
	v_lshlrev_b32_e32 v46, 16, v42
	v_and_b32_e32 v47, 0xffff0000, v42
	v_lshlrev_b32_e32 v42, 16, v43
	v_and_b32_e32 v43, 0xffff0000, v43
	v_pk_add_f32 v[38:39], v[38:39], v[40:41]
	v_pk_add_f32 v[36:37], v[36:37], v[44:45]
	v_pk_add_f32 v[40:41], v[34:35], v[42:43]
	v_pk_add_f32 v[34:35], v[32:33], v[46:47]
	v_cvt_pk_bf16_f32 v32, v36, v37
	v_cvt_pk_bf16_f32 v33, v38, v39
	v_cvt_pk_bf16_f32 v34, v34, v35
	v_cvt_pk_bf16_f32 v35, v40, v41
	global_store_dwordx4 v[48:49], v[32:35], off offset:256
	s_nop 1
	v_lshl_add_u64 v[32:33], v[144:145], 0, s[2:3]
	s_mov_b32 s2, 0xa0000
	v_add_co_u32_e32 v38, vcc, s2, v144
	s_mov_b64 s[2:3], 0xb0000
	s_nop 0
	v_addc_co_u32_e32 v39, vcc, 0, v145, vcc
	s_waitcnt vmcnt(15)
	s_nop 1
	v_mov_b32_e32 v34, v210
	v_mov_b32_e32 v35, v211
	v_mov_b32_e32 v36, v212
	v_mov_b32_e32 v37, v213
	s_waitcnt lgkmcnt(0)
	v_lshlrev_b32_e32 v40, 16, v34
	v_and_b32_e32 v41, 0xffff0000, v34
	v_lshlrev_b32_e32 v34, 16, v35
	v_and_b32_e32 v35, 0xffff0000, v35
	v_lshlrev_b32_e32 v42, 16, v36
	v_and_b32_e32 v43, 0xffff0000, v36
	v_lshlrev_b32_e32 v36, 16, v37
	v_and_b32_e32 v37, 0xffff0000, v37
	v_pk_add_f32 v[30:31], v[30:31], v[34:35]
	v_pk_add_f32 v[28:29], v[28:29], v[40:41]
	v_pk_add_f32 v[34:35], v[26:27], v[36:37]
	v_pk_add_f32 v[26:27], v[24:25], v[42:43]
	v_cvt_pk_bf16_f32 v24, v28, v29
	v_cvt_pk_bf16_f32 v25, v30, v31
	v_cvt_pk_bf16_f32 v26, v26, v27
	v_cvt_pk_bf16_f32 v27, v34, v35
	global_store_dwordx4 v[38:39], v[24:27], off
	s_waitcnt vmcnt(15)
	s_nop 1
	v_mov_b32_e32 v24, v214
	v_mov_b32_e32 v25, v215
	v_mov_b32_e32 v26, v216
	v_mov_b32_e32 v27, v217
	s_waitcnt lgkmcnt(0)
	v_lshlrev_b32_e32 v28, 16, v24
	v_and_b32_e32 v29, 0xffff0000, v24
	v_lshlrev_b32_e32 v24, 16, v25
	v_and_b32_e32 v25, 0xffff0000, v25
	v_lshlrev_b32_e32 v30, 16, v26
	v_and_b32_e32 v31, 0xffff0000, v26
	v_lshlrev_b32_e32 v26, 16, v27
	v_and_b32_e32 v27, 0xffff0000, v27
	v_pk_add_f32 v[22:23], v[22:23], v[24:25]
	v_pk_add_f32 v[20:21], v[20:21], v[28:29]
	v_pk_add_f32 v[24:25], v[18:19], v[26:27]
	v_pk_add_f32 v[18:19], v[16:17], v[30:31]
	v_cvt_pk_bf16_f32 v16, v20, v21
	v_cvt_pk_bf16_f32 v17, v22, v23
	v_cvt_pk_bf16_f32 v18, v18, v19
	v_cvt_pk_bf16_f32 v19, v24, v25
	global_store_dwordx4 v[32:33], v[16:19], off offset:256
	s_nop 1
	v_lshl_add_u64 v[16:17], v[144:145], 0, s[2:3]
	s_mov_b32 s2, 0xb0000
	v_add_co_u32_e32 v22, vcc, s2, v144
	s_mov_b32 s2, s55
	s_nop 0
	v_addc_co_u32_e32 v23, vcc, 0, v145, vcc
	s_waitcnt vmcnt(15)
	s_nop 1
	v_mov_b32_e32 v18, v248
	v_mov_b32_e32 v19, v249
	v_mov_b32_e32 v20, v250
	v_mov_b32_e32 v21, v251
	s_and_b64 vcc, exec, s[40:41]
	s_waitcnt lgkmcnt(0)
	v_lshlrev_b32_e32 v24, 16, v18
	v_and_b32_e32 v25, 0xffff0000, v18
	v_lshlrev_b32_e32 v18, 16, v19
	v_and_b32_e32 v19, 0xffff0000, v19
	v_lshlrev_b32_e32 v26, 16, v20
	v_and_b32_e32 v27, 0xffff0000, v20
	v_lshlrev_b32_e32 v20, 16, v21
	v_and_b32_e32 v21, 0xffff0000, v21
	v_pk_add_f32 v[14:15], v[14:15], v[18:19]
	v_pk_add_f32 v[12:13], v[12:13], v[24:25]
	v_pk_add_f32 v[18:19], v[10:11], v[20:21]
	v_pk_add_f32 v[10:11], v[8:9], v[26:27]
	v_cvt_pk_bf16_f32 v8, v12, v13
	v_cvt_pk_bf16_f32 v9, v14, v15
	v_cvt_pk_bf16_f32 v10, v10, v11
	v_cvt_pk_bf16_f32 v11, v18, v19
	global_store_dwordx4 v[22:23], v[8:11], off
	s_waitcnt vmcnt(15)
	s_nop 1
	v_mov_b32_e32 v8, v252
	v_mov_b32_e32 v9, v253
	v_mov_b32_e32 v10, v254
	v_mov_b32_e32 v11, v255
	s_waitcnt lgkmcnt(0)
	v_lshlrev_b32_e32 v12, 16, v8
	v_and_b32_e32 v13, 0xffff0000, v8
	v_lshlrev_b32_e32 v8, 16, v9
	v_and_b32_e32 v9, 0xffff0000, v9
	v_lshlrev_b32_e32 v14, 16, v10
	v_and_b32_e32 v15, 0xffff0000, v10
	v_lshlrev_b32_e32 v10, 16, v11
	v_and_b32_e32 v11, 0xffff0000, v11
	v_pk_add_f32 v[6:7], v[6:7], v[8:9]
	v_pk_add_f32 v[4:5], v[4:5], v[12:13]
	v_pk_add_f32 v[8:9], v[2:3], v[10:11]
	v_pk_add_f32 v[2:3], v[0:1], v[14:15]
	v_cvt_pk_bf16_f32 v0, v4, v5
	v_cvt_pk_bf16_f32 v1, v6, v7
	v_cvt_pk_bf16_f32 v2, v2, v3
	v_cvt_pk_bf16_f32 v3, v8, v9
	global_store_dwordx4 v[16:17], v[0:3], off offset:256
	s_cbranch_vccz .LBB1_543
	s_waitcnt vmcnt(0)
	s_cmpk_gt_u32 s17, 0xff
	s_cbranch_scc1 .LBB1_554
	s_barrier

; #define PG8_STAGE(bufoff, gbase, voff) do { _Pragma("unroll") for (int _i = 0; _i < 2; ++_i) \
;         __builtin_amdgcn_global_load_lds((const unsigned*)((const char*)(gbase) + (voff)[_i]), (LAS unsigned*)(lds + (bufoff) + ldsw + _i * 8192), 16, 0, 0); } while (0)
; #define PG8_LDA(dst, b, h) do { _Pragma("unroll") for (int m = 0; m < 4; ++m) _Pragma("unroll") for (int k = 0; k < 2; ++k) dst[m][k] = *(const LAS bf16x8*)(lds + PG8_SA(b, h) + aoff + m * 2048 + k * 1024); } while (0)
; #define PG8_LDB(dst, b, h) do { _Pragma("unroll") for (int n = 0; n < 2; ++n) _Pragma("unroll") for (int k = 0; k < 2; ++k) dst[n][k] = *(const LAS bf16x8*)(lds + PG8_SB(b, h) + boff + n * 2048 + k * 1024); } while (0)
; #define PG8_MMA(ai, bj, At, Bt) do { __builtin_amdgcn_s_setprio(1); _Pragma("unroll") for (int m = 0; m < 4; ++m) _Pragma("unroll") for (int n = 0; n < 2; ++n) _Pragma("unroll") for (int k = 0; k < 2; ++k) \
;         acc[ai][bj][m][n] = __builtin_amdgcn_mfma_f32_16x16x32_bf16(Bt[n][k], At[m][k], acc[ai][bj][m][n], 0, 0, 0); __builtin_amdgcn_s_setprio(0); } while (0)
; #define PG8_WAIT_V(n) asm volatile("s_waitcnt vmcnt(" #n ")" ::: "memory")
; #define PG8_WAIT_L(n) asm volatile("s_waitcnt lgkmcnt(" #n ")" ::: "memory")
; template <class Map, class Epi>
; DI void gemm_phase(LAS unsigned char* lds, const Map& MP, const Epi& E, const int nM, const int nN, const int K, const int lda, const int ldb) {
;     ...
;             const bool last = (t == nt - 2);
;             const char* a1 = cA + (size_t)(t + 1) * kstep;
;             const char* a2 = last ? nA : cA + (size_t)(t + 2) * kstep; const char* b2 = last ? nB : cB + (size_t)(t + 2) * kstep;
;             const char* a3 = a2 + kstep; const char* b3 = b2 + kstep;
;             PG8_LDB(B0, 0, 0); PG8_SCHED; PG8_LDA(At, 0, 0); PG8_STAGE(PG8_SA(1, 1), a1 + hstepA, voffA);
;             PG8_WAIT_L(8); PG8_BAR; PG8_WAIT_L(0); PG8_MMA(0, 0, At, B0); PG8_BAR; PG8_SCHED;
;             PG8_LDB(B1, 0, 1); PG8_STAGE(PG8_SB(0, 0), b2, voffB);
;             PG8_BAR; PG8_WAIT_L(0); PG8_MMA(0, 1, At, B1); PG8_BAR;
;             PG8_LDA(At, 0, 1); PG8_STAGE(PG8_SA(0, 0), a2, voffA);
;             PG8_BAR; PG8_WAIT_L(0); PG8_MMA(1, 0, At, B0); PG8_BAR; PG8_SCHED;
;             PG8_STAGE(PG8_SB(0, 1), b2 + hstepB, voffB);
;             PG8_WAIT_V(6); PG8_BAR; PG8_MMA(1, 1, At, B1); PG8_BAR;
.LBB1_693:
	s_add_u32 s3, s20, 0xfff80080
	s_addc_u32 s22, s21, -1
	s_cmp_eq_u32 s54, 28
	s_cselect_b32 s25, s15, s22
	s_cselect_b32 s24, s48, s3
	s_cselect_b32 s23, s13, s53
	s_cselect_b32 s22, s49, s52
	s_add_i32 m0, s31, 0xc000
	ds_read_b128 v[166:169], v148
	ds_read_b128 v[170:173], v148 offset:1024
	ds_read_b128 v[174:177], v148 offset:2048
	ds_read_b128 v[178:181], v148 offset:3072
	ds_read_b128 v[182:185], v148 offset:4096
	ds_read_b128 v[186:189], v148 offset:5120
	ds_read_b128 v[190:193], v148 offset:6144
	ds_read_b128 v[198:201], v148 offset:7168
	global_load_lds_dwordx4 v138, s[20:21]
	s_add_i32 m0, s31, 0xe000
	s_nop 0
	global_load_lds_dwordx4 v136, s[20:21]
	s_waitcnt lgkmcnt(7)
	s_setprio 1
	s_barrier
	v_mfma_f32_16x16x32_bf16 v[124:127], v[150:153], v[166:169], v[124:127]
	v_mfma_f32_16x16x32_bf16 v[120:123], v[158:161], v[166:169], v[120:123]
	s_waitcnt lgkmcnt(5)
	v_mfma_f32_16x16x32_bf16 v[116:119], v[150:153], v[174:177], v[116:119]
	v_mfma_f32_16x16x32_bf16 v[112:115], v[158:161], v[174:177], v[112:115]
	s_waitcnt lgkmcnt(3)
	v_mfma_f32_16x16x32_bf16 v[100:103], v[150:153], v[182:185], v[100:103]
	v_mfma_f32_16x16x32_bf16 v[96:99], v[158:161], v[182:185], v[96:99]
	s_waitcnt lgkmcnt(1)
	v_mfma_f32_16x16x32_bf16 v[84:87], v[150:153], v[190:193], v[84:87]
	v_mfma_f32_16x16x32_bf16 v[80:83], v[158:161], v[190:193], v[80:83]
	v_mfma_f32_16x16x32_bf16 v[124:127], v[154:157], v[170:173], v[124:127]
	v_mfma_f32_16x16x32_bf16 v[120:123], v[162:165], v[170:173], v[120:123]
	v_mfma_f32_16x16x32_bf16 v[116:119], v[154:157], v[178:181], v[116:119]
	v_mfma_f32_16x16x32_bf16 v[112:115], v[162:165], v[178:181], v[112:115]
	v_mfma_f32_16x16x32_bf16 v[100:103], v[154:157], v[186:189], v[100:103]
	v_mfma_f32_16x16x32_bf16 v[96:99], v[162:165], v[186:189], v[96:99]
	s_waitcnt lgkmcnt(0)
	v_mfma_f32_16x16x32_bf16 v[84:87], v[154:157], v[198:201], v[84:87]
	v_mfma_f32_16x16x32_bf16 v[80:83], v[162:165], v[198:201], v[80:83]
	s_barrier
	s_setprio 0
	s_add_i32 s3, s44, s29
	v_lshl_add_u64 v[194:195], s[22:23], 0, v[132:133]
	s_mov_b32 m0, s3
	ds_read_b128 v[202:205], v149
	ds_read_b128 v[206:209], v149 offset:1024
	ds_read_b128 v[210:213], v149 offset:2048
	ds_read_b128 v[214:217], v149 offset:3072
	global_load_lds_dwordx4 v[194:195], off
	v_lshl_add_u64 v[218:219], s[22:23], 0, v[128:129]
	s_add_i32 m0, s3, 0x2000
	s_nop 0
	global_load_lds_dwordx4 v[218:219], off
	s_waitcnt lgkmcnt(3)
	s_setprio 1
	s_barrier
	v_mfma_f32_16x16x32_bf16 v[108:111], v[202:205], v[166:169], v[108:111]
	s_waitcnt lgkmcnt(1)
	v_mfma_f32_16x16x32_bf16 v[104:107], v[210:213], v[166:169], v[104:107]
	v_mfma_f32_16x16x32_bf16 v[92:95], v[202:205], v[174:177], v[92:95]
	v_mfma_f32_16x16x32_bf16 v[88:91], v[210:213], v[174:177], v[88:91]
	v_mfma_f32_16x16x32_bf16 v[76:79], v[202:205], v[182:185], v[76:79]
	v_mfma_f32_16x16x32_bf16 v[72:75], v[210:213], v[182:185], v[72:75]
	v_mfma_f32_16x16x32_bf16 v[68:71], v[202:205], v[190:193], v[68:71]
	v_mfma_f32_16x16x32_bf16 v[64:67], v[210:213], v[190:193], v[64:67]
	v_mfma_f32_16x16x32_bf16 v[108:111], v[206:209], v[170:173], v[108:111]
	s_mov_b32 m0, s31
	s_waitcnt lgkmcnt(0)
	v_mfma_f32_16x16x32_bf16 v[104:107], v[214:217], v[170:173], v[104:107]
	v_lshl_add_u64 v[220:221], s[24:25], 0, v[134:135]
	v_mfma_f32_16x16x32_bf16 v[92:95], v[206:209], v[178:181], v[92:95]
	v_mfma_f32_16x16x32_bf16 v[88:91], v[214:217], v[178:181], v[88:91]
	v_mfma_f32_16x16x32_bf16 v[76:79], v[206:209], v[186:189], v[76:79]
	v_mfma_f32_16x16x32_bf16 v[72:75], v[214:217], v[186:189], v[72:75]
	v_mfma_f32_16x16x32_bf16 v[68:71], v[206:209], v[198:201], v[68:71]
	v_mfma_f32_16x16x32_bf16 v[64:67], v[214:217], v[198:201], v[64:67]
	s_barrier
	s_setprio 0
	ds_read_b128 v[166:169], v148 offset:16384
	ds_read_b128 v[170:173], v148 offset:17408
	ds_read_b128 v[174:177], v148 offset:18432
	ds_read_b128 v[178:181], v148 offset:19456
	ds_read_b128 v[182:185], v148 offset:20480
	ds_read_b128 v[186:189], v148 offset:21504
	ds_read_b128 v[190:193], v148 offset:22528
	ds_read_b128 v[198:201], v148 offset:23552
	global_load_lds_dwordx4 v[220:221], off
	v_lshl_add_u64 v[222:223], s[24:25], 0, v[130:131]
	s_mov_b32 m0, s11
	s_nop 0
	global_load_lds_dwordx4 v[222:223], off
	s_waitcnt vmcnt(10) lgkmcnt(7)
	s_setprio 1
	s_barrier
	v_mfma_f32_16x16x32_bf16 v[60:63], v[150:153], v[166:169], v[60:63]
	v_mfma_f32_16x16x32_bf16 v[56:59], v[158:161], v[166:169], v[56:59]
	s_waitcnt lgkmcnt(5)
	v_mfma_f32_16x16x32_bf16 v[52:55], v[150:153], v[174:177], v[52:55]
	v_mfma_f32_16x16x32_bf16 v[48:51], v[158:161], v[174:177], v[48:51]
	s_waitcnt lgkmcnt(3)
	v_mfma_f32_16x16x32_bf16 v[36:39], v[150:153], v[182:185], v[36:39]
	v_mfma_f32_16x16x32_bf16 v[32:35], v[158:161], v[182:185], v[32:35]
	s_waitcnt lgkmcnt(1)
	v_mfma_f32_16x16x32_bf16 v[20:23], v[150:153], v[190:193], v[20:23]
	v_mfma_f32_16x16x32_bf16 v[16:19], v[158:161], v[190:193], v[16:19]
	v_mfma_f32_16x16x32_bf16 v[60:63], v[154:157], v[170:173], v[60:63]
	v_mfma_f32_16x16x32_bf16 v[56:59], v[162:165], v[170:173], v[56:59]
	v_mfma_f32_16x16x32_bf16 v[52:55], v[154:157], v[178:181], v[52:55]
	v_mfma_f32_16x16x32_bf16 v[48:51], v[162:165], v[178:181], v[48:51]
	v_mfma_f32_16x16x32_bf16 v[36:39], v[154:157], v[186:189], v[36:39]
	v_mfma_f32_16x16x32_bf16 v[32:35], v[162:165], v[186:189], v[32:35]
	s_waitcnt lgkmcnt(0)
	v_mfma_f32_16x16x32_bf16 v[20:23], v[154:157], v[198:201], v[20:23]
	v_mfma_f32_16x16x32_bf16 v[16:19], v[162:165], v[198:201], v[16:19]
	s_barrier
	s_setprio 0
	s_add_u32 s56, s22, 0x80000
	s_addc_u32 s57, s23, 0
	s_add_i32 s3, s45, s29
	s_mov_b32 m0, s3
	s_nop 0
	global_load_lds_dwordx4 v132, s[56:57]
	s_add_i32 m0, s3, 0x2000
	s_nop 0
	global_load_lds_dwordx4 v128, s[56:57]
	s_waitcnt vmcnt(6)
	s_setprio 1
	s_barrier
; #define PG8_STAGE(bufoff, gbase, voff) do { _Pragma("unroll") for (int _i = 0; _i < 2; ++_i) \
;         __builtin_amdgcn_global_load_lds((const unsigned*)((const char*)(gbase) + (voff)[_i]), (LAS unsigned*)(lds + (bufoff) + ldsw + _i * 8192), 16, 0, 0); } while (0)
; #define PG8_LDA(dst, b, h) do { _Pragma("unroll") for (int m = 0; m < 4; ++m) _Pragma("unroll") for (int k = 0; k < 2; ++k) dst[m][k] = *(const LAS bf16x8*)(lds + PG8_SA(b, h) + aoff + m * 2048 + k * 1024); } while (0)
; #define PG8_LDB(dst, b, h) do { _Pragma("unroll") for (int n = 0; n < 2; ++n) _Pragma("unroll") for (int k = 0; k < 2; ++k) dst[n][k] = *(const LAS bf16x8*)(lds + PG8_SB(b, h) + boff + n * 2048 + k * 1024); } while (0)
; #define PG8_MMA(ai, bj, At, Bt) do { __builtin_amdgcn_s_setprio(1); _Pragma("unroll") for (int m = 0; m < 4; ++m) _Pragma("unroll") for (int n = 0; n < 2; ++n) _Pragma("unroll") for (int k = 0; k < 2; ++k) \
;         acc[ai][bj][m][n] = __builtin_amdgcn_mfma_f32_16x16x32_bf16(Bt[n][k], At[m][k], acc[ai][bj][m][n], 0, 0, 0); __builtin_amdgcn_s_setprio(0); } while (0)
; #define PG8_WAIT_V(n) asm volatile("s_waitcnt vmcnt(" #n ")" ::: "memory")
; #define PG8_WAIT_L(n) asm volatile("s_waitcnt lgkmcnt(" #n ")" ::: "memory")
; #define PG8_BAR __builtin_amdgcn_s_barrier()
; #define PG8_SCHED __builtin_amdgcn_sched_barrier(0)
; template <class Map, class Epi>
; DI void gemm_phase(LAS unsigned char* lds, const Map& MP, const Epi& E, const int nM, const int nN, const int K, const int lda, const int ldb) {
;     ...
;             PG8_WAIT_V(6); PG8_BAR; PG8_MMA(1, 1, At, B1); PG8_BAR;
;             PG8_LDB(B0, 1, 0); PG8_SCHED; PG8_LDA(At, 1, 0); PG8_STAGE(PG8_SA(0, 1), a2 + hstepA, voffA);
;             PG8_WAIT_L(8); PG8_BAR; PG8_WAIT_L(0); PG8_MMA(0, 0, At, B0); PG8_BAR; PG8_SCHED;
;             PG8_LDB(B1, 1, 1); PG8_STAGE(PG8_SB(1, 0), b3, voffB);
;             PG8_BAR; PG8_WAIT_L(0); PG8_MMA(0, 1, At, B1); PG8_BAR;
;             PG8_LDA(At, 1, 1); PG8_STAGE(PG8_SA(1, 0), a3, voffA);
;             PG8_BAR; PG8_WAIT_L(0); PG8_MMA(1, 0, At, B0); PG8_BAR; PG8_SCHED;
	v_mfma_f32_16x16x32_bf16 v[44:47], v[202:205], v[166:169], v[44:47]
	v_mfma_f32_16x16x32_bf16 v[40:43], v[210:213], v[166:169], v[40:43]
	s_add_i32 s3, 0, 0x18000
	v_add_u32_e32 v162, s3, v146
	ds_read_b128 v[150:153], v162
	v_mfma_f32_16x16x32_bf16 v[28:31], v[202:205], v[174:177], v[28:31]
	v_mfma_f32_16x16x32_bf16 v[24:27], v[210:213], v[174:177], v[24:27]
	ds_read_b128 v[154:157], v162 offset:1024
	v_mfma_f32_16x16x32_bf16 v[12:15], v[202:205], v[182:185], v[12:15]
	v_mfma_f32_16x16x32_bf16 v[8:11], v[210:213], v[182:185], v[8:11]
	ds_read_b128 v[158:161], v162 offset:2048
	v_mfma_f32_16x16x32_bf16 v[4:7], v[202:205], v[190:193], v[4:7]
	v_mfma_f32_16x16x32_bf16 v[0:3], v[210:213], v[190:193], v[0:3]
	ds_read_b128 v[162:165], v162 offset:3072
	v_mfma_f32_16x16x32_bf16 v[44:47], v[206:209], v[170:173], v[44:47]
	v_mfma_f32_16x16x32_bf16 v[40:43], v[214:217], v[170:173], v[40:43]
	v_mfma_f32_16x16x32_bf16 v[28:31], v[206:209], v[178:181], v[28:31]
	v_mfma_f32_16x16x32_bf16 v[24:27], v[214:217], v[178:181], v[24:27]
	v_mfma_f32_16x16x32_bf16 v[12:15], v[206:209], v[186:189], v[12:15]
	v_mfma_f32_16x16x32_bf16 v[8:11], v[214:217], v[186:189], v[8:11]
	v_mfma_f32_16x16x32_bf16 v[4:7], v[206:209], v[198:201], v[4:7]
	v_mfma_f32_16x16x32_bf16 v[0:3], v[214:217], v[198:201], v[0:3]
	s_barrier
	s_setprio 0
	s_add_u32 s24, s24, 0x80000
	s_addc_u32 s25, s25, 0
	s_mov_b32 m0, s34
	ds_read_b128 v[166:169], v148 offset:32768
	ds_read_b128 v[170:173], v148 offset:33792
	ds_read_b128 v[174:177], v148 offset:34816
	ds_read_b128 v[178:181], v148 offset:35840
	ds_read_b128 v[182:185], v148 offset:36864
	ds_read_b128 v[186:189], v148 offset:37888
	ds_read_b128 v[190:193], v148 offset:38912
	ds_read_b128 v[198:201], v148 offset:39936
	global_load_lds_dwordx4 v134, s[24:25]
	s_mov_b32 m0, s35
	s_nop 0
	global_load_lds_dwordx4 v130, s[24:25]
	s_waitcnt lgkmcnt(7)
	s_setprio 1
	s_barrier
	v_mfma_f32_16x16x32_bf16 v[124:127], v[150:153], v[166:169], v[124:127]
	v_mfma_f32_16x16x32_bf16 v[120:123], v[158:161], v[166:169], v[120:123]
	s_waitcnt lgkmcnt(5)
	v_mfma_f32_16x16x32_bf16 v[116:119], v[150:153], v[174:177], v[116:119]
	v_mfma_f32_16x16x32_bf16 v[112:115], v[158:161], v[174:177], v[112:115]
	s_waitcnt lgkmcnt(3)
	v_mfma_f32_16x16x32_bf16 v[100:103], v[150:153], v[182:185], v[100:103]
	v_mfma_f32_16x16x32_bf16 v[96:99], v[158:161], v[182:185], v[96:99]
	s_waitcnt lgkmcnt(1)
	v_mfma_f32_16x16x32_bf16 v[84:87], v[150:153], v[190:193], v[84:87]
	v_mfma_f32_16x16x32_bf16 v[80:83], v[158:161], v[190:193], v[80:83]
	v_mfma_f32_16x16x32_bf16 v[124:127], v[154:157], v[170:173], v[124:127]
	v_mfma_f32_16x16x32_bf16 v[120:123], v[162:165], v[170:173], v[120:123]
	v_mfma_f32_16x16x32_bf16 v[116:119], v[154:157], v[178:181], v[116:119]
	v_mfma_f32_16x16x32_bf16 v[112:115], v[162:165], v[178:181], v[112:115]
	v_mfma_f32_16x16x32_bf16 v[100:103], v[154:157], v[186:189], v[100:103]
	v_mfma_f32_16x16x32_bf16 v[96:99], v[162:165], v[186:189], v[96:99]
	s_waitcnt lgkmcnt(0)
	v_mfma_f32_16x16x32_bf16 v[84:87], v[154:157], v[198:201], v[84:87]
	v_mfma_f32_16x16x32_bf16 v[80:83], v[162:165], v[198:201], v[80:83]
	s_barrier
	s_setprio 0
	s_add_i32 s24, 0, 0x1c000
	s_add_i32 s3, s3, s29
	v_add_u32_e32 v196, s24, v146
	v_lshl_add_u64 v[194:195], v[194:195], 0, s[8:9]
	s_mov_b32 m0, s3
	ds_read_b128 v[202:205], v196
	ds_read_b128 v[206:209], v196 offset:1024
	ds_read_b128 v[210:213], v196 offset:2048
	ds_read_b128 v[214:217], v196 offset:3072
	global_load_lds_dwordx4 v[194:195], off
	v_lshl_add_u64 v[194:195], v[218:219], 0, s[8:9]
	s_add_i32 m0, s3, 0x2000
	s_nop 0
	global_load_lds_dwordx4 v[194:195], off
	s_waitcnt lgkmcnt(3)
	s_setprio 1
	s_barrier
	v_mfma_f32_16x16x32_bf16 v[108:111], v[202:205], v[166:169], v[108:111]
	s_waitcnt lgkmcnt(1)
	v_mfma_f32_16x16x32_bf16 v[104:107], v[210:213], v[166:169], v[104:107]
	v_mfma_f32_16x16x32_bf16 v[92:95], v[202:205], v[174:177], v[92:95]
	v_mfma_f32_16x16x32_bf16 v[88:91], v[210:213], v[174:177], v[88:91]
	v_mfma_f32_16x16x32_bf16 v[76:79], v[202:205], v[182:185], v[76:79]
	v_mfma_f32_16x16x32_bf16 v[72:75], v[210:213], v[182:185], v[72:75]
	v_mfma_f32_16x16x32_bf16 v[68:71], v[202:205], v[190:193], v[68:71]
	v_mfma_f32_16x16x32_bf16 v[64:67], v[210:213], v[190:193], v[64:67]
	v_mfma_f32_16x16x32_bf16 v[108:111], v[206:209], v[170:173], v[108:111]
	s_mov_b32 m0, s39
	s_waitcnt lgkmcnt(0)
	v_mfma_f32_16x16x32_bf16 v[104:107], v[214:217], v[170:173], v[104:107]
	v_lshl_add_u64 v[194:195], v[220:221], 0, s[8:9]
	v_mfma_f32_16x16x32_bf16 v[92:95], v[206:209], v[178:181], v[92:95]
	v_mfma_f32_16x16x32_bf16 v[88:91], v[214:217], v[178:181], v[88:91]
	v_mfma_f32_16x16x32_bf16 v[76:79], v[206:209], v[186:189], v[76:79]
	v_mfma_f32_16x16x32_bf16 v[72:75], v[214:217], v[186:189], v[72:75]
	v_mfma_f32_16x16x32_bf16 v[68:71], v[206:209], v[198:201], v[68:71]
	v_mfma_f32_16x16x32_bf16 v[64:67], v[214:217], v[198:201], v[64:67]
	s_barrier
	s_setprio 0
	ds_read_b128 v[166:169], v148 offset:49152
	ds_read_b128 v[170:173], v148 offset:50176
	ds_read_b128 v[174:177], v148 offset:51200
	ds_read_b128 v[178:181], v148 offset:52224
	ds_read_b128 v[182:185], v148 offset:53248
	ds_read_b128 v[186:189], v148 offset:54272
	ds_read_b128 v[190:193], v148 offset:55296
	ds_read_b128 v[198:201], v148 offset:56320
	global_load_lds_dwordx4 v[194:195], off
	v_lshl_add_u64 v[194:195], v[222:223], 0, s[8:9]
	s_mov_b32 m0, s42
	s_nop 0
	global_load_lds_dwordx4 v[194:195], off
	s_waitcnt vmcnt(10) lgkmcnt(7)
	s_setprio 1
	s_barrier
; #define PG8_STAGE(bufoff, gbase, voff) do { _Pragma("unroll") for (int _i = 0; _i < 2; ++_i) \
;         __builtin_amdgcn_global_load_lds((const unsigned*)((const char*)(gbase) + (voff)[_i]), (LAS unsigned*)(lds + (bufoff) + ldsw + _i * 8192), 16, 0, 0); } while (0)
; #define PG8_MMA(ai, bj, At, Bt) do { __builtin_amdgcn_s_setprio(1); _Pragma("unroll") for (int m = 0; m < 4; ++m) _Pragma("unroll") for (int n = 0; n < 2; ++n) _Pragma("unroll") for (int k = 0; k < 2; ++k) \
;         acc[ai][bj][m][n] = __builtin_amdgcn_mfma_f32_16x16x32_bf16(Bt[n][k], At[m][k], acc[ai][bj][m][n], 0, 0, 0); __builtin_amdgcn_s_setprio(0); } while (0)
; #define PG8_WAIT_V(n) asm volatile("s_waitcnt vmcnt(" #n ")" ::: "memory")
; #define PG8_WAIT_L(n) asm volatile("s_waitcnt lgkmcnt(" #n ")" ::: "memory")
; #define PG8_BAR __builtin_amdgcn_s_barrier()
; #define PG8_SCHED __builtin_amdgcn_sched_barrier(0)
; template <class Map, class Epi>
; DI void gemm_phase(LAS unsigned char* lds, const Map& MP, const Epi& E, const int nM, const int nN, const int K, const int lda, const int ldb) {
;     ...
;             PG8_BAR; PG8_WAIT_L(0); PG8_MMA(1, 0, At, B0); PG8_BAR; PG8_SCHED;
;             PG8_STAGE(PG8_SB(1, 1), b3 + hstepB, voffB);
;             PG8_WAIT_V(6); PG8_BAR; PG8_MMA(1, 1, At, B1); PG8_BAR;
;         }
	v_mfma_f32_16x16x32_bf16 v[60:63], v[150:153], v[166:169], v[60:63]
	v_mfma_f32_16x16x32_bf16 v[56:59], v[158:161], v[166:169], v[56:59]
	s_waitcnt lgkmcnt(5)
	v_mfma_f32_16x16x32_bf16 v[52:55], v[150:153], v[174:177], v[52:55]
	v_mfma_f32_16x16x32_bf16 v[48:51], v[158:161], v[174:177], v[48:51]
	s_waitcnt lgkmcnt(3)
	v_mfma_f32_16x16x32_bf16 v[36:39], v[150:153], v[182:185], v[36:39]
	v_mfma_f32_16x16x32_bf16 v[32:35], v[158:161], v[182:185], v[32:35]
	s_waitcnt lgkmcnt(1)
	v_mfma_f32_16x16x32_bf16 v[20:23], v[150:153], v[190:193], v[20:23]
	v_mfma_f32_16x16x32_bf16 v[16:19], v[158:161], v[190:193], v[16:19]
	v_mfma_f32_16x16x32_bf16 v[60:63], v[154:157], v[170:173], v[60:63]
	v_mfma_f32_16x16x32_bf16 v[56:59], v[162:165], v[170:173], v[56:59]
	v_mfma_f32_16x16x32_bf16 v[52:55], v[154:157], v[178:181], v[52:55]
	v_mfma_f32_16x16x32_bf16 v[48:51], v[162:165], v[178:181], v[48:51]
	v_mfma_f32_16x16x32_bf16 v[36:39], v[154:157], v[186:189], v[36:39]
	v_mfma_f32_16x16x32_bf16 v[32:35], v[162:165], v[186:189], v[32:35]
	s_waitcnt lgkmcnt(0)
	v_mfma_f32_16x16x32_bf16 v[20:23], v[154:157], v[198:201], v[20:23]
	v_mfma_f32_16x16x32_bf16 v[16:19], v[162:165], v[198:201], v[16:19]
	s_barrier
	s_setprio 0
	s_add_u32 s22, s22, 0x80080
	s_addc_u32 s23, s23, 0
	s_add_i32 s3, s24, s29
	s_mov_b32 m0, s3
	s_nop 0
	global_load_lds_dwordx4 v132, s[22:23]
	s_add_i32 m0, s3, 0x2000
	s_nop 0
	global_load_lds_dwordx4 v128, s[22:23]
	s_waitcnt vmcnt(6)
	s_setprio 1
	s_barrier
	v_mfma_f32_16x16x32_bf16 v[44:47], v[202:205], v[166:169], v[44:47]
	v_mfma_f32_16x16x32_bf16 v[40:43], v[210:213], v[166:169], v[40:43]
	ds_read_b128 v[150:153], v147
	v_mfma_f32_16x16x32_bf16 v[28:31], v[202:205], v[174:177], v[28:31]
	v_mfma_f32_16x16x32_bf16 v[24:27], v[210:213], v[174:177], v[24:27]
	ds_read_b128 v[154:157], v147 offset:1024
	v_mfma_f32_16x16x32_bf16 v[12:15], v[202:205], v[182:185], v[12:15]
	v_mfma_f32_16x16x32_bf16 v[8:11], v[210:213], v[182:185], v[8:11]
	ds_read_b128 v[158:161], v147 offset:2048
	v_mfma_f32_16x16x32_bf16 v[4:7], v[202:205], v[190:193], v[4:7]
	v_mfma_f32_16x16x32_bf16 v[0:3], v[210:213], v[190:193], v[0:3]
	ds_read_b128 v[162:165], v147 offset:3072
	v_mfma_f32_16x16x32_bf16 v[44:47], v[206:209], v[170:173], v[44:47]
	s_add_i32 s54, s54, 2
	v_mfma_f32_16x16x32_bf16 v[40:43], v[214:217], v[170:173], v[40:43]
	s_add_u32 s52, s52, 0x100
	s_addc_u32 s53, s53, 0
	v_mfma_f32_16x16x32_bf16 v[28:31], v[206:209], v[178:181], v[28:31]
	s_add_u32 s20, s20, 0x100
	s_addc_u32 s21, s21, 0
	v_mfma_f32_16x16x32_bf16 v[24:27], v[214:217], v[178:181], v[24:27]
	s_cmp_gt_u32 s54, 29
	v_mfma_f32_16x16x32_bf16 v[12:15], v[206:209], v[186:189], v[12:15]
	v_mfma_f32_16x16x32_bf16 v[8:11], v[214:217], v[186:189], v[8:11]
	v_mfma_f32_16x16x32_bf16 v[4:7], v[206:209], v[198:201], v[4:7]
	v_mfma_f32_16x16x32_bf16 v[0:3], v[214:217], v[198:201], v[0:3]
	s_barrier
	s_setprio 0
	s_cbranch_scc0 .LBB1_693
; DI unsigned pack2(float a, float b) { f32x2 v = {a, b}; hwbf16x2 r = __builtin_convertvector(v, hwbf16x2); return __builtin_bit_cast(unsigned, r); }
;     DI const char* a(const Unit& u) const { return (const char*)(A + (size_t)u.pm * BM * lda); }
;     DI const char* a(const Unit& u) const { return (const char*)(A + (size_t)u.pm * BM * 2048 + (u.pn >> 1) * 512); }
;     DI const char* a(const Unit& u) const { return (const char*)((u.pn < 12 ? A1 : A2) + (size_t)u.pm * BM * 512); }
; #define PG8_WAIT_V(n) asm volatile("s_waitcnt vmcnt(" #n ")" ::: "memory")
; #define PG8_BAR __builtin_amdgcn_s_barrier()
;     DI void operator()(const f32x4 (&acc)[2][2][4][2], const Unit& u, int wr, int wc, int fr, int fq) const {
;         bf16_t* O = O1; int ldc = ldc1, pn = u.pn; if (pn >= split) { O = O2; ldc = ldc2; pn -= split; }
;         const int row0 = u.pm * BM + wr * 64 + fr, col0 = pn * BM + wc * 32 + 8 * fq;
; #pragma unroll
;         for (int ai = 0; ai < 2; ++ai)
; #pragma unroll
;             for (int m = 0; m < 4; ++m) { bf16_t* rowp = O + (size_t)(row0 + ai * HALF + m * 16) * ldc + col0;
; #pragma unroll
;                 for (int bj = 0; bj < 2; ++bj) { const f32x4 v0 = acc[ai][bj][m][0], v1 = acc[ai][bj][m][1];
;                     u32x4 o; o[0] = pack2(v0[0], v0[1]); o[1] = pack2(v0[2], v0[3]); o[2] = pack2(v1[0], v1[1]); o[3] = pack2(v1[2], v1[3]);
;                     *(u32x4*)(rowp + bj * HALF) = o; } }
;     }
; template <class Map, class Epi>
; DI void gemm_phase(LAS unsigned char* lds, const Map& MP, const Epi& E, const int nM, const int nN, const int K, const int lda, const int ldb) {
;     ...
;         if (!has_next) break;
; #pragma unroll
;         for (int a = 0; a < 2; ++a)
; #pragma unroll
;             for (int b = 0; b < 2; ++b)
; #pragma unroll
;                 for (int m = 0; m < 4; ++m)
; #pragma unroll
;                     for (int n = 0; n < 2; ++n) acc[a][b][m][n] = (f32x4){0.f, 0.f, 0.f, 0.f};
;         cur = nxt; cA = nA; cB = nB; ++ui;
;     }
;     PG8_WAIT_V(0);
;     if (wr == 0) PG8_BAR;
;     PG8_BAR;
	s_waitcnt lgkmcnt(0)
	s_lshl_b32 s3, s10, 8
	v_mov_b32_e32 v150, v144
	v_mov_b32_e32 v151, v145
	s_add_i32 s3, s3, s37
	v_cvt_pk_bf16_f32 v68, v68, v69
	v_add_u32_e32 v154, s3, v150
	s_lshl_b32 s3, s47, 8
	s_or_b32 s3, s3, s38
	v_lshl_add_u32 v150, v151, 3, s3
	v_ashrrev_i32_e32 v151, 31, v150
	v_lshl_add_u64 v[150:151], v[150:151], 1, s[6:7]
	v_cvt_pk_bf16_f32 v69, v70, v71
	v_cvt_pk_bf16_f32 v70, v64, v65
	v_add_u32_e32 v64, 0x80, v154
	v_mad_i64_i32 v[152:153], s[20:21], v154, s46, v[150:151]
	v_cvt_pk_bf16_f32 v108, v108, v109
	v_cvt_pk_bf16_f32 v109, v110, v111
	v_cvt_pk_bf16_f32 v110, v104, v105
	v_cvt_pk_bf16_f32 v111, v106, v107
	v_add_u32_e32 v104, 16, v154
	v_mad_i64_i32 v[64:65], s[20:21], v64, s46, v[150:151]
	v_cvt_pk_bf16_f32 v44, v44, v45
	v_cvt_pk_bf16_f32 v45, v46, v47
	v_cvt_pk_bf16_f32 v46, v40, v41
	v_cvt_pk_bf16_f32 v47, v42, v43
	v_add_u32_e32 v40, 0x90, v154
	global_store_dwordx4 v[152:153], v[108:111], off offset:256
	v_cvt_pk_bf16_f32 v92, v92, v93
	v_cvt_pk_bf16_f32 v93, v94, v95
	v_mad_i64_i32 v[108:109], s[20:21], v104, s46, v[150:151]
	v_cvt_pk_bf16_f32 v94, v88, v89
	v_cvt_pk_bf16_f32 v95, v90, v91
	v_add_u32_e32 v88, 32, v154
	global_store_dwordx4 v[64:65], v[44:47], off offset:256
	v_cvt_pk_bf16_f32 v28, v28, v29
	v_cvt_pk_bf16_f32 v29, v30, v31
	v_mad_i64_i32 v[44:45], s[20:21], v40, s46, v[150:151]
	v_cvt_pk_bf16_f32 v30, v24, v25
	v_cvt_pk_bf16_f32 v31, v26, v27
	v_add_u32_e32 v24, 0xa0, v154
	global_store_dwordx4 v[108:109], v[92:95], off offset:256
	v_cvt_pk_bf16_f32 v76, v76, v77
	v_cvt_pk_bf16_f32 v77, v78, v79
	v_mad_i64_i32 v[92:93], s[20:21], v88, s46, v[150:151]
	v_cvt_pk_bf16_f32 v78, v72, v73
	v_cvt_pk_bf16_f32 v79, v74, v75
	v_add_u32_e32 v72, 48, v154
	global_store_dwordx4 v[44:45], v[28:31], off offset:256
	v_cvt_pk_bf16_f32 v12, v12, v13
	v_cvt_pk_bf16_f32 v13, v14, v15
	v_mad_i64_i32 v[28:29], s[20:21], v24, s46, v[150:151]
	v_cvt_pk_bf16_f32 v14, v8, v9
	v_cvt_pk_bf16_f32 v15, v10, v11
	v_add_u32_e32 v8, 0xb0, v154
	global_store_dwordx4 v[92:93], v[76:79], off offset:256
	global_store_dwordx4 v[28:29], v[12:15], off offset:256
	v_cvt_pk_bf16_f32 v124, v124, v125
	v_mad_i64_i32 v[76:77], s[20:21], v72, s46, v[150:151]
	v_mad_i64_i32 v[12:13], s[20:21], v8, s46, v[150:151]
	v_cvt_pk_bf16_f32 v125, v126, v127
	v_cvt_pk_bf16_f32 v126, v120, v121
	v_cvt_pk_bf16_f32 v127, v122, v123
	v_cvt_pk_bf16_f32 v104, v116, v117
	v_cvt_pk_bf16_f32 v105, v118, v119
	v_cvt_pk_bf16_f32 v106, v112, v113
	v_cvt_pk_bf16_f32 v107, v114, v115
	v_cvt_pk_bf16_f32 v88, v100, v101
	v_cvt_pk_bf16_f32 v89, v102, v103
	v_cvt_pk_bf16_f32 v90, v96, v97
	v_cvt_pk_bf16_f32 v91, v98, v99
	v_cvt_pk_bf16_f32 v72, v84, v85
	v_cvt_pk_bf16_f32 v73, v86, v87
	v_cvt_pk_bf16_f32 v74, v80, v81
	v_cvt_pk_bf16_f32 v75, v82, v83
	v_cvt_pk_bf16_f32 v71, v66, v67
	v_cvt_pk_bf16_f32 v60, v60, v61
	v_cvt_pk_bf16_f32 v61, v62, v63
	v_cvt_pk_bf16_f32 v62, v56, v57
	v_cvt_pk_bf16_f32 v63, v58, v59
	v_cvt_pk_bf16_f32 v40, v52, v53
	v_cvt_pk_bf16_f32 v41, v54, v55
	v_cvt_pk_bf16_f32 v42, v48, v49
	v_cvt_pk_bf16_f32 v43, v50, v51
	v_cvt_pk_bf16_f32 v24, v36, v37
	v_cvt_pk_bf16_f32 v25, v38, v39
	v_cvt_pk_bf16_f32 v26, v32, v33
	v_cvt_pk_bf16_f32 v27, v34, v35
	v_cvt_pk_bf16_f32 v8, v20, v21
	v_cvt_pk_bf16_f32 v9, v22, v23
	v_cvt_pk_bf16_f32 v10, v16, v17
	v_cvt_pk_bf16_f32 v11, v18, v19
	v_cvt_pk_bf16_f32 v4, v4, v5
	v_cvt_pk_bf16_f32 v5, v6, v7
	v_cvt_pk_bf16_f32 v6, v0, v1
	v_cvt_pk_bf16_f32 v7, v2, v3
	s_and_b64 vcc, exec, s[40:41]
	s_mov_b32 s47, s12
	s_mov_b32 s10, s14
	s_mov_b64 s[20:21], s[18:19]
	s_mov_b64 s[22:23], s[16:17]
	global_store_dwordx4 v[152:153], v[124:127], off
	global_store_dwordx4 v[108:109], v[104:107], off
	global_store_dwordx4 v[92:93], v[88:91], off
	global_store_dwordx4 v[76:77], v[72:75], off
	global_store_dwordx4 v[76:77], v[68:71], off offset:256
	global_store_dwordx4 v[64:65], v[60:63], off
	global_store_dwordx4 v[44:45], v[40:43], off
	global_store_dwordx4 v[28:29], v[24:27], off
	global_store_dwordx4 v[12:13], v[8:11], off
	global_store_dwordx4 v[12:13], v[4:7], off offset:256
	s_cbranch_vccz .LBB1_690
	s_waitcnt vmcnt(0)
	s_cmpk_gt_u32 s4, 0xff
	s_cbranch_scc1 .LBB1_697
	s_barrier

; #define PG8_STAGE(bufoff, gbase, voff) do { _Pragma("unroll") for (int _i = 0; _i < 2; ++_i) \
;         __builtin_amdgcn_global_load_lds((const unsigned*)((const char*)(gbase) + (voff)[_i]), (LAS unsigned*)(lds + (bufoff) + ldsw + _i * 8192), 16, 0, 0); } while (0)
; #define PG8_LDA(dst, b, h) do { _Pragma("unroll") for (int m = 0; m < 4; ++m) _Pragma("unroll") for (int k = 0; k < 2; ++k) dst[m][k] = *(const LAS bf16x8*)(lds + PG8_SA(b, h) + aoff + m * 2048 + k * 1024); } while (0)
; #define PG8_LDB(dst, b, h) do { _Pragma("unroll") for (int n = 0; n < 2; ++n) _Pragma("unroll") for (int k = 0; k < 2; ++k) dst[n][k] = *(const LAS bf16x8*)(lds + PG8_SB(b, h) + boff + n * 2048 + k * 1024); } while (0)
; #define PG8_MMA(ai, bj, At, Bt) do { __builtin_amdgcn_s_setprio(1); _Pragma("unroll") for (int m = 0; m < 4; ++m) _Pragma("unroll") for (int n = 0; n < 2; ++n) _Pragma("unroll") for (int k = 0; k < 2; ++k) \
;         acc[ai][bj][m][n] = __builtin_amdgcn_mfma_f32_16x16x32_bf16(Bt[n][k], At[m][k], acc[ai][bj][m][n], 0, 0, 0); __builtin_amdgcn_s_setprio(0); } while (0)
; #define PG8_WAIT_V(n) asm volatile("s_waitcnt vmcnt(" #n ")" ::: "memory")
; #define PG8_WAIT_L(n) asm volatile("s_waitcnt lgkmcnt(" #n ")" ::: "memory")
; template <class Map, class Epi>
; DI void gemm_phase(LAS unsigned char* lds, const Map& MP, const Epi& E, const int nM, const int nN, const int K, const int lda, const int ldb) {
;     ...
;             const bool last = (t == nt - 2);
;             const char* a1 = cA + (size_t)(t + 1) * kstep;
;             const char* a2 = last ? nA : cA + (size_t)(t + 2) * kstep; const char* b2 = last ? nB : cB + (size_t)(t + 2) * kstep;
;             const char* a3 = a2 + kstep; const char* b3 = b2 + kstep;
;             PG8_LDB(B0, 0, 0); PG8_SCHED; PG8_LDA(At, 0, 0); PG8_STAGE(PG8_SA(1, 1), a1 + hstepA, voffA);
;             PG8_WAIT_L(8); PG8_BAR; PG8_WAIT_L(0); PG8_MMA(0, 0, At, B0); PG8_BAR; PG8_SCHED;
;             PG8_LDB(B1, 0, 1); PG8_STAGE(PG8_SB(0, 0), b2, voffB);
;             PG8_BAR; PG8_WAIT_L(0); PG8_MMA(0, 1, At, B1); PG8_BAR;
;             PG8_LDA(At, 0, 1); PG8_STAGE(PG8_SA(0, 0), a2, voffA);
;             PG8_BAR; PG8_WAIT_L(0); PG8_MMA(1, 0, At, B0); PG8_BAR; PG8_SCHED;
;             PG8_STAGE(PG8_SB(0, 1), b2 + hstepB, voffB);
;             PG8_WAIT_V(6); PG8_BAR; PG8_MMA(1, 1, At, B1); PG8_BAR;
.LBB1_925:
	s_add_u32 s3, s10, 0xfff80080
	s_addc_u32 s12, s11, -1
	s_cmp_eq_u32 s48, 28
	s_cselect_b32 s15, s4, s12
	s_cselect_b32 s14, s5, s3
	s_cselect_b32 s13, s37, s47
	s_cselect_b32 s12, s38, s39
	s_add_i32 m0, s24, 0xc000
	ds_read_b128 v[168:171], v150
	ds_read_b128 v[172:175], v150 offset:1024
	ds_read_b128 v[176:179], v150 offset:2048
	ds_read_b128 v[180:183], v150 offset:3072
	ds_read_b128 v[184:187], v150 offset:4096
	ds_read_b128 v[188:191], v150 offset:5120
	ds_read_b128 v[192:195], v150 offset:6144
	ds_read_b128 v[198:201], v150 offset:7168
	global_load_lds_dwordx4 v138, s[10:11]
	s_add_i32 m0, s24, 0xe000
	s_nop 0
	global_load_lds_dwordx4 v136, s[10:11]
	s_waitcnt lgkmcnt(7)
	s_setprio 1
	s_barrier
	v_mfma_f32_16x16x32_bf16 v[124:127], v[152:155], v[168:171], v[124:127]
	v_mfma_f32_16x16x32_bf16 v[120:123], v[160:163], v[168:171], v[120:123]
	s_waitcnt lgkmcnt(5)
	v_mfma_f32_16x16x32_bf16 v[108:111], v[152:155], v[176:179], v[108:111]
	v_mfma_f32_16x16x32_bf16 v[104:107], v[160:163], v[176:179], v[104:107]
	s_waitcnt lgkmcnt(3)
	v_mfma_f32_16x16x32_bf16 v[92:95], v[152:155], v[184:187], v[92:95]
	v_mfma_f32_16x16x32_bf16 v[88:91], v[160:163], v[184:187], v[88:91]
	s_waitcnt lgkmcnt(1)
	v_mfma_f32_16x16x32_bf16 v[76:79], v[152:155], v[192:195], v[76:79]
	v_mfma_f32_16x16x32_bf16 v[72:75], v[160:163], v[192:195], v[72:75]
	v_mfma_f32_16x16x32_bf16 v[124:127], v[156:159], v[172:175], v[124:127]
	v_mfma_f32_16x16x32_bf16 v[120:123], v[164:167], v[172:175], v[120:123]
	v_mfma_f32_16x16x32_bf16 v[108:111], v[156:159], v[180:183], v[108:111]
	v_mfma_f32_16x16x32_bf16 v[104:107], v[164:167], v[180:183], v[104:107]
	v_mfma_f32_16x16x32_bf16 v[92:95], v[156:159], v[188:191], v[92:95]
	v_mfma_f32_16x16x32_bf16 v[88:91], v[164:167], v[188:191], v[88:91]
	s_waitcnt lgkmcnt(0)
	v_mfma_f32_16x16x32_bf16 v[76:79], v[156:159], v[198:201], v[76:79]
	v_mfma_f32_16x16x32_bf16 v[72:75], v[164:167], v[198:201], v[72:75]
	s_barrier
	s_setprio 0
	s_add_i32 s3, s35, s22
	v_lshl_add_u64 v[144:145], s[12:13], 0, v[132:133]
	s_mov_b32 m0, s3
	ds_read_b128 v[202:205], v151
	ds_read_b128 v[206:209], v151 offset:1024
	ds_read_b128 v[210:213], v151 offset:2048
	ds_read_b128 v[214:217], v151 offset:3072
	global_load_lds_dwordx4 v[144:145], off
	v_lshl_add_u64 v[218:219], s[12:13], 0, v[128:129]
	s_add_i32 m0, s3, 0x2000
	s_nop 0
	global_load_lds_dwordx4 v[218:219], off
	s_waitcnt lgkmcnt(3)
	s_setprio 1
	s_barrier
	v_mfma_f32_16x16x32_bf16 v[116:119], v[202:205], v[168:171], v[116:119]
	s_waitcnt lgkmcnt(1)
	v_mfma_f32_16x16x32_bf16 v[112:115], v[210:213], v[168:171], v[112:115]
	v_mfma_f32_16x16x32_bf16 v[100:103], v[202:205], v[176:179], v[100:103]
	v_mfma_f32_16x16x32_bf16 v[96:99], v[210:213], v[176:179], v[96:99]
	v_mfma_f32_16x16x32_bf16 v[84:87], v[202:205], v[184:187], v[84:87]
	v_mfma_f32_16x16x32_bf16 v[80:83], v[210:213], v[184:187], v[80:83]
	v_mfma_f32_16x16x32_bf16 v[68:71], v[202:205], v[192:195], v[68:71]
	v_mfma_f32_16x16x32_bf16 v[64:67], v[210:213], v[192:195], v[64:67]
	v_mfma_f32_16x16x32_bf16 v[116:119], v[206:209], v[172:175], v[116:119]
	s_mov_b32 m0, s24
	s_waitcnt lgkmcnt(0)
	v_mfma_f32_16x16x32_bf16 v[112:115], v[214:217], v[172:175], v[112:115]
	v_lshl_add_u64 v[220:221], s[14:15], 0, v[134:135]
	v_mfma_f32_16x16x32_bf16 v[100:103], v[206:209], v[180:183], v[100:103]
	v_mfma_f32_16x16x32_bf16 v[96:99], v[214:217], v[180:183], v[96:99]
	v_mfma_f32_16x16x32_bf16 v[84:87], v[206:209], v[188:191], v[84:87]
	v_mfma_f32_16x16x32_bf16 v[80:83], v[214:217], v[188:191], v[80:83]
	v_mfma_f32_16x16x32_bf16 v[68:71], v[206:209], v[198:201], v[68:71]
	v_mfma_f32_16x16x32_bf16 v[64:67], v[214:217], v[198:201], v[64:67]
	s_barrier
	s_setprio 0
	ds_read_b128 v[168:171], v150 offset:16384
	ds_read_b128 v[172:175], v150 offset:17408
	ds_read_b128 v[176:179], v150 offset:18432
	ds_read_b128 v[180:183], v150 offset:19456
	ds_read_b128 v[184:187], v150 offset:20480
	ds_read_b128 v[188:191], v150 offset:21504
	ds_read_b128 v[192:195], v150 offset:22528
	ds_read_b128 v[198:201], v150 offset:23552
	global_load_lds_dwordx4 v[220:221], off
	v_lshl_add_u64 v[222:223], s[14:15], 0, v[130:131]
	s_mov_b32 m0, s9
	s_nop 0
	global_load_lds_dwordx4 v[222:223], off
	s_waitcnt vmcnt(10) lgkmcnt(7)
	s_setprio 1
	s_barrier
	v_mfma_f32_16x16x32_bf16 v[60:63], v[152:155], v[168:171], v[60:63]
	v_mfma_f32_16x16x32_bf16 v[56:59], v[160:163], v[168:171], v[56:59]
	s_waitcnt lgkmcnt(5)
	v_mfma_f32_16x16x32_bf16 v[44:47], v[152:155], v[176:179], v[44:47]
	v_mfma_f32_16x16x32_bf16 v[40:43], v[160:163], v[176:179], v[40:43]
	s_waitcnt lgkmcnt(3)
	v_mfma_f32_16x16x32_bf16 v[28:31], v[152:155], v[184:187], v[28:31]
	v_mfma_f32_16x16x32_bf16 v[24:27], v[160:163], v[184:187], v[24:27]
	s_waitcnt lgkmcnt(1)
	v_mfma_f32_16x16x32_bf16 v[12:15], v[152:155], v[192:195], v[12:15]
	v_mfma_f32_16x16x32_bf16 v[8:11], v[160:163], v[192:195], v[8:11]
	v_mfma_f32_16x16x32_bf16 v[60:63], v[156:159], v[172:175], v[60:63]
	v_mfma_f32_16x16x32_bf16 v[56:59], v[164:167], v[172:175], v[56:59]
	v_mfma_f32_16x16x32_bf16 v[44:47], v[156:159], v[180:183], v[44:47]
	v_mfma_f32_16x16x32_bf16 v[40:43], v[164:167], v[180:183], v[40:43]
	v_mfma_f32_16x16x32_bf16 v[28:31], v[156:159], v[188:191], v[28:31]
	v_mfma_f32_16x16x32_bf16 v[24:27], v[164:167], v[188:191], v[24:27]
	s_waitcnt lgkmcnt(0)
	v_mfma_f32_16x16x32_bf16 v[12:15], v[156:159], v[198:201], v[12:15]
	v_mfma_f32_16x16x32_bf16 v[8:11], v[164:167], v[198:201], v[8:11]
	s_barrier
	s_setprio 0
	s_add_u32 s56, s12, 0x80000
	s_addc_u32 s57, s13, 0
	s_add_i32 s3, s36, s22
	s_mov_b32 m0, s3
	s_nop 0
	global_load_lds_dwordx4 v132, s[56:57]
	s_add_i32 m0, s3, 0x2000
	s_nop 0
	global_load_lds_dwordx4 v128, s[56:57]
	s_waitcnt vmcnt(6)
	s_setprio 1
	s_barrier
; #define PG8_STAGE(bufoff, gbase, voff) do { _Pragma("unroll") for (int _i = 0; _i < 2; ++_i) \
;         __builtin_amdgcn_global_load_lds((const unsigned*)((const char*)(gbase) + (voff)[_i]), (LAS unsigned*)(lds + (bufoff) + ldsw + _i * 8192), 16, 0, 0); } while (0)
; #define PG8_LDA(dst, b, h) do { _Pragma("unroll") for (int m = 0; m < 4; ++m) _Pragma("unroll") for (int k = 0; k < 2; ++k) dst[m][k] = *(const LAS bf16x8*)(lds + PG8_SA(b, h) + aoff + m * 2048 + k * 1024); } while (0)
; #define PG8_LDB(dst, b, h) do { _Pragma("unroll") for (int n = 0; n < 2; ++n) _Pragma("unroll") for (int k = 0; k < 2; ++k) dst[n][k] = *(const LAS bf16x8*)(lds + PG8_SB(b, h) + boff + n * 2048 + k * 1024); } while (0)
; #define PG8_MMA(ai, bj, At, Bt) do { __builtin_amdgcn_s_setprio(1); _Pragma("unroll") for (int m = 0; m < 4; ++m) _Pragma("unroll") for (int n = 0; n < 2; ++n) _Pragma("unroll") for (int k = 0; k < 2; ++k) \
;         acc[ai][bj][m][n] = __builtin_amdgcn_mfma_f32_16x16x32_bf16(Bt[n][k], At[m][k], acc[ai][bj][m][n], 0, 0, 0); __builtin_amdgcn_s_setprio(0); } while (0)
; #define PG8_WAIT_V(n) asm volatile("s_waitcnt vmcnt(" #n ")" ::: "memory")
; #define PG8_WAIT_L(n) asm volatile("s_waitcnt lgkmcnt(" #n ")" ::: "memory")
; #define PG8_BAR __builtin_amdgcn_s_barrier()
; #define PG8_SCHED __builtin_amdgcn_sched_barrier(0)
; template <class Map, class Epi>
; DI void gemm_phase(LAS unsigned char* lds, const Map& MP, const Epi& E, const int nM, const int nN, const int K, const int lda, const int ldb) {
;     ...
;             PG8_WAIT_V(6); PG8_BAR; PG8_MMA(1, 1, At, B1); PG8_BAR;
;             PG8_LDB(B0, 1, 0); PG8_SCHED; PG8_LDA(At, 1, 0); PG8_STAGE(PG8_SA(0, 1), a2 + hstepA, voffA);
;             PG8_WAIT_L(8); PG8_BAR; PG8_WAIT_L(0); PG8_MMA(0, 0, At, B0); PG8_BAR; PG8_SCHED;
;             PG8_LDB(B1, 1, 1); PG8_STAGE(PG8_SB(1, 0), b3, voffB);
;             PG8_BAR; PG8_WAIT_L(0); PG8_MMA(0, 1, At, B1); PG8_BAR;
;             PG8_LDA(At, 1, 1); PG8_STAGE(PG8_SA(1, 0), a3, voffA);
;             PG8_BAR; PG8_WAIT_L(0); PG8_MMA(1, 0, At, B0); PG8_BAR; PG8_SCHED;
	v_mfma_f32_16x16x32_bf16 v[52:55], v[202:205], v[168:171], v[52:55]
	v_mfma_f32_16x16x32_bf16 v[48:51], v[210:213], v[168:171], v[48:51]
	s_add_i32 s3, 0, 0x18000
	v_add_u32_e32 v164, s3, v148
	ds_read_b128 v[152:155], v164
	v_mfma_f32_16x16x32_bf16 v[36:39], v[202:205], v[176:179], v[36:39]
	v_mfma_f32_16x16x32_bf16 v[32:35], v[210:213], v[176:179], v[32:35]
	ds_read_b128 v[156:159], v164 offset:1024
	v_mfma_f32_16x16x32_bf16 v[20:23], v[202:205], v[184:187], v[20:23]
	v_mfma_f32_16x16x32_bf16 v[16:19], v[210:213], v[184:187], v[16:19]
	ds_read_b128 v[160:163], v164 offset:2048
	v_mfma_f32_16x16x32_bf16 v[4:7], v[202:205], v[192:195], v[4:7]
	v_mfma_f32_16x16x32_bf16 v[0:3], v[210:213], v[192:195], v[0:3]
	ds_read_b128 v[164:167], v164 offset:3072
	v_mfma_f32_16x16x32_bf16 v[52:55], v[206:209], v[172:175], v[52:55]
	v_mfma_f32_16x16x32_bf16 v[48:51], v[214:217], v[172:175], v[48:51]
	v_mfma_f32_16x16x32_bf16 v[36:39], v[206:209], v[180:183], v[36:39]
	v_mfma_f32_16x16x32_bf16 v[32:35], v[214:217], v[180:183], v[32:35]
	v_mfma_f32_16x16x32_bf16 v[20:23], v[206:209], v[188:191], v[20:23]
	v_mfma_f32_16x16x32_bf16 v[16:19], v[214:217], v[188:191], v[16:19]
	v_mfma_f32_16x16x32_bf16 v[4:7], v[206:209], v[198:201], v[4:7]
	v_mfma_f32_16x16x32_bf16 v[0:3], v[214:217], v[198:201], v[0:3]
	s_barrier
	s_setprio 0
	s_add_u32 s14, s14, 0x80000
	s_addc_u32 s15, s15, 0
	s_mov_b32 m0, s25
	ds_read_b128 v[168:171], v150 offset:32768
	ds_read_b128 v[172:175], v150 offset:33792
	ds_read_b128 v[176:179], v150 offset:34816
	ds_read_b128 v[180:183], v150 offset:35840
	ds_read_b128 v[184:187], v150 offset:36864
	ds_read_b128 v[188:191], v150 offset:37888
	ds_read_b128 v[192:195], v150 offset:38912
	ds_read_b128 v[198:201], v150 offset:39936
	global_load_lds_dwordx4 v134, s[14:15]
	s_mov_b32 m0, s26
	s_nop 0
	global_load_lds_dwordx4 v130, s[14:15]
	s_waitcnt lgkmcnt(7)
	s_setprio 1
	s_barrier
	v_mfma_f32_16x16x32_bf16 v[124:127], v[152:155], v[168:171], v[124:127]
	v_mfma_f32_16x16x32_bf16 v[120:123], v[160:163], v[168:171], v[120:123]
	s_waitcnt lgkmcnt(5)
	v_mfma_f32_16x16x32_bf16 v[108:111], v[152:155], v[176:179], v[108:111]
	v_mfma_f32_16x16x32_bf16 v[104:107], v[160:163], v[176:179], v[104:107]
	s_waitcnt lgkmcnt(3)
	v_mfma_f32_16x16x32_bf16 v[92:95], v[152:155], v[184:187], v[92:95]
	v_mfma_f32_16x16x32_bf16 v[88:91], v[160:163], v[184:187], v[88:91]
	s_waitcnt lgkmcnt(1)
	v_mfma_f32_16x16x32_bf16 v[76:79], v[152:155], v[192:195], v[76:79]
	v_mfma_f32_16x16x32_bf16 v[72:75], v[160:163], v[192:195], v[72:75]
	v_mfma_f32_16x16x32_bf16 v[124:127], v[156:159], v[172:175], v[124:127]
	v_mfma_f32_16x16x32_bf16 v[120:123], v[164:167], v[172:175], v[120:123]
	v_mfma_f32_16x16x32_bf16 v[108:111], v[156:159], v[180:183], v[108:111]
	v_mfma_f32_16x16x32_bf16 v[104:107], v[164:167], v[180:183], v[104:107]
	v_mfma_f32_16x16x32_bf16 v[92:95], v[156:159], v[188:191], v[92:95]
	v_mfma_f32_16x16x32_bf16 v[88:91], v[164:167], v[188:191], v[88:91]
	s_waitcnt lgkmcnt(0)
	v_mfma_f32_16x16x32_bf16 v[76:79], v[156:159], v[198:201], v[76:79]
	v_mfma_f32_16x16x32_bf16 v[72:75], v[164:167], v[198:201], v[72:75]
	s_barrier
	s_setprio 0
	s_add_i32 s14, 0, 0x1c000
	s_add_i32 s3, s3, s22
	v_add_u32_e32 v196, s14, v148
	v_lshl_add_u64 v[144:145], v[144:145], 0, s[44:45]
	s_mov_b32 m0, s3
	ds_read_b128 v[202:205], v196
	ds_read_b128 v[206:209], v196 offset:1024
	ds_read_b128 v[210:213], v196 offset:2048
	ds_read_b128 v[214:217], v196 offset:3072
	global_load_lds_dwordx4 v[144:145], off
	v_lshl_add_u64 v[144:145], v[218:219], 0, s[44:45]
	s_add_i32 m0, s3, 0x2000
	s_nop 0
	global_load_lds_dwordx4 v[144:145], off
	s_waitcnt lgkmcnt(3)
	s_setprio 1
	s_barrier
	v_mfma_f32_16x16x32_bf16 v[116:119], v[202:205], v[168:171], v[116:119]
	s_waitcnt lgkmcnt(1)
	v_mfma_f32_16x16x32_bf16 v[112:115], v[210:213], v[168:171], v[112:115]
	v_mfma_f32_16x16x32_bf16 v[100:103], v[202:205], v[176:179], v[100:103]
	v_mfma_f32_16x16x32_bf16 v[96:99], v[210:213], v[176:179], v[96:99]
	v_mfma_f32_16x16x32_bf16 v[84:87], v[202:205], v[184:187], v[84:87]
	v_mfma_f32_16x16x32_bf16 v[80:83], v[210:213], v[184:187], v[80:83]
	v_mfma_f32_16x16x32_bf16 v[68:71], v[202:205], v[192:195], v[68:71]
	v_mfma_f32_16x16x32_bf16 v[64:67], v[210:213], v[192:195], v[64:67]
	v_mfma_f32_16x16x32_bf16 v[116:119], v[206:209], v[172:175], v[116:119]
	s_mov_b32 m0, s30
	s_waitcnt lgkmcnt(0)
	v_mfma_f32_16x16x32_bf16 v[112:115], v[214:217], v[172:175], v[112:115]
	v_lshl_add_u64 v[144:145], v[220:221], 0, s[44:45]
	v_mfma_f32_16x16x32_bf16 v[100:103], v[206:209], v[180:183], v[100:103]
	v_mfma_f32_16x16x32_bf16 v[96:99], v[214:217], v[180:183], v[96:99]
	v_mfma_f32_16x16x32_bf16 v[84:87], v[206:209], v[188:191], v[84:87]
	v_mfma_f32_16x16x32_bf16 v[80:83], v[214:217], v[188:191], v[80:83]
	v_mfma_f32_16x16x32_bf16 v[68:71], v[206:209], v[198:201], v[68:71]
	v_mfma_f32_16x16x32_bf16 v[64:67], v[214:217], v[198:201], v[64:67]
	s_barrier
	s_setprio 0
	ds_read_b128 v[168:171], v150 offset:49152
	ds_read_b128 v[172:175], v150 offset:50176
	ds_read_b128 v[176:179], v150 offset:51200
	ds_read_b128 v[180:183], v150 offset:52224
	ds_read_b128 v[184:187], v150 offset:53248
	ds_read_b128 v[188:191], v150 offset:54272
	ds_read_b128 v[192:195], v150 offset:55296
	ds_read_b128 v[198:201], v150 offset:56320
	global_load_lds_dwordx4 v[144:145], off
	v_lshl_add_u64 v[144:145], v[222:223], 0, s[44:45]
	s_mov_b32 m0, s31
	s_nop 0
	global_load_lds_dwordx4 v[144:145], off
	s_waitcnt vmcnt(10) lgkmcnt(7)
	s_setprio 1
	s_barrier
; DI unsigned pack2(float a, float b) { f32x2 v = {a, b}; hwbf16x2 r = __builtin_convertvector(v, hwbf16x2); return __builtin_bit_cast(unsigned, r); }
; DI float bflo(unsigned w) { return __uint_as_float(w << 16); }
; DI float bfhi(unsigned w) { return __uint_as_float(w & 0xffff0000u); }
; #define PG8_STAGE(bufoff, gbase, voff) do { _Pragma("unroll") for (int _i = 0; _i < 2; ++_i) \
;         __builtin_amdgcn_global_load_lds((const unsigned*)((const char*)(gbase) + (voff)[_i]), (LAS unsigned*)(lds + (bufoff) + ldsw + _i * 8192), 16, 0, 0); } while (0)
; #define PG8_WAIT_V(n) asm volatile("s_waitcnt vmcnt(" #n ")" ::: "memory")
; #define PG8_WAIT_L(n) asm volatile("s_waitcnt lgkmcnt(" #n ")" ::: "memory")
; #define PG8_BAR __builtin_amdgcn_s_barrier()
;     DI void operator()(const f32x4 (&acc)[2][2][4][2], const Unit& u, int wr, int wc, int fr, int fq) const {
;     ...
;             for (int m = 0; m < 4; ++m) { const size_t ro = (size_t)(row0 + ai * HALF + m * 16) * D + col0;
; #pragma unroll
;                 for (int bj = 0; bj < 2; ++bj) {
;                     f32x4 x0, x1;
;                     if constexpr (IB) { const u32x4 w = *(const u32x4*)((const bf16_t*)Xin + ro + bj * HALF);
;                         x0 = (f32x4){bflo(w[0]), bfhi(w[0]), bflo(w[1]), bfhi(w[1])}; x1 = (f32x4){bflo(w[2]), bfhi(w[2]), bflo(w[3]), bfhi(w[3])}; }
;                     else { x0 = *(const f32x4*)((const float*)Xin + ro + bj * HALF); x1 = *(const f32x4*)((const float*)Xin + ro + bj * HALF + 4); }
;                     x0 += acc[ai][bj][m][0] * sc[bj][0]; x1 += acc[ai][bj][m][1] * sc[bj][1];
;                     if constexpr (OB) { u32x4 o; o[0] = pack2(x0[0], x0[1]); o[1] = pack2(x0[2], x0[3]); o[2] = pack2(x1[0], x1[1]); o[3] = pack2(x1[2], x1[3]);
;                         *(u32x4*)((bf16_t*)Xout + ro + bj * HALF) = o; }
;                     else { *(f32x4*)((float*)Xout + ro + bj * HALF) = x0; *(f32x4*)((float*)Xout + ro + bj * HALF + 4) = x1; } } }
; template <class Map, class Epi>
; DI void gemm_phase(LAS unsigned char* lds, const Map& MP, const Epi& E, const int nM, const int nN, const int K, const int lda, const int ldb) {
;     ...
;             PG8_BAR; PG8_WAIT_L(0); PG8_MMA(1, 0, At, B0); PG8_BAR; PG8_SCHED;
;             PG8_STAGE(PG8_SB(1, 1), b3 + hstepB, voffB);
;             PG8_WAIT_V(6); PG8_BAR; PG8_MMA(1, 1, At, B1); PG8_BAR;
;         }
	v_mfma_f32_16x16x32_bf16 v[60:63], v[152:155], v[168:171], v[60:63]
	v_mfma_f32_16x16x32_bf16 v[56:59], v[160:163], v[168:171], v[56:59]
	s_waitcnt lgkmcnt(5)
	v_mfma_f32_16x16x32_bf16 v[44:47], v[152:155], v[176:179], v[44:47]
	v_mfma_f32_16x16x32_bf16 v[40:43], v[160:163], v[176:179], v[40:43]
	s_waitcnt lgkmcnt(3)
	v_mfma_f32_16x16x32_bf16 v[28:31], v[152:155], v[184:187], v[28:31]
	v_mfma_f32_16x16x32_bf16 v[24:27], v[160:163], v[184:187], v[24:27]
	s_waitcnt lgkmcnt(1)
	v_mfma_f32_16x16x32_bf16 v[12:15], v[152:155], v[192:195], v[12:15]
	v_mfma_f32_16x16x32_bf16 v[8:11], v[160:163], v[192:195], v[8:11]
	v_mfma_f32_16x16x32_bf16 v[60:63], v[156:159], v[172:175], v[60:63]
	v_mfma_f32_16x16x32_bf16 v[56:59], v[164:167], v[172:175], v[56:59]
	v_mfma_f32_16x16x32_bf16 v[44:47], v[156:159], v[180:183], v[44:47]
	v_mfma_f32_16x16x32_bf16 v[40:43], v[164:167], v[180:183], v[40:43]
	v_mfma_f32_16x16x32_bf16 v[28:31], v[156:159], v[188:191], v[28:31]
	v_mfma_f32_16x16x32_bf16 v[24:27], v[164:167], v[188:191], v[24:27]
	s_waitcnt lgkmcnt(0)
	v_mfma_f32_16x16x32_bf16 v[12:15], v[156:159], v[198:201], v[12:15]
	v_mfma_f32_16x16x32_bf16 v[8:11], v[164:167], v[198:201], v[8:11]
	s_barrier
	s_setprio 0
	s_add_u32 s12, s12, 0x80080
	s_addc_u32 s13, s13, 0
	s_add_i32 s3, s14, s22
	s_mov_b32 m0, s3
	s_nop 0
	global_load_lds_dwordx4 v132, s[12:13]
	s_add_i32 m0, s3, 0x2000
	s_nop 0
	global_load_lds_dwordx4 v128, s[12:13]
	s_waitcnt vmcnt(6)
	s_setprio 1
	s_barrier
	v_mfma_f32_16x16x32_bf16 v[52:55], v[202:205], v[168:171], v[52:55]
	v_mfma_f32_16x16x32_bf16 v[48:51], v[210:213], v[168:171], v[48:51]
	ds_read_b128 v[152:155], v149
	v_mfma_f32_16x16x32_bf16 v[36:39], v[202:205], v[176:179], v[36:39]
	v_mfma_f32_16x16x32_bf16 v[32:35], v[210:213], v[176:179], v[32:35]
	ds_read_b128 v[156:159], v149 offset:1024
	v_mfma_f32_16x16x32_bf16 v[20:23], v[202:205], v[184:187], v[20:23]
	v_mfma_f32_16x16x32_bf16 v[16:19], v[210:213], v[184:187], v[16:19]
	ds_read_b128 v[160:163], v149 offset:2048
	v_mfma_f32_16x16x32_bf16 v[4:7], v[202:205], v[192:195], v[4:7]
	v_mfma_f32_16x16x32_bf16 v[0:3], v[210:213], v[192:195], v[0:3]
	ds_read_b128 v[164:167], v149 offset:3072
	v_mfma_f32_16x16x32_bf16 v[52:55], v[206:209], v[172:175], v[52:55]
	s_add_i32 s48, s48, 2
	v_mfma_f32_16x16x32_bf16 v[48:51], v[214:217], v[172:175], v[48:51]
	s_add_u32 s39, s39, 0x100
	s_addc_u32 s47, s47, 0
	v_mfma_f32_16x16x32_bf16 v[36:39], v[206:209], v[180:183], v[36:39]
	s_add_u32 s10, s10, 0x100
	s_addc_u32 s11, s11, 0
	v_mfma_f32_16x16x32_bf16 v[32:35], v[214:217], v[180:183], v[32:35]
	s_cmp_gt_u32 s48, 29
	v_mfma_f32_16x16x32_bf16 v[20:23], v[206:209], v[188:191], v[20:23]
	v_mfma_f32_16x16x32_bf16 v[16:19], v[214:217], v[188:191], v[16:19]
	v_mfma_f32_16x16x32_bf16 v[4:7], v[206:209], v[198:201], v[4:7]
	v_mfma_f32_16x16x32_bf16 v[0:3], v[214:217], v[198:201], v[0:3]
	s_barrier
	s_setprio 0
	s_cbranch_scc0 .LBB1_925
	s_waitcnt lgkmcnt(0)
	v_mov_b32_e32 v152, v147
	v_mov_b32_e32 v144, v146
	s_lshl_b32 s2, s2, 8
	s_or_b32 s2, s2, s29
	v_lshl_add_u32 v144, v144, 3, s2
	s_lshl_b32 s2, s8, 8
	s_add_i32 s2, s2, s28
	v_add_u32_e32 v152, s2, v152
	v_ashrrev_i32_e32 v153, 31, v152
	v_lshlrev_b64 v[152:153], 12, v[152:153]
	v_ashrrev_i32_e32 v145, 31, v144
	v_lshl_add_u64 v[152:153], s[42:43], 0, v[152:153]
	v_lshl_add_u64 v[144:145], v[144:145], 1, v[152:153]
	global_load_dwordx4 v[160:163], v[144:145], off
	global_load_dwordx4 v[164:167], v[144:145], off offset:256
	s_mov_b64 s[98:99], 0x10000
	v_lshl_add_u64 v[154:155], v[144:145], 0, s[98:99]
	global_load_dwordx4 v[168:171], v[154:155], off
	global_load_dwordx4 v[172:175], v[154:155], off offset:256
	s_mov_b64 s[98:99], 0x20000
	v_lshl_add_u64 v[154:155], v[144:145], 0, s[98:99]
	global_load_dwordx4 v[176:179], v[154:155], off
	global_load_dwordx4 v[180:183], v[154:155], off offset:256
	s_mov_b64 s[98:99], 0x30000
	v_lshl_add_u64 v[154:155], v[144:145], 0, s[98:99]
	global_load_dwordx4 v[184:187], v[154:155], off
	global_load_dwordx4 v[188:191], v[154:155], off offset:256
	s_mov_b64 s[98:99], 0x80000
	v_lshl_add_u64 v[154:155], v[144:145], 0, s[98:99]
	global_load_dwordx4 v[192:195], v[154:155], off
	global_load_dwordx4 v[198:201], v[154:155], off offset:256
	s_mov_b64 s[98:99], 0x90000
	v_lshl_add_u64 v[154:155], v[144:145], 0, s[98:99]
	global_load_dwordx4 v[202:205], v[154:155], off
	global_load_dwordx4 v[206:209], v[154:155], off offset:256
	s_mov_b64 s[98:99], 0xa0000
	v_lshl_add_u64 v[154:155], v[144:145], 0, s[98:99]
	global_load_dwordx4 v[210:213], v[154:155], off
	global_load_dwordx4 v[214:217], v[154:155], off offset:256
	s_mov_b64 s[98:99], 0xb0000
	v_lshl_add_u64 v[154:155], v[144:145], 0, s[98:99]
	global_load_dwordx4 v[248:251], v[154:155], off
	global_load_dwordx4 v[252:255], v[154:155], off offset:256
	s_waitcnt vmcnt(15)
	s_nop 1
	v_mov_b32_e32 v152, v160
	v_mov_b32_e32 v153, v161
	v_mov_b32_e32 v154, v162
	v_mov_b32_e32 v155, v163
	s_mov_b64 s[2:3], 0x10000
	s_mov_b32 s8, s52
	s_mov_b64 s[10:11], s[6:7]
	s_mov_b64 s[12:13], s[54:55]
	s_waitcnt lgkmcnt(0)
	v_lshlrev_b32_e32 v156, 16, v152
	v_and_b32_e32 v157, 0xffff0000, v152
	v_lshlrev_b32_e32 v152, 16, v153
	v_and_b32_e32 v153, 0xffff0000, v153
	v_lshlrev_b32_e32 v158, 16, v154
	v_and_b32_e32 v159, 0xffff0000, v154
	v_lshlrev_b32_e32 v154, 16, v155
	v_and_b32_e32 v155, 0xffff0000, v155
	v_pk_add_f32 v[126:127], v[126:127], v[152:153]
	v_pk_add_f32 v[124:125], v[124:125], v[156:157]
	v_pk_add_f32 v[152:153], v[122:123], v[154:155]
	v_pk_add_f32 v[122:123], v[120:121], v[158:159]
	v_cvt_pk_bf16_f32 v120, v124, v125
	v_cvt_pk_bf16_f32 v121, v126, v127
	v_cvt_pk_bf16_f32 v122, v122, v123
	v_cvt_pk_bf16_f32 v123, v152, v153
	global_store_dwordx4 v[144:145], v[120:123], off
	s_waitcnt vmcnt(15)
; DI unsigned pack2(float a, float b) { f32x2 v = {a, b}; hwbf16x2 r = __builtin_convertvector(v, hwbf16x2); return __builtin_bit_cast(unsigned, r); }
; DI float bflo(unsigned w) { return __uint_as_float(w << 16); }
; DI float bfhi(unsigned w) { return __uint_as_float(w & 0xffff0000u); }
;     DI void operator()(const f32x4 (&acc)[2][2][4][2], const Unit& u, int wr, int wc, int fr, int fq) const {
;     ...
;             for (int m = 0; m < 4; ++m) { const size_t ro = (size_t)(row0 + ai * HALF + m * 16) * D + col0;
; #pragma unroll
;                 for (int bj = 0; bj < 2; ++bj) {
;                     f32x4 x0, x1;
;                     if constexpr (IB) { const u32x4 w = *(const u32x4*)((const bf16_t*)Xin + ro + bj * HALF);
;                         x0 = (f32x4){bflo(w[0]), bfhi(w[0]), bflo(w[1]), bfhi(w[1])}; x1 = (f32x4){bflo(w[2]), bfhi(w[2]), bflo(w[3]), bfhi(w[3])}; }
;                     else { x0 = *(const f32x4*)((const float*)Xin + ro + bj * HALF); x1 = *(const f32x4*)((const float*)Xin + ro + bj * HALF + 4); }
;                     x0 += acc[ai][bj][m][0] * sc[bj][0]; x1 += acc[ai][bj][m][1] * sc[bj][1];
;                     if constexpr (OB) { u32x4 o; o[0] = pack2(x0[0], x0[1]); o[1] = pack2(x0[2], x0[3]); o[2] = pack2(x1[0], x1[1]); o[3] = pack2(x1[2], x1[3]);
;                         *(u32x4*)((bf16_t*)Xout + ro + bj * HALF) = o; }
;                     else { *(f32x4*)((float*)Xout + ro + bj * HALF) = x0; *(f32x4*)((float*)Xout + ro + bj * HALF + 4) = x1; } } }
	s_nop 1
	v_mov_b32_e32 v120, v164
	v_mov_b32_e32 v121, v165
	v_mov_b32_e32 v122, v166
	v_mov_b32_e32 v123, v167
	s_waitcnt lgkmcnt(0)
	v_lshlrev_b32_e32 v124, 16, v120
	v_and_b32_e32 v125, 0xffff0000, v120
	v_lshlrev_b32_e32 v120, 16, v121
	v_and_b32_e32 v121, 0xffff0000, v121
	v_lshlrev_b32_e32 v126, 16, v122
	v_and_b32_e32 v127, 0xffff0000, v122
	v_lshlrev_b32_e32 v122, 16, v123
	v_and_b32_e32 v123, 0xffff0000, v123
	v_pk_add_f32 v[116:117], v[116:117], v[124:125]
	v_pk_add_f32 v[118:119], v[118:119], v[120:121]
	v_pk_add_f32 v[120:121], v[114:115], v[122:123]
	v_pk_add_f32 v[114:115], v[112:113], v[126:127]
	v_cvt_pk_bf16_f32 v112, v116, v117
	v_lshl_add_u64 v[116:117], v[144:145], 0, s[2:3]
	s_mov_b32 s2, 0x10000
	v_cvt_pk_bf16_f32 v113, v118, v119
	v_add_co_u32_e32 v118, vcc, s2, v144
	v_cvt_pk_bf16_f32 v114, v114, v115
	v_cvt_pk_bf16_f32 v115, v120, v121
	v_addc_co_u32_e32 v119, vcc, 0, v145, vcc
	global_store_dwordx4 v[144:145], v[112:115], off offset:256
	s_waitcnt vmcnt(15)
	s_nop 1
	v_mov_b32_e32 v112, v168
	v_mov_b32_e32 v113, v169
	v_mov_b32_e32 v114, v170
	v_mov_b32_e32 v115, v171
	s_mov_b64 s[2:3], 0x20000
	s_waitcnt lgkmcnt(0)
	v_lshlrev_b32_e32 v120, 16, v112
	v_and_b32_e32 v121, 0xffff0000, v112
	v_lshlrev_b32_e32 v112, 16, v113
	v_and_b32_e32 v113, 0xffff0000, v113
	v_lshlrev_b32_e32 v122, 16, v114
	v_and_b32_e32 v123, 0xffff0000, v114
	v_lshlrev_b32_e32 v114, 16, v115
	v_and_b32_e32 v115, 0xffff0000, v115
	v_pk_add_f32 v[110:111], v[110:111], v[112:113]
	v_pk_add_f32 v[108:109], v[108:109], v[120:121]
	v_pk_add_f32 v[112:113], v[106:107], v[114:115]
	v_pk_add_f32 v[106:107], v[104:105], v[122:123]
	v_cvt_pk_bf16_f32 v104, v108, v109
	v_cvt_pk_bf16_f32 v105, v110, v111
	v_cvt_pk_bf16_f32 v106, v106, v107
	v_cvt_pk_bf16_f32 v107, v112, v113
	global_store_dwordx4 v[118:119], v[104:107], off
	s_waitcnt vmcnt(15)
	s_nop 1
	v_mov_b32_e32 v104, v172
	v_mov_b32_e32 v105, v173
	v_mov_b32_e32 v106, v174
	v_mov_b32_e32 v107, v175
	s_waitcnt lgkmcnt(0)
	v_lshlrev_b32_e32 v108, 16, v104
	v_and_b32_e32 v109, 0xffff0000, v104
	v_lshlrev_b32_e32 v104, 16, v105
	v_and_b32_e32 v105, 0xffff0000, v105
	v_lshlrev_b32_e32 v110, 16, v106
	v_and_b32_e32 v111, 0xffff0000, v106
	v_lshlrev_b32_e32 v106, 16, v107
	v_and_b32_e32 v107, 0xffff0000, v107
	v_pk_add_f32 v[100:101], v[100:101], v[108:109]
	v_pk_add_f32 v[102:103], v[102:103], v[104:105]
	v_pk_add_f32 v[104:105], v[98:99], v[106:107]
	v_pk_add_f32 v[98:99], v[96:97], v[110:111]
	v_cvt_pk_bf16_f32 v96, v100, v101
	v_lshl_add_u64 v[100:101], v[144:145], 0, s[2:3]
	s_mov_b32 s2, 0x20000
	v_cvt_pk_bf16_f32 v97, v102, v103
	v_add_co_u32_e32 v102, vcc, s2, v144
	v_cvt_pk_bf16_f32 v98, v98, v99
	v_cvt_pk_bf16_f32 v99, v104, v105
	v_addc_co_u32_e32 v103, vcc, 0, v145, vcc
	global_store_dwordx4 v[116:117], v[96:99], off offset:256
	s_waitcnt vmcnt(15)
	s_nop 1
	v_mov_b32_e32 v96, v176
	v_mov_b32_e32 v97, v177
	v_mov_b32_e32 v98, v178
	v_mov_b32_e32 v99, v179
	s_mov_b64 s[2:3], 0x30000
	s_waitcnt lgkmcnt(0)
	v_lshlrev_b32_e32 v104, 16, v96
	v_and_b32_e32 v105, 0xffff0000, v96
	v_lshlrev_b32_e32 v96, 16, v97
	v_and_b32_e32 v97, 0xffff0000, v97
	v_lshlrev_b32_e32 v106, 16, v98
	v_and_b32_e32 v107, 0xffff0000, v98
	v_lshlrev_b32_e32 v98, 16, v99
	v_and_b32_e32 v99, 0xffff0000, v99
	v_pk_add_f32 v[94:95], v[94:95], v[96:97]
	v_pk_add_f32 v[92:93], v[92:93], v[104:105]
	v_pk_add_f32 v[96:97], v[90:91], v[98:99]
	v_pk_add_f32 v[90:91], v[88:89], v[106:107]
	v_cvt_pk_bf16_f32 v88, v92, v93
	v_cvt_pk_bf16_f32 v89, v94, v95
	v_cvt_pk_bf16_f32 v90, v90, v91
	v_cvt_pk_bf16_f32 v91, v96, v97
	global_store_dwordx4 v[102:103], v[88:91], off
	s_waitcnt vmcnt(15)
	s_nop 1
	v_mov_b32_e32 v88, v180
	v_mov_b32_e32 v89, v181
	v_mov_b32_e32 v90, v182
	v_mov_b32_e32 v91, v183
	s_waitcnt lgkmcnt(0)
	v_lshlrev_b32_e32 v92, 16, v88
	v_and_b32_e32 v93, 0xffff0000, v88
	v_lshlrev_b32_e32 v88, 16, v89
	v_and_b32_e32 v89, 0xffff0000, v89
	v_lshlrev_b32_e32 v94, 16, v90
	v_and_b32_e32 v95, 0xffff0000, v90
	v_lshlrev_b32_e32 v90, 16, v91
	v_and_b32_e32 v91, 0xffff0000, v91
	v_pk_add_f32 v[86:87], v[86:87], v[88:89]
	v_pk_add_f32 v[84:85], v[84:85], v[92:93]
	v_pk_add_f32 v[88:89], v[82:83], v[90:91]
	v_pk_add_f32 v[82:83], v[80:81], v[94:95]
	v_cvt_pk_bf16_f32 v80, v84, v85
	v_cvt_pk_bf16_f32 v81, v86, v87
	v_cvt_pk_bf16_f32 v82, v82, v83
	v_cvt_pk_bf16_f32 v83, v88, v89
	global_store_dwordx4 v[100:101], v[80:83], off offset:256
	s_nop 1
	v_lshl_add_u64 v[80:81], v[144:145], 0, s[2:3]
	s_mov_b32 s2, 0x30000
	v_add_co_u32_e32 v86, vcc, s2, v144
	s_mov_b64 s[2:3], 0x80000
	s_nop 0
	v_addc_co_u32_e32 v87, vcc, 0, v145, vcc
	s_waitcnt vmcnt(15)
	s_nop 1
	v_mov_b32_e32 v82, v184
	v_mov_b32_e32 v83, v185
	v_mov_b32_e32 v84, v186
	v_mov_b32_e32 v85, v187
	s_waitcnt lgkmcnt(0)
	v_lshlrev_b32_e32 v88, 16, v82
	v_and_b32_e32 v89, 0xffff0000, v82
	v_lshlrev_b32_e32 v82, 16, v83
	v_and_b32_e32 v83, 0xffff0000, v83
	v_lshlrev_b32_e32 v90, 16, v84
	v_and_b32_e32 v91, 0xffff0000, v84
	v_lshlrev_b32_e32 v84, 16, v85
	v_and_b32_e32 v85, 0xffff0000, v85
	v_pk_add_f32 v[78:79], v[78:79], v[82:83]
	v_pk_add_f32 v[76:77], v[76:77], v[88:89]
	v_pk_add_f32 v[82:83], v[74:75], v[84:85]
	v_pk_add_f32 v[74:75], v[72:73], v[90:91]
	v_cvt_pk_bf16_f32 v72, v76, v77
	v_cvt_pk_bf16_f32 v73, v78, v79
	v_cvt_pk_bf16_f32 v74, v74, v75
	v_cvt_pk_bf16_f32 v75, v82, v83
	global_store_dwordx4 v[86:87], v[72:75], off
	s_waitcnt vmcnt(15)
	s_nop 1
	v_mov_b32_e32 v72, v188
	v_mov_b32_e32 v73, v189
	v_mov_b32_e32 v74, v190
	v_mov_b32_e32 v75, v191
	s_waitcnt lgkmcnt(0)
; DI unsigned pack2(float a, float b) { f32x2 v = {a, b}; hwbf16x2 r = __builtin_convertvector(v, hwbf16x2); return __builtin_bit_cast(unsigned, r); }
; DI float bflo(unsigned w) { return __uint_as_float(w << 16); }
; DI float bfhi(unsigned w) { return __uint_as_float(w & 0xffff0000u); }
;     DI void operator()(const f32x4 (&acc)[2][2][4][2], const Unit& u, int wr, int wc, int fr, int fq) const {
;     ...
;             for (int m = 0; m < 4; ++m) { const size_t ro = (size_t)(row0 + ai * HALF + m * 16) * D + col0;
; #pragma unroll
;                 for (int bj = 0; bj < 2; ++bj) {
;                     f32x4 x0, x1;
;                     if constexpr (IB) { const u32x4 w = *(const u32x4*)((const bf16_t*)Xin + ro + bj * HALF);
;                         x0 = (f32x4){bflo(w[0]), bfhi(w[0]), bflo(w[1]), bfhi(w[1])}; x1 = (f32x4){bflo(w[2]), bfhi(w[2]), bflo(w[3]), bfhi(w[3])}; }
;                     else { x0 = *(const f32x4*)((const float*)Xin + ro + bj * HALF); x1 = *(const f32x4*)((const float*)Xin + ro + bj * HALF + 4); }
;                     x0 += acc[ai][bj][m][0] * sc[bj][0]; x1 += acc[ai][bj][m][1] * sc[bj][1];
;                     if constexpr (OB) { u32x4 o; o[0] = pack2(x0[0], x0[1]); o[1] = pack2(x0[2], x0[3]); o[2] = pack2(x1[0], x1[1]); o[3] = pack2(x1[2], x1[3]);
;                         *(u32x4*)((bf16_t*)Xout + ro + bj * HALF) = o; }
;                     else { *(f32x4*)((float*)Xout + ro + bj * HALF) = x0; *(f32x4*)((float*)Xout + ro + bj * HALF + 4) = x1; } } }
	v_lshlrev_b32_e32 v76, 16, v72
	v_and_b32_e32 v77, 0xffff0000, v72
	v_lshlrev_b32_e32 v72, 16, v73
	v_and_b32_e32 v73, 0xffff0000, v73
	v_lshlrev_b32_e32 v78, 16, v74
	v_and_b32_e32 v79, 0xffff0000, v74
	v_lshlrev_b32_e32 v74, 16, v75
	v_and_b32_e32 v75, 0xffff0000, v75
	v_pk_add_f32 v[70:71], v[70:71], v[72:73]
	v_pk_add_f32 v[68:69], v[68:69], v[76:77]
	v_pk_add_f32 v[72:73], v[66:67], v[74:75]
	v_pk_add_f32 v[66:67], v[64:65], v[78:79]
	v_cvt_pk_bf16_f32 v64, v68, v69
	v_cvt_pk_bf16_f32 v65, v70, v71
	v_cvt_pk_bf16_f32 v66, v66, v67
	v_cvt_pk_bf16_f32 v67, v72, v73
	global_store_dwordx4 v[80:81], v[64:67], off offset:256
	s_nop 1
	v_lshl_add_u64 v[64:65], v[144:145], 0, s[2:3]
	s_mov_b32 s2, 0x80000
	v_add_co_u32_e32 v70, vcc, s2, v144
	s_mov_b64 s[2:3], 0x90000
	s_nop 0
	v_addc_co_u32_e32 v71, vcc, 0, v145, vcc
	s_waitcnt vmcnt(15)
	s_nop 1
	v_mov_b32_e32 v66, v192
	v_mov_b32_e32 v67, v193
	v_mov_b32_e32 v68, v194
	v_mov_b32_e32 v69, v195
	s_waitcnt lgkmcnt(0)
	v_lshlrev_b32_e32 v72, 16, v66
	v_and_b32_e32 v73, 0xffff0000, v66
	v_lshlrev_b32_e32 v66, 16, v67
	v_and_b32_e32 v67, 0xffff0000, v67
	v_lshlrev_b32_e32 v74, 16, v68
	v_and_b32_e32 v75, 0xffff0000, v68
	v_lshlrev_b32_e32 v68, 16, v69
	v_and_b32_e32 v69, 0xffff0000, v69
	v_pk_add_f32 v[62:63], v[62:63], v[66:67]
	v_pk_add_f32 v[60:61], v[60:61], v[72:73]
	v_pk_add_f32 v[66:67], v[58:59], v[68:69]
	v_pk_add_f32 v[58:59], v[56:57], v[74:75]
	v_cvt_pk_bf16_f32 v56, v60, v61
	v_cvt_pk_bf16_f32 v57, v62, v63
	v_cvt_pk_bf16_f32 v58, v58, v59
	v_cvt_pk_bf16_f32 v59, v66, v67
	global_store_dwordx4 v[70:71], v[56:59], off
	s_waitcnt vmcnt(15)
	s_nop 1
	v_mov_b32_e32 v56, v198
	v_mov_b32_e32 v57, v199
	v_mov_b32_e32 v58, v200
	v_mov_b32_e32 v59, v201
	s_waitcnt lgkmcnt(0)
	v_lshlrev_b32_e32 v60, 16, v56
	v_and_b32_e32 v61, 0xffff0000, v56
	v_lshlrev_b32_e32 v56, 16, v57
	v_and_b32_e32 v57, 0xffff0000, v57
	v_lshlrev_b32_e32 v62, 16, v58
	v_and_b32_e32 v63, 0xffff0000, v58
	v_lshlrev_b32_e32 v58, 16, v59
	v_and_b32_e32 v59, 0xffff0000, v59
	v_pk_add_f32 v[54:55], v[54:55], v[56:57]
	v_pk_add_f32 v[52:53], v[52:53], v[60:61]
	v_pk_add_f32 v[56:57], v[50:51], v[58:59]
	v_pk_add_f32 v[50:51], v[48:49], v[62:63]
	v_cvt_pk_bf16_f32 v48, v52, v53
	v_cvt_pk_bf16_f32 v49, v54, v55
	v_cvt_pk_bf16_f32 v50, v50, v51
	v_cvt_pk_bf16_f32 v51, v56, v57
	global_store_dwordx4 v[64:65], v[48:51], off offset:256
	s_nop 1
	v_lshl_add_u64 v[48:49], v[144:145], 0, s[2:3]
	s_mov_b32 s2, 0x90000
	v_add_co_u32_e32 v54, vcc, s2, v144
	s_mov_b64 s[2:3], 0xa0000
	s_nop 0
	v_addc_co_u32_e32 v55, vcc, 0, v145, vcc
	s_waitcnt vmcnt(15)
	s_nop 1
	v_mov_b32_e32 v50, v202
	v_mov_b32_e32 v51, v203
	v_mov_b32_e32 v52, v204
	v_mov_b32_e32 v53, v205
	s_waitcnt lgkmcnt(0)
	v_lshlrev_b32_e32 v56, 16, v50
	v_and_b32_e32 v57, 0xffff0000, v50
	v_lshlrev_b32_e32 v50, 16, v51
	v_and_b32_e32 v51, 0xffff0000, v51
	v_lshlrev_b32_e32 v58, 16, v52
	v_and_b32_e32 v59, 0xffff0000, v52
	v_lshlrev_b32_e32 v52, 16, v53
	v_and_b32_e32 v53, 0xffff0000, v53
	v_pk_add_f32 v[46:47], v[46:47], v[50:51]
	v_pk_add_f32 v[44:45], v[44:45], v[56:57]
	v_pk_add_f32 v[50:51], v[42:43], v[52:53]
	v_pk_add_f32 v[42:43], v[40:41], v[58:59]
	v_cvt_pk_bf16_f32 v40, v44, v45
	v_cvt_pk_bf16_f32 v41, v46, v47
	v_cvt_pk_bf16_f32 v42, v42, v43
	v_cvt_pk_bf16_f32 v43, v50, v51
	global_store_dwordx4 v[54:55], v[40:43], off
	s_waitcnt vmcnt(15)
	s_nop 1
	v_mov_b32_e32 v40, v206
	v_mov_b32_e32 v41, v207
	v_mov_b32_e32 v42, v208
	v_mov_b32_e32 v43, v209
	s_waitcnt lgkmcnt(0)
; DI unsigned pack2(float a, float b) { f32x2 v = {a, b}; hwbf16x2 r = __builtin_convertvector(v, hwbf16x2); return __builtin_bit_cast(unsigned, r); }
; DI float bflo(unsigned w) { return __uint_as_float(w << 16); }
; DI float bfhi(unsigned w) { return __uint_as_float(w & 0xffff0000u); }
;     DI const char* a(const Unit& u) const { return (const char*)(A + (size_t)u.pm * BM * lda); }
;     DI const char* a(const Unit& u) const { return (const char*)(A + (size_t)u.pm * BM * 2048 + (u.pn >> 1) * 512); }
; #define PG8_BAR __builtin_amdgcn_s_barrier()
;     DI void operator()(const f32x4 (&acc)[2][2][4][2], const Unit& u, int wr, int wc, int fr, int fq) const {
;     ...
;             for (int m = 0; m < 4; ++m) { const size_t ro = (size_t)(row0 + ai * HALF + m * 16) * D + col0;
; #pragma unroll
;                 for (int bj = 0; bj < 2; ++bj) {
;                     f32x4 x0, x1;
;                     if constexpr (IB) { const u32x4 w = *(const u32x4*)((const bf16_t*)Xin + ro + bj * HALF);
;                         x0 = (f32x4){bflo(w[0]), bfhi(w[0]), bflo(w[1]), bfhi(w[1])}; x1 = (f32x4){bflo(w[2]), bfhi(w[2]), bflo(w[3]), bfhi(w[3])}; }
;                     else { x0 = *(const f32x4*)((const float*)Xin + ro + bj * HALF); x1 = *(const f32x4*)((const float*)Xin + ro + bj * HALF + 4); }
;                     x0 += acc[ai][bj][m][0] * sc[bj][0]; x1 += acc[ai][bj][m][1] * sc[bj][1];
;                     if constexpr (OB) { u32x4 o; o[0] = pack2(x0[0], x0[1]); o[1] = pack2(x0[2], x0[3]); o[2] = pack2(x1[0], x1[1]); o[3] = pack2(x1[2], x1[3]);
;                         *(u32x4*)((bf16_t*)Xout + ro + bj * HALF) = o; }
;                     else { *(f32x4*)((float*)Xout + ro + bj * HALF) = x0; *(f32x4*)((float*)Xout + ro + bj * HALF + 4) = x1; } } }
; template <class Map, class Epi>
; DI void gemm_phase(LAS unsigned char* lds, const Map& MP, const Epi& E, const int nM, const int nN, const int K, const int lda, const int ldb) {
;     ...
;         if (!has_next) break;
; #pragma unroll
;         for (int a = 0; a < 2; ++a)
; #pragma unroll
;             for (int b = 0; b < 2; ++b)
; #pragma unroll
;                 for (int m = 0; m < 4; ++m)
; #pragma unroll
;                     for (int n = 0; n < 2; ++n) acc[a][b][m][n] = (f32x4){0.f, 0.f, 0.f, 0.f};
;         cur = nxt; cA = nA; cB = nB; ++ui;
;     }
;     PG8_WAIT_V(0);
;     if (wr == 0) PG8_BAR;
;     PG8_BAR;
	v_lshlrev_b32_e32 v44, 16, v40
	v_and_b32_e32 v45, 0xffff0000, v40
	v_lshlrev_b32_e32 v40, 16, v41
	v_and_b32_e32 v41, 0xffff0000, v41
	v_lshlrev_b32_e32 v46, 16, v42
	v_and_b32_e32 v47, 0xffff0000, v42
	v_lshlrev_b32_e32 v42, 16, v43
	v_and_b32_e32 v43, 0xffff0000, v43
	v_pk_add_f32 v[38:39], v[38:39], v[40:41]
	v_pk_add_f32 v[36:37], v[36:37], v[44:45]
	v_pk_add_f32 v[40:41], v[34:35], v[42:43]
	v_pk_add_f32 v[34:35], v[32:33], v[46:47]
	v_cvt_pk_bf16_f32 v32, v36, v37
	v_cvt_pk_bf16_f32 v33, v38, v39
	v_cvt_pk_bf16_f32 v34, v34, v35
	v_cvt_pk_bf16_f32 v35, v40, v41
	global_store_dwordx4 v[48:49], v[32:35], off offset:256
	s_nop 1
	v_lshl_add_u64 v[32:33], v[144:145], 0, s[2:3]
	s_mov_b32 s2, 0xa0000
	v_add_co_u32_e32 v38, vcc, s2, v144
	s_mov_b64 s[2:3], 0xb0000
	s_nop 0
	v_addc_co_u32_e32 v39, vcc, 0, v145, vcc
	s_waitcnt vmcnt(15)
	s_nop 1
	v_mov_b32_e32 v34, v210
	v_mov_b32_e32 v35, v211
	v_mov_b32_e32 v36, v212
	v_mov_b32_e32 v37, v213
	s_waitcnt lgkmcnt(0)
	v_lshlrev_b32_e32 v40, 16, v34
	v_and_b32_e32 v41, 0xffff0000, v34
	v_lshlrev_b32_e32 v34, 16, v35
	v_and_b32_e32 v35, 0xffff0000, v35
	v_lshlrev_b32_e32 v42, 16, v36
	v_and_b32_e32 v43, 0xffff0000, v36
	v_lshlrev_b32_e32 v36, 16, v37
	v_and_b32_e32 v37, 0xffff0000, v37
	v_pk_add_f32 v[30:31], v[30:31], v[34:35]
	v_pk_add_f32 v[28:29], v[28:29], v[40:41]
	v_pk_add_f32 v[34:35], v[26:27], v[36:37]
	v_pk_add_f32 v[26:27], v[24:25], v[42:43]
	v_cvt_pk_bf16_f32 v24, v28, v29
	v_cvt_pk_bf16_f32 v25, v30, v31
	v_cvt_pk_bf16_f32 v26, v26, v27
	v_cvt_pk_bf16_f32 v27, v34, v35
	global_store_dwordx4 v[38:39], v[24:27], off
	s_waitcnt vmcnt(15)
	s_nop 1
	v_mov_b32_e32 v24, v214
	v_mov_b32_e32 v25, v215
	v_mov_b32_e32 v26, v216
	v_mov_b32_e32 v27, v217
	s_waitcnt lgkmcnt(0)
	v_lshlrev_b32_e32 v28, 16, v24
	v_and_b32_e32 v29, 0xffff0000, v24
	v_lshlrev_b32_e32 v24, 16, v25
	v_and_b32_e32 v25, 0xffff0000, v25
	v_lshlrev_b32_e32 v30, 16, v26
	v_and_b32_e32 v31, 0xffff0000, v26
	v_lshlrev_b32_e32 v26, 16, v27
	v_and_b32_e32 v27, 0xffff0000, v27
	v_pk_add_f32 v[22:23], v[22:23], v[24:25]
	v_pk_add_f32 v[20:21], v[20:21], v[28:29]
	v_pk_add_f32 v[24:25], v[18:19], v[26:27]
	v_pk_add_f32 v[18:19], v[16:17], v[30:31]
	v_cvt_pk_bf16_f32 v16, v20, v21
	v_cvt_pk_bf16_f32 v17, v22, v23
	v_cvt_pk_bf16_f32 v18, v18, v19
	v_cvt_pk_bf16_f32 v19, v24, v25
	global_store_dwordx4 v[32:33], v[16:19], off offset:256
	s_nop 1
	v_lshl_add_u64 v[16:17], v[144:145], 0, s[2:3]
	s_mov_b32 s2, 0xb0000
	v_add_co_u32_e32 v22, vcc, s2, v144
	s_mov_b32 s2, s46
	s_nop 0
	v_addc_co_u32_e32 v23, vcc, 0, v145, vcc
	s_waitcnt vmcnt(15)
	s_nop 1
	v_mov_b32_e32 v18, v248
	v_mov_b32_e32 v19, v249
	v_mov_b32_e32 v20, v250
	v_mov_b32_e32 v21, v251
	s_and_b64 vcc, exec, s[40:41]
	s_waitcnt lgkmcnt(0)
	v_lshlrev_b32_e32 v24, 16, v18
	v_and_b32_e32 v25, 0xffff0000, v18
	v_lshlrev_b32_e32 v18, 16, v19
	v_and_b32_e32 v19, 0xffff0000, v19
	v_lshlrev_b32_e32 v26, 16, v20
	v_and_b32_e32 v27, 0xffff0000, v20
	v_lshlrev_b32_e32 v20, 16, v21
	v_and_b32_e32 v21, 0xffff0000, v21
	v_pk_add_f32 v[14:15], v[14:15], v[18:19]
	v_pk_add_f32 v[12:13], v[12:13], v[24:25]
	v_pk_add_f32 v[18:19], v[10:11], v[20:21]
	v_pk_add_f32 v[10:11], v[8:9], v[26:27]
	v_cvt_pk_bf16_f32 v8, v12, v13
	v_cvt_pk_bf16_f32 v9, v14, v15
	v_cvt_pk_bf16_f32 v10, v10, v11
	v_cvt_pk_bf16_f32 v11, v18, v19
	global_store_dwordx4 v[22:23], v[8:11], off
	s_waitcnt vmcnt(15)
	s_nop 1
	v_mov_b32_e32 v8, v252
	v_mov_b32_e32 v9, v253
	v_mov_b32_e32 v10, v254
	v_mov_b32_e32 v11, v255
	s_waitcnt lgkmcnt(0)
	v_lshlrev_b32_e32 v12, 16, v8
	v_and_b32_e32 v13, 0xffff0000, v8
	v_lshlrev_b32_e32 v8, 16, v9
	v_and_b32_e32 v9, 0xffff0000, v9
	v_lshlrev_b32_e32 v14, 16, v10
	v_and_b32_e32 v15, 0xffff0000, v10
	v_lshlrev_b32_e32 v10, 16, v11
	v_and_b32_e32 v11, 0xffff0000, v11
	v_pk_add_f32 v[6:7], v[6:7], v[8:9]
	v_pk_add_f32 v[4:5], v[4:5], v[12:13]
	v_pk_add_f32 v[8:9], v[2:3], v[10:11]
	v_pk_add_f32 v[2:3], v[0:1], v[14:15]
	v_cvt_pk_bf16_f32 v0, v4, v5
	v_cvt_pk_bf16_f32 v1, v6, v7
	v_cvt_pk_bf16_f32 v2, v2, v3
	v_cvt_pk_bf16_f32 v3, v8, v9
	global_store_dwordx4 v[16:17], v[0:3], off offset:256
	s_cbranch_vccz .LBB1_922
	s_waitcnt vmcnt(0)
	s_cmpk_gt_u32 s17, 0xff
	s_cbranch_scc1 .LBB1_929
	s_barrier

; #define PG8_STAGE(bufoff, gbase, voff) do { _Pragma("unroll") for (int _i = 0; _i < 2; ++_i) \
;         __builtin_amdgcn_global_load_lds((const unsigned*)((const char*)(gbase) + (voff)[_i]), (LAS unsigned*)(lds + (bufoff) + ldsw + _i * 8192), 16, 0, 0); } while (0)
; #define PG8_LDA(dst, b, h) do { _Pragma("unroll") for (int m = 0; m < 4; ++m) _Pragma("unroll") for (int k = 0; k < 2; ++k) dst[m][k] = *(const LAS bf16x8*)(lds + PG8_SA(b, h) + aoff + m * 2048 + k * 1024); } while (0)
; #define PG8_LDB(dst, b, h) do { _Pragma("unroll") for (int n = 0; n < 2; ++n) _Pragma("unroll") for (int k = 0; k < 2; ++k) dst[n][k] = *(const LAS bf16x8*)(lds + PG8_SB(b, h) + boff + n * 2048 + k * 1024); } while (0)
; #define PG8_MMA(ai, bj, At, Bt) do { __builtin_amdgcn_s_setprio(1); _Pragma("unroll") for (int m = 0; m < 4; ++m) _Pragma("unroll") for (int n = 0; n < 2; ++n) _Pragma("unroll") for (int k = 0; k < 2; ++k) \
;         acc[ai][bj][m][n] = __builtin_amdgcn_mfma_f32_16x16x32_bf16(Bt[n][k], At[m][k], acc[ai][bj][m][n], 0, 0, 0); __builtin_amdgcn_s_setprio(0); } while (0)
; #define PG8_WAIT_V(n) asm volatile("s_waitcnt vmcnt(" #n ")" ::: "memory")
; #define PG8_WAIT_L(n) asm volatile("s_waitcnt lgkmcnt(" #n ")" ::: "memory")
; template <class Map, class Epi>
; DI void gemm_phase(LAS unsigned char* lds, const Map& MP, const Epi& E, const int nM, const int nN, const int K, const int lda, const int ldb) {
;     ...
;             const bool last = (t == nt - 2);
;             const char* a1 = cA + (size_t)(t + 1) * kstep;
;             const char* a2 = last ? nA : cA + (size_t)(t + 2) * kstep; const char* b2 = last ? nB : cB + (size_t)(t + 2) * kstep;
;             const char* a3 = a2 + kstep; const char* b3 = b2 + kstep;
;             PG8_LDB(B0, 0, 0); PG8_SCHED; PG8_LDA(At, 0, 0); PG8_STAGE(PG8_SA(1, 1), a1 + hstepA, voffA);
;             PG8_WAIT_L(8); PG8_BAR; PG8_WAIT_L(0); PG8_MMA(0, 0, At, B0); PG8_BAR; PG8_SCHED;
;             PG8_LDB(B1, 0, 1); PG8_STAGE(PG8_SB(0, 0), b2, voffB);
;             PG8_BAR; PG8_WAIT_L(0); PG8_MMA(0, 1, At, B1); PG8_BAR;
;             PG8_LDA(At, 0, 1); PG8_STAGE(PG8_SA(0, 0), a2, voffA);
;             PG8_BAR; PG8_WAIT_L(0); PG8_MMA(1, 0, At, B0); PG8_BAR; PG8_SCHED;
;             PG8_STAGE(PG8_SB(0, 1), b2 + hstepB, voffB);
;             PG8_WAIT_V(6); PG8_BAR; PG8_MMA(1, 1, At, B1); PG8_BAR;
.LBB1_1069:
	s_add_u32 s24, s42, 0xfff80080
	s_addc_u32 s25, s43, -1
	s_cmp_eq_u32 s3, 28
	s_cselect_b32 s47, s23, s25
	s_cselect_b32 s46, s58, s24
	s_cselect_b32 s25, s21, vcc_hi
	s_cselect_b32 s24, s59, vcc_lo
	s_add_i32 m0, s38, 0xc000
	ds_read_b128 v[96:99], v190
	ds_read_b128 v[100:103], v190 offset:1024
	ds_read_b128 v[108:111], v190 offset:2048
	ds_read_b128 v[112:115], v190 offset:3072
	ds_read_b128 v[160:163], v190 offset:4096
	ds_read_b128 v[164:167], v190 offset:5120
	ds_read_b128 v[198:201], v190 offset:6144
	ds_read_b128 v[202:205], v190 offset:7168
	global_load_lds_dwordx4 v178, s[42:43]
	s_add_i32 m0, s38, 0xe000
	s_nop 0
	global_load_lds_dwordx4 v176, s[42:43]
	s_waitcnt lgkmcnt(7)
	s_setprio 1
	s_barrier
	v_mfma_f32_16x16x32_bf16 v[148:151], v[80:83], v[96:99], v[148:151]
	v_mfma_f32_16x16x32_bf16 v[144:147], v[88:91], v[96:99], v[144:147]
	s_waitcnt lgkmcnt(5)
	v_mfma_f32_16x16x32_bf16 v[136:139], v[80:83], v[108:111], v[136:139]
	v_mfma_f32_16x16x32_bf16 v[128:131], v[88:91], v[108:111], v[128:131]
	s_waitcnt lgkmcnt(3)
	v_mfma_f32_16x16x32_bf16 v[120:123], v[80:83], v[160:163], v[120:123]
	v_mfma_f32_16x16x32_bf16 v[104:107], v[88:91], v[160:163], v[104:107]
	s_waitcnt lgkmcnt(1)
	v_mfma_f32_16x16x32_bf16 v[76:79], v[80:83], v[198:201], v[76:79]
	v_mfma_f32_16x16x32_bf16 v[72:75], v[88:91], v[198:201], v[72:75]
	v_mfma_f32_16x16x32_bf16 v[148:151], v[84:87], v[100:103], v[148:151]
	v_mfma_f32_16x16x32_bf16 v[144:147], v[92:95], v[100:103], v[144:147]
	v_mfma_f32_16x16x32_bf16 v[136:139], v[84:87], v[112:115], v[136:139]
	v_mfma_f32_16x16x32_bf16 v[128:131], v[92:95], v[112:115], v[128:131]
	v_mfma_f32_16x16x32_bf16 v[120:123], v[84:87], v[164:167], v[120:123]
	v_mfma_f32_16x16x32_bf16 v[104:107], v[92:95], v[164:167], v[104:107]
	s_waitcnt lgkmcnt(0)
	v_mfma_f32_16x16x32_bf16 v[76:79], v[84:87], v[202:205], v[76:79]
	v_mfma_f32_16x16x32_bf16 v[72:75], v[92:95], v[202:205], v[72:75]
	s_barrier
	s_setprio 0
	s_add_i32 s68, s31, s66
	v_lshl_add_u64 v[184:185], s[24:25], 0, v[172:173]
	s_mov_b32 m0, s68
	ds_read_b128 v[206:209], v191
	ds_read_b128 v[210:213], v191 offset:1024
	ds_read_b128 v[214:217], v191 offset:2048
	ds_read_b128 v[218:221], v191 offset:3072
	global_load_lds_dwordx4 v[184:185], off
	v_lshl_add_u64 v[194:195], s[24:25], 0, v[168:169]
	s_add_i32 m0, s68, 0x2000
	s_nop 0
	global_load_lds_dwordx4 v[194:195], off
	s_waitcnt lgkmcnt(3)
	s_setprio 1
	s_barrier
	v_mfma_f32_16x16x32_bf16 v[156:159], v[206:209], v[96:99], v[156:159]
	s_waitcnt lgkmcnt(1)
	v_mfma_f32_16x16x32_bf16 v[96:99], v[214:217], v[96:99], v[152:155]
	v_mfma_f32_16x16x32_bf16 v[156:159], v[210:213], v[100:103], v[156:159]
	s_waitcnt lgkmcnt(0)
	v_mfma_f32_16x16x32_bf16 v[96:99], v[218:221], v[100:103], v[96:99]
	v_mfma_f32_16x16x32_bf16 v[100:103], v[206:209], v[108:111], v[140:143]
	v_mfma_f32_16x16x32_bf16 v[108:111], v[214:217], v[108:111], v[132:135]
	v_mfma_f32_16x16x32_bf16 v[116:119], v[214:217], v[160:163], v[116:119]
	v_mfma_f32_16x16x32_bf16 v[68:71], v[206:209], v[198:201], v[68:71]
	v_mfma_f32_16x16x32_bf16 v[64:67], v[214:217], v[198:201], v[64:67]
	s_mov_b32 m0, s38
	v_mfma_f32_16x16x32_bf16 v[100:103], v[210:213], v[112:115], v[100:103]
	v_lshl_add_u64 v[226:227], s[46:47], 0, v[174:175]
	v_mfma_f32_16x16x32_bf16 v[108:111], v[218:221], v[112:115], v[108:111]
	v_mfma_f32_16x16x32_bf16 v[112:115], v[206:209], v[160:163], v[124:127]
	v_mfma_f32_16x16x32_bf16 v[116:119], v[218:221], v[164:167], v[116:119]
	v_mfma_f32_16x16x32_bf16 v[68:71], v[210:213], v[202:205], v[68:71]
	v_mfma_f32_16x16x32_bf16 v[64:67], v[218:221], v[202:205], v[64:67]
	v_mfma_f32_16x16x32_bf16 v[112:115], v[210:213], v[164:167], v[112:115]
	s_barrier
	s_setprio 0
	ds_read_b128 v[124:127], v190 offset:16384
	ds_read_b128 v[132:135], v190 offset:17408
	ds_read_b128 v[140:143], v190 offset:18432
	ds_read_b128 v[152:155], v190 offset:19456
	ds_read_b128 v[160:163], v190 offset:20480
	ds_read_b128 v[164:167], v190 offset:21504
	ds_read_b128 v[198:201], v190 offset:22528
	ds_read_b128 v[202:205], v190 offset:23552
	global_load_lds_dwordx4 v[226:227], off
	v_lshl_add_u64 v[234:235], s[46:47], 0, v[170:171]
	s_mov_b32 m0, s39
	s_nop 0
	global_load_lds_dwordx4 v[234:235], off
	s_waitcnt vmcnt(10) lgkmcnt(7)
	s_setprio 1
	s_barrier
	v_mfma_f32_16x16x32_bf16 v[60:63], v[80:83], v[124:127], v[60:63]
	v_mfma_f32_16x16x32_bf16 v[48:51], v[88:91], v[124:127], v[48:51]
	s_waitcnt lgkmcnt(5)
	v_mfma_f32_16x16x32_bf16 v[40:43], v[80:83], v[140:143], v[40:43]
	v_mfma_f32_16x16x32_bf16 v[32:35], v[88:91], v[140:143], v[32:35]
	s_waitcnt lgkmcnt(3)
	v_mfma_f32_16x16x32_bf16 v[24:27], v[80:83], v[160:163], v[24:27]
	v_mfma_f32_16x16x32_bf16 v[16:19], v[88:91], v[160:163], v[16:19]
	s_waitcnt lgkmcnt(1)
	v_mfma_f32_16x16x32_bf16 v[12:15], v[80:83], v[198:201], v[12:15]
	v_mfma_f32_16x16x32_bf16 v[8:11], v[88:91], v[198:201], v[8:11]
	v_mfma_f32_16x16x32_bf16 v[60:63], v[84:87], v[132:135], v[60:63]
	v_mfma_f32_16x16x32_bf16 v[48:51], v[92:95], v[132:135], v[48:51]
	v_mfma_f32_16x16x32_bf16 v[40:43], v[84:87], v[152:155], v[40:43]
	v_mfma_f32_16x16x32_bf16 v[32:35], v[92:95], v[152:155], v[32:35]
	v_mfma_f32_16x16x32_bf16 v[24:27], v[84:87], v[164:167], v[24:27]
	v_mfma_f32_16x16x32_bf16 v[16:19], v[92:95], v[164:167], v[16:19]
	s_waitcnt lgkmcnt(0)
	v_mfma_f32_16x16x32_bf16 v[12:15], v[84:87], v[202:205], v[12:15]
	v_mfma_f32_16x16x32_bf16 v[8:11], v[92:95], v[202:205], v[8:11]
	s_barrier
	s_setprio 0
	s_add_u32 s68, s24, 0x80000
	s_addc_u32 s69, s25, 0
	s_add_i32 s70, s2, s66
	s_mov_b32 m0, s70
	s_nop 0
	global_load_lds_dwordx4 v172, s[68:69]
	s_add_i32 m0, s70, 0x2000
	s_nop 0
	global_load_lds_dwordx4 v168, s[68:69]
	s_waitcnt vmcnt(6)
	s_setprio 1
	s_barrier
; #define PG8_STAGE(bufoff, gbase, voff) do { _Pragma("unroll") for (int _i = 0; _i < 2; ++_i) \
;         __builtin_amdgcn_global_load_lds((const unsigned*)((const char*)(gbase) + (voff)[_i]), (LAS unsigned*)(lds + (bufoff) + ldsw + _i * 8192), 16, 0, 0); } while (0)
; #define PG8_LDA(dst, b, h) do { _Pragma("unroll") for (int m = 0; m < 4; ++m) _Pragma("unroll") for (int k = 0; k < 2; ++k) dst[m][k] = *(const LAS bf16x8*)(lds + PG8_SA(b, h) + aoff + m * 2048 + k * 1024); } while (0)
; #define PG8_LDB(dst, b, h) do { _Pragma("unroll") for (int n = 0; n < 2; ++n) _Pragma("unroll") for (int k = 0; k < 2; ++k) dst[n][k] = *(const LAS bf16x8*)(lds + PG8_SB(b, h) + boff + n * 2048 + k * 1024); } while (0)
; #define PG8_MMA(ai, bj, At, Bt) do { __builtin_amdgcn_s_setprio(1); _Pragma("unroll") for (int m = 0; m < 4; ++m) _Pragma("unroll") for (int n = 0; n < 2; ++n) _Pragma("unroll") for (int k = 0; k < 2; ++k) \
;         acc[ai][bj][m][n] = __builtin_amdgcn_mfma_f32_16x16x32_bf16(Bt[n][k], At[m][k], acc[ai][bj][m][n], 0, 0, 0); __builtin_amdgcn_s_setprio(0); } while (0)
; #define PG8_WAIT_V(n) asm volatile("s_waitcnt vmcnt(" #n ")" ::: "memory")
; #define PG8_WAIT_L(n) asm volatile("s_waitcnt lgkmcnt(" #n ")" ::: "memory")
; #define PG8_BAR __builtin_amdgcn_s_barrier()
; #define PG8_SCHED __builtin_amdgcn_sched_barrier(0)
; template <class Map, class Epi>
; DI void gemm_phase(LAS unsigned char* lds, const Map& MP, const Epi& E, const int nM, const int nN, const int K, const int lda, const int ldb) {
;     ...
;             PG8_WAIT_V(6); PG8_BAR; PG8_MMA(1, 1, At, B1); PG8_BAR;
;             PG8_LDB(B0, 1, 0); PG8_SCHED; PG8_LDA(At, 1, 0); PG8_STAGE(PG8_SA(0, 1), a2 + hstepA, voffA);
;             PG8_WAIT_L(8); PG8_BAR; PG8_WAIT_L(0); PG8_MMA(0, 0, At, B0); PG8_BAR; PG8_SCHED;
;             PG8_LDB(B1, 1, 1); PG8_STAGE(PG8_SB(1, 0), b3, voffB);
;             PG8_BAR; PG8_WAIT_L(0); PG8_MMA(0, 1, At, B1); PG8_BAR;
;             PG8_LDA(At, 1, 1); PG8_STAGE(PG8_SA(1, 0), a3, voffA);
;             PG8_BAR; PG8_WAIT_L(0); PG8_MMA(1, 0, At, B0); PG8_BAR; PG8_SCHED;
	v_mfma_f32_16x16x32_bf16 v[56:59], v[206:209], v[124:127], v[56:59]
	v_mfma_f32_16x16x32_bf16 v[52:55], v[214:217], v[124:127], v[52:55]
	s_add_i32 s68, 0, 0x18000
	v_add_u32_e32 v92, s68, v188
	ds_read_b128 v[80:83], v92
	v_mfma_f32_16x16x32_bf16 v[44:47], v[206:209], v[140:143], v[44:47]
	v_mfma_f32_16x16x32_bf16 v[36:39], v[214:217], v[140:143], v[36:39]
	ds_read_b128 v[84:87], v92 offset:1024
	v_mfma_f32_16x16x32_bf16 v[28:31], v[206:209], v[160:163], v[28:31]
	v_mfma_f32_16x16x32_bf16 v[20:23], v[214:217], v[160:163], v[20:23]
	ds_read_b128 v[88:91], v92 offset:2048
	v_mfma_f32_16x16x32_bf16 v[4:7], v[206:209], v[198:201], v[4:7]
	v_mfma_f32_16x16x32_bf16 v[0:3], v[214:217], v[198:201], v[0:3]
	ds_read_b128 v[92:95], v92 offset:3072
	v_mfma_f32_16x16x32_bf16 v[56:59], v[210:213], v[132:135], v[56:59]
	v_mfma_f32_16x16x32_bf16 v[52:55], v[218:221], v[132:135], v[52:55]
	v_mfma_f32_16x16x32_bf16 v[44:47], v[210:213], v[152:155], v[44:47]
	v_mfma_f32_16x16x32_bf16 v[36:39], v[218:221], v[152:155], v[36:39]
	v_mfma_f32_16x16x32_bf16 v[28:31], v[210:213], v[164:167], v[28:31]
	v_mfma_f32_16x16x32_bf16 v[20:23], v[218:221], v[164:167], v[20:23]
	v_mfma_f32_16x16x32_bf16 v[4:7], v[210:213], v[202:205], v[4:7]
	v_mfma_f32_16x16x32_bf16 v[0:3], v[218:221], v[202:205], v[0:3]
	s_barrier
	s_setprio 0
	s_add_u32 s46, s46, 0x80000
	s_addc_u32 s47, s47, 0
	s_mov_b32 m0, s56
	ds_read_b128 v[124:127], v190 offset:32768
	ds_read_b128 v[132:135], v190 offset:33792
	ds_read_b128 v[160:163], v190 offset:34816
	ds_read_b128 v[164:167], v190 offset:35840
	ds_read_b128 v[198:201], v190 offset:36864
	ds_read_b128 v[202:205], v190 offset:37888
	ds_read_b128 v[206:209], v190 offset:38912
	ds_read_b128 v[210:213], v190 offset:39936
	global_load_lds_dwordx4 v174, s[46:47]
	s_mov_b32 m0, s57
	s_nop 0
	global_load_lds_dwordx4 v170, s[46:47]
	s_waitcnt lgkmcnt(7)
	s_setprio 1
	s_barrier
	v_mfma_f32_16x16x32_bf16 v[140:143], v[80:83], v[124:127], v[148:151]
	s_waitcnt lgkmcnt(6)
	v_mfma_f32_16x16x32_bf16 v[148:151], v[84:87], v[132:135], v[140:143]
	v_mfma_f32_16x16x32_bf16 v[140:143], v[88:91], v[124:127], v[144:147]
	s_waitcnt lgkmcnt(5)
	v_mfma_f32_16x16x32_bf16 v[136:139], v[80:83], v[160:163], v[136:139]
	v_mfma_f32_16x16x32_bf16 v[128:131], v[88:91], v[160:163], v[128:131]
	s_waitcnt lgkmcnt(3)
	v_mfma_f32_16x16x32_bf16 v[120:123], v[80:83], v[198:201], v[120:123]
	v_mfma_f32_16x16x32_bf16 v[104:107], v[88:91], v[198:201], v[104:107]
	s_waitcnt lgkmcnt(1)
	v_mfma_f32_16x16x32_bf16 v[76:79], v[80:83], v[206:209], v[76:79]
	v_mfma_f32_16x16x32_bf16 v[72:75], v[88:91], v[206:209], v[72:75]
	v_mfma_f32_16x16x32_bf16 v[144:147], v[92:95], v[132:135], v[140:143]
	v_mfma_f32_16x16x32_bf16 v[136:139], v[84:87], v[164:167], v[136:139]
	v_mfma_f32_16x16x32_bf16 v[128:131], v[92:95], v[164:167], v[128:131]
	v_mfma_f32_16x16x32_bf16 v[120:123], v[84:87], v[202:205], v[120:123]
	v_mfma_f32_16x16x32_bf16 v[104:107], v[92:95], v[202:205], v[104:107]
	s_waitcnt lgkmcnt(0)
	v_mfma_f32_16x16x32_bf16 v[76:79], v[84:87], v[210:213], v[76:79]
	v_mfma_f32_16x16x32_bf16 v[72:75], v[92:95], v[210:213], v[72:75]
	s_barrier
	s_setprio 0
	s_add_i32 s46, 0, 0x1c000
	v_add_u32_e32 v140, s46, v188
	s_add_i32 s47, s68, s66
	ds_read_b128 v[214:217], v140
	ds_read_b128 v[218:221], v140 offset:1024
	ds_read_b128 v[222:225], v140 offset:2048
	ds_read_b128 v[230:233], v140 offset:3072
	v_lshl_add_u64 v[140:141], v[184:185], 0, s[14:15]
	s_mov_b32 m0, s47
	s_nop 0
	global_load_lds_dwordx4 v[140:141], off
	v_lshl_add_u64 v[140:141], v[194:195], 0, s[14:15]
	s_add_i32 m0, s47, 0x2000
	s_nop 0
	global_load_lds_dwordx4 v[140:141], off
	s_waitcnt lgkmcnt(1)
	s_setprio 1
	s_barrier
	v_mfma_f32_16x16x32_bf16 v[96:99], v[222:225], v[124:127], v[96:99]
	v_mfma_f32_16x16x32_bf16 v[140:143], v[214:217], v[124:127], v[156:159]
	s_waitcnt lgkmcnt(0)
	v_mfma_f32_16x16x32_bf16 v[152:155], v[230:233], v[132:135], v[96:99]
	v_mfma_f32_16x16x32_bf16 v[96:99], v[214:217], v[160:163], v[100:103]
	v_mfma_f32_16x16x32_bf16 v[156:159], v[218:221], v[132:135], v[140:143]
	v_mfma_f32_16x16x32_bf16 v[140:143], v[218:221], v[164:167], v[96:99]
	v_mfma_f32_16x16x32_bf16 v[96:99], v[222:225], v[160:163], v[108:111]
	v_mfma_f32_16x16x32_bf16 v[132:135], v[230:233], v[164:167], v[96:99]
	v_mfma_f32_16x16x32_bf16 v[96:99], v[214:217], v[198:201], v[112:115]
	s_mov_b32 m0, s63
	v_mfma_f32_16x16x32_bf16 v[124:127], v[218:221], v[202:205], v[96:99]
	v_lshl_add_u64 v[184:185], v[226:227], 0, s[14:15]
	v_mfma_f32_16x16x32_bf16 v[96:99], v[222:225], v[198:201], v[116:119]
	v_mfma_f32_16x16x32_bf16 v[68:71], v[214:217], v[206:209], v[68:71]
	v_mfma_f32_16x16x32_bf16 v[64:67], v[222:225], v[206:209], v[64:67]
	v_mfma_f32_16x16x32_bf16 v[116:119], v[230:233], v[202:205], v[96:99]
	v_mfma_f32_16x16x32_bf16 v[68:71], v[218:221], v[210:213], v[68:71]
	v_mfma_f32_16x16x32_bf16 v[64:67], v[230:233], v[210:213], v[64:67]
	s_barrier
	s_setprio 0
	ds_read_b128 v[96:99], v190 offset:49152
	ds_read_b128 v[100:103], v190 offset:50176
	ds_read_b128 v[108:111], v190 offset:51200
	ds_read_b128 v[112:115], v190 offset:52224
	ds_read_b128 v[160:163], v190 offset:53248
	ds_read_b128 v[164:167], v190 offset:54272
	ds_read_b128 v[198:201], v190 offset:55296
	ds_read_b128 v[202:205], v190 offset:56320
	global_load_lds_dwordx4 v[184:185], off
	v_lshl_add_u64 v[184:185], v[234:235], 0, s[14:15]
	s_mov_b32 m0, s4
	s_nop 0
	global_load_lds_dwordx4 v[184:185], off
	s_waitcnt vmcnt(10) lgkmcnt(7)
	s_setprio 1
	s_barrier
; #define PG8_STAGE(bufoff, gbase, voff) do { _Pragma("unroll") for (int _i = 0; _i < 2; ++_i) \
;         __builtin_amdgcn_global_load_lds((const unsigned*)((const char*)(gbase) + (voff)[_i]), (LAS unsigned*)(lds + (bufoff) + ldsw + _i * 8192), 16, 0, 0); } while (0)
; #define PG8_MMA(ai, bj, At, Bt) do { __builtin_amdgcn_s_setprio(1); _Pragma("unroll") for (int m = 0; m < 4; ++m) _Pragma("unroll") for (int n = 0; n < 2; ++n) _Pragma("unroll") for (int k = 0; k < 2; ++k) \
;         acc[ai][bj][m][n] = __builtin_amdgcn_mfma_f32_16x16x32_bf16(Bt[n][k], At[m][k], acc[ai][bj][m][n], 0, 0, 0); __builtin_amdgcn_s_setprio(0); } while (0)
; #define PG8_WAIT_V(n) asm volatile("s_waitcnt vmcnt(" #n ")" ::: "memory")
; #define PG8_WAIT_L(n) asm volatile("s_waitcnt lgkmcnt(" #n ")" ::: "memory")
; #define PG8_BAR __builtin_amdgcn_s_barrier()
; #define PG8_SCHED __builtin_amdgcn_sched_barrier(0)
; template <class Map, class Epi>
; DI void gemm_phase(LAS unsigned char* lds, const Map& MP, const Epi& E, const int nM, const int nN, const int K, const int lda, const int ldb) {
;     ...
;             PG8_BAR; PG8_WAIT_L(0); PG8_MMA(1, 0, At, B0); PG8_BAR; PG8_SCHED;
;             PG8_STAGE(PG8_SB(1, 1), b3 + hstepB, voffB);
;             PG8_WAIT_V(6); PG8_BAR; PG8_MMA(1, 1, At, B1); PG8_BAR;
;         }
	v_mfma_f32_16x16x32_bf16 v[60:63], v[80:83], v[96:99], v[60:63]
	v_mfma_f32_16x16x32_bf16 v[48:51], v[88:91], v[96:99], v[48:51]
	s_waitcnt lgkmcnt(5)
	v_mfma_f32_16x16x32_bf16 v[40:43], v[80:83], v[108:111], v[40:43]
	v_mfma_f32_16x16x32_bf16 v[32:35], v[88:91], v[108:111], v[32:35]
	s_waitcnt lgkmcnt(3)
	v_mfma_f32_16x16x32_bf16 v[24:27], v[80:83], v[160:163], v[24:27]
	v_mfma_f32_16x16x32_bf16 v[16:19], v[88:91], v[160:163], v[16:19]
	s_waitcnt lgkmcnt(1)
	v_mfma_f32_16x16x32_bf16 v[12:15], v[80:83], v[198:201], v[12:15]
	v_mfma_f32_16x16x32_bf16 v[8:11], v[88:91], v[198:201], v[8:11]
	v_mfma_f32_16x16x32_bf16 v[60:63], v[84:87], v[100:103], v[60:63]
	v_mfma_f32_16x16x32_bf16 v[48:51], v[92:95], v[100:103], v[48:51]
	v_mfma_f32_16x16x32_bf16 v[40:43], v[84:87], v[112:115], v[40:43]
	v_mfma_f32_16x16x32_bf16 v[32:35], v[92:95], v[112:115], v[32:35]
	v_mfma_f32_16x16x32_bf16 v[24:27], v[84:87], v[164:167], v[24:27]
	v_mfma_f32_16x16x32_bf16 v[16:19], v[92:95], v[164:167], v[16:19]
	s_waitcnt lgkmcnt(0)
	v_mfma_f32_16x16x32_bf16 v[12:15], v[84:87], v[202:205], v[12:15]
	v_mfma_f32_16x16x32_bf16 v[8:11], v[92:95], v[202:205], v[8:11]
	s_barrier
	s_setprio 0
	s_add_u32 s24, s24, 0x80080
	s_addc_u32 s25, s25, 0
	s_add_i32 s46, s46, s66
	s_mov_b32 m0, s46
	s_nop 0
	global_load_lds_dwordx4 v172, s[24:25]
	s_add_i32 m0, s46, 0x2000
	s_nop 0
	global_load_lds_dwordx4 v168, s[24:25]
	s_waitcnt vmcnt(6)
	s_setprio 1
	s_barrier
	v_mfma_f32_16x16x32_bf16 v[56:59], v[214:217], v[96:99], v[56:59]
	v_mfma_f32_16x16x32_bf16 v[52:55], v[222:225], v[96:99], v[52:55]
	ds_read_b128 v[80:83], v189
	v_mfma_f32_16x16x32_bf16 v[44:47], v[214:217], v[108:111], v[44:47]
	v_mfma_f32_16x16x32_bf16 v[36:39], v[222:225], v[108:111], v[36:39]
	ds_read_b128 v[84:87], v189 offset:1024
	v_mfma_f32_16x16x32_bf16 v[28:31], v[214:217], v[160:163], v[28:31]
	v_mfma_f32_16x16x32_bf16 v[20:23], v[222:225], v[160:163], v[20:23]
	ds_read_b128 v[88:91], v189 offset:2048
	v_mfma_f32_16x16x32_bf16 v[4:7], v[214:217], v[198:201], v[4:7]
	v_mfma_f32_16x16x32_bf16 v[0:3], v[222:225], v[198:201], v[0:3]
	ds_read_b128 v[92:95], v189 offset:3072
	v_mfma_f32_16x16x32_bf16 v[56:59], v[218:221], v[100:103], v[56:59]
	s_add_i32 s3, s3, 2
	v_mfma_f32_16x16x32_bf16 v[52:55], v[230:233], v[100:103], v[52:55]
	s_add_u32 vcc_lo, vcc_lo, 0x100
	s_addc_u32 vcc_hi, vcc_hi, 0
	v_mfma_f32_16x16x32_bf16 v[44:47], v[218:221], v[112:115], v[44:47]
	s_add_u32 s42, s42, 0x100
	s_addc_u32 s43, s43, 0
	v_mfma_f32_16x16x32_bf16 v[36:39], v[230:233], v[112:115], v[36:39]
	s_cmp_gt_u32 s3, 29
	v_mfma_f32_16x16x32_bf16 v[28:31], v[218:221], v[164:167], v[28:31]
	v_mfma_f32_16x16x32_bf16 v[20:23], v[230:233], v[164:167], v[20:23]
	v_mfma_f32_16x16x32_bf16 v[4:7], v[218:221], v[202:205], v[4:7]
	v_mfma_f32_16x16x32_bf16 v[0:3], v[230:233], v[202:205], v[0:3]
	s_barrier
	s_setprio 0
	s_cbranch_scc0 .LBB1_1069
; DI float silu_mul(float g, float v) { return g * v * __builtin_amdgcn_rcpf(1.0f + __builtin_amdgcn_exp2f(-LOG2E * g)); }
;     DI void operator()(const f32x4 (&acc)[2][2][4][2], const Unit& u, int wr, int wc, int fr, int fq) const {
;         const int row0 = u.pm * BM + wr * 64 + fr, ch0 = u.pn * 128 + wc * 32 + 8 * fq;
;         f32x4 w0[2], w1[2], w2[2], bb[2];
; #pragma unroll
;         for (int n = 0; n < 2; ++n) { w0[n] = *(const f32x4*)(cw + ch0 + 4 * n); w1[n] = *(const f32x4*)(cw + DFF + ch0 + 4 * n); w2[n] = *(const f32x4*)(cw + 2 * DFF + ch0 + 4 * n); bb[n] = *(const f32x4*)(cb + ch0 + 4 * n); }
; #pragma unroll
;         for (int ai = 0; ai < 2; ++ai)
; #pragma unroll
;             for (int m = 0; m < 4; ++m) {
;                 const bool efirst = (m == 0) && (fr == 0), elast = (m == 3) && (fr == 15);
;                 const int row = row0 + ai * HALF + m * 16;
;                 f32x4 gc[2];
; #pragma unroll
;                 for (int n = 0; n < 2; ++n) {
;                     const f32x4 g = acc[ai][0][m][n];
;                     const f32x4 gprev = acc[ai][0][m > 0 ? m - 1 : 0][n], gnext = acc[ai][0][m < 3 ? m + 1 : 3][n];
;                     f32x4 up, dn;
; #pragma unroll
;                     for (int e = 0; e < 4; ++e) {
;                         const float pu = (m > 0 && fr == 15) ? gprev[e] : g[e];
;                         const float pd = (m < 3 && fr == 0) ? gnext[e] : g[e];
;                         up[e] = dpp_ror1(pu); dn[e] = dpp_ror15(pd);
;                     }
;                     if (efirst) up = (f32x4){0.f, 0.f, 0.f, 0.f};
;                     if (elast) dn = (f32x4){0.f, 0.f, 0.f, 0.f};
;                     gc[n] = w0[n] * up + w1[n] * g + w2[n] * dn + bb[n];
;                 }
;                 if (efirst || elast) {
;                     const size_t eo = (size_t)((row >> 6) * 2 + (elast ? 1 : 0)) * DFF + ch0;
; #pragma unroll
;                     for (int n = 0; n < 2; ++n) { *(f32x4*)(EP + eo + 4 * n) = gc[n]; *(f32x4*)(ER + eo + 4 * n) = acc[ai][0][m][n]; *(f32x4*)(EV + eo + 4 * n) = acc[ai][1][m][n]; }
;                 } else {
;                     const f32x4 v0 = acc[ai][1][m][0], v1 = acc[ai][1][m][1];
;                     u32x4 o;
;                     o[0] = pack2(silu_mul(gc[0][0], v0[0]), silu_mul(gc[0][1], v0[1])); o[1] = pack2(silu_mul(gc[0][2], v0[2]), silu_mul(gc[0][3], v0[3]));
	s_waitcnt lgkmcnt(0)
	s_lshl_b32 s21, s45, 7
	v_mov_b32_e32 v194, v186
	v_mov_b32_e32 v80, v187
	s_or_b32 s21, s21, s62
	v_mov_b32_e32 v160, 0
	v_lshl_add_u32 v184, v80, 3, s21
	v_ashrrev_i32_e32 v185, 31, v184
	v_lshlrev_b64 v[80:81], 2, v[184:185]
	v_lshl_add_u64 v[84:85], s[6:7], 0, v[80:81]
	v_lshl_add_u64 v[88:89], s[16:17], 0, v[80:81]
	v_lshl_add_u64 v[92:93], s[18:19], 0, v[80:81]
	v_lshl_add_u64 v[112:113], s[52:53], 0, v[80:81]
	global_load_dwordx4 v[80:83], v[84:85], off offset:16
	global_load_dwordx4 v[96:99], v[84:85], off
	s_nop 0
	global_load_dwordx4 v[84:87], v[88:89], off offset:16
	global_load_dwordx4 v[100:103], v[88:89], off
	s_nop 0
	global_load_dwordx4 v[88:91], v[92:93], off offset:16
	global_load_dwordx4 v[108:111], v[92:93], off
	s_nop 0
	global_load_dwordx4 v[92:95], v[112:113], off offset:16
	s_nop 0
	global_load_dwordx4 v[112:115], v[112:113], off
	v_cmp_eq_u32_e32 vcc, 0, v194
	v_mov_b32_e32 v164, 0
	v_mov_b32_e32 v195, 0
	v_cndmask_b32_e32 v161, v148, v136, vcc
	v_cndmask_b32_e32 v162, v149, v137, vcc
	v_cndmask_b32_e32 v163, v150, v138, vcc
	v_mov_b32_dpp v160, v161 row_ror:15 row_mask:0xf bank_mask:0xf
	v_mov_b32_e32 v161, 0
	v_mov_b32_e32 v166, 0
	v_mov_b32_e32 v167, 0
	v_mov_b32_dpp v161, v162 row_ror:15 row_mask:0xf bank_mask:0xf
	v_mov_b32_e32 v162, 0
	v_mov_b32_dpp v164, v150 row_ror:1 row_mask:0xf bank_mask:0xf
	v_cndmask_b32_e32 v165, v151, v139, vcc
	v_mov_b32_dpp v162, v163 row_ror:15 row_mask:0xf bank_mask:0xf
	v_mov_b32_dpp v195, v151 row_ror:1 row_mask:0xf bank_mask:0xf
	v_mov_b32_e32 v163, 0
	v_mov_b32_dpp v166, v148 row_ror:1 row_mask:0xf bank_mask:0xf
	v_mov_b32_dpp v167, v149 row_ror:1 row_mask:0xf bank_mask:0xf
	v_mov_b32_dpp v163, v165 row_ror:15 row_mask:0xf bank_mask:0xf
	v_cndmask_b32_e64 v165, v195, 0, vcc
	v_cndmask_b32_e64 v164, v164, 0, vcc
	v_cndmask_b32_e64 v167, v167, 0, vcc
	v_cndmask_b32_e64 v166, v166, 0, vcc
	v_mov_b32_e32 v195, 0
	v_mov_b32_e32 v196, 0
	v_mov_b32_e32 v198, 0
	v_mov_b32_e32 v200, 0
	v_mov_b32_dpp v195, v144 row_ror:1 row_mask:0xf bank_mask:0xf
	v_mov_b32_dpp v196, v145 row_ror:1 row_mask:0xf bank_mask:0xf
	v_mov_b32_dpp v198, v146 row_ror:1 row_mask:0xf bank_mask:0xf
	v_cndmask_b32_e32 v199, v147, v131, vcc
	v_mov_b32_dpp v200, v147 row_ror:1 row_mask:0xf bank_mask:0xf
	v_cndmask_b32_e64 v198, v198, 0, vcc
	v_cndmask_b32_e64 v201, v196, 0, vcc
	s_lshl_b32 s3, s44, 8
	s_add_i32 s3, s3, s49
	v_add_u32_e32 v193, s3, v194
	v_cmp_ne_u32_e64 s[46:47], 0, v194
	s_waitcnt vmcnt(0)
	v_pk_mul_f32 v[164:165], v[98:99], v[164:165]
	v_pk_mul_f32 v[166:167], v[96:97], v[166:167]
	v_pk_fma_f32 v[164:165], v[150:151], v[102:103], v[164:165]
	v_pk_fma_f32 v[166:167], v[148:149], v[100:101], v[166:167]
	v_pk_fma_f32 v[162:163], v[110:111], v[162:163], v[164:165]
	v_cndmask_b32_e32 v165, v144, v128, vcc
	v_mov_b32_e32 v164, 0
	v_pk_fma_f32 v[160:161], v[108:109], v[160:161], v[166:167]
	v_cndmask_b32_e32 v166, v145, v129, vcc
	v_mov_b32_dpp v164, v165 row_ror:15 row_mask:0xf bank_mask:0xf
	v_mov_b32_e32 v165, 0
	v_cndmask_b32_e32 v167, v146, v130, vcc
	v_pk_add_f32 v[162:163], v[114:115], v[162:163]
	v_mov_b32_dpp v165, v166 row_ror:15 row_mask:0xf bank_mask:0xf
	v_mov_b32_e32 v166, 0
	v_pk_add_f32 v[160:161], v[112:113], v[160:161]
	s_nop 0
	v_mov_b32_dpp v166, v167 row_ror:15 row_mask:0xf bank_mask:0xf
	v_mov_b32_e32 v167, 0
	s_nop 1
	v_mov_b32_dpp v167, v199 row_ror:15 row_mask:0xf bank_mask:0xf
	v_cndmask_b32_e64 v199, v200, 0, vcc
	v_cndmask_b32_e64 v200, v195, 0, vcc
	v_pk_mul_f32 v[200:201], v[80:81], v[200:201]
	v_pk_mul_f32 v[198:199], v[82:83], v[198:199]
	v_pk_fma_f32 v[200:201], v[144:145], v[84:85], v[200:201]
	v_pk_fma_f32 v[198:199], v[146:147], v[86:87], v[198:199]
	v_pk_fma_f32 v[164:165], v[88:89], v[164:165], v[200:201]
	v_pk_fma_f32 v[166:167], v[90:91], v[166:167], v[198:199]
	v_pk_add_f32 v[164:165], v[92:93], v[164:165]
	v_pk_add_f32 v[166:167], v[94:95], v[166:167]
	s_and_saveexec_b64 s[24:25], s[46:47]
	s_xor_b64 s[24:25], exec, s[24:25]
	s_cbranch_execz .LBB1_1072
	v_mul_f32_e32 v195, 0xbfb8aa3b, v160
	v_exp_f32_e32 v195, v195
	v_mul_f32_e32 v196, 0xbfb8aa3b, v161
	v_exp_f32_e32 v196, v196
	v_pk_mul_f32 v[160:161], v[156:157], v[160:161]
	v_add_f32_e32 v195, 1.0, v195
	v_rcp_f32_e32 v198, v195
	v_add_f32_e32 v196, 1.0, v196
	v_mul_f32_e32 v195, 0xbfb8aa3b, v162
	v_rcp_f32_e32 v199, v196
	v_exp_f32_e32 v195, v195
	v_mul_f32_e32 v196, 0xbfb8aa3b, v163
	v_exp_f32_e32 v196, v196
	v_pk_mul_f32 v[160:161], v[160:161], v[198:199]
	v_add_f32_e32 v195, 1.0, v195
	v_rcp_f32_e32 v200, v195
	v_add_f32_e32 v195, 1.0, v196
	v_rcp_f32_e32 v201, v195
	v_cvt_pk_bf16_f32 v160, v160, v161
	v_mul_f32_e32 v161, 0xbfb8aa3b, v164
	v_exp_f32_e32 v195, v161
	v_mul_f32_e32 v161, 0xbfb8aa3b, v165
	v_exp_f32_e32 v196, v161
	v_pk_mul_f32 v[162:163], v[158:159], v[162:163]
	v_pk_mul_f32 v[164:165], v[152:153], v[164:165]
	v_pk_mul_f32 v[162:163], v[162:163], v[200:201]
	s_nop 0
	v_cvt_pk_bf16_f32 v161, v162, v163
	v_add_f32_e32 v162, 1.0, v195
	v_mul_f32_e32 v195, 0xbfb8aa3b, v166
	v_add_f32_e32 v163, 1.0, v196
	v_exp_f32_e32 v195, v195
	v_mul_f32_e32 v196, 0xbfb8aa3b, v167
	v_exp_f32_e32 v196, v196
	v_rcp_f32_e32 v162, v162
	v_add_f32_e32 v195, 1.0, v195
	v_rcp_f32_e32 v198, v195
	v_add_f32_e32 v195, 1.0, v196
	v_rcp_f32_e32 v163, v163
	v_rcp_f32_e32 v199, v195
	v_pk_mul_f32 v[166:167], v[154:155], v[166:167]
	v_pk_mul_f32 v[162:163], v[164:165], v[162:163]
	v_pk_mul_f32 v[164:165], v[166:167], v[198:199]
	v_cvt_pk_bf16_f32 v162, v162, v163
	v_cvt_pk_bf16_f32 v163, v164, v165
	v_mov_b64_e32 v[164:165], s[54:55]
	v_mad_i64_i32 v[164:165], s[42:43], v193, s60, v[164:165]
	v_lshl_add_u64 v[164:165], v[184:185], 1, v[164:165]
	global_store_dwordx4 v[164:165], v[160:163], off

; #define PG8_STAGE(bufoff, gbase, voff) do { _Pragma("unroll") for (int _i = 0; _i < 2; ++_i) \
;         __builtin_amdgcn_global_load_lds((const unsigned*)((const char*)(gbase) + (voff)[_i]), (LAS unsigned*)(lds + (bufoff) + ldsw + _i * 8192), 16, 0, 0); } while (0)
; #define PG8_LDA(dst, b, h) do { _Pragma("unroll") for (int m = 0; m < 4; ++m) _Pragma("unroll") for (int k = 0; k < 2; ++k) dst[m][k] = *(const LAS bf16x8*)(lds + PG8_SA(b, h) + aoff + m * 2048 + k * 1024); } while (0)
; #define PG8_LDB(dst, b, h) do { _Pragma("unroll") for (int n = 0; n < 2; ++n) _Pragma("unroll") for (int k = 0; k < 2; ++k) dst[n][k] = *(const LAS bf16x8*)(lds + PG8_SB(b, h) + boff + n * 2048 + k * 1024); } while (0)
; #define PG8_MMA(ai, bj, At, Bt) do { __builtin_amdgcn_s_setprio(1); _Pragma("unroll") for (int m = 0; m < 4; ++m) _Pragma("unroll") for (int n = 0; n < 2; ++n) _Pragma("unroll") for (int k = 0; k < 2; ++k) \
;         acc[ai][bj][m][n] = __builtin_amdgcn_mfma_f32_16x16x32_bf16(Bt[n][k], At[m][k], acc[ai][bj][m][n], 0, 0, 0); __builtin_amdgcn_s_setprio(0); } while (0)
; #define PG8_WAIT_V(n) asm volatile("s_waitcnt vmcnt(" #n ")" ::: "memory")
; #define PG8_WAIT_L(n) asm volatile("s_waitcnt lgkmcnt(" #n ")" ::: "memory")
; template <class Map, class Epi>
; DI void gemm_phase(LAS unsigned char* lds, const Map& MP, const Epi& E, const int nM, const int nN, const int K, const int lda, const int ldb) {
;     ...
;             const bool last = (t == nt - 2);
;             const char* a1 = cA + (size_t)(t + 1) * kstep;
;             const char* a2 = last ? nA : cA + (size_t)(t + 2) * kstep; const char* b2 = last ? nB : cB + (size_t)(t + 2) * kstep;
;             const char* a3 = a2 + kstep; const char* b3 = b2 + kstep;
;             PG8_LDB(B0, 0, 0); PG8_SCHED; PG8_LDA(At, 0, 0); PG8_STAGE(PG8_SA(1, 1), a1 + hstepA, voffA);
;             PG8_WAIT_L(8); PG8_BAR; PG8_WAIT_L(0); PG8_MMA(0, 0, At, B0); PG8_BAR; PG8_SCHED;
;             PG8_LDB(B1, 0, 1); PG8_STAGE(PG8_SB(0, 0), b2, voffB);
;             PG8_BAR; PG8_WAIT_L(0); PG8_MMA(0, 1, At, B1); PG8_BAR;
;             PG8_LDA(At, 0, 1); PG8_STAGE(PG8_SA(0, 0), a2, voffA);
;             PG8_BAR; PG8_WAIT_L(0); PG8_MMA(1, 0, At, B0); PG8_BAR; PG8_SCHED;
;             PG8_STAGE(PG8_SB(0, 1), b2 + hstepB, voffB);
;             PG8_WAIT_V(6); PG8_BAR; PG8_MMA(1, 1, At, B1); PG8_BAR;
.LBB1_1239:
	s_add_u32 s10, s8, 0x100
	s_addc_u32 s11, s9, 0
	s_cmpk_eq_i32 s3, 0x54
	s_cselect_b32 s15, s43, s11
	s_cselect_b32 s14, s42, s10
	s_cselect_b32 s13, s7, s38
	s_cselect_b32 s12, s6, s5
	s_add_i32 m0, s24, 0xc000
	ds_read_b128 v[168:171], v150
	ds_read_b128 v[172:175], v150 offset:1024
	ds_read_b128 v[176:179], v150 offset:2048
	ds_read_b128 v[180:183], v150 offset:3072
	ds_read_b128 v[184:187], v150 offset:4096
	ds_read_b128 v[188:191], v150 offset:5120
	ds_read_b128 v[192:195], v150 offset:6144
	ds_read_b128 v[198:201], v150 offset:7168
	global_load_lds_dwordx4 v138, s[8:9]
	s_add_i32 m0, s24, 0xe000
	s_nop 0
	global_load_lds_dwordx4 v136, s[8:9]
	s_waitcnt lgkmcnt(7)
	s_setprio 1
	s_barrier
	v_mfma_f32_16x16x32_bf16 v[124:127], v[152:155], v[168:171], v[124:127]
	v_mfma_f32_16x16x32_bf16 v[120:123], v[160:163], v[168:171], v[120:123]
	s_waitcnt lgkmcnt(5)
	v_mfma_f32_16x16x32_bf16 v[108:111], v[152:155], v[176:179], v[108:111]
	v_mfma_f32_16x16x32_bf16 v[104:107], v[160:163], v[176:179], v[104:107]
	s_waitcnt lgkmcnt(3)
	v_mfma_f32_16x16x32_bf16 v[92:95], v[152:155], v[184:187], v[92:95]
	v_mfma_f32_16x16x32_bf16 v[88:91], v[160:163], v[184:187], v[88:91]
	s_waitcnt lgkmcnt(1)
	v_mfma_f32_16x16x32_bf16 v[76:79], v[152:155], v[192:195], v[76:79]
	v_mfma_f32_16x16x32_bf16 v[72:75], v[160:163], v[192:195], v[72:75]
	v_mfma_f32_16x16x32_bf16 v[124:127], v[156:159], v[172:175], v[124:127]
	v_mfma_f32_16x16x32_bf16 v[120:123], v[164:167], v[172:175], v[120:123]
	v_mfma_f32_16x16x32_bf16 v[108:111], v[156:159], v[180:183], v[108:111]
	v_mfma_f32_16x16x32_bf16 v[104:107], v[164:167], v[180:183], v[104:107]
	v_mfma_f32_16x16x32_bf16 v[92:95], v[156:159], v[188:191], v[92:95]
	v_mfma_f32_16x16x32_bf16 v[88:91], v[164:167], v[188:191], v[88:91]
	s_waitcnt lgkmcnt(0)
	v_mfma_f32_16x16x32_bf16 v[76:79], v[156:159], v[198:201], v[76:79]
	v_mfma_f32_16x16x32_bf16 v[72:75], v[164:167], v[198:201], v[72:75]
	s_barrier
	s_setprio 0
	s_add_i32 s8, s35, s22
	v_lshl_add_u64 v[144:145], s[12:13], 0, v[132:133]
	s_mov_b32 m0, s8
	ds_read_b128 v[202:205], v151
	ds_read_b128 v[206:209], v151 offset:1024
	ds_read_b128 v[210:213], v151 offset:2048
	ds_read_b128 v[214:217], v151 offset:3072
	global_load_lds_dwordx4 v[144:145], off
	v_lshl_add_u64 v[218:219], s[12:13], 0, v[128:129]
	s_add_i32 m0, s8, 0x2000
	s_nop 0
	global_load_lds_dwordx4 v[218:219], off
	s_waitcnt lgkmcnt(3)
	s_setprio 1
	s_barrier
	v_mfma_f32_16x16x32_bf16 v[116:119], v[202:205], v[168:171], v[116:119]
	s_waitcnt lgkmcnt(1)
	v_mfma_f32_16x16x32_bf16 v[112:115], v[210:213], v[168:171], v[112:115]
	v_mfma_f32_16x16x32_bf16 v[100:103], v[202:205], v[176:179], v[100:103]
	v_mfma_f32_16x16x32_bf16 v[96:99], v[210:213], v[176:179], v[96:99]
	v_mfma_f32_16x16x32_bf16 v[84:87], v[202:205], v[184:187], v[84:87]
	v_mfma_f32_16x16x32_bf16 v[80:83], v[210:213], v[184:187], v[80:83]
	v_mfma_f32_16x16x32_bf16 v[68:71], v[202:205], v[192:195], v[68:71]
	v_mfma_f32_16x16x32_bf16 v[64:67], v[210:213], v[192:195], v[64:67]
	v_mfma_f32_16x16x32_bf16 v[116:119], v[206:209], v[172:175], v[116:119]
	s_mov_b32 m0, s24
	s_waitcnt lgkmcnt(0)
	v_mfma_f32_16x16x32_bf16 v[112:115], v[214:217], v[172:175], v[112:115]
	v_lshl_add_u64 v[220:221], s[14:15], 0, v[134:135]
	v_mfma_f32_16x16x32_bf16 v[100:103], v[206:209], v[180:183], v[100:103]
	v_mfma_f32_16x16x32_bf16 v[96:99], v[214:217], v[180:183], v[96:99]
	v_mfma_f32_16x16x32_bf16 v[84:87], v[206:209], v[188:191], v[84:87]
	v_mfma_f32_16x16x32_bf16 v[80:83], v[214:217], v[188:191], v[80:83]
	v_mfma_f32_16x16x32_bf16 v[68:71], v[206:209], v[198:201], v[68:71]
	v_mfma_f32_16x16x32_bf16 v[64:67], v[214:217], v[198:201], v[64:67]
	s_barrier
	s_setprio 0
	ds_read_b128 v[168:171], v150 offset:16384
	ds_read_b128 v[172:175], v150 offset:17408
	ds_read_b128 v[176:179], v150 offset:18432
	ds_read_b128 v[180:183], v150 offset:19456
	ds_read_b128 v[184:187], v150 offset:20480
	ds_read_b128 v[188:191], v150 offset:21504
	ds_read_b128 v[192:195], v150 offset:22528
	ds_read_b128 v[198:201], v150 offset:23552
	global_load_lds_dwordx4 v[220:221], off
	v_lshl_add_u64 v[222:223], s[14:15], 0, v[130:131]
	s_mov_b32 m0, s25
	s_nop 0
	global_load_lds_dwordx4 v[222:223], off
	s_waitcnt vmcnt(10) lgkmcnt(7)
	s_setprio 1
	s_barrier
	v_mfma_f32_16x16x32_bf16 v[60:63], v[152:155], v[168:171], v[60:63]
	v_mfma_f32_16x16x32_bf16 v[56:59], v[160:163], v[168:171], v[56:59]
	s_waitcnt lgkmcnt(5)
	v_mfma_f32_16x16x32_bf16 v[44:47], v[152:155], v[176:179], v[44:47]
	v_mfma_f32_16x16x32_bf16 v[40:43], v[160:163], v[176:179], v[40:43]
	s_waitcnt lgkmcnt(3)
	v_mfma_f32_16x16x32_bf16 v[28:31], v[152:155], v[184:187], v[28:31]
	v_mfma_f32_16x16x32_bf16 v[24:27], v[160:163], v[184:187], v[24:27]
	s_waitcnt lgkmcnt(1)
	v_mfma_f32_16x16x32_bf16 v[12:15], v[152:155], v[192:195], v[12:15]
	v_mfma_f32_16x16x32_bf16 v[8:11], v[160:163], v[192:195], v[8:11]
	v_mfma_f32_16x16x32_bf16 v[60:63], v[156:159], v[172:175], v[60:63]
	v_mfma_f32_16x16x32_bf16 v[56:59], v[164:167], v[172:175], v[56:59]
	v_mfma_f32_16x16x32_bf16 v[44:47], v[156:159], v[180:183], v[44:47]
	v_mfma_f32_16x16x32_bf16 v[40:43], v[164:167], v[180:183], v[40:43]
	v_mfma_f32_16x16x32_bf16 v[28:31], v[156:159], v[188:191], v[28:31]
	v_mfma_f32_16x16x32_bf16 v[24:27], v[164:167], v[188:191], v[24:27]
	s_waitcnt lgkmcnt(0)
	v_mfma_f32_16x16x32_bf16 v[12:15], v[156:159], v[198:201], v[12:15]
	v_mfma_f32_16x16x32_bf16 v[8:11], v[164:167], v[198:201], v[8:11]
	s_barrier
	s_setprio 0
	s_add_u32 s8, s12, 0x160000
	s_addc_u32 s9, s13, 0
	s_add_i32 s39, s36, s22
	s_mov_b32 m0, s39
	s_nop 0
	global_load_lds_dwordx4 v132, s[8:9]
	s_add_i32 m0, s39, 0x2000
	s_nop 0
	global_load_lds_dwordx4 v128, s[8:9]
	s_waitcnt vmcnt(6)
	s_setprio 1
	s_barrier
; #define PG8_STAGE(bufoff, gbase, voff) do { _Pragma("unroll") for (int _i = 0; _i < 2; ++_i) \
;         __builtin_amdgcn_global_load_lds((const unsigned*)((const char*)(gbase) + (voff)[_i]), (LAS unsigned*)(lds + (bufoff) + ldsw + _i * 8192), 16, 0, 0); } while (0)
; #define PG8_LDA(dst, b, h) do { _Pragma("unroll") for (int m = 0; m < 4; ++m) _Pragma("unroll") for (int k = 0; k < 2; ++k) dst[m][k] = *(const LAS bf16x8*)(lds + PG8_SA(b, h) + aoff + m * 2048 + k * 1024); } while (0)
; #define PG8_LDB(dst, b, h) do { _Pragma("unroll") for (int n = 0; n < 2; ++n) _Pragma("unroll") for (int k = 0; k < 2; ++k) dst[n][k] = *(const LAS bf16x8*)(lds + PG8_SB(b, h) + boff + n * 2048 + k * 1024); } while (0)
; #define PG8_MMA(ai, bj, At, Bt) do { __builtin_amdgcn_s_setprio(1); _Pragma("unroll") for (int m = 0; m < 4; ++m) _Pragma("unroll") for (int n = 0; n < 2; ++n) _Pragma("unroll") for (int k = 0; k < 2; ++k) \
;         acc[ai][bj][m][n] = __builtin_amdgcn_mfma_f32_16x16x32_bf16(Bt[n][k], At[m][k], acc[ai][bj][m][n], 0, 0, 0); __builtin_amdgcn_s_setprio(0); } while (0)
; #define PG8_WAIT_V(n) asm volatile("s_waitcnt vmcnt(" #n ")" ::: "memory")
; #define PG8_WAIT_L(n) asm volatile("s_waitcnt lgkmcnt(" #n ")" ::: "memory")
; #define PG8_BAR __builtin_amdgcn_s_barrier()
; #define PG8_SCHED __builtin_amdgcn_sched_barrier(0)
; template <class Map, class Epi>
; DI void gemm_phase(LAS unsigned char* lds, const Map& MP, const Epi& E, const int nM, const int nN, const int K, const int lda, const int ldb) {
;     ...
;             PG8_WAIT_V(6); PG8_BAR; PG8_MMA(1, 1, At, B1); PG8_BAR;
;             PG8_LDB(B0, 1, 0); PG8_SCHED; PG8_LDA(At, 1, 0); PG8_STAGE(PG8_SA(0, 1), a2 + hstepA, voffA);
;             PG8_WAIT_L(8); PG8_BAR; PG8_WAIT_L(0); PG8_MMA(0, 0, At, B0); PG8_BAR; PG8_SCHED;
;             PG8_LDB(B1, 1, 1); PG8_STAGE(PG8_SB(1, 0), b3, voffB);
;             PG8_BAR; PG8_WAIT_L(0); PG8_MMA(0, 1, At, B1); PG8_BAR;
;             PG8_LDA(At, 1, 1); PG8_STAGE(PG8_SA(1, 0), a3, voffA);
;             PG8_BAR; PG8_WAIT_L(0); PG8_MMA(1, 0, At, B0); PG8_BAR; PG8_SCHED;
	v_mfma_f32_16x16x32_bf16 v[52:55], v[202:205], v[168:171], v[52:55]
	v_mfma_f32_16x16x32_bf16 v[48:51], v[210:213], v[168:171], v[48:51]
	s_add_i32 s39, 0, 0x18000
	v_add_u32_e32 v164, s39, v148
	ds_read_b128 v[152:155], v164
	v_mfma_f32_16x16x32_bf16 v[36:39], v[202:205], v[176:179], v[36:39]
	v_mfma_f32_16x16x32_bf16 v[32:35], v[210:213], v[176:179], v[32:35]
	ds_read_b128 v[156:159], v164 offset:1024
	v_mfma_f32_16x16x32_bf16 v[20:23], v[202:205], v[184:187], v[20:23]
	v_mfma_f32_16x16x32_bf16 v[16:19], v[210:213], v[184:187], v[16:19]
	ds_read_b128 v[160:163], v164 offset:2048
	v_mfma_f32_16x16x32_bf16 v[4:7], v[202:205], v[192:195], v[4:7]
	v_mfma_f32_16x16x32_bf16 v[0:3], v[210:213], v[192:195], v[0:3]
	ds_read_b128 v[164:167], v164 offset:3072
	v_mfma_f32_16x16x32_bf16 v[52:55], v[206:209], v[172:175], v[52:55]
	v_mfma_f32_16x16x32_bf16 v[48:51], v[214:217], v[172:175], v[48:51]
	v_mfma_f32_16x16x32_bf16 v[36:39], v[206:209], v[180:183], v[36:39]
	v_mfma_f32_16x16x32_bf16 v[32:35], v[214:217], v[180:183], v[32:35]
	v_mfma_f32_16x16x32_bf16 v[20:23], v[206:209], v[188:191], v[20:23]
	v_mfma_f32_16x16x32_bf16 v[16:19], v[214:217], v[188:191], v[16:19]
	v_mfma_f32_16x16x32_bf16 v[4:7], v[206:209], v[198:201], v[4:7]
	v_mfma_f32_16x16x32_bf16 v[0:3], v[214:217], v[198:201], v[0:3]
	s_barrier
	s_setprio 0
	s_add_u32 s8, s14, 0x160000
	s_addc_u32 s9, s15, 0
	s_mov_b32 m0, s26
	ds_read_b128 v[168:171], v150 offset:32768
	ds_read_b128 v[172:175], v150 offset:33792
	ds_read_b128 v[176:179], v150 offset:34816
	ds_read_b128 v[180:183], v150 offset:35840
	ds_read_b128 v[184:187], v150 offset:36864
	ds_read_b128 v[188:191], v150 offset:37888
	ds_read_b128 v[192:195], v150 offset:38912
	ds_read_b128 v[198:201], v150 offset:39936
	global_load_lds_dwordx4 v134, s[8:9]
	s_mov_b32 m0, s27
	s_nop 0
	global_load_lds_dwordx4 v130, s[8:9]
	s_waitcnt lgkmcnt(7)
	s_setprio 1
	s_barrier
	v_mfma_f32_16x16x32_bf16 v[124:127], v[152:155], v[168:171], v[124:127]
	v_mfma_f32_16x16x32_bf16 v[120:123], v[160:163], v[168:171], v[120:123]
	s_waitcnt lgkmcnt(5)
	v_mfma_f32_16x16x32_bf16 v[108:111], v[152:155], v[176:179], v[108:111]
	v_mfma_f32_16x16x32_bf16 v[104:107], v[160:163], v[176:179], v[104:107]
	s_waitcnt lgkmcnt(3)
	v_mfma_f32_16x16x32_bf16 v[92:95], v[152:155], v[184:187], v[92:95]
	v_mfma_f32_16x16x32_bf16 v[88:91], v[160:163], v[184:187], v[88:91]
	s_waitcnt lgkmcnt(1)
	v_mfma_f32_16x16x32_bf16 v[76:79], v[152:155], v[192:195], v[76:79]
	v_mfma_f32_16x16x32_bf16 v[72:75], v[160:163], v[192:195], v[72:75]
	v_mfma_f32_16x16x32_bf16 v[124:127], v[156:159], v[172:175], v[124:127]
	v_mfma_f32_16x16x32_bf16 v[120:123], v[164:167], v[172:175], v[120:123]
	v_mfma_f32_16x16x32_bf16 v[108:111], v[156:159], v[180:183], v[108:111]
	v_mfma_f32_16x16x32_bf16 v[104:107], v[164:167], v[180:183], v[104:107]
	v_mfma_f32_16x16x32_bf16 v[92:95], v[156:159], v[188:191], v[92:95]
	v_mfma_f32_16x16x32_bf16 v[88:91], v[164:167], v[188:191], v[88:91]
	s_waitcnt lgkmcnt(0)
	v_mfma_f32_16x16x32_bf16 v[76:79], v[156:159], v[198:201], v[76:79]
	v_mfma_f32_16x16x32_bf16 v[72:75], v[164:167], v[198:201], v[72:75]
	s_barrier
	s_setprio 0
	s_add_i32 s14, 0, 0x1c000
	s_add_i32 s8, s39, s22
	v_add_u32_e32 v196, s14, v148
	v_lshl_add_u64 v[144:145], v[144:145], 0, s[52:53]
	s_mov_b32 m0, s8
	ds_read_b128 v[202:205], v196
	ds_read_b128 v[206:209], v196 offset:1024
	ds_read_b128 v[210:213], v196 offset:2048
	ds_read_b128 v[214:217], v196 offset:3072
	global_load_lds_dwordx4 v[144:145], off
	v_lshl_add_u64 v[144:145], v[218:219], 0, s[52:53]
	s_add_i32 m0, s8, 0x2000
	s_nop 0
	global_load_lds_dwordx4 v[144:145], off
	s_waitcnt lgkmcnt(3)
	s_setprio 1
	s_barrier
	v_mfma_f32_16x16x32_bf16 v[116:119], v[202:205], v[168:171], v[116:119]
	s_waitcnt lgkmcnt(1)
	v_mfma_f32_16x16x32_bf16 v[112:115], v[210:213], v[168:171], v[112:115]
	v_mfma_f32_16x16x32_bf16 v[100:103], v[202:205], v[176:179], v[100:103]
	v_mfma_f32_16x16x32_bf16 v[96:99], v[210:213], v[176:179], v[96:99]
	v_mfma_f32_16x16x32_bf16 v[84:87], v[202:205], v[184:187], v[84:87]
	v_mfma_f32_16x16x32_bf16 v[80:83], v[210:213], v[184:187], v[80:83]
	v_mfma_f32_16x16x32_bf16 v[68:71], v[202:205], v[192:195], v[68:71]
	v_mfma_f32_16x16x32_bf16 v[64:67], v[210:213], v[192:195], v[64:67]
	v_mfma_f32_16x16x32_bf16 v[116:119], v[206:209], v[172:175], v[116:119]
	s_mov_b32 m0, s30
	s_waitcnt lgkmcnt(0)
	v_mfma_f32_16x16x32_bf16 v[112:115], v[214:217], v[172:175], v[112:115]
	v_lshl_add_u64 v[144:145], v[220:221], 0, s[52:53]
	v_mfma_f32_16x16x32_bf16 v[100:103], v[206:209], v[180:183], v[100:103]
	v_mfma_f32_16x16x32_bf16 v[96:99], v[214:217], v[180:183], v[96:99]
	v_mfma_f32_16x16x32_bf16 v[84:87], v[206:209], v[188:191], v[84:87]
	v_mfma_f32_16x16x32_bf16 v[80:83], v[214:217], v[188:191], v[80:83]
	v_mfma_f32_16x16x32_bf16 v[68:71], v[206:209], v[198:201], v[68:71]
	v_mfma_f32_16x16x32_bf16 v[64:67], v[214:217], v[198:201], v[64:67]
	s_barrier
	s_setprio 0
	ds_read_b128 v[168:171], v150 offset:49152
	ds_read_b128 v[172:175], v150 offset:50176
	ds_read_b128 v[176:179], v150 offset:51200
	ds_read_b128 v[180:183], v150 offset:52224
	ds_read_b128 v[184:187], v150 offset:53248
	ds_read_b128 v[188:191], v150 offset:54272
	ds_read_b128 v[192:195], v150 offset:55296
	ds_read_b128 v[198:201], v150 offset:56320
	global_load_lds_dwordx4 v[144:145], off
	v_lshl_add_u64 v[144:145], v[222:223], 0, s[52:53]
	s_mov_b32 m0, s31
	s_nop 0
	global_load_lds_dwordx4 v[144:145], off
	s_waitcnt vmcnt(10) lgkmcnt(7)
	s_setprio 1
	s_barrier
; DI unsigned pack2(float a, float b) { f32x2 v = {a, b}; hwbf16x2 r = __builtin_convertvector(v, hwbf16x2); return __builtin_bit_cast(unsigned, r); }
; DI float bflo(unsigned w) { return __uint_as_float(w << 16); }
; DI float bfhi(unsigned w) { return __uint_as_float(w & 0xffff0000u); }
; #define PG8_WAIT_V(n) asm volatile("s_waitcnt vmcnt(" #n ")" ::: "memory")
; #define PG8_BAR __builtin_amdgcn_s_barrier()
;     DI void operator()(const f32x4 (&acc)[2][2][4][2], const Unit& u, int wr, int wc, int fr, int fq) const {
;     ...
;         for (int ai = 0; ai < 2; ++ai)
; #pragma unroll
;             for (int m = 0; m < 4; ++m) { const size_t ro = (size_t)(row0 + ai * HALF + m * 16) * D + col0;
; #pragma unroll
;                 for (int bj = 0; bj < 2; ++bj) {
;                     f32x4 x0, x1;
;                     if constexpr (IB) { const u32x4 w = *(const u32x4*)((const bf16_t*)Xin + ro + bj * HALF);
;                         x0 = (f32x4){bflo(w[0]), bfhi(w[0]), bflo(w[1]), bfhi(w[1])}; x1 = (f32x4){bflo(w[2]), bfhi(w[2]), bflo(w[3]), bfhi(w[3])}; }
;                     else { x0 = *(const f32x4*)((const float*)Xin + ro + bj * HALF); x1 = *(const f32x4*)((const float*)Xin + ro + bj * HALF + 4); }
;                     x0 += acc[ai][bj][m][0] * sc[bj][0]; x1 += acc[ai][bj][m][1] * sc[bj][1];
;                     if constexpr (OB) { u32x4 o; o[0] = pack2(x0[0], x0[1]); o[1] = pack2(x0[2], x0[3]); o[2] = pack2(x1[0], x1[1]); o[3] = pack2(x1[2], x1[3]);
;                         *(u32x4*)((bf16_t*)Xout + ro + bj * HALF) = o; }
;                     else { *(f32x4*)((float*)Xout + ro + bj * HALF) = x0; *(f32x4*)((float*)Xout + ro + bj * HALF + 4) = x1; } } }
; template <class Map, class Epi>
; DI void gemm_phase(LAS unsigned char* lds, const Map& MP, const Epi& E, const int nM, const int nN, const int K, const int lda, const int ldb) {
;     ...
;             PG8_WAIT_L(8); PG8_BAR; PG8_WAIT_L(0); PG8_MMA(0, 0, At, B0); PG8_BAR; PG8_SCHED;
;             PG8_LDB(B1, 1, 1); PG8_STAGE(PG8_SB(1, 0), b3, voffB);
;             PG8_BAR; PG8_WAIT_L(0); PG8_MMA(0, 1, At, B1); PG8_BAR;
;             PG8_LDA(At, 1, 1); PG8_STAGE(PG8_SA(1, 0), a3, voffA);
;             PG8_BAR; PG8_WAIT_L(0); PG8_MMA(1, 0, At, B0); PG8_BAR; PG8_SCHED;
;             PG8_STAGE(PG8_SB(1, 1), b3 + hstepB, voffB);
;             PG8_WAIT_V(6); PG8_BAR; PG8_MMA(1, 1, At, B1); PG8_BAR;
	v_mfma_f32_16x16x32_bf16 v[60:63], v[152:155], v[168:171], v[60:63]
	v_mfma_f32_16x16x32_bf16 v[56:59], v[160:163], v[168:171], v[56:59]
	s_waitcnt lgkmcnt(5)
	v_mfma_f32_16x16x32_bf16 v[44:47], v[152:155], v[176:179], v[44:47]
	v_mfma_f32_16x16x32_bf16 v[40:43], v[160:163], v[176:179], v[40:43]
	s_waitcnt lgkmcnt(3)
	v_mfma_f32_16x16x32_bf16 v[28:31], v[152:155], v[184:187], v[28:31]
	v_mfma_f32_16x16x32_bf16 v[24:27], v[160:163], v[184:187], v[24:27]
	s_waitcnt lgkmcnt(1)
	v_mfma_f32_16x16x32_bf16 v[12:15], v[152:155], v[192:195], v[12:15]
	v_mfma_f32_16x16x32_bf16 v[8:11], v[160:163], v[192:195], v[8:11]
	v_mfma_f32_16x16x32_bf16 v[60:63], v[156:159], v[172:175], v[60:63]
	v_mfma_f32_16x16x32_bf16 v[56:59], v[164:167], v[172:175], v[56:59]
	v_mfma_f32_16x16x32_bf16 v[44:47], v[156:159], v[180:183], v[44:47]
	v_mfma_f32_16x16x32_bf16 v[40:43], v[164:167], v[180:183], v[40:43]
	v_mfma_f32_16x16x32_bf16 v[28:31], v[156:159], v[188:191], v[28:31]
	v_mfma_f32_16x16x32_bf16 v[24:27], v[164:167], v[188:191], v[24:27]
	s_waitcnt lgkmcnt(0)
	v_mfma_f32_16x16x32_bf16 v[12:15], v[156:159], v[198:201], v[12:15]
	v_mfma_f32_16x16x32_bf16 v[8:11], v[164:167], v[198:201], v[8:11]
	s_barrier
	s_setprio 0
	s_add_u32 s8, s12, 0x160080
	s_addc_u32 s9, s13, 0
	s_add_i32 s12, s14, s22
	s_mov_b32 m0, s12
	s_nop 0
	global_load_lds_dwordx4 v132, s[8:9]
	s_add_i32 m0, s12, 0x2000
	s_nop 0
	global_load_lds_dwordx4 v128, s[8:9]
	s_waitcnt vmcnt(6)
	s_setprio 1
	s_barrier
	v_mfma_f32_16x16x32_bf16 v[52:55], v[202:205], v[168:171], v[52:55]
	v_mfma_f32_16x16x32_bf16 v[48:51], v[210:213], v[168:171], v[48:51]
	ds_read_b128 v[152:155], v149
	v_mfma_f32_16x16x32_bf16 v[36:39], v[202:205], v[176:179], v[36:39]
	v_mfma_f32_16x16x32_bf16 v[32:35], v[210:213], v[176:179], v[32:35]
	ds_read_b128 v[156:159], v149 offset:1024
	v_mfma_f32_16x16x32_bf16 v[20:23], v[202:205], v[184:187], v[20:23]
	v_mfma_f32_16x16x32_bf16 v[16:19], v[210:213], v[184:187], v[16:19]
	ds_read_b128 v[160:163], v149 offset:2048
	v_mfma_f32_16x16x32_bf16 v[4:7], v[202:205], v[192:195], v[4:7]
	v_mfma_f32_16x16x32_bf16 v[0:3], v[210:213], v[192:195], v[0:3]
	ds_read_b128 v[164:167], v149 offset:3072
	v_mfma_f32_16x16x32_bf16 v[52:55], v[206:209], v[172:175], v[52:55]
	s_add_i32 s3, s3, 2
	v_mfma_f32_16x16x32_bf16 v[48:51], v[214:217], v[172:175], v[48:51]
	s_add_u32 s5, s5, 0x100
	s_addc_u32 s38, s38, 0
	v_mfma_f32_16x16x32_bf16 v[36:39], v[206:209], v[180:183], v[36:39]
	s_cmpk_gt_u32 s3, 0x55
	v_mfma_f32_16x16x32_bf16 v[32:35], v[214:217], v[180:183], v[32:35]
	s_mov_b64 s[8:9], s[10:11]
	v_mfma_f32_16x16x32_bf16 v[20:23], v[206:209], v[188:191], v[20:23]
	v_mfma_f32_16x16x32_bf16 v[16:19], v[214:217], v[188:191], v[16:19]
	v_mfma_f32_16x16x32_bf16 v[4:7], v[206:209], v[198:201], v[4:7]
	v_mfma_f32_16x16x32_bf16 v[0:3], v[214:217], v[198:201], v[0:3]
	s_barrier
	s_setprio 0
	s_cbranch_scc0 .LBB1_1239
	s_waitcnt lgkmcnt(0)
	v_mov_b32_e32 v152, v147
	v_mov_b32_e32 v144, v146
	s_lshl_b32 s2, s2, 8
	s_add_i32 s2, s2, s29
	s_lshl_b32 s3, s4, 8
	v_add_u32_e32 v152, s2, v152
	s_or_b32 s3, s3, s54
	v_ashrrev_i32_e32 v153, 31, v152
	v_lshl_add_u32 v144, v144, 3, s3
	v_lshlrev_b64 v[152:153], 12, v[152:153]
	v_ashrrev_i32_e32 v145, 31, v144
	v_lshl_add_u64 v[152:153], s[46:47], 0, v[152:153]
	v_lshl_add_u64 v[144:145], v[144:145], 1, v[152:153]
	global_load_dwordx4 v[160:163], v[144:145], off
	global_load_dwordx4 v[164:167], v[144:145], off offset:256
	s_mov_b64 s[98:99], 0x10000
	v_lshl_add_u64 v[154:155], v[144:145], 0, s[98:99]
	global_load_dwordx4 v[168:171], v[154:155], off
	global_load_dwordx4 v[172:175], v[154:155], off offset:256
	s_mov_b64 s[98:99], 0x20000
	v_lshl_add_u64 v[154:155], v[144:145], 0, s[98:99]
	global_load_dwordx4 v[176:179], v[154:155], off
	global_load_dwordx4 v[180:183], v[154:155], off offset:256
	s_mov_b64 s[98:99], 0x30000
	v_lshl_add_u64 v[154:155], v[144:145], 0, s[98:99]
	global_load_dwordx4 v[184:187], v[154:155], off
	global_load_dwordx4 v[188:191], v[154:155], off offset:256
	s_mov_b64 s[98:99], 0x80000
	v_lshl_add_u64 v[154:155], v[144:145], 0, s[98:99]
	global_load_dwordx4 v[192:195], v[154:155], off
	global_load_dwordx4 v[198:201], v[154:155], off offset:256
	s_mov_b64 s[98:99], 0x90000
	v_lshl_add_u64 v[154:155], v[144:145], 0, s[98:99]
	global_load_dwordx4 v[202:205], v[154:155], off
	global_load_dwordx4 v[206:209], v[154:155], off offset:256
	s_mov_b64 s[98:99], 0xa0000
	v_lshl_add_u64 v[154:155], v[144:145], 0, s[98:99]
	global_load_dwordx4 v[210:213], v[154:155], off
	global_load_dwordx4 v[214:217], v[154:155], off offset:256
	s_mov_b64 s[98:99], 0xb0000
	v_lshl_add_u64 v[154:155], v[144:145], 0, s[98:99]
	global_load_dwordx4 v[248:251], v[154:155], off
	global_load_dwordx4 v[252:255], v[154:155], off offset:256
	s_waitcnt vmcnt(15)
	s_nop 1
	v_mov_b32_e32 v152, v160
	v_mov_b32_e32 v153, v161
	v_mov_b32_e32 v154, v162
	v_mov_b32_e32 v155, v163
	s_mov_b64 s[2:3], 0x10000
	s_mov_b32 s4, s37
	s_mov_b64 s[10:11], s[6:7]
	s_mov_b64 s[8:9], s[42:43]
	s_waitcnt lgkmcnt(0)
	v_lshlrev_b32_e32 v156, 16, v152
	v_and_b32_e32 v157, 0xffff0000, v152
	v_lshlrev_b32_e32 v152, 16, v153
	v_and_b32_e32 v153, 0xffff0000, v153
	v_lshlrev_b32_e32 v158, 16, v154
	v_and_b32_e32 v159, 0xffff0000, v154
	v_lshlrev_b32_e32 v154, 16, v155
	v_and_b32_e32 v155, 0xffff0000, v155
	v_pk_add_f32 v[126:127], v[126:127], v[152:153]
	v_pk_add_f32 v[124:125], v[124:125], v[156:157]
	v_pk_add_f32 v[152:153], v[122:123], v[154:155]
	v_pk_add_f32 v[122:123], v[120:121], v[158:159]
	v_cvt_pk_bf16_f32 v120, v124, v125
	v_cvt_pk_bf16_f32 v121, v126, v127
	v_cvt_pk_bf16_f32 v122, v122, v123
	v_cvt_pk_bf16_f32 v123, v152, v153
	global_store_dwordx4 v[144:145], v[120:123], off
	s_waitcnt vmcnt(15)
; DI unsigned pack2(float a, float b) { f32x2 v = {a, b}; hwbf16x2 r = __builtin_convertvector(v, hwbf16x2); return __builtin_bit_cast(unsigned, r); }
; DI float bflo(unsigned w) { return __uint_as_float(w << 16); }
; DI float bfhi(unsigned w) { return __uint_as_float(w & 0xffff0000u); }
;     DI void operator()(const f32x4 (&acc)[2][2][4][2], const Unit& u, int wr, int wc, int fr, int fq) const {
;     ...
;         for (int ai = 0; ai < 2; ++ai)
; #pragma unroll
;             for (int m = 0; m < 4; ++m) { const size_t ro = (size_t)(row0 + ai * HALF + m * 16) * D + col0;
; #pragma unroll
;                 for (int bj = 0; bj < 2; ++bj) {
;                     f32x4 x0, x1;
;                     if constexpr (IB) { const u32x4 w = *(const u32x4*)((const bf16_t*)Xin + ro + bj * HALF);
;                         x0 = (f32x4){bflo(w[0]), bfhi(w[0]), bflo(w[1]), bfhi(w[1])}; x1 = (f32x4){bflo(w[2]), bfhi(w[2]), bflo(w[3]), bfhi(w[3])}; }
;                     else { x0 = *(const f32x4*)((const float*)Xin + ro + bj * HALF); x1 = *(const f32x4*)((const float*)Xin + ro + bj * HALF + 4); }
;                     x0 += acc[ai][bj][m][0] * sc[bj][0]; x1 += acc[ai][bj][m][1] * sc[bj][1];
;                     if constexpr (OB) { u32x4 o; o[0] = pack2(x0[0], x0[1]); o[1] = pack2(x0[2], x0[3]); o[2] = pack2(x1[0], x1[1]); o[3] = pack2(x1[2], x1[3]);
;                         *(u32x4*)((bf16_t*)Xout + ro + bj * HALF) = o; }
;                     else { *(f32x4*)((float*)Xout + ro + bj * HALF) = x0; *(f32x4*)((float*)Xout + ro + bj * HALF + 4) = x1; } } }
	s_nop 1
	v_mov_b32_e32 v120, v164
	v_mov_b32_e32 v121, v165
	v_mov_b32_e32 v122, v166
	v_mov_b32_e32 v123, v167
	s_waitcnt lgkmcnt(0)
	v_lshlrev_b32_e32 v124, 16, v120
	v_and_b32_e32 v125, 0xffff0000, v120
	v_lshlrev_b32_e32 v120, 16, v121
	v_and_b32_e32 v121, 0xffff0000, v121
	v_lshlrev_b32_e32 v126, 16, v122
	v_and_b32_e32 v127, 0xffff0000, v122
	v_lshlrev_b32_e32 v122, 16, v123
	v_and_b32_e32 v123, 0xffff0000, v123
	v_pk_add_f32 v[116:117], v[116:117], v[124:125]
	v_pk_add_f32 v[118:119], v[118:119], v[120:121]
	v_pk_add_f32 v[120:121], v[114:115], v[122:123]
	v_pk_add_f32 v[114:115], v[112:113], v[126:127]
	v_cvt_pk_bf16_f32 v112, v116, v117
	v_lshl_add_u64 v[116:117], v[144:145], 0, s[2:3]
	s_mov_b32 s2, 0x10000
	v_cvt_pk_bf16_f32 v113, v118, v119
	v_add_co_u32_e32 v118, vcc, s2, v144
	v_cvt_pk_bf16_f32 v114, v114, v115
	v_cvt_pk_bf16_f32 v115, v120, v121
	v_addc_co_u32_e32 v119, vcc, 0, v145, vcc
	global_store_dwordx4 v[144:145], v[112:115], off offset:256
	s_waitcnt vmcnt(15)
	s_nop 1
	v_mov_b32_e32 v112, v168
	v_mov_b32_e32 v113, v169
	v_mov_b32_e32 v114, v170
	v_mov_b32_e32 v115, v171
	s_mov_b64 s[2:3], 0x20000
	s_waitcnt lgkmcnt(0)
	v_lshlrev_b32_e32 v120, 16, v112
	v_and_b32_e32 v121, 0xffff0000, v112
	v_lshlrev_b32_e32 v112, 16, v113
	v_and_b32_e32 v113, 0xffff0000, v113
	v_lshlrev_b32_e32 v122, 16, v114
	v_and_b32_e32 v123, 0xffff0000, v114
	v_lshlrev_b32_e32 v114, 16, v115
	v_and_b32_e32 v115, 0xffff0000, v115
	v_pk_add_f32 v[110:111], v[110:111], v[112:113]
	v_pk_add_f32 v[108:109], v[108:109], v[120:121]
	v_pk_add_f32 v[112:113], v[106:107], v[114:115]
	v_pk_add_f32 v[106:107], v[104:105], v[122:123]
	v_cvt_pk_bf16_f32 v104, v108, v109
	v_cvt_pk_bf16_f32 v105, v110, v111
	v_cvt_pk_bf16_f32 v106, v106, v107
	v_cvt_pk_bf16_f32 v107, v112, v113
	global_store_dwordx4 v[118:119], v[104:107], off
	s_waitcnt vmcnt(15)
	s_nop 1
	v_mov_b32_e32 v104, v172
	v_mov_b32_e32 v105, v173
	v_mov_b32_e32 v106, v174
	v_mov_b32_e32 v107, v175
	s_waitcnt lgkmcnt(0)
	v_lshlrev_b32_e32 v108, 16, v104
	v_and_b32_e32 v109, 0xffff0000, v104
	v_lshlrev_b32_e32 v104, 16, v105
	v_and_b32_e32 v105, 0xffff0000, v105
	v_lshlrev_b32_e32 v110, 16, v106
	v_and_b32_e32 v111, 0xffff0000, v106
	v_lshlrev_b32_e32 v106, 16, v107
	v_and_b32_e32 v107, 0xffff0000, v107
	v_pk_add_f32 v[100:101], v[100:101], v[108:109]
	v_pk_add_f32 v[102:103], v[102:103], v[104:105]
	v_pk_add_f32 v[104:105], v[98:99], v[106:107]
	v_pk_add_f32 v[98:99], v[96:97], v[110:111]
	v_cvt_pk_bf16_f32 v96, v100, v101
	v_lshl_add_u64 v[100:101], v[144:145], 0, s[2:3]
	s_mov_b32 s2, 0x20000
	v_cvt_pk_bf16_f32 v97, v102, v103
	v_add_co_u32_e32 v102, vcc, s2, v144
	v_cvt_pk_bf16_f32 v98, v98, v99
	v_cvt_pk_bf16_f32 v99, v104, v105
	v_addc_co_u32_e32 v103, vcc, 0, v145, vcc
	global_store_dwordx4 v[116:117], v[96:99], off offset:256
	s_waitcnt vmcnt(15)
	s_nop 1
	v_mov_b32_e32 v96, v176
	v_mov_b32_e32 v97, v177
	v_mov_b32_e32 v98, v178
	v_mov_b32_e32 v99, v179
	s_mov_b64 s[2:3], 0x30000
	s_waitcnt lgkmcnt(0)
	v_lshlrev_b32_e32 v104, 16, v96
	v_and_b32_e32 v105, 0xffff0000, v96
	v_lshlrev_b32_e32 v96, 16, v97
	v_and_b32_e32 v97, 0xffff0000, v97
	v_lshlrev_b32_e32 v106, 16, v98
	v_and_b32_e32 v107, 0xffff0000, v98
	v_lshlrev_b32_e32 v98, 16, v99
	v_and_b32_e32 v99, 0xffff0000, v99
	v_pk_add_f32 v[94:95], v[94:95], v[96:97]
	v_pk_add_f32 v[92:93], v[92:93], v[104:105]
	v_pk_add_f32 v[96:97], v[90:91], v[98:99]
	v_pk_add_f32 v[90:91], v[88:89], v[106:107]
	v_cvt_pk_bf16_f32 v88, v92, v93
	v_cvt_pk_bf16_f32 v89, v94, v95
	v_cvt_pk_bf16_f32 v90, v90, v91
	v_cvt_pk_bf16_f32 v91, v96, v97
	global_store_dwordx4 v[102:103], v[88:91], off
	s_waitcnt vmcnt(15)
	s_nop 1
	v_mov_b32_e32 v88, v180
	v_mov_b32_e32 v89, v181
	v_mov_b32_e32 v90, v182
	v_mov_b32_e32 v91, v183
	s_waitcnt lgkmcnt(0)
	v_lshlrev_b32_e32 v92, 16, v88
	v_and_b32_e32 v93, 0xffff0000, v88
	v_lshlrev_b32_e32 v88, 16, v89
	v_and_b32_e32 v89, 0xffff0000, v89
	v_lshlrev_b32_e32 v94, 16, v90
	v_and_b32_e32 v95, 0xffff0000, v90
	v_lshlrev_b32_e32 v90, 16, v91
	v_and_b32_e32 v91, 0xffff0000, v91
	v_pk_add_f32 v[86:87], v[86:87], v[88:89]
	v_pk_add_f32 v[84:85], v[84:85], v[92:93]
	v_pk_add_f32 v[88:89], v[82:83], v[90:91]
	v_pk_add_f32 v[82:83], v[80:81], v[94:95]
	v_cvt_pk_bf16_f32 v80, v84, v85
	v_cvt_pk_bf16_f32 v81, v86, v87
	v_cvt_pk_bf16_f32 v82, v82, v83
	v_cvt_pk_bf16_f32 v83, v88, v89
	global_store_dwordx4 v[100:101], v[80:83], off offset:256
	s_nop 1
	v_lshl_add_u64 v[80:81], v[144:145], 0, s[2:3]
	s_mov_b32 s2, 0x30000
	v_add_co_u32_e32 v86, vcc, s2, v144
	s_mov_b64 s[2:3], 0x80000
	s_nop 0
	v_addc_co_u32_e32 v87, vcc, 0, v145, vcc
	s_waitcnt vmcnt(15)
	s_nop 1
	v_mov_b32_e32 v82, v184
	v_mov_b32_e32 v83, v185
	v_mov_b32_e32 v84, v186
	v_mov_b32_e32 v85, v187
	s_waitcnt lgkmcnt(0)
	v_lshlrev_b32_e32 v88, 16, v82
	v_and_b32_e32 v89, 0xffff0000, v82
	v_lshlrev_b32_e32 v82, 16, v83
	v_and_b32_e32 v83, 0xffff0000, v83
	v_lshlrev_b32_e32 v90, 16, v84
	v_and_b32_e32 v91, 0xffff0000, v84
	v_lshlrev_b32_e32 v84, 16, v85
	v_and_b32_e32 v85, 0xffff0000, v85
	v_pk_add_f32 v[78:79], v[78:79], v[82:83]
	v_pk_add_f32 v[76:77], v[76:77], v[88:89]
	v_pk_add_f32 v[82:83], v[74:75], v[84:85]
	v_pk_add_f32 v[74:75], v[72:73], v[90:91]
	v_cvt_pk_bf16_f32 v72, v76, v77
	v_cvt_pk_bf16_f32 v73, v78, v79
	v_cvt_pk_bf16_f32 v74, v74, v75
	v_cvt_pk_bf16_f32 v75, v82, v83
	global_store_dwordx4 v[86:87], v[72:75], off
	s_waitcnt vmcnt(15)
	s_nop 1
	v_mov_b32_e32 v72, v188
	v_mov_b32_e32 v73, v189
	v_mov_b32_e32 v74, v190
	v_mov_b32_e32 v75, v191
	s_waitcnt lgkmcnt(0)
; DI unsigned pack2(float a, float b) { f32x2 v = {a, b}; hwbf16x2 r = __builtin_convertvector(v, hwbf16x2); return __builtin_bit_cast(unsigned, r); }
; DI float bflo(unsigned w) { return __uint_as_float(w << 16); }
; DI float bfhi(unsigned w) { return __uint_as_float(w & 0xffff0000u); }
;     DI void operator()(const f32x4 (&acc)[2][2][4][2], const Unit& u, int wr, int wc, int fr, int fq) const {
;     ...
;         for (int ai = 0; ai < 2; ++ai)
; #pragma unroll
;             for (int m = 0; m < 4; ++m) { const size_t ro = (size_t)(row0 + ai * HALF + m * 16) * D + col0;
; #pragma unroll
;                 for (int bj = 0; bj < 2; ++bj) {
;                     f32x4 x0, x1;
;                     if constexpr (IB) { const u32x4 w = *(const u32x4*)((const bf16_t*)Xin + ro + bj * HALF);
;                         x0 = (f32x4){bflo(w[0]), bfhi(w[0]), bflo(w[1]), bfhi(w[1])}; x1 = (f32x4){bflo(w[2]), bfhi(w[2]), bflo(w[3]), bfhi(w[3])}; }
;                     else { x0 = *(const f32x4*)((const float*)Xin + ro + bj * HALF); x1 = *(const f32x4*)((const float*)Xin + ro + bj * HALF + 4); }
;                     x0 += acc[ai][bj][m][0] * sc[bj][0]; x1 += acc[ai][bj][m][1] * sc[bj][1];
;                     if constexpr (OB) { u32x4 o; o[0] = pack2(x0[0], x0[1]); o[1] = pack2(x0[2], x0[3]); o[2] = pack2(x1[0], x1[1]); o[3] = pack2(x1[2], x1[3]);
;                         *(u32x4*)((bf16_t*)Xout + ro + bj * HALF) = o; }
;                     else { *(f32x4*)((float*)Xout + ro + bj * HALF) = x0; *(f32x4*)((float*)Xout + ro + bj * HALF + 4) = x1; } } }
	v_lshlrev_b32_e32 v76, 16, v72
	v_and_b32_e32 v77, 0xffff0000, v72
	v_lshlrev_b32_e32 v72, 16, v73
	v_and_b32_e32 v73, 0xffff0000, v73
	v_lshlrev_b32_e32 v78, 16, v74
	v_and_b32_e32 v79, 0xffff0000, v74
	v_lshlrev_b32_e32 v74, 16, v75
	v_and_b32_e32 v75, 0xffff0000, v75
	v_pk_add_f32 v[70:71], v[70:71], v[72:73]
	v_pk_add_f32 v[68:69], v[68:69], v[76:77]
	v_pk_add_f32 v[72:73], v[66:67], v[74:75]
	v_pk_add_f32 v[66:67], v[64:65], v[78:79]
	v_cvt_pk_bf16_f32 v64, v68, v69
	v_cvt_pk_bf16_f32 v65, v70, v71
	v_cvt_pk_bf16_f32 v66, v66, v67
	v_cvt_pk_bf16_f32 v67, v72, v73
	global_store_dwordx4 v[80:81], v[64:67], off offset:256
	s_nop 1
	v_lshl_add_u64 v[64:65], v[144:145], 0, s[2:3]
	s_mov_b32 s2, 0x80000
	v_add_co_u32_e32 v70, vcc, s2, v144
	s_mov_b64 s[2:3], 0x90000
	s_nop 0
	v_addc_co_u32_e32 v71, vcc, 0, v145, vcc
	s_waitcnt vmcnt(15)
	s_nop 1
	v_mov_b32_e32 v66, v192
	v_mov_b32_e32 v67, v193
	v_mov_b32_e32 v68, v194
	v_mov_b32_e32 v69, v195
	s_waitcnt lgkmcnt(0)
	v_lshlrev_b32_e32 v72, 16, v66
	v_and_b32_e32 v73, 0xffff0000, v66
	v_lshlrev_b32_e32 v66, 16, v67
	v_and_b32_e32 v67, 0xffff0000, v67
	v_lshlrev_b32_e32 v74, 16, v68
	v_and_b32_e32 v75, 0xffff0000, v68
	v_lshlrev_b32_e32 v68, 16, v69
	v_and_b32_e32 v69, 0xffff0000, v69
	v_pk_add_f32 v[62:63], v[62:63], v[66:67]
	v_pk_add_f32 v[60:61], v[60:61], v[72:73]
	v_pk_add_f32 v[66:67], v[58:59], v[68:69]
	v_pk_add_f32 v[58:59], v[56:57], v[74:75]
	v_cvt_pk_bf16_f32 v56, v60, v61
	v_cvt_pk_bf16_f32 v57, v62, v63
	v_cvt_pk_bf16_f32 v58, v58, v59
	v_cvt_pk_bf16_f32 v59, v66, v67
	global_store_dwordx4 v[70:71], v[56:59], off
	s_waitcnt vmcnt(15)
	s_nop 1
	v_mov_b32_e32 v56, v198
	v_mov_b32_e32 v57, v199
	v_mov_b32_e32 v58, v200
	v_mov_b32_e32 v59, v201
	s_waitcnt lgkmcnt(0)
	v_lshlrev_b32_e32 v60, 16, v56
	v_and_b32_e32 v61, 0xffff0000, v56
	v_lshlrev_b32_e32 v56, 16, v57
	v_and_b32_e32 v57, 0xffff0000, v57
	v_lshlrev_b32_e32 v62, 16, v58
	v_and_b32_e32 v63, 0xffff0000, v58
	v_lshlrev_b32_e32 v58, 16, v59
	v_and_b32_e32 v59, 0xffff0000, v59
	v_pk_add_f32 v[54:55], v[54:55], v[56:57]
	v_pk_add_f32 v[52:53], v[52:53], v[60:61]
	v_pk_add_f32 v[56:57], v[50:51], v[58:59]
	v_pk_add_f32 v[50:51], v[48:49], v[62:63]
	v_cvt_pk_bf16_f32 v48, v52, v53
	v_cvt_pk_bf16_f32 v49, v54, v55
	v_cvt_pk_bf16_f32 v50, v50, v51
	v_cvt_pk_bf16_f32 v51, v56, v57
	global_store_dwordx4 v[64:65], v[48:51], off offset:256
	s_nop 1
	v_lshl_add_u64 v[48:49], v[144:145], 0, s[2:3]
	s_mov_b32 s2, 0x90000
	v_add_co_u32_e32 v54, vcc, s2, v144
	s_mov_b64 s[2:3], 0xa0000
	s_nop 0
	v_addc_co_u32_e32 v55, vcc, 0, v145, vcc
	s_waitcnt vmcnt(15)
	s_nop 1
	v_mov_b32_e32 v50, v202
	v_mov_b32_e32 v51, v203
	v_mov_b32_e32 v52, v204
	v_mov_b32_e32 v53, v205
	s_waitcnt lgkmcnt(0)
	v_lshlrev_b32_e32 v56, 16, v50
	v_and_b32_e32 v57, 0xffff0000, v50
	v_lshlrev_b32_e32 v50, 16, v51
	v_and_b32_e32 v51, 0xffff0000, v51
	v_lshlrev_b32_e32 v58, 16, v52
	v_and_b32_e32 v59, 0xffff0000, v52
	v_lshlrev_b32_e32 v52, 16, v53
	v_and_b32_e32 v53, 0xffff0000, v53
	v_pk_add_f32 v[46:47], v[46:47], v[50:51]
	v_pk_add_f32 v[44:45], v[44:45], v[56:57]
	v_pk_add_f32 v[50:51], v[42:43], v[52:53]
	v_pk_add_f32 v[42:43], v[40:41], v[58:59]
	v_cvt_pk_bf16_f32 v40, v44, v45
	v_cvt_pk_bf16_f32 v41, v46, v47
	v_cvt_pk_bf16_f32 v42, v42, v43
	v_cvt_pk_bf16_f32 v43, v50, v51
	global_store_dwordx4 v[54:55], v[40:43], off
	s_waitcnt vmcnt(15)
	s_nop 1
	v_mov_b32_e32 v40, v206
	v_mov_b32_e32 v41, v207
	v_mov_b32_e32 v42, v208
	v_mov_b32_e32 v43, v209
	s_waitcnt lgkmcnt(0)
; DI unsigned pack2(float a, float b) { f32x2 v = {a, b}; hwbf16x2 r = __builtin_convertvector(v, hwbf16x2); return __builtin_bit_cast(unsigned, r); }
; DI float bflo(unsigned w) { return __uint_as_float(w << 16); }
; DI float bfhi(unsigned w) { return __uint_as_float(w & 0xffff0000u); }
; #define PG8_WAIT_V(n) asm volatile("s_waitcnt vmcnt(" #n ")" ::: "memory")
; #define PG8_BAR __builtin_amdgcn_s_barrier()
;     DI void operator()(const f32x4 (&acc)[2][2][4][2], const Unit& u, int wr, int wc, int fr, int fq) const {
;     ...
;         for (int ai = 0; ai < 2; ++ai)
; #pragma unroll
;             for (int m = 0; m < 4; ++m) { const size_t ro = (size_t)(row0 + ai * HALF + m * 16) * D + col0;
; #pragma unroll
;                 for (int bj = 0; bj < 2; ++bj) {
;                     f32x4 x0, x1;
;                     if constexpr (IB) { const u32x4 w = *(const u32x4*)((const bf16_t*)Xin + ro + bj * HALF);
;                         x0 = (f32x4){bflo(w[0]), bfhi(w[0]), bflo(w[1]), bfhi(w[1])}; x1 = (f32x4){bflo(w[2]), bfhi(w[2]), bflo(w[3]), bfhi(w[3])}; }
;                     else { x0 = *(const f32x4*)((const float*)Xin + ro + bj * HALF); x1 = *(const f32x4*)((const float*)Xin + ro + bj * HALF + 4); }
;                     x0 += acc[ai][bj][m][0] * sc[bj][0]; x1 += acc[ai][bj][m][1] * sc[bj][1];
;                     if constexpr (OB) { u32x4 o; o[0] = pack2(x0[0], x0[1]); o[1] = pack2(x0[2], x0[3]); o[2] = pack2(x1[0], x1[1]); o[3] = pack2(x1[2], x1[3]);
;                         *(u32x4*)((bf16_t*)Xout + ro + bj * HALF) = o; }
;                     else { *(f32x4*)((float*)Xout + ro + bj * HALF) = x0; *(f32x4*)((float*)Xout + ro + bj * HALF + 4) = x1; } } }
; template <class Map, class Epi>
; DI void gemm_phase(LAS unsigned char* lds, const Map& MP, const Epi& E, const int nM, const int nN, const int K, const int lda, const int ldb) {
;     ...
;         cur = nxt; cA = nA; cB = nB; ++ui;
;     }
;     PG8_WAIT_V(0);
;     if (wr == 0) PG8_BAR;
;     PG8_BAR;
	v_lshlrev_b32_e32 v44, 16, v40
	v_and_b32_e32 v45, 0xffff0000, v40
	v_lshlrev_b32_e32 v40, 16, v41
	v_and_b32_e32 v41, 0xffff0000, v41
	v_lshlrev_b32_e32 v46, 16, v42
	v_and_b32_e32 v47, 0xffff0000, v42
	v_lshlrev_b32_e32 v42, 16, v43
	v_and_b32_e32 v43, 0xffff0000, v43
	v_pk_add_f32 v[38:39], v[38:39], v[40:41]
	v_pk_add_f32 v[36:37], v[36:37], v[44:45]
	v_pk_add_f32 v[40:41], v[34:35], v[42:43]
	v_pk_add_f32 v[34:35], v[32:33], v[46:47]
	v_cvt_pk_bf16_f32 v32, v36, v37
	v_cvt_pk_bf16_f32 v33, v38, v39
	v_cvt_pk_bf16_f32 v34, v34, v35
	v_cvt_pk_bf16_f32 v35, v40, v41
	global_store_dwordx4 v[48:49], v[32:35], off offset:256
	s_nop 1
	v_lshl_add_u64 v[32:33], v[144:145], 0, s[2:3]
	s_mov_b32 s2, 0xa0000
	v_add_co_u32_e32 v38, vcc, s2, v144
	s_mov_b64 s[2:3], 0xb0000
	s_nop 0
	v_addc_co_u32_e32 v39, vcc, 0, v145, vcc
	s_waitcnt vmcnt(15)
	s_nop 1
	v_mov_b32_e32 v34, v210
	v_mov_b32_e32 v35, v211
	v_mov_b32_e32 v36, v212
	v_mov_b32_e32 v37, v213
	s_waitcnt lgkmcnt(0)
	v_lshlrev_b32_e32 v40, 16, v34
	v_and_b32_e32 v41, 0xffff0000, v34
	v_lshlrev_b32_e32 v34, 16, v35
	v_and_b32_e32 v35, 0xffff0000, v35
	v_lshlrev_b32_e32 v42, 16, v36
	v_and_b32_e32 v43, 0xffff0000, v36
	v_lshlrev_b32_e32 v36, 16, v37
	v_and_b32_e32 v37, 0xffff0000, v37
	v_pk_add_f32 v[30:31], v[30:31], v[34:35]
	v_pk_add_f32 v[28:29], v[28:29], v[40:41]
	v_pk_add_f32 v[34:35], v[26:27], v[36:37]
	v_pk_add_f32 v[26:27], v[24:25], v[42:43]
	v_cvt_pk_bf16_f32 v24, v28, v29
	v_cvt_pk_bf16_f32 v25, v30, v31
	v_cvt_pk_bf16_f32 v26, v26, v27
	v_cvt_pk_bf16_f32 v27, v34, v35
	global_store_dwordx4 v[38:39], v[24:27], off
	s_waitcnt vmcnt(15)
	s_nop 1
	v_mov_b32_e32 v24, v214
	v_mov_b32_e32 v25, v215
	v_mov_b32_e32 v26, v216
	v_mov_b32_e32 v27, v217
	s_waitcnt lgkmcnt(0)
	v_lshlrev_b32_e32 v28, 16, v24
	v_and_b32_e32 v29, 0xffff0000, v24
	v_lshlrev_b32_e32 v24, 16, v25
	v_and_b32_e32 v25, 0xffff0000, v25
	v_lshlrev_b32_e32 v30, 16, v26
	v_and_b32_e32 v31, 0xffff0000, v26
	v_lshlrev_b32_e32 v26, 16, v27
	v_and_b32_e32 v27, 0xffff0000, v27
	v_pk_add_f32 v[22:23], v[22:23], v[24:25]
	v_pk_add_f32 v[20:21], v[20:21], v[28:29]
	v_pk_add_f32 v[24:25], v[18:19], v[26:27]
	v_pk_add_f32 v[18:19], v[16:17], v[30:31]
	v_cvt_pk_bf16_f32 v16, v20, v21
	v_cvt_pk_bf16_f32 v17, v22, v23
	v_cvt_pk_bf16_f32 v18, v18, v19
	v_cvt_pk_bf16_f32 v19, v24, v25
	global_store_dwordx4 v[32:33], v[16:19], off offset:256
	s_nop 1
	v_lshl_add_u64 v[16:17], v[144:145], 0, s[2:3]
	s_mov_b32 s2, 0xb0000
	v_add_co_u32_e32 v22, vcc, s2, v144
	s_mov_b32 s2, s55
	s_nop 0
	v_addc_co_u32_e32 v23, vcc, 0, v145, vcc
	s_waitcnt vmcnt(15)
	s_nop 1
	v_mov_b32_e32 v18, v248
	v_mov_b32_e32 v19, v249
	v_mov_b32_e32 v20, v250
	v_mov_b32_e32 v21, v251
	s_and_b64 vcc, exec, s[40:41]
	s_waitcnt lgkmcnt(0)
	v_lshlrev_b32_e32 v24, 16, v18
	v_and_b32_e32 v25, 0xffff0000, v18
	v_lshlrev_b32_e32 v18, 16, v19
	v_and_b32_e32 v19, 0xffff0000, v19
	v_lshlrev_b32_e32 v26, 16, v20
	v_and_b32_e32 v27, 0xffff0000, v20
	v_lshlrev_b32_e32 v20, 16, v21
	v_and_b32_e32 v21, 0xffff0000, v21
	v_pk_add_f32 v[14:15], v[14:15], v[18:19]
	v_pk_add_f32 v[12:13], v[12:13], v[24:25]
	v_pk_add_f32 v[18:19], v[10:11], v[20:21]
	v_pk_add_f32 v[10:11], v[8:9], v[26:27]
	v_cvt_pk_bf16_f32 v8, v12, v13
	v_cvt_pk_bf16_f32 v9, v14, v15
	v_cvt_pk_bf16_f32 v10, v10, v11
	v_cvt_pk_bf16_f32 v11, v18, v19
	global_store_dwordx4 v[22:23], v[8:11], off
	s_waitcnt vmcnt(15)
	s_nop 1
	v_mov_b32_e32 v8, v252
	v_mov_b32_e32 v9, v253
	v_mov_b32_e32 v10, v254
	v_mov_b32_e32 v11, v255
	s_waitcnt lgkmcnt(0)
	v_lshlrev_b32_e32 v12, 16, v8
	v_and_b32_e32 v13, 0xffff0000, v8
	v_lshlrev_b32_e32 v8, 16, v9
	v_and_b32_e32 v9, 0xffff0000, v9
	v_lshlrev_b32_e32 v14, 16, v10
	v_and_b32_e32 v15, 0xffff0000, v10
	v_lshlrev_b32_e32 v10, 16, v11
	v_and_b32_e32 v11, 0xffff0000, v11
	v_pk_add_f32 v[6:7], v[6:7], v[8:9]
	v_pk_add_f32 v[4:5], v[4:5], v[12:13]
	v_pk_add_f32 v[8:9], v[2:3], v[10:11]
	v_pk_add_f32 v[2:3], v[0:1], v[14:15]
	v_cvt_pk_bf16_f32 v0, v4, v5
	v_cvt_pk_bf16_f32 v1, v6, v7
	v_cvt_pk_bf16_f32 v2, v2, v3
	v_cvt_pk_bf16_f32 v3, v8, v9
	global_store_dwordx4 v[16:17], v[0:3], off offset:256
	s_cbranch_vccz .LBB1_1232
	s_waitcnt vmcnt(0)
	s_cmpk_gt_u32 s17, 0xff
	s_cbranch_scc1 .LBB1_1243
	s_barrier

; #define PG8_STAGE(bufoff, gbase, voff) do { _Pragma("unroll") for (int _i = 0; _i < 2; ++_i) \
;         __builtin_amdgcn_global_load_lds((const unsigned*)((const char*)(gbase) + (voff)[_i]), (LAS unsigned*)(lds + (bufoff) + ldsw + _i * 8192), 16, 0, 0); } while (0)
; #define PG8_LDA(dst, b, h) do { _Pragma("unroll") for (int m = 0; m < 4; ++m) _Pragma("unroll") for (int k = 0; k < 2; ++k) dst[m][k] = *(const LAS bf16x8*)(lds + PG8_SA(b, h) + aoff + m * 2048 + k * 1024); } while (0)
; #define PG8_LDB(dst, b, h) do { _Pragma("unroll") for (int n = 0; n < 2; ++n) _Pragma("unroll") for (int k = 0; k < 2; ++k) dst[n][k] = *(const LAS bf16x8*)(lds + PG8_SB(b, h) + boff + n * 2048 + k * 1024); } while (0)
; #define PG8_MMA(ai, bj, At, Bt) do { __builtin_amdgcn_s_setprio(1); _Pragma("unroll") for (int m = 0; m < 4; ++m) _Pragma("unroll") for (int n = 0; n < 2; ++n) _Pragma("unroll") for (int k = 0; k < 2; ++k) \
;         acc[ai][bj][m][n] = __builtin_amdgcn_mfma_f32_16x16x32_bf16(Bt[n][k], At[m][k], acc[ai][bj][m][n], 0, 0, 0); __builtin_amdgcn_s_setprio(0); } while (0)
; #define PG8_WAIT_V(n) asm volatile("s_waitcnt vmcnt(" #n ")" ::: "memory")
; #define PG8_WAIT_L(n) asm volatile("s_waitcnt lgkmcnt(" #n ")" ::: "memory")
; #define PG8_BAR __builtin_amdgcn_s_barrier()
; #define PG8_SCHED __builtin_amdgcn_sched_barrier(0)
; template <class Map, class Epi>
; DI void gemm_phase(LAS unsigned char* lds, const Map& MP, const Epi& E, const int nM, const int nN, const int K, const int lda, const int ldb) {
;     ...
;             PG8_LDB(B0, 0, 0); PG8_SCHED; PG8_LDA(At, 0, 0); PG8_STAGE(PG8_SA(1, 1), a1 + hstepA, voffA);
;             PG8_WAIT_L(8); PG8_BAR; PG8_WAIT_L(0); PG8_MMA(0, 0, At, B0); PG8_BAR; PG8_SCHED;
;             PG8_LDB(B1, 0, 1); PG8_STAGE(PG8_SB(0, 0), b2, voffB);
;             PG8_BAR; PG8_WAIT_L(0); PG8_MMA(0, 1, At, B1); PG8_BAR;
;             PG8_LDA(At, 0, 1); PG8_STAGE(PG8_SA(0, 0), a2, voffA);
;             PG8_BAR; PG8_WAIT_L(0); PG8_MMA(1, 0, At, B0); PG8_BAR; PG8_SCHED;
;             PG8_STAGE(PG8_SB(0, 1), b2 + hstepB, voffB);
;             PG8_WAIT_V(6); PG8_BAR; PG8_MMA(1, 1, At, B1); PG8_BAR;
.LBB1_1382:
	s_add_u32 s22, s20, 0xfff80080
	s_addc_u32 s23, s21, -1
	s_cmp_eq_u32 s3, 28
	s_cselect_b32 s25, s15, s23
	s_cselect_b32 s24, s48, s22
	s_cselect_b32 s23, s13, s53
	s_cselect_b32 s22, s49, s52
	s_add_i32 m0, s31, 0xc000
	ds_read_b128 v[166:169], v148
	ds_read_b128 v[170:173], v148 offset:1024
	ds_read_b128 v[174:177], v148 offset:2048
	ds_read_b128 v[178:181], v148 offset:3072
	ds_read_b128 v[182:185], v148 offset:4096
	ds_read_b128 v[186:189], v148 offset:5120
	ds_read_b128 v[190:193], v148 offset:6144
	ds_read_b128 v[198:201], v148 offset:7168
	global_load_lds_dwordx4 v138, s[20:21]
	s_add_i32 m0, s31, 0xe000
	s_nop 0
	global_load_lds_dwordx4 v136, s[20:21]
	s_waitcnt lgkmcnt(7)
	s_setprio 1
	s_barrier
	v_mfma_f32_16x16x32_bf16 v[124:127], v[150:153], v[166:169], v[124:127]
	v_mfma_f32_16x16x32_bf16 v[120:123], v[158:161], v[166:169], v[120:123]
	s_waitcnt lgkmcnt(5)
	v_mfma_f32_16x16x32_bf16 v[116:119], v[150:153], v[174:177], v[116:119]
	v_mfma_f32_16x16x32_bf16 v[112:115], v[158:161], v[174:177], v[112:115]
	s_waitcnt lgkmcnt(3)
	v_mfma_f32_16x16x32_bf16 v[100:103], v[150:153], v[182:185], v[100:103]
	v_mfma_f32_16x16x32_bf16 v[96:99], v[158:161], v[182:185], v[96:99]
	s_waitcnt lgkmcnt(1)
	v_mfma_f32_16x16x32_bf16 v[84:87], v[150:153], v[190:193], v[84:87]
	v_mfma_f32_16x16x32_bf16 v[80:83], v[158:161], v[190:193], v[80:83]
	v_mfma_f32_16x16x32_bf16 v[124:127], v[154:157], v[170:173], v[124:127]
	v_mfma_f32_16x16x32_bf16 v[120:123], v[162:165], v[170:173], v[120:123]
	v_mfma_f32_16x16x32_bf16 v[116:119], v[154:157], v[178:181], v[116:119]
	v_mfma_f32_16x16x32_bf16 v[112:115], v[162:165], v[178:181], v[112:115]
	v_mfma_f32_16x16x32_bf16 v[100:103], v[154:157], v[186:189], v[100:103]
	v_mfma_f32_16x16x32_bf16 v[96:99], v[162:165], v[186:189], v[96:99]
	s_waitcnt lgkmcnt(0)
	v_mfma_f32_16x16x32_bf16 v[84:87], v[154:157], v[198:201], v[84:87]
	v_mfma_f32_16x16x32_bf16 v[80:83], v[162:165], v[198:201], v[80:83]
	s_barrier
	s_setprio 0
	s_add_i32 s54, s44, s29
	v_lshl_add_u64 v[194:195], s[22:23], 0, v[132:133]
	s_mov_b32 m0, s54
	ds_read_b128 v[202:205], v149
	ds_read_b128 v[206:209], v149 offset:1024
	ds_read_b128 v[210:213], v149 offset:2048
	ds_read_b128 v[214:217], v149 offset:3072
	global_load_lds_dwordx4 v[194:195], off
	v_lshl_add_u64 v[218:219], s[22:23], 0, v[128:129]
	s_add_i32 m0, s54, 0x2000
	s_nop 0
	global_load_lds_dwordx4 v[218:219], off
	s_waitcnt lgkmcnt(3)
	s_setprio 1
	s_barrier
	v_mfma_f32_16x16x32_bf16 v[108:111], v[202:205], v[166:169], v[108:111]
	s_waitcnt lgkmcnt(1)
	v_mfma_f32_16x16x32_bf16 v[104:107], v[210:213], v[166:169], v[104:107]
	v_mfma_f32_16x16x32_bf16 v[92:95], v[202:205], v[174:177], v[92:95]
	v_mfma_f32_16x16x32_bf16 v[88:91], v[210:213], v[174:177], v[88:91]
	v_mfma_f32_16x16x32_bf16 v[76:79], v[202:205], v[182:185], v[76:79]
	v_mfma_f32_16x16x32_bf16 v[72:75], v[210:213], v[182:185], v[72:75]
	v_mfma_f32_16x16x32_bf16 v[68:71], v[202:205], v[190:193], v[68:71]
	v_mfma_f32_16x16x32_bf16 v[64:67], v[210:213], v[190:193], v[64:67]
	v_mfma_f32_16x16x32_bf16 v[108:111], v[206:209], v[170:173], v[108:111]
	s_mov_b32 m0, s31
	s_waitcnt lgkmcnt(0)
	v_mfma_f32_16x16x32_bf16 v[104:107], v[214:217], v[170:173], v[104:107]
	v_lshl_add_u64 v[220:221], s[24:25], 0, v[134:135]
	v_mfma_f32_16x16x32_bf16 v[92:95], v[206:209], v[178:181], v[92:95]
	v_mfma_f32_16x16x32_bf16 v[88:91], v[214:217], v[178:181], v[88:91]
	v_mfma_f32_16x16x32_bf16 v[76:79], v[206:209], v[186:189], v[76:79]
	v_mfma_f32_16x16x32_bf16 v[72:75], v[214:217], v[186:189], v[72:75]
	v_mfma_f32_16x16x32_bf16 v[68:71], v[206:209], v[198:201], v[68:71]
	v_mfma_f32_16x16x32_bf16 v[64:67], v[214:217], v[198:201], v[64:67]
	s_barrier
	s_setprio 0
	ds_read_b128 v[166:169], v148 offset:16384
	ds_read_b128 v[170:173], v148 offset:17408
	ds_read_b128 v[174:177], v148 offset:18432
	ds_read_b128 v[178:181], v148 offset:19456
	ds_read_b128 v[182:185], v148 offset:20480
	ds_read_b128 v[186:189], v148 offset:21504
	ds_read_b128 v[190:193], v148 offset:22528
	ds_read_b128 v[198:201], v148 offset:23552
	global_load_lds_dwordx4 v[220:221], off
	v_lshl_add_u64 v[222:223], s[24:25], 0, v[130:131]
	s_mov_b32 m0, s11
	s_nop 0
	global_load_lds_dwordx4 v[222:223], off
	s_waitcnt vmcnt(10) lgkmcnt(7)
	s_setprio 1
	s_barrier
	v_mfma_f32_16x16x32_bf16 v[60:63], v[150:153], v[166:169], v[60:63]
	v_mfma_f32_16x16x32_bf16 v[56:59], v[158:161], v[166:169], v[56:59]
	s_waitcnt lgkmcnt(5)
	v_mfma_f32_16x16x32_bf16 v[52:55], v[150:153], v[174:177], v[52:55]
	v_mfma_f32_16x16x32_bf16 v[48:51], v[158:161], v[174:177], v[48:51]
	s_waitcnt lgkmcnt(3)
	v_mfma_f32_16x16x32_bf16 v[36:39], v[150:153], v[182:185], v[36:39]
	v_mfma_f32_16x16x32_bf16 v[32:35], v[158:161], v[182:185], v[32:35]
	s_waitcnt lgkmcnt(1)
	v_mfma_f32_16x16x32_bf16 v[20:23], v[150:153], v[190:193], v[20:23]
	v_mfma_f32_16x16x32_bf16 v[16:19], v[158:161], v[190:193], v[16:19]
	v_mfma_f32_16x16x32_bf16 v[60:63], v[154:157], v[170:173], v[60:63]
	v_mfma_f32_16x16x32_bf16 v[56:59], v[162:165], v[170:173], v[56:59]
	v_mfma_f32_16x16x32_bf16 v[52:55], v[154:157], v[178:181], v[52:55]
	v_mfma_f32_16x16x32_bf16 v[48:51], v[162:165], v[178:181], v[48:51]
	v_mfma_f32_16x16x32_bf16 v[36:39], v[154:157], v[186:189], v[36:39]
	v_mfma_f32_16x16x32_bf16 v[32:35], v[162:165], v[186:189], v[32:35]
	s_waitcnt lgkmcnt(0)
	v_mfma_f32_16x16x32_bf16 v[20:23], v[154:157], v[198:201], v[20:23]
	v_mfma_f32_16x16x32_bf16 v[16:19], v[162:165], v[198:201], v[16:19]
	s_barrier
	s_setprio 0
	s_add_u32 s54, s22, 0x80000
	s_addc_u32 s55, s23, 0
	s_add_i32 s56, s45, s29
	s_mov_b32 m0, s56
	s_nop 0
	global_load_lds_dwordx4 v132, s[54:55]
	s_add_i32 m0, s56, 0x2000
	s_nop 0
	global_load_lds_dwordx4 v128, s[54:55]
	s_waitcnt vmcnt(6)
	s_setprio 1
	s_barrier
; #define PG8_STAGE(bufoff, gbase, voff) do { _Pragma("unroll") for (int _i = 0; _i < 2; ++_i) \
;         __builtin_amdgcn_global_load_lds((const unsigned*)((const char*)(gbase) + (voff)[_i]), (LAS unsigned*)(lds + (bufoff) + ldsw + _i * 8192), 16, 0, 0); } while (0)
; #define PG8_LDA(dst, b, h) do { _Pragma("unroll") for (int m = 0; m < 4; ++m) _Pragma("unroll") for (int k = 0; k < 2; ++k) dst[m][k] = *(const LAS bf16x8*)(lds + PG8_SA(b, h) + aoff + m * 2048 + k * 1024); } while (0)
; #define PG8_LDB(dst, b, h) do { _Pragma("unroll") for (int n = 0; n < 2; ++n) _Pragma("unroll") for (int k = 0; k < 2; ++k) dst[n][k] = *(const LAS bf16x8*)(lds + PG8_SB(b, h) + boff + n * 2048 + k * 1024); } while (0)
; #define PG8_MMA(ai, bj, At, Bt) do { __builtin_amdgcn_s_setprio(1); _Pragma("unroll") for (int m = 0; m < 4; ++m) _Pragma("unroll") for (int n = 0; n < 2; ++n) _Pragma("unroll") for (int k = 0; k < 2; ++k) \
;         acc[ai][bj][m][n] = __builtin_amdgcn_mfma_f32_16x16x32_bf16(Bt[n][k], At[m][k], acc[ai][bj][m][n], 0, 0, 0); __builtin_amdgcn_s_setprio(0); } while (0)
; #define PG8_WAIT_V(n) asm volatile("s_waitcnt vmcnt(" #n ")" ::: "memory")
; #define PG8_WAIT_L(n) asm volatile("s_waitcnt lgkmcnt(" #n ")" ::: "memory")
; #define PG8_BAR __builtin_amdgcn_s_barrier()
; #define PG8_SCHED __builtin_amdgcn_sched_barrier(0)
; template <class Map, class Epi>
; DI void gemm_phase(LAS unsigned char* lds, const Map& MP, const Epi& E, const int nM, const int nN, const int K, const int lda, const int ldb) {
;     ...
;             PG8_WAIT_V(6); PG8_BAR; PG8_MMA(1, 1, At, B1); PG8_BAR;
;             PG8_LDB(B0, 1, 0); PG8_SCHED; PG8_LDA(At, 1, 0); PG8_STAGE(PG8_SA(0, 1), a2 + hstepA, voffA);
;             PG8_WAIT_L(8); PG8_BAR; PG8_WAIT_L(0); PG8_MMA(0, 0, At, B0); PG8_BAR; PG8_SCHED;
;             PG8_LDB(B1, 1, 1); PG8_STAGE(PG8_SB(1, 0), b3, voffB);
;             PG8_BAR; PG8_WAIT_L(0); PG8_MMA(0, 1, At, B1); PG8_BAR;
;             PG8_LDA(At, 1, 1); PG8_STAGE(PG8_SA(1, 0), a3, voffA);
;             PG8_BAR; PG8_WAIT_L(0); PG8_MMA(1, 0, At, B0); PG8_BAR; PG8_SCHED;
	v_mfma_f32_16x16x32_bf16 v[44:47], v[202:205], v[166:169], v[44:47]
	v_mfma_f32_16x16x32_bf16 v[40:43], v[210:213], v[166:169], v[40:43]
	s_add_i32 s54, 0, 0x18000
	v_add_u32_e32 v162, s54, v146
	ds_read_b128 v[150:153], v162
	v_mfma_f32_16x16x32_bf16 v[28:31], v[202:205], v[174:177], v[28:31]
	v_mfma_f32_16x16x32_bf16 v[24:27], v[210:213], v[174:177], v[24:27]
	ds_read_b128 v[154:157], v162 offset:1024
	v_mfma_f32_16x16x32_bf16 v[12:15], v[202:205], v[182:185], v[12:15]
	v_mfma_f32_16x16x32_bf16 v[8:11], v[210:213], v[182:185], v[8:11]
	ds_read_b128 v[158:161], v162 offset:2048
	v_mfma_f32_16x16x32_bf16 v[4:7], v[202:205], v[190:193], v[4:7]
	v_mfma_f32_16x16x32_bf16 v[0:3], v[210:213], v[190:193], v[0:3]
	ds_read_b128 v[162:165], v162 offset:3072
	v_mfma_f32_16x16x32_bf16 v[44:47], v[206:209], v[170:173], v[44:47]
	v_mfma_f32_16x16x32_bf16 v[40:43], v[214:217], v[170:173], v[40:43]
	v_mfma_f32_16x16x32_bf16 v[28:31], v[206:209], v[178:181], v[28:31]
	v_mfma_f32_16x16x32_bf16 v[24:27], v[214:217], v[178:181], v[24:27]
	v_mfma_f32_16x16x32_bf16 v[12:15], v[206:209], v[186:189], v[12:15]
	v_mfma_f32_16x16x32_bf16 v[8:11], v[214:217], v[186:189], v[8:11]
	v_mfma_f32_16x16x32_bf16 v[4:7], v[206:209], v[198:201], v[4:7]
	v_mfma_f32_16x16x32_bf16 v[0:3], v[214:217], v[198:201], v[0:3]
	s_barrier
	s_setprio 0
	s_add_u32 s24, s24, 0x80000
	s_addc_u32 s25, s25, 0
	s_mov_b32 m0, s34
	ds_read_b128 v[166:169], v148 offset:32768
	ds_read_b128 v[170:173], v148 offset:33792
	ds_read_b128 v[174:177], v148 offset:34816
	ds_read_b128 v[178:181], v148 offset:35840
	ds_read_b128 v[182:185], v148 offset:36864
	ds_read_b128 v[186:189], v148 offset:37888
	ds_read_b128 v[190:193], v148 offset:38912
	ds_read_b128 v[198:201], v148 offset:39936
	global_load_lds_dwordx4 v134, s[24:25]
	s_mov_b32 m0, s35
	s_nop 0
	global_load_lds_dwordx4 v130, s[24:25]
	s_waitcnt lgkmcnt(7)
	s_setprio 1
	s_barrier
	v_mfma_f32_16x16x32_bf16 v[124:127], v[150:153], v[166:169], v[124:127]
	v_mfma_f32_16x16x32_bf16 v[120:123], v[158:161], v[166:169], v[120:123]
	s_waitcnt lgkmcnt(5)
	v_mfma_f32_16x16x32_bf16 v[116:119], v[150:153], v[174:177], v[116:119]
	v_mfma_f32_16x16x32_bf16 v[112:115], v[158:161], v[174:177], v[112:115]
	s_waitcnt lgkmcnt(3)
	v_mfma_f32_16x16x32_bf16 v[100:103], v[150:153], v[182:185], v[100:103]
	v_mfma_f32_16x16x32_bf16 v[96:99], v[158:161], v[182:185], v[96:99]
	s_waitcnt lgkmcnt(1)
	v_mfma_f32_16x16x32_bf16 v[84:87], v[150:153], v[190:193], v[84:87]
	v_mfma_f32_16x16x32_bf16 v[80:83], v[158:161], v[190:193], v[80:83]
	v_mfma_f32_16x16x32_bf16 v[124:127], v[154:157], v[170:173], v[124:127]
	v_mfma_f32_16x16x32_bf16 v[120:123], v[162:165], v[170:173], v[120:123]
	v_mfma_f32_16x16x32_bf16 v[116:119], v[154:157], v[178:181], v[116:119]
	v_mfma_f32_16x16x32_bf16 v[112:115], v[162:165], v[178:181], v[112:115]
	v_mfma_f32_16x16x32_bf16 v[100:103], v[154:157], v[186:189], v[100:103]
	v_mfma_f32_16x16x32_bf16 v[96:99], v[162:165], v[186:189], v[96:99]
	s_waitcnt lgkmcnt(0)
	v_mfma_f32_16x16x32_bf16 v[84:87], v[154:157], v[198:201], v[84:87]
	v_mfma_f32_16x16x32_bf16 v[80:83], v[162:165], v[198:201], v[80:83]
	s_barrier
	s_setprio 0
	s_add_i32 s24, 0, 0x1c000
	s_add_i32 s25, s54, s29
	v_add_u32_e32 v196, s24, v146
	v_lshl_add_u64 v[194:195], v[194:195], 0, s[8:9]
	s_mov_b32 m0, s25
	ds_read_b128 v[202:205], v196
	ds_read_b128 v[206:209], v196 offset:1024
	ds_read_b128 v[210:213], v196 offset:2048
	ds_read_b128 v[214:217], v196 offset:3072
	global_load_lds_dwordx4 v[194:195], off
	v_lshl_add_u64 v[194:195], v[218:219], 0, s[8:9]
	s_add_i32 m0, s25, 0x2000
	s_nop 0
	global_load_lds_dwordx4 v[194:195], off
	s_waitcnt lgkmcnt(3)
	s_setprio 1
	s_barrier
	v_mfma_f32_16x16x32_bf16 v[108:111], v[202:205], v[166:169], v[108:111]
	s_waitcnt lgkmcnt(1)
	v_mfma_f32_16x16x32_bf16 v[104:107], v[210:213], v[166:169], v[104:107]
	v_mfma_f32_16x16x32_bf16 v[92:95], v[202:205], v[174:177], v[92:95]
	v_mfma_f32_16x16x32_bf16 v[88:91], v[210:213], v[174:177], v[88:91]
	v_mfma_f32_16x16x32_bf16 v[76:79], v[202:205], v[182:185], v[76:79]
	v_mfma_f32_16x16x32_bf16 v[72:75], v[210:213], v[182:185], v[72:75]
	v_mfma_f32_16x16x32_bf16 v[68:71], v[202:205], v[190:193], v[68:71]
	v_mfma_f32_16x16x32_bf16 v[64:67], v[210:213], v[190:193], v[64:67]
	v_mfma_f32_16x16x32_bf16 v[108:111], v[206:209], v[170:173], v[108:111]
	s_mov_b32 m0, s39
	s_waitcnt lgkmcnt(0)
	v_mfma_f32_16x16x32_bf16 v[104:107], v[214:217], v[170:173], v[104:107]
	v_lshl_add_u64 v[194:195], v[220:221], 0, s[8:9]
	v_mfma_f32_16x16x32_bf16 v[92:95], v[206:209], v[178:181], v[92:95]
	v_mfma_f32_16x16x32_bf16 v[88:91], v[214:217], v[178:181], v[88:91]
	v_mfma_f32_16x16x32_bf16 v[76:79], v[206:209], v[186:189], v[76:79]
	v_mfma_f32_16x16x32_bf16 v[72:75], v[214:217], v[186:189], v[72:75]
	v_mfma_f32_16x16x32_bf16 v[68:71], v[206:209], v[198:201], v[68:71]
	v_mfma_f32_16x16x32_bf16 v[64:67], v[214:217], v[198:201], v[64:67]
	s_barrier
	s_setprio 0
	ds_read_b128 v[166:169], v148 offset:49152
	ds_read_b128 v[170:173], v148 offset:50176
	ds_read_b128 v[174:177], v148 offset:51200
	ds_read_b128 v[178:181], v148 offset:52224
	ds_read_b128 v[182:185], v148 offset:53248
	ds_read_b128 v[186:189], v148 offset:54272
	ds_read_b128 v[190:193], v148 offset:55296
	ds_read_b128 v[198:201], v148 offset:56320
	global_load_lds_dwordx4 v[194:195], off
	v_lshl_add_u64 v[194:195], v[222:223], 0, s[8:9]
	s_mov_b32 m0, s42
	s_nop 0
	global_load_lds_dwordx4 v[194:195], off
	s_waitcnt vmcnt(10) lgkmcnt(7)
	s_setprio 1
	s_barrier
; #define PG8_STAGE(bufoff, gbase, voff) do { _Pragma("unroll") for (int _i = 0; _i < 2; ++_i) \
;         __builtin_amdgcn_global_load_lds((const unsigned*)((const char*)(gbase) + (voff)[_i]), (LAS unsigned*)(lds + (bufoff) + ldsw + _i * 8192), 16, 0, 0); } while (0)
; #define PG8_MMA(ai, bj, At, Bt) do { __builtin_amdgcn_s_setprio(1); _Pragma("unroll") for (int m = 0; m < 4; ++m) _Pragma("unroll") for (int n = 0; n < 2; ++n) _Pragma("unroll") for (int k = 0; k < 2; ++k) \
;         acc[ai][bj][m][n] = __builtin_amdgcn_mfma_f32_16x16x32_bf16(Bt[n][k], At[m][k], acc[ai][bj][m][n], 0, 0, 0); __builtin_amdgcn_s_setprio(0); } while (0)
; #define PG8_WAIT_V(n) asm volatile("s_waitcnt vmcnt(" #n ")" ::: "memory")
; #define PG8_WAIT_L(n) asm volatile("s_waitcnt lgkmcnt(" #n ")" ::: "memory")
; #define PG8_BAR __builtin_amdgcn_s_barrier()
; #define PG8_SCHED __builtin_amdgcn_sched_barrier(0)
; template <class Map, class Epi>
; DI void gemm_phase(LAS unsigned char* lds, const Map& MP, const Epi& E, const int nM, const int nN, const int K, const int lda, const int ldb) {
;     ...
;             PG8_BAR; PG8_WAIT_L(0); PG8_MMA(1, 0, At, B0); PG8_BAR; PG8_SCHED;
;             PG8_STAGE(PG8_SB(1, 1), b3 + hstepB, voffB);
;             PG8_WAIT_V(6); PG8_BAR; PG8_MMA(1, 1, At, B1); PG8_BAR;
;         }
	v_mfma_f32_16x16x32_bf16 v[60:63], v[150:153], v[166:169], v[60:63]
	v_mfma_f32_16x16x32_bf16 v[56:59], v[158:161], v[166:169], v[56:59]
	s_waitcnt lgkmcnt(5)
	v_mfma_f32_16x16x32_bf16 v[52:55], v[150:153], v[174:177], v[52:55]
	v_mfma_f32_16x16x32_bf16 v[48:51], v[158:161], v[174:177], v[48:51]
	s_waitcnt lgkmcnt(3)
	v_mfma_f32_16x16x32_bf16 v[36:39], v[150:153], v[182:185], v[36:39]
	v_mfma_f32_16x16x32_bf16 v[32:35], v[158:161], v[182:185], v[32:35]
	s_waitcnt lgkmcnt(1)
	v_mfma_f32_16x16x32_bf16 v[20:23], v[150:153], v[190:193], v[20:23]
	v_mfma_f32_16x16x32_bf16 v[16:19], v[158:161], v[190:193], v[16:19]
	v_mfma_f32_16x16x32_bf16 v[60:63], v[154:157], v[170:173], v[60:63]
	v_mfma_f32_16x16x32_bf16 v[56:59], v[162:165], v[170:173], v[56:59]
	v_mfma_f32_16x16x32_bf16 v[52:55], v[154:157], v[178:181], v[52:55]
	v_mfma_f32_16x16x32_bf16 v[48:51], v[162:165], v[178:181], v[48:51]
	v_mfma_f32_16x16x32_bf16 v[36:39], v[154:157], v[186:189], v[36:39]
	v_mfma_f32_16x16x32_bf16 v[32:35], v[162:165], v[186:189], v[32:35]
	s_waitcnt lgkmcnt(0)
	v_mfma_f32_16x16x32_bf16 v[20:23], v[154:157], v[198:201], v[20:23]
	v_mfma_f32_16x16x32_bf16 v[16:19], v[162:165], v[198:201], v[16:19]
	s_barrier
	s_setprio 0
	s_add_u32 s22, s22, 0x80080
	s_addc_u32 s23, s23, 0
	s_add_i32 s24, s24, s29
	s_mov_b32 m0, s24
	s_nop 0
	global_load_lds_dwordx4 v132, s[22:23]
	s_add_i32 m0, s24, 0x2000
	s_nop 0
	global_load_lds_dwordx4 v128, s[22:23]
	s_waitcnt vmcnt(6)
	s_setprio 1
	s_barrier
	v_mfma_f32_16x16x32_bf16 v[44:47], v[202:205], v[166:169], v[44:47]
	v_mfma_f32_16x16x32_bf16 v[40:43], v[210:213], v[166:169], v[40:43]
	ds_read_b128 v[150:153], v147
	v_mfma_f32_16x16x32_bf16 v[28:31], v[202:205], v[174:177], v[28:31]
	v_mfma_f32_16x16x32_bf16 v[24:27], v[210:213], v[174:177], v[24:27]
	ds_read_b128 v[154:157], v147 offset:1024
	v_mfma_f32_16x16x32_bf16 v[12:15], v[202:205], v[182:185], v[12:15]
	v_mfma_f32_16x16x32_bf16 v[8:11], v[210:213], v[182:185], v[8:11]
	ds_read_b128 v[158:161], v147 offset:2048
	v_mfma_f32_16x16x32_bf16 v[4:7], v[202:205], v[190:193], v[4:7]
	v_mfma_f32_16x16x32_bf16 v[0:3], v[210:213], v[190:193], v[0:3]
	ds_read_b128 v[162:165], v147 offset:3072
	v_mfma_f32_16x16x32_bf16 v[44:47], v[206:209], v[170:173], v[44:47]
	s_add_i32 s3, s3, 2
	v_mfma_f32_16x16x32_bf16 v[40:43], v[214:217], v[170:173], v[40:43]
	s_add_u32 s52, s52, 0x100
	s_addc_u32 s53, s53, 0
	v_mfma_f32_16x16x32_bf16 v[28:31], v[206:209], v[178:181], v[28:31]
	s_add_u32 s20, s20, 0x100
	s_addc_u32 s21, s21, 0
	v_mfma_f32_16x16x32_bf16 v[24:27], v[214:217], v[178:181], v[24:27]
	s_cmp_gt_u32 s3, 29
	v_mfma_f32_16x16x32_bf16 v[12:15], v[206:209], v[186:189], v[12:15]
	v_mfma_f32_16x16x32_bf16 v[8:11], v[214:217], v[186:189], v[8:11]
	v_mfma_f32_16x16x32_bf16 v[4:7], v[206:209], v[198:201], v[4:7]
	v_mfma_f32_16x16x32_bf16 v[0:3], v[214:217], v[198:201], v[0:3]
	s_barrier
	s_setprio 0
	s_cbranch_scc0 .LBB1_1382
; DI unsigned pack2(float a, float b) { f32x2 v = {a, b}; hwbf16x2 r = __builtin_convertvector(v, hwbf16x2); return __builtin_bit_cast(unsigned, r); }
;     DI void operator()(const f32x4 (&acc)[2][2][4][2], const Unit& u, int wr, int wc, int fr, int fq) const {
;         bf16_t* O = O1; int ldc = ldc1, pn = u.pn; if (pn >= split) { O = O2; ldc = ldc2; pn -= split; }
;         const int row0 = u.pm * BM + wr * 64 + fr, col0 = pn * BM + wc * 32 + 8 * fq;
; #pragma unroll
;         for (int ai = 0; ai < 2; ++ai)
; #pragma unroll
;             for (int m = 0; m < 4; ++m) { bf16_t* rowp = O + (size_t)(row0 + ai * HALF + m * 16) * ldc + col0;
; #pragma unroll
;                 for (int bj = 0; bj < 2; ++bj) { const f32x4 v0 = acc[ai][bj][m][0], v1 = acc[ai][bj][m][1];
;                     u32x4 o; o[0] = pack2(v0[0], v0[1]); o[1] = pack2(v0[2], v0[3]); o[2] = pack2(v1[0], v1[1]); o[3] = pack2(v1[2], v1[3]);
;                     *(u32x4*)(rowp + bj * HALF) = o; } }
;     }
	s_waitcnt lgkmcnt(0)
	s_lshl_b32 s3, s10, 8
	v_mov_b32_e32 v150, v144
	v_mov_b32_e32 v151, v145
	s_add_i32 s3, s3, s37
	v_cvt_pk_bf16_f32 v68, v68, v69
	v_add_u32_e32 v154, s3, v150
	s_lshl_b32 s3, s47, 8
	s_or_b32 s3, s3, s38
	v_lshl_add_u32 v150, v151, 3, s3
	v_ashrrev_i32_e32 v151, 31, v150
	v_lshl_add_u64 v[150:151], v[150:151], 1, s[6:7]
	v_cvt_pk_bf16_f32 v69, v70, v71
	v_cvt_pk_bf16_f32 v70, v64, v65
	v_add_u32_e32 v64, 0x80, v154
	v_mad_i64_i32 v[152:153], s[20:21], v154, s46, v[150:151]
	v_cvt_pk_bf16_f32 v108, v108, v109
	v_cvt_pk_bf16_f32 v109, v110, v111
	v_cvt_pk_bf16_f32 v110, v104, v105
	v_cvt_pk_bf16_f32 v111, v106, v107
	v_add_u32_e32 v104, 16, v154
	v_mad_i64_i32 v[64:65], s[20:21], v64, s46, v[150:151]
	v_cvt_pk_bf16_f32 v44, v44, v45
	v_cvt_pk_bf16_f32 v45, v46, v47
	v_cvt_pk_bf16_f32 v46, v40, v41
	v_cvt_pk_bf16_f32 v47, v42, v43
	v_add_u32_e32 v40, 0x90, v154
	global_store_dwordx4 v[152:153], v[108:111], off offset:256
	v_cvt_pk_bf16_f32 v92, v92, v93
	v_cvt_pk_bf16_f32 v93, v94, v95
	v_mad_i64_i32 v[108:109], s[20:21], v104, s46, v[150:151]
	v_cvt_pk_bf16_f32 v94, v88, v89
	v_cvt_pk_bf16_f32 v95, v90, v91
	v_add_u32_e32 v88, 32, v154
	global_store_dwordx4 v[64:65], v[44:47], off offset:256
	v_cvt_pk_bf16_f32 v28, v28, v29
	v_cvt_pk_bf16_f32 v29, v30, v31
	v_mad_i64_i32 v[44:45], s[20:21], v40, s46, v[150:151]
	v_cvt_pk_bf16_f32 v30, v24, v25
	v_cvt_pk_bf16_f32 v31, v26, v27
	v_add_u32_e32 v24, 0xa0, v154
	global_store_dwordx4 v[108:109], v[92:95], off offset:256
	v_cvt_pk_bf16_f32 v76, v76, v77
	v_cvt_pk_bf16_f32 v77, v78, v79
	v_mad_i64_i32 v[92:93], s[20:21], v88, s46, v[150:151]
	v_cvt_pk_bf16_f32 v78, v72, v73
	v_cvt_pk_bf16_f32 v79, v74, v75
	v_add_u32_e32 v72, 48, v154
	global_store_dwordx4 v[44:45], v[28:31], off offset:256
	v_cvt_pk_bf16_f32 v12, v12, v13
	v_cvt_pk_bf16_f32 v13, v14, v15
	v_mad_i64_i32 v[28:29], s[20:21], v24, s46, v[150:151]
	v_cvt_pk_bf16_f32 v14, v8, v9
	v_cvt_pk_bf16_f32 v15, v10, v11
	v_add_u32_e32 v8, 0xb0, v154
	global_store_dwordx4 v[92:93], v[76:79], off offset:256
	global_store_dwordx4 v[28:29], v[12:15], off offset:256
	v_cvt_pk_bf16_f32 v124, v124, v125
	v_mad_i64_i32 v[76:77], s[20:21], v72, s46, v[150:151]
	v_mad_i64_i32 v[12:13], s[20:21], v8, s46, v[150:151]
	v_cvt_pk_bf16_f32 v125, v126, v127
	v_cvt_pk_bf16_f32 v126, v120, v121
	v_cvt_pk_bf16_f32 v127, v122, v123
	v_cvt_pk_bf16_f32 v104, v116, v117
	v_cvt_pk_bf16_f32 v105, v118, v119
	v_cvt_pk_bf16_f32 v106, v112, v113
	v_cvt_pk_bf16_f32 v107, v114, v115
	v_cvt_pk_bf16_f32 v88, v100, v101
	v_cvt_pk_bf16_f32 v89, v102, v103
	v_cvt_pk_bf16_f32 v90, v96, v97
	v_cvt_pk_bf16_f32 v91, v98, v99
	v_cvt_pk_bf16_f32 v72, v84, v85
	v_cvt_pk_bf16_f32 v73, v86, v87
	v_cvt_pk_bf16_f32 v74, v80, v81
	v_cvt_pk_bf16_f32 v75, v82, v83
	v_cvt_pk_bf16_f32 v71, v66, v67
	v_cvt_pk_bf16_f32 v60, v60, v61
	v_cvt_pk_bf16_f32 v61, v62, v63
	v_cvt_pk_bf16_f32 v62, v56, v57
	v_cvt_pk_bf16_f32 v63, v58, v59
	v_cvt_pk_bf16_f32 v40, v52, v53
	v_cvt_pk_bf16_f32 v41, v54, v55
	v_cvt_pk_bf16_f32 v42, v48, v49
	v_cvt_pk_bf16_f32 v43, v50, v51
	v_cvt_pk_bf16_f32 v24, v36, v37
	v_cvt_pk_bf16_f32 v25, v38, v39
	v_cvt_pk_bf16_f32 v26, v32, v33
	v_cvt_pk_bf16_f32 v27, v34, v35
	v_cvt_pk_bf16_f32 v8, v20, v21
	v_cvt_pk_bf16_f32 v9, v22, v23
	v_cvt_pk_bf16_f32 v10, v16, v17
	v_cvt_pk_bf16_f32 v11, v18, v19
	v_cvt_pk_bf16_f32 v4, v4, v5
	v_cvt_pk_bf16_f32 v5, v6, v7
	v_cvt_pk_bf16_f32 v6, v0, v1
	v_cvt_pk_bf16_f32 v7, v2, v3
	s_and_b64 vcc, exec, s[40:41]
	s_mov_b32 s47, s12
	s_mov_b32 s10, s14
	s_mov_b64 s[20:21], s[18:19]
	s_mov_b64 s[22:23], s[16:17]
	global_store_dwordx4 v[152:153], v[124:127], off
	global_store_dwordx4 v[108:109], v[104:107], off
	global_store_dwordx4 v[92:93], v[88:91], off
	global_store_dwordx4 v[76:77], v[72:75], off
	global_store_dwordx4 v[76:77], v[68:71], off offset:256
	global_store_dwordx4 v[64:65], v[60:63], off
	global_store_dwordx4 v[44:45], v[40:43], off
	global_store_dwordx4 v[28:29], v[24:27], off
	global_store_dwordx4 v[12:13], v[8:11], off
	global_store_dwordx4 v[12:13], v[4:7], off offset:256
	s_cbranch_vccz .LBB1_1379
	s_waitcnt vmcnt(0)
	s_cmpk_gt_u32 s4, 0xff
	s_cbranch_scc1 .LBB1_1386
	s_barrier

; #define PG8_STAGE(bufoff, gbase, voff) do { _Pragma("unroll") for (int _i = 0; _i < 2; ++_i) \
;         __builtin_amdgcn_global_load_lds((const unsigned*)((const char*)(gbase) + (voff)[_i]), (LAS unsigned*)(lds + (bufoff) + ldsw + _i * 8192), 16, 0, 0); } while (0)
; #define PG8_LDA(dst, b, h) do { _Pragma("unroll") for (int m = 0; m < 4; ++m) _Pragma("unroll") for (int k = 0; k < 2; ++k) dst[m][k] = *(const LAS bf16x8*)(lds + PG8_SA(b, h) + aoff + m * 2048 + k * 1024); } while (0)
; #define PG8_LDB(dst, b, h) do { _Pragma("unroll") for (int n = 0; n < 2; ++n) _Pragma("unroll") for (int k = 0; k < 2; ++k) dst[n][k] = *(const LAS bf16x8*)(lds + PG8_SB(b, h) + boff + n * 2048 + k * 1024); } while (0)
; #define PG8_MMA(ai, bj, At, Bt) do { __builtin_amdgcn_s_setprio(1); _Pragma("unroll") for (int m = 0; m < 4; ++m) _Pragma("unroll") for (int n = 0; n < 2; ++n) _Pragma("unroll") for (int k = 0; k < 2; ++k) \
;         acc[ai][bj][m][n] = __builtin_amdgcn_mfma_f32_16x16x32_bf16(Bt[n][k], At[m][k], acc[ai][bj][m][n], 0, 0, 0); __builtin_amdgcn_s_setprio(0); } while (0)
; #define PG8_WAIT_V(n) asm volatile("s_waitcnt vmcnt(" #n ")" ::: "memory")
; #define PG8_WAIT_L(n) asm volatile("s_waitcnt lgkmcnt(" #n ")" ::: "memory")
; #define PG8_BAR __builtin_amdgcn_s_barrier()
; #define PG8_SCHED __builtin_amdgcn_sched_barrier(0)
; template <class Map, class Epi>
; DI void gemm_phase(LAS unsigned char* lds, const Map& MP, const Epi& E, const int nM, const int nN, const int K, const int lda, const int ldb) {
;     ...
;             PG8_LDB(B0, 0, 0); PG8_SCHED; PG8_LDA(At, 0, 0); PG8_STAGE(PG8_SA(1, 1), a1 + hstepA, voffA);
;             PG8_WAIT_L(8); PG8_BAR; PG8_WAIT_L(0); PG8_MMA(0, 0, At, B0); PG8_BAR; PG8_SCHED;
;             PG8_LDB(B1, 0, 1); PG8_STAGE(PG8_SB(0, 0), b2, voffB);
;             PG8_BAR; PG8_WAIT_L(0); PG8_MMA(0, 1, At, B1); PG8_BAR;
;             PG8_LDA(At, 0, 1); PG8_STAGE(PG8_SA(0, 0), a2, voffA);
;             PG8_BAR; PG8_WAIT_L(0); PG8_MMA(1, 0, At, B0); PG8_BAR; PG8_SCHED;
;             PG8_STAGE(PG8_SB(0, 1), b2 + hstepB, voffB);
;             PG8_WAIT_V(6); PG8_BAR; PG8_MMA(1, 1, At, B1); PG8_BAR;
.LBB1_1529:
	s_add_u32 s20, s18, 0xfffe0080
	s_addc_u32 s21, s19, -1
	s_cmp_eq_u32 s3, 4
	s_cselect_b32 s23, s13, s21
	s_cselect_b32 s22, s52, s20
	s_cselect_b32 s21, s53, s56
	s_cselect_b32 s20, s54, s55
	s_add_i32 m0, s11, 0xc000
	ds_read_b128 v[166:169], v148
	ds_read_b128 v[170:173], v148 offset:1024
	ds_read_b128 v[174:177], v148 offset:2048
	ds_read_b128 v[178:181], v148 offset:3072
	ds_read_b128 v[182:185], v148 offset:4096
	ds_read_b128 v[186:189], v148 offset:5120
	ds_read_b128 v[190:193], v148 offset:6144
	ds_read_b128 v[198:201], v148 offset:7168
	global_load_lds_dwordx4 v138, s[18:19]
	s_add_i32 m0, s11, 0xe000
	s_nop 0
	global_load_lds_dwordx4 v136, s[18:19]
	s_waitcnt lgkmcnt(7)
	s_setprio 1
	s_barrier
	v_mfma_f32_16x16x32_bf16 v[124:127], v[150:153], v[166:169], v[124:127]
	v_mfma_f32_16x16x32_bf16 v[120:123], v[158:161], v[166:169], v[120:123]
	s_waitcnt lgkmcnt(5)
	v_mfma_f32_16x16x32_bf16 v[116:119], v[150:153], v[174:177], v[116:119]
	v_mfma_f32_16x16x32_bf16 v[112:115], v[158:161], v[174:177], v[112:115]
	s_waitcnt lgkmcnt(3)
	v_mfma_f32_16x16x32_bf16 v[100:103], v[150:153], v[182:185], v[100:103]
	v_mfma_f32_16x16x32_bf16 v[96:99], v[158:161], v[182:185], v[96:99]
	s_waitcnt lgkmcnt(1)
	v_mfma_f32_16x16x32_bf16 v[84:87], v[150:153], v[190:193], v[84:87]
	v_mfma_f32_16x16x32_bf16 v[80:83], v[158:161], v[190:193], v[80:83]
	v_mfma_f32_16x16x32_bf16 v[124:127], v[154:157], v[170:173], v[124:127]
	v_mfma_f32_16x16x32_bf16 v[120:123], v[162:165], v[170:173], v[120:123]
	v_mfma_f32_16x16x32_bf16 v[116:119], v[154:157], v[178:181], v[116:119]
	v_mfma_f32_16x16x32_bf16 v[112:115], v[162:165], v[178:181], v[112:115]
	v_mfma_f32_16x16x32_bf16 v[100:103], v[154:157], v[186:189], v[100:103]
	v_mfma_f32_16x16x32_bf16 v[96:99], v[162:165], v[186:189], v[96:99]
	s_waitcnt lgkmcnt(0)
	v_mfma_f32_16x16x32_bf16 v[84:87], v[154:157], v[198:201], v[84:87]
	v_mfma_f32_16x16x32_bf16 v[80:83], v[162:165], v[198:201], v[80:83]
	s_barrier
	s_setprio 0
	s_add_i32 s57, s47, s31
	v_lshl_add_u64 v[194:195], s[20:21], 0, v[132:133]
	s_mov_b32 m0, s57
	ds_read_b128 v[202:205], v149
	ds_read_b128 v[206:209], v149 offset:1024
	ds_read_b128 v[210:213], v149 offset:2048
	ds_read_b128 v[214:217], v149 offset:3072
	global_load_lds_dwordx4 v[194:195], off
	v_lshl_add_u64 v[218:219], s[20:21], 0, v[128:129]
	s_add_i32 m0, s57, 0x2000
	s_nop 0
	global_load_lds_dwordx4 v[218:219], off
	s_waitcnt lgkmcnt(3)
	s_setprio 1
	s_barrier
	v_mfma_f32_16x16x32_bf16 v[108:111], v[202:205], v[166:169], v[108:111]
	s_waitcnt lgkmcnt(1)
	v_mfma_f32_16x16x32_bf16 v[104:107], v[210:213], v[166:169], v[104:107]
	v_mfma_f32_16x16x32_bf16 v[92:95], v[202:205], v[174:177], v[92:95]
	v_mfma_f32_16x16x32_bf16 v[88:91], v[210:213], v[174:177], v[88:91]
	v_mfma_f32_16x16x32_bf16 v[76:79], v[202:205], v[182:185], v[76:79]
	v_mfma_f32_16x16x32_bf16 v[72:75], v[210:213], v[182:185], v[72:75]
	v_mfma_f32_16x16x32_bf16 v[68:71], v[202:205], v[190:193], v[68:71]
	v_mfma_f32_16x16x32_bf16 v[64:67], v[210:213], v[190:193], v[64:67]
	v_mfma_f32_16x16x32_bf16 v[108:111], v[206:209], v[170:173], v[108:111]
	s_mov_b32 m0, s11
	s_waitcnt lgkmcnt(0)
	v_mfma_f32_16x16x32_bf16 v[104:107], v[214:217], v[170:173], v[104:107]
	v_lshl_add_u64 v[220:221], s[22:23], 0, v[134:135]
	v_mfma_f32_16x16x32_bf16 v[92:95], v[206:209], v[178:181], v[92:95]
	v_mfma_f32_16x16x32_bf16 v[88:91], v[214:217], v[178:181], v[88:91]
	v_mfma_f32_16x16x32_bf16 v[76:79], v[206:209], v[186:189], v[76:79]
	v_mfma_f32_16x16x32_bf16 v[72:75], v[214:217], v[186:189], v[72:75]
	v_mfma_f32_16x16x32_bf16 v[68:71], v[206:209], v[198:201], v[68:71]
	v_mfma_f32_16x16x32_bf16 v[64:67], v[214:217], v[198:201], v[64:67]
	s_barrier
	s_setprio 0
	ds_read_b128 v[166:169], v148 offset:16384
	ds_read_b128 v[170:173], v148 offset:17408
	ds_read_b128 v[174:177], v148 offset:18432
	ds_read_b128 v[178:181], v148 offset:19456
	ds_read_b128 v[182:185], v148 offset:20480
	ds_read_b128 v[186:189], v148 offset:21504
	ds_read_b128 v[190:193], v148 offset:22528
	ds_read_b128 v[198:201], v148 offset:23552
	global_load_lds_dwordx4 v[220:221], off
	v_lshl_add_u64 v[222:223], s[22:23], 0, v[130:131]
	s_mov_b32 m0, s35
	s_nop 0
	global_load_lds_dwordx4 v[222:223], off
	s_waitcnt vmcnt(10) lgkmcnt(7)
	s_setprio 1
	s_barrier
	v_mfma_f32_16x16x32_bf16 v[60:63], v[150:153], v[166:169], v[60:63]
	v_mfma_f32_16x16x32_bf16 v[56:59], v[158:161], v[166:169], v[56:59]
	s_waitcnt lgkmcnt(5)
	v_mfma_f32_16x16x32_bf16 v[52:55], v[150:153], v[174:177], v[52:55]
	v_mfma_f32_16x16x32_bf16 v[48:51], v[158:161], v[174:177], v[48:51]
	s_waitcnt lgkmcnt(3)
	v_mfma_f32_16x16x32_bf16 v[36:39], v[150:153], v[182:185], v[36:39]
	v_mfma_f32_16x16x32_bf16 v[32:35], v[158:161], v[182:185], v[32:35]
	s_waitcnt lgkmcnt(1)
	v_mfma_f32_16x16x32_bf16 v[20:23], v[150:153], v[190:193], v[20:23]
	v_mfma_f32_16x16x32_bf16 v[16:19], v[158:161], v[190:193], v[16:19]
	v_mfma_f32_16x16x32_bf16 v[60:63], v[154:157], v[170:173], v[60:63]
	v_mfma_f32_16x16x32_bf16 v[56:59], v[162:165], v[170:173], v[56:59]
	v_mfma_f32_16x16x32_bf16 v[52:55], v[154:157], v[178:181], v[52:55]
	v_mfma_f32_16x16x32_bf16 v[48:51], v[162:165], v[178:181], v[48:51]
	v_mfma_f32_16x16x32_bf16 v[36:39], v[154:157], v[186:189], v[36:39]
	v_mfma_f32_16x16x32_bf16 v[32:35], v[162:165], v[186:189], v[32:35]
	s_waitcnt lgkmcnt(0)
	v_mfma_f32_16x16x32_bf16 v[20:23], v[154:157], v[198:201], v[20:23]
	v_mfma_f32_16x16x32_bf16 v[16:19], v[162:165], v[198:201], v[16:19]
	s_barrier
	s_setprio 0
	s_add_u32 s58, s20, 0x20000
	s_addc_u32 s59, s21, 0
	s_add_i32 s57, s48, s31
	s_mov_b32 m0, s57
	s_nop 0
	global_load_lds_dwordx4 v132, s[58:59]
	s_add_i32 m0, s57, 0x2000
	s_nop 0
	global_load_lds_dwordx4 v128, s[58:59]
	s_waitcnt vmcnt(6)
	s_setprio 1
	s_barrier
; #define PG8_STAGE(bufoff, gbase, voff) do { _Pragma("unroll") for (int _i = 0; _i < 2; ++_i) \
;         __builtin_amdgcn_global_load_lds((const unsigned*)((const char*)(gbase) + (voff)[_i]), (LAS unsigned*)(lds + (bufoff) + ldsw + _i * 8192), 16, 0, 0); } while (0)
; #define PG8_LDA(dst, b, h) do { _Pragma("unroll") for (int m = 0; m < 4; ++m) _Pragma("unroll") for (int k = 0; k < 2; ++k) dst[m][k] = *(const LAS bf16x8*)(lds + PG8_SA(b, h) + aoff + m * 2048 + k * 1024); } while (0)
; #define PG8_LDB(dst, b, h) do { _Pragma("unroll") for (int n = 0; n < 2; ++n) _Pragma("unroll") for (int k = 0; k < 2; ++k) dst[n][k] = *(const LAS bf16x8*)(lds + PG8_SB(b, h) + boff + n * 2048 + k * 1024); } while (0)
; #define PG8_MMA(ai, bj, At, Bt) do { __builtin_amdgcn_s_setprio(1); _Pragma("unroll") for (int m = 0; m < 4; ++m) _Pragma("unroll") for (int n = 0; n < 2; ++n) _Pragma("unroll") for (int k = 0; k < 2; ++k) \
;         acc[ai][bj][m][n] = __builtin_amdgcn_mfma_f32_16x16x32_bf16(Bt[n][k], At[m][k], acc[ai][bj][m][n], 0, 0, 0); __builtin_amdgcn_s_setprio(0); } while (0)
; #define PG8_WAIT_V(n) asm volatile("s_waitcnt vmcnt(" #n ")" ::: "memory")
; #define PG8_WAIT_L(n) asm volatile("s_waitcnt lgkmcnt(" #n ")" ::: "memory")
; #define PG8_BAR __builtin_amdgcn_s_barrier()
; #define PG8_SCHED __builtin_amdgcn_sched_barrier(0)
; template <class Map, class Epi>
; DI void gemm_phase(LAS unsigned char* lds, const Map& MP, const Epi& E, const int nM, const int nN, const int K, const int lda, const int ldb) {
;     ...
;             PG8_WAIT_V(6); PG8_BAR; PG8_MMA(1, 1, At, B1); PG8_BAR;
;             PG8_LDB(B0, 1, 0); PG8_SCHED; PG8_LDA(At, 1, 0); PG8_STAGE(PG8_SA(0, 1), a2 + hstepA, voffA);
;             PG8_WAIT_L(8); PG8_BAR; PG8_WAIT_L(0); PG8_MMA(0, 0, At, B0); PG8_BAR; PG8_SCHED;
;             PG8_LDB(B1, 1, 1); PG8_STAGE(PG8_SB(1, 0), b3, voffB);
;             PG8_BAR; PG8_WAIT_L(0); PG8_MMA(0, 1, At, B1); PG8_BAR;
;             PG8_LDA(At, 1, 1); PG8_STAGE(PG8_SA(1, 0), a3, voffA);
;             PG8_BAR; PG8_WAIT_L(0); PG8_MMA(1, 0, At, B0); PG8_BAR; PG8_SCHED;
	v_mfma_f32_16x16x32_bf16 v[44:47], v[202:205], v[166:169], v[44:47]
	v_mfma_f32_16x16x32_bf16 v[40:43], v[210:213], v[166:169], v[40:43]
	s_add_i32 s57, 0, 0x18000
	v_add_u32_e32 v162, s57, v146
	ds_read_b128 v[150:153], v162
	v_mfma_f32_16x16x32_bf16 v[28:31], v[202:205], v[174:177], v[28:31]
	v_mfma_f32_16x16x32_bf16 v[24:27], v[210:213], v[174:177], v[24:27]
	ds_read_b128 v[154:157], v162 offset:1024
	v_mfma_f32_16x16x32_bf16 v[12:15], v[202:205], v[182:185], v[12:15]
	v_mfma_f32_16x16x32_bf16 v[8:11], v[210:213], v[182:185], v[8:11]
	ds_read_b128 v[158:161], v162 offset:2048
	v_mfma_f32_16x16x32_bf16 v[4:7], v[202:205], v[190:193], v[4:7]
	v_mfma_f32_16x16x32_bf16 v[0:3], v[210:213], v[190:193], v[0:3]
	ds_read_b128 v[162:165], v162 offset:3072
	v_mfma_f32_16x16x32_bf16 v[44:47], v[206:209], v[170:173], v[44:47]
	v_mfma_f32_16x16x32_bf16 v[40:43], v[214:217], v[170:173], v[40:43]
	v_mfma_f32_16x16x32_bf16 v[28:31], v[206:209], v[178:181], v[28:31]
	v_mfma_f32_16x16x32_bf16 v[24:27], v[214:217], v[178:181], v[24:27]
	v_mfma_f32_16x16x32_bf16 v[12:15], v[206:209], v[186:189], v[12:15]
	v_mfma_f32_16x16x32_bf16 v[8:11], v[214:217], v[186:189], v[8:11]
	v_mfma_f32_16x16x32_bf16 v[4:7], v[206:209], v[198:201], v[4:7]
	v_mfma_f32_16x16x32_bf16 v[0:3], v[214:217], v[198:201], v[0:3]
	s_barrier
	s_setprio 0
	s_add_u32 s22, s22, 0x20000
	s_addc_u32 s23, s23, 0
	s_mov_b32 m0, s36
	ds_read_b128 v[166:169], v148 offset:32768
	ds_read_b128 v[170:173], v148 offset:33792
	ds_read_b128 v[174:177], v148 offset:34816
	ds_read_b128 v[178:181], v148 offset:35840
	ds_read_b128 v[182:185], v148 offset:36864
	ds_read_b128 v[186:189], v148 offset:37888
	ds_read_b128 v[190:193], v148 offset:38912
	ds_read_b128 v[198:201], v148 offset:39936
	global_load_lds_dwordx4 v134, s[22:23]
	s_mov_b32 m0, s37
	s_nop 0
	global_load_lds_dwordx4 v130, s[22:23]
	s_waitcnt lgkmcnt(7)
	s_setprio 1
	s_barrier
	v_mfma_f32_16x16x32_bf16 v[124:127], v[150:153], v[166:169], v[124:127]
	v_mfma_f32_16x16x32_bf16 v[120:123], v[158:161], v[166:169], v[120:123]
	s_waitcnt lgkmcnt(5)
	v_mfma_f32_16x16x32_bf16 v[116:119], v[150:153], v[174:177], v[116:119]
	v_mfma_f32_16x16x32_bf16 v[112:115], v[158:161], v[174:177], v[112:115]
	s_waitcnt lgkmcnt(3)
	v_mfma_f32_16x16x32_bf16 v[100:103], v[150:153], v[182:185], v[100:103]
	v_mfma_f32_16x16x32_bf16 v[96:99], v[158:161], v[182:185], v[96:99]
	s_waitcnt lgkmcnt(1)
	v_mfma_f32_16x16x32_bf16 v[84:87], v[150:153], v[190:193], v[84:87]
	v_mfma_f32_16x16x32_bf16 v[80:83], v[158:161], v[190:193], v[80:83]
	v_mfma_f32_16x16x32_bf16 v[124:127], v[154:157], v[170:173], v[124:127]
	v_mfma_f32_16x16x32_bf16 v[120:123], v[162:165], v[170:173], v[120:123]
	v_mfma_f32_16x16x32_bf16 v[116:119], v[154:157], v[178:181], v[116:119]
	v_mfma_f32_16x16x32_bf16 v[112:115], v[162:165], v[178:181], v[112:115]
	v_mfma_f32_16x16x32_bf16 v[100:103], v[154:157], v[186:189], v[100:103]
	v_mfma_f32_16x16x32_bf16 v[96:99], v[162:165], v[186:189], v[96:99]
	s_waitcnt lgkmcnt(0)
	v_mfma_f32_16x16x32_bf16 v[84:87], v[154:157], v[198:201], v[84:87]
	v_mfma_f32_16x16x32_bf16 v[80:83], v[162:165], v[198:201], v[80:83]
	s_barrier
	s_setprio 0
	s_add_i32 s22, 0, 0x1c000
	s_add_i32 s23, s57, s31
	v_add_u32_e32 v196, s22, v146
	v_lshl_add_u64 v[194:195], v[194:195], 0, s[8:9]
	s_mov_b32 m0, s23
	ds_read_b128 v[202:205], v196
	ds_read_b128 v[206:209], v196 offset:1024
	ds_read_b128 v[210:213], v196 offset:2048
	ds_read_b128 v[214:217], v196 offset:3072
	global_load_lds_dwordx4 v[194:195], off
	v_lshl_add_u64 v[194:195], v[218:219], 0, s[8:9]
	s_add_i32 m0, s23, 0x2000
	s_nop 0
	global_load_lds_dwordx4 v[194:195], off
	s_waitcnt lgkmcnt(3)
	s_setprio 1
	s_barrier
	v_mfma_f32_16x16x32_bf16 v[108:111], v[202:205], v[166:169], v[108:111]
	s_waitcnt lgkmcnt(1)
	v_mfma_f32_16x16x32_bf16 v[104:107], v[210:213], v[166:169], v[104:107]
	v_mfma_f32_16x16x32_bf16 v[92:95], v[202:205], v[174:177], v[92:95]
	v_mfma_f32_16x16x32_bf16 v[88:91], v[210:213], v[174:177], v[88:91]
	v_mfma_f32_16x16x32_bf16 v[76:79], v[202:205], v[182:185], v[76:79]
	v_mfma_f32_16x16x32_bf16 v[72:75], v[210:213], v[182:185], v[72:75]
	v_mfma_f32_16x16x32_bf16 v[68:71], v[202:205], v[190:193], v[68:71]
	v_mfma_f32_16x16x32_bf16 v[64:67], v[210:213], v[190:193], v[64:67]
	v_mfma_f32_16x16x32_bf16 v[108:111], v[206:209], v[170:173], v[108:111]
	s_mov_b32 m0, s43
	s_waitcnt lgkmcnt(0)
	v_mfma_f32_16x16x32_bf16 v[104:107], v[214:217], v[170:173], v[104:107]
	v_lshl_add_u64 v[194:195], v[220:221], 0, s[8:9]
	v_mfma_f32_16x16x32_bf16 v[92:95], v[206:209], v[178:181], v[92:95]
	v_mfma_f32_16x16x32_bf16 v[88:91], v[214:217], v[178:181], v[88:91]
	v_mfma_f32_16x16x32_bf16 v[76:79], v[206:209], v[186:189], v[76:79]
	v_mfma_f32_16x16x32_bf16 v[72:75], v[214:217], v[186:189], v[72:75]
	v_mfma_f32_16x16x32_bf16 v[68:71], v[206:209], v[198:201], v[68:71]
	v_mfma_f32_16x16x32_bf16 v[64:67], v[214:217], v[198:201], v[64:67]
	s_barrier
	s_setprio 0
	ds_read_b128 v[166:169], v148 offset:49152
	ds_read_b128 v[170:173], v148 offset:50176
	ds_read_b128 v[174:177], v148 offset:51200
	ds_read_b128 v[178:181], v148 offset:52224
	ds_read_b128 v[182:185], v148 offset:53248
	ds_read_b128 v[186:189], v148 offset:54272
	ds_read_b128 v[190:193], v148 offset:55296
	ds_read_b128 v[198:201], v148 offset:56320
	global_load_lds_dwordx4 v[194:195], off
	v_lshl_add_u64 v[194:195], v[222:223], 0, s[8:9]
	s_mov_b32 m0, s44
	s_nop 0
	global_load_lds_dwordx4 v[194:195], off
	s_waitcnt vmcnt(10) lgkmcnt(7)
	s_setprio 1
	s_barrier
; #define PG8_STAGE(bufoff, gbase, voff) do { _Pragma("unroll") for (int _i = 0; _i < 2; ++_i) \
;         __builtin_amdgcn_global_load_lds((const unsigned*)((const char*)(gbase) + (voff)[_i]), (LAS unsigned*)(lds + (bufoff) + ldsw + _i * 8192), 16, 0, 0); } while (0)
; #define PG8_MMA(ai, bj, At, Bt) do { __builtin_amdgcn_s_setprio(1); _Pragma("unroll") for (int m = 0; m < 4; ++m) _Pragma("unroll") for (int n = 0; n < 2; ++n) _Pragma("unroll") for (int k = 0; k < 2; ++k) \
;         acc[ai][bj][m][n] = __builtin_amdgcn_mfma_f32_16x16x32_bf16(Bt[n][k], At[m][k], acc[ai][bj][m][n], 0, 0, 0); __builtin_amdgcn_s_setprio(0); } while (0)
; #define PG8_WAIT_V(n) asm volatile("s_waitcnt vmcnt(" #n ")" ::: "memory")
; #define PG8_WAIT_L(n) asm volatile("s_waitcnt lgkmcnt(" #n ")" ::: "memory")
; #define PG8_BAR __builtin_amdgcn_s_barrier()
; #define PG8_SCHED __builtin_amdgcn_sched_barrier(0)
; template <class Map, class Epi>
; DI void gemm_phase(LAS unsigned char* lds, const Map& MP, const Epi& E, const int nM, const int nN, const int K, const int lda, const int ldb) {
;     ...
;             PG8_BAR; PG8_WAIT_L(0); PG8_MMA(1, 0, At, B0); PG8_BAR; PG8_SCHED;
;             PG8_STAGE(PG8_SB(1, 1), b3 + hstepB, voffB);
;             PG8_WAIT_V(6); PG8_BAR; PG8_MMA(1, 1, At, B1); PG8_BAR;
;         }
	v_mfma_f32_16x16x32_bf16 v[60:63], v[150:153], v[166:169], v[60:63]
	v_mfma_f32_16x16x32_bf16 v[56:59], v[158:161], v[166:169], v[56:59]
	s_waitcnt lgkmcnt(5)
	v_mfma_f32_16x16x32_bf16 v[52:55], v[150:153], v[174:177], v[52:55]
	v_mfma_f32_16x16x32_bf16 v[48:51], v[158:161], v[174:177], v[48:51]
	s_waitcnt lgkmcnt(3)
	v_mfma_f32_16x16x32_bf16 v[36:39], v[150:153], v[182:185], v[36:39]
	v_mfma_f32_16x16x32_bf16 v[32:35], v[158:161], v[182:185], v[32:35]
	s_waitcnt lgkmcnt(1)
	v_mfma_f32_16x16x32_bf16 v[20:23], v[150:153], v[190:193], v[20:23]
	v_mfma_f32_16x16x32_bf16 v[16:19], v[158:161], v[190:193], v[16:19]
	v_mfma_f32_16x16x32_bf16 v[60:63], v[154:157], v[170:173], v[60:63]
	v_mfma_f32_16x16x32_bf16 v[56:59], v[162:165], v[170:173], v[56:59]
	v_mfma_f32_16x16x32_bf16 v[52:55], v[154:157], v[178:181], v[52:55]
	v_mfma_f32_16x16x32_bf16 v[48:51], v[162:165], v[178:181], v[48:51]
	v_mfma_f32_16x16x32_bf16 v[36:39], v[154:157], v[186:189], v[36:39]
	v_mfma_f32_16x16x32_bf16 v[32:35], v[162:165], v[186:189], v[32:35]
	s_waitcnt lgkmcnt(0)
	v_mfma_f32_16x16x32_bf16 v[20:23], v[154:157], v[198:201], v[20:23]
	v_mfma_f32_16x16x32_bf16 v[16:19], v[162:165], v[198:201], v[16:19]
	s_barrier
	s_setprio 0
	s_add_u32 s20, s20, 0x20080
	s_addc_u32 s21, s21, 0
	s_add_i32 s22, s22, s31
	s_mov_b32 m0, s22
	s_nop 0
	global_load_lds_dwordx4 v132, s[20:21]
	s_add_i32 m0, s22, 0x2000
	s_nop 0
	global_load_lds_dwordx4 v128, s[20:21]
	s_waitcnt vmcnt(6)
	s_setprio 1
	s_barrier
	v_mfma_f32_16x16x32_bf16 v[44:47], v[202:205], v[166:169], v[44:47]
	v_mfma_f32_16x16x32_bf16 v[40:43], v[210:213], v[166:169], v[40:43]
	ds_read_b128 v[150:153], v147
	v_mfma_f32_16x16x32_bf16 v[28:31], v[202:205], v[174:177], v[28:31]
	v_mfma_f32_16x16x32_bf16 v[24:27], v[210:213], v[174:177], v[24:27]
	ds_read_b128 v[154:157], v147 offset:1024
	v_mfma_f32_16x16x32_bf16 v[12:15], v[202:205], v[182:185], v[12:15]
	v_mfma_f32_16x16x32_bf16 v[8:11], v[210:213], v[182:185], v[8:11]
	ds_read_b128 v[158:161], v147 offset:2048
	v_mfma_f32_16x16x32_bf16 v[4:7], v[202:205], v[190:193], v[4:7]
	v_mfma_f32_16x16x32_bf16 v[0:3], v[210:213], v[190:193], v[0:3]
	ds_read_b128 v[162:165], v147 offset:3072
	v_mfma_f32_16x16x32_bf16 v[44:47], v[206:209], v[170:173], v[44:47]
	s_add_i32 s3, s3, 2
	v_mfma_f32_16x16x32_bf16 v[40:43], v[214:217], v[170:173], v[40:43]
	s_add_u32 s55, s55, 0x100
	s_addc_u32 s56, s56, 0
	v_mfma_f32_16x16x32_bf16 v[28:31], v[206:209], v[178:181], v[28:31]
	s_add_u32 s18, s18, 0x100
	s_addc_u32 s19, s19, 0
	v_mfma_f32_16x16x32_bf16 v[24:27], v[214:217], v[178:181], v[24:27]
	s_cmp_gt_u32 s3, 5
	v_mfma_f32_16x16x32_bf16 v[12:15], v[206:209], v[186:189], v[12:15]
	v_mfma_f32_16x16x32_bf16 v[8:11], v[214:217], v[186:189], v[8:11]
	v_mfma_f32_16x16x32_bf16 v[4:7], v[206:209], v[198:201], v[4:7]
	v_mfma_f32_16x16x32_bf16 v[0:3], v[214:217], v[198:201], v[0:3]
	s_barrier
	s_setprio 0
	s_cbranch_scc0 .LBB1_1529
; DI unsigned pack2(float a, float b) { f32x2 v = {a, b}; hwbf16x2 r = __builtin_convertvector(v, hwbf16x2); return __builtin_bit_cast(unsigned, r); }
;     DI void operator()(const f32x4 (&acc)[2][2][4][2], const Unit& u, int wr, int wc, int fr, int fq) const {
;         bf16_t* O = O1; int ldc = ldc1, pn = u.pn; if (pn >= split) { O = O2; ldc = ldc2; pn -= split; }
;         const int row0 = u.pm * BM + wr * 64 + fr, col0 = pn * BM + wc * 32 + 8 * fq;
; #pragma unroll
;         for (int ai = 0; ai < 2; ++ai)
; #pragma unroll
;             for (int m = 0; m < 4; ++m) { bf16_t* rowp = O + (size_t)(row0 + ai * HALF + m * 16) * ldc + col0;
; #pragma unroll
;                 for (int bj = 0; bj < 2; ++bj) { const f32x4 v0 = acc[ai][bj][m][0], v1 = acc[ai][bj][m][1];
;                     u32x4 o; o[0] = pack2(v0[0], v0[1]); o[1] = pack2(v0[2], v0[3]); o[2] = pack2(v1[0], v1[1]); o[3] = pack2(v1[2], v1[3]);
;                     *(u32x4*)(rowp + bj * HALF) = o; } }
;     }
	s_waitcnt lgkmcnt(0)
	s_cmp_lt_i32 s45, 12
	s_cselect_b32 s3, 0, -12
	s_mov_b32 s13, 0x1e510000
	s_movk_i32 s18, 0xc00
	s_cselect_b32 s13, s13, 0x2a510000
	s_cselect_b32 s20, s18, 0x1000
	s_add_i32 s3, s3, s45
	s_add_u32 s18, s6, s13
	v_mov_b32_e32 v150, v144
	v_mov_b32_e32 v151, v145
	s_addc_u32 s19, s7, 0
	s_lshl_b32 s10, s10, 8
	s_lshl_b32 s3, s3, 8
	s_add_i32 s10, s10, s39
	s_or_b32 s3, s3, s42
	v_add_u32_e32 v154, s10, v150
	v_lshl_add_u32 v150, v151, 3, s3
	v_ashrrev_i32_e32 v151, 31, v150
	v_lshl_add_u64 v[150:151], v[150:151], 1, s[18:19]
	v_mad_i64_i32 v[152:153], s[18:19], s20, v154, 0
	v_cvt_pk_bf16_f32 v108, v108, v109
	v_cvt_pk_bf16_f32 v109, v110, v111
	v_cvt_pk_bf16_f32 v110, v104, v105
	v_add_u32_e32 v104, 16, v154
	v_lshl_add_u64 v[152:153], v[152:153], 1, v[150:151]
	v_cvt_pk_bf16_f32 v111, v106, v107
	v_mad_i64_i32 v[104:105], s[18:19], s20, v104, 0
	v_cvt_pk_bf16_f32 v92, v92, v93
	v_cvt_pk_bf16_f32 v93, v94, v95
	v_cvt_pk_bf16_f32 v94, v88, v89
	v_add_u32_e32 v88, 32, v154
	v_cvt_pk_bf16_f32 v124, v124, v125
	v_cvt_pk_bf16_f32 v125, v126, v127
	v_cvt_pk_bf16_f32 v126, v120, v121
	v_cvt_pk_bf16_f32 v127, v122, v123
	global_store_dwordx4 v[152:153], v[108:111], off offset:256
	v_cvt_pk_bf16_f32 v95, v90, v91
	v_mad_i64_i32 v[88:89], s[18:19], s20, v88, 0
	v_lshl_add_u64 v[108:109], v[104:105], 1, v[150:151]
	v_cvt_pk_bf16_f32 v76, v76, v77
	v_cvt_pk_bf16_f32 v77, v78, v79
	v_cvt_pk_bf16_f32 v78, v72, v73
	v_add_u32_e32 v72, 48, v154
	v_cvt_pk_bf16_f32 v68, v68, v69
	v_cvt_pk_bf16_f32 v69, v70, v71
	v_cvt_pk_bf16_f32 v70, v64, v65
	v_add_u32_e32 v64, 0x80, v154
	global_store_dwordx4 v[152:153], v[124:127], off
	v_cvt_pk_bf16_f32 v104, v116, v117
	v_cvt_pk_bf16_f32 v105, v118, v119
	v_cvt_pk_bf16_f32 v106, v112, v113
	v_cvt_pk_bf16_f32 v107, v114, v115
	global_store_dwordx4 v[108:109], v[92:95], off offset:256
	v_cvt_pk_bf16_f32 v79, v74, v75
	v_mad_i64_i32 v[72:73], s[18:19], s20, v72, 0
	v_lshl_add_u64 v[92:93], v[88:89], 1, v[150:151]
	v_mad_i64_i32 v[64:65], s[18:19], s20, v64, 0
	v_cvt_pk_bf16_f32 v44, v44, v45
	v_cvt_pk_bf16_f32 v45, v46, v47
	v_cvt_pk_bf16_f32 v46, v40, v41
	v_add_u32_e32 v40, 0x90, v154
	global_store_dwordx4 v[108:109], v[104:107], off
	v_cvt_pk_bf16_f32 v88, v100, v101
	v_cvt_pk_bf16_f32 v89, v102, v103
	v_cvt_pk_bf16_f32 v90, v96, v97
	v_cvt_pk_bf16_f32 v91, v98, v99
	global_store_dwordx4 v[92:93], v[76:79], off offset:256
	v_cvt_pk_bf16_f32 v74, v80, v81
	v_cvt_pk_bf16_f32 v75, v82, v83
	v_lshl_add_u64 v[76:77], v[72:73], 1, v[150:151]
	v_cvt_pk_bf16_f32 v72, v84, v85
	v_cvt_pk_bf16_f32 v73, v86, v87
	v_cvt_pk_bf16_f32 v71, v66, v67
	v_lshl_add_u64 v[64:65], v[64:65], 1, v[150:151]
	v_cvt_pk_bf16_f32 v47, v42, v43
	v_mad_i64_i32 v[40:41], s[18:19], s20, v40, 0
	v_cvt_pk_bf16_f32 v28, v28, v29
	v_cvt_pk_bf16_f32 v29, v30, v31
	v_cvt_pk_bf16_f32 v30, v24, v25
	v_add_u32_e32 v24, 0xa0, v154
	global_store_dwordx4 v[92:93], v[88:91], off
	global_store_dwordx4 v[76:77], v[72:75], off
	global_store_dwordx4 v[76:77], v[68:71], off offset:256
	v_cvt_pk_bf16_f32 v60, v60, v61
	v_cvt_pk_bf16_f32 v61, v62, v63
	v_cvt_pk_bf16_f32 v62, v56, v57
	v_cvt_pk_bf16_f32 v63, v58, v59
	global_store_dwordx4 v[64:65], v[44:47], off offset:256
	v_cvt_pk_bf16_f32 v31, v26, v27
	v_mad_i64_i32 v[24:25], s[18:19], s20, v24, 0
	v_lshl_add_u64 v[44:45], v[40:41], 1, v[150:151]
	v_cvt_pk_bf16_f32 v12, v12, v13
	v_cvt_pk_bf16_f32 v13, v14, v15
	v_cvt_pk_bf16_f32 v14, v8, v9
	v_add_u32_e32 v8, 0xb0, v154
	global_store_dwordx4 v[64:65], v[60:63], off
	v_cvt_pk_bf16_f32 v40, v52, v53
	v_cvt_pk_bf16_f32 v41, v54, v55
	v_cvt_pk_bf16_f32 v42, v48, v49
	v_cvt_pk_bf16_f32 v43, v50, v51
	global_store_dwordx4 v[44:45], v[28:31], off offset:256
	v_cvt_pk_bf16_f32 v15, v10, v11
	v_mad_i64_i32 v[8:9], s[18:19], s20, v8, 0
	v_lshl_add_u64 v[28:29], v[24:25], 1, v[150:151]
	global_store_dwordx4 v[44:45], v[40:43], off
	v_cvt_pk_bf16_f32 v24, v36, v37
	v_cvt_pk_bf16_f32 v25, v38, v39
	v_cvt_pk_bf16_f32 v26, v32, v33
	v_cvt_pk_bf16_f32 v27, v34, v35
	global_store_dwordx4 v[28:29], v[12:15], off offset:256
	v_cvt_pk_bf16_f32 v10, v16, v17
	v_cvt_pk_bf16_f32 v11, v18, v19
	v_lshl_add_u64 v[12:13], v[8:9], 1, v[150:151]
	v_cvt_pk_bf16_f32 v8, v20, v21
	v_cvt_pk_bf16_f32 v9, v22, v23
	v_cvt_pk_bf16_f32 v4, v4, v5
	v_cvt_pk_bf16_f32 v5, v6, v7
	v_cvt_pk_bf16_f32 v6, v0, v1
	v_cvt_pk_bf16_f32 v7, v2, v3
	s_and_b64 vcc, exec, s[40:41]
	s_mov_b32 s45, s49
	s_mov_b32 s10, s12
	s_mov_b64 s[18:19], s[16:17]
	s_mov_b64 s[20:21], s[14:15]
	global_store_dwordx4 v[28:29], v[24:27], off
	global_store_dwordx4 v[12:13], v[8:11], off
	global_store_dwordx4 v[12:13], v[4:7], off offset:256
	s_cbranch_vccz .LBB1_1526
	s_waitcnt vmcnt(0)
	s_cmpk_gt_u32 s4, 0xff
	s_cbranch_scc1 .LBB1_1533
	s_barrier

; #define PG8_STAGE(bufoff, gbase, voff) do { _Pragma("unroll") for (int _i = 0; _i < 2; ++_i) \
;         __builtin_amdgcn_global_load_lds((const unsigned*)((const char*)(gbase) + (voff)[_i]), (LAS unsigned*)(lds + (bufoff) + ldsw + _i * 8192), 16, 0, 0); } while (0)
; #define PG8_LDA(dst, b, h) do { _Pragma("unroll") for (int m = 0; m < 4; ++m) _Pragma("unroll") for (int k = 0; k < 2; ++k) dst[m][k] = *(const LAS bf16x8*)(lds + PG8_SA(b, h) + aoff + m * 2048 + k * 1024); } while (0)
; #define PG8_LDB(dst, b, h) do { _Pragma("unroll") for (int n = 0; n < 2; ++n) _Pragma("unroll") for (int k = 0; k < 2; ++k) dst[n][k] = *(const LAS bf16x8*)(lds + PG8_SB(b, h) + boff + n * 2048 + k * 1024); } while (0)
; #define PG8_MMA(ai, bj, At, Bt) do { __builtin_amdgcn_s_setprio(1); _Pragma("unroll") for (int m = 0; m < 4; ++m) _Pragma("unroll") for (int n = 0; n < 2; ++n) _Pragma("unroll") for (int k = 0; k < 2; ++k) \
;         acc[ai][bj][m][n] = __builtin_amdgcn_mfma_f32_16x16x32_bf16(Bt[n][k], At[m][k], acc[ai][bj][m][n], 0, 0, 0); __builtin_amdgcn_s_setprio(0); } while (0)
; #define PG8_WAIT_V(n) asm volatile("s_waitcnt vmcnt(" #n ")" ::: "memory")
; #define PG8_WAIT_L(n) asm volatile("s_waitcnt lgkmcnt(" #n ")" ::: "memory")
; #define PG8_BAR __builtin_amdgcn_s_barrier()
; #define PG8_SCHED __builtin_amdgcn_sched_barrier(0)
; template <class Map, class Epi>
; DI void gemm_phase(LAS unsigned char* lds, const Map& MP, const Epi& E, const int nM, const int nN, const int K, const int lda, const int ldb) {
;     ...
;             PG8_LDB(B0, 0, 0); PG8_SCHED; PG8_LDA(At, 0, 0); PG8_STAGE(PG8_SA(1, 1), a1 + hstepA, voffA);
;             PG8_WAIT_L(8); PG8_BAR; PG8_WAIT_L(0); PG8_MMA(0, 0, At, B0); PG8_BAR; PG8_SCHED;
;             PG8_LDB(B1, 0, 1); PG8_STAGE(PG8_SB(0, 0), b2, voffB);
;             PG8_BAR; PG8_WAIT_L(0); PG8_MMA(0, 1, At, B1); PG8_BAR;
;             PG8_LDA(At, 0, 1); PG8_STAGE(PG8_SA(0, 0), a2, voffA);
;             PG8_BAR; PG8_WAIT_L(0); PG8_MMA(1, 0, At, B0); PG8_BAR; PG8_SCHED;
;             PG8_STAGE(PG8_SB(0, 1), b2 + hstepB, voffB);
;             PG8_WAIT_V(6); PG8_BAR; PG8_MMA(1, 1, At, B1); PG8_BAR;
.LBB1_1764:
	s_add_u32 s12, s10, 0xfff80080
	s_addc_u32 s13, s11, -1
	s_cmp_eq_u32 s3, 28
	s_cselect_b32 s15, s37, s13
	s_cselect_b32 s14, s38, s12
	s_cselect_b32 s13, s39, s48
	s_cselect_b32 s12, s45, s47
	s_add_i32 m0, s24, 0xc000
	ds_read_b128 v[168:171], v150
	ds_read_b128 v[172:175], v150 offset:1024
	ds_read_b128 v[176:179], v150 offset:2048
	ds_read_b128 v[180:183], v150 offset:3072
	ds_read_b128 v[184:187], v150 offset:4096
	ds_read_b128 v[188:191], v150 offset:5120
	ds_read_b128 v[192:195], v150 offset:6144
	ds_read_b128 v[198:201], v150 offset:7168
	global_load_lds_dwordx4 v138, s[10:11]
	s_add_i32 m0, s24, 0xe000
	s_nop 0
	global_load_lds_dwordx4 v136, s[10:11]
	s_waitcnt lgkmcnt(7)
	s_setprio 1
	s_barrier
	v_mfma_f32_16x16x32_bf16 v[124:127], v[152:155], v[168:171], v[124:127]
	v_mfma_f32_16x16x32_bf16 v[120:123], v[160:163], v[168:171], v[120:123]
	s_waitcnt lgkmcnt(5)
	v_mfma_f32_16x16x32_bf16 v[108:111], v[152:155], v[176:179], v[108:111]
	v_mfma_f32_16x16x32_bf16 v[104:107], v[160:163], v[176:179], v[104:107]
	s_waitcnt lgkmcnt(3)
	v_mfma_f32_16x16x32_bf16 v[92:95], v[152:155], v[184:187], v[92:95]
	v_mfma_f32_16x16x32_bf16 v[88:91], v[160:163], v[184:187], v[88:91]
	s_waitcnt lgkmcnt(1)
	v_mfma_f32_16x16x32_bf16 v[76:79], v[152:155], v[192:195], v[76:79]
	v_mfma_f32_16x16x32_bf16 v[72:75], v[160:163], v[192:195], v[72:75]
	v_mfma_f32_16x16x32_bf16 v[124:127], v[156:159], v[172:175], v[124:127]
	v_mfma_f32_16x16x32_bf16 v[120:123], v[164:167], v[172:175], v[120:123]
	v_mfma_f32_16x16x32_bf16 v[108:111], v[156:159], v[180:183], v[108:111]
	v_mfma_f32_16x16x32_bf16 v[104:107], v[164:167], v[180:183], v[104:107]
	v_mfma_f32_16x16x32_bf16 v[92:95], v[156:159], v[188:191], v[92:95]
	v_mfma_f32_16x16x32_bf16 v[88:91], v[164:167], v[188:191], v[88:91]
	s_waitcnt lgkmcnt(0)
	v_mfma_f32_16x16x32_bf16 v[76:79], v[156:159], v[198:201], v[76:79]
	v_mfma_f32_16x16x32_bf16 v[72:75], v[164:167], v[198:201], v[72:75]
	s_barrier
	s_setprio 0
	s_add_i32 s49, s35, s22
	v_lshl_add_u64 v[144:145], s[12:13], 0, v[132:133]
	s_mov_b32 m0, s49
	ds_read_b128 v[202:205], v151
	ds_read_b128 v[206:209], v151 offset:1024
	ds_read_b128 v[210:213], v151 offset:2048
	ds_read_b128 v[214:217], v151 offset:3072
	global_load_lds_dwordx4 v[144:145], off
	v_lshl_add_u64 v[218:219], s[12:13], 0, v[128:129]
	s_add_i32 m0, s49, 0x2000
	s_nop 0
	global_load_lds_dwordx4 v[218:219], off
	s_waitcnt lgkmcnt(3)
	s_setprio 1
	s_barrier
	v_mfma_f32_16x16x32_bf16 v[116:119], v[202:205], v[168:171], v[116:119]
	s_waitcnt lgkmcnt(1)
	v_mfma_f32_16x16x32_bf16 v[112:115], v[210:213], v[168:171], v[112:115]
	v_mfma_f32_16x16x32_bf16 v[100:103], v[202:205], v[176:179], v[100:103]
	v_mfma_f32_16x16x32_bf16 v[96:99], v[210:213], v[176:179], v[96:99]
	v_mfma_f32_16x16x32_bf16 v[84:87], v[202:205], v[184:187], v[84:87]
	v_mfma_f32_16x16x32_bf16 v[80:83], v[210:213], v[184:187], v[80:83]
	v_mfma_f32_16x16x32_bf16 v[68:71], v[202:205], v[192:195], v[68:71]
	v_mfma_f32_16x16x32_bf16 v[64:67], v[210:213], v[192:195], v[64:67]
	v_mfma_f32_16x16x32_bf16 v[116:119], v[206:209], v[172:175], v[116:119]
	s_mov_b32 m0, s24
	s_waitcnt lgkmcnt(0)
	v_mfma_f32_16x16x32_bf16 v[112:115], v[214:217], v[172:175], v[112:115]
	v_lshl_add_u64 v[220:221], s[14:15], 0, v[134:135]
	v_mfma_f32_16x16x32_bf16 v[100:103], v[206:209], v[180:183], v[100:103]
	v_mfma_f32_16x16x32_bf16 v[96:99], v[214:217], v[180:183], v[96:99]
	v_mfma_f32_16x16x32_bf16 v[84:87], v[206:209], v[188:191], v[84:87]
	v_mfma_f32_16x16x32_bf16 v[80:83], v[214:217], v[188:191], v[80:83]
	v_mfma_f32_16x16x32_bf16 v[68:71], v[206:209], v[198:201], v[68:71]
	v_mfma_f32_16x16x32_bf16 v[64:67], v[214:217], v[198:201], v[64:67]
	s_barrier
	s_setprio 0
	ds_read_b128 v[168:171], v150 offset:16384
	ds_read_b128 v[172:175], v150 offset:17408
	ds_read_b128 v[176:179], v150 offset:18432
	ds_read_b128 v[180:183], v150 offset:19456
	ds_read_b128 v[184:187], v150 offset:20480
	ds_read_b128 v[188:191], v150 offset:21504
	ds_read_b128 v[192:195], v150 offset:22528
	ds_read_b128 v[198:201], v150 offset:23552
	global_load_lds_dwordx4 v[220:221], off
	v_lshl_add_u64 v[222:223], s[14:15], 0, v[130:131]
	s_mov_b32 m0, s9
	s_nop 0
	global_load_lds_dwordx4 v[222:223], off
	s_waitcnt vmcnt(10) lgkmcnt(7)
	s_setprio 1
	s_barrier
	v_mfma_f32_16x16x32_bf16 v[60:63], v[152:155], v[168:171], v[60:63]
	v_mfma_f32_16x16x32_bf16 v[56:59], v[160:163], v[168:171], v[56:59]
	s_waitcnt lgkmcnt(5)
	v_mfma_f32_16x16x32_bf16 v[44:47], v[152:155], v[176:179], v[44:47]
	v_mfma_f32_16x16x32_bf16 v[40:43], v[160:163], v[176:179], v[40:43]
	s_waitcnt lgkmcnt(3)
	v_mfma_f32_16x16x32_bf16 v[28:31], v[152:155], v[184:187], v[28:31]
	v_mfma_f32_16x16x32_bf16 v[24:27], v[160:163], v[184:187], v[24:27]
	s_waitcnt lgkmcnt(1)
	v_mfma_f32_16x16x32_bf16 v[12:15], v[152:155], v[192:195], v[12:15]
	v_mfma_f32_16x16x32_bf16 v[8:11], v[160:163], v[192:195], v[8:11]
	v_mfma_f32_16x16x32_bf16 v[60:63], v[156:159], v[172:175], v[60:63]
	v_mfma_f32_16x16x32_bf16 v[56:59], v[164:167], v[172:175], v[56:59]
	v_mfma_f32_16x16x32_bf16 v[44:47], v[156:159], v[180:183], v[44:47]
	v_mfma_f32_16x16x32_bf16 v[40:43], v[164:167], v[180:183], v[40:43]
	v_mfma_f32_16x16x32_bf16 v[28:31], v[156:159], v[188:191], v[28:31]
	v_mfma_f32_16x16x32_bf16 v[24:27], v[164:167], v[188:191], v[24:27]
	s_waitcnt lgkmcnt(0)
	v_mfma_f32_16x16x32_bf16 v[12:15], v[156:159], v[198:201], v[12:15]
	v_mfma_f32_16x16x32_bf16 v[8:11], v[164:167], v[198:201], v[8:11]
	s_barrier
	s_setprio 0
	s_add_u32 s54, s12, 0x80000
	s_addc_u32 s55, s13, 0
	s_add_i32 s49, s36, s22
	s_mov_b32 m0, s49
	s_nop 0
	global_load_lds_dwordx4 v132, s[54:55]
	s_add_i32 m0, s49, 0x2000
	s_nop 0
	global_load_lds_dwordx4 v128, s[54:55]
	s_waitcnt vmcnt(6)
	s_setprio 1
	s_barrier
; #define PG8_STAGE(bufoff, gbase, voff) do { _Pragma("unroll") for (int _i = 0; _i < 2; ++_i) \
;         __builtin_amdgcn_global_load_lds((const unsigned*)((const char*)(gbase) + (voff)[_i]), (LAS unsigned*)(lds + (bufoff) + ldsw + _i * 8192), 16, 0, 0); } while (0)
; #define PG8_LDA(dst, b, h) do { _Pragma("unroll") for (int m = 0; m < 4; ++m) _Pragma("unroll") for (int k = 0; k < 2; ++k) dst[m][k] = *(const LAS bf16x8*)(lds + PG8_SA(b, h) + aoff + m * 2048 + k * 1024); } while (0)
; #define PG8_LDB(dst, b, h) do { _Pragma("unroll") for (int n = 0; n < 2; ++n) _Pragma("unroll") for (int k = 0; k < 2; ++k) dst[n][k] = *(const LAS bf16x8*)(lds + PG8_SB(b, h) + boff + n * 2048 + k * 1024); } while (0)
; #define PG8_MMA(ai, bj, At, Bt) do { __builtin_amdgcn_s_setprio(1); _Pragma("unroll") for (int m = 0; m < 4; ++m) _Pragma("unroll") for (int n = 0; n < 2; ++n) _Pragma("unroll") for (int k = 0; k < 2; ++k) \
;         acc[ai][bj][m][n] = __builtin_amdgcn_mfma_f32_16x16x32_bf16(Bt[n][k], At[m][k], acc[ai][bj][m][n], 0, 0, 0); __builtin_amdgcn_s_setprio(0); } while (0)
; #define PG8_WAIT_V(n) asm volatile("s_waitcnt vmcnt(" #n ")" ::: "memory")
; #define PG8_WAIT_L(n) asm volatile("s_waitcnt lgkmcnt(" #n ")" ::: "memory")
; #define PG8_BAR __builtin_amdgcn_s_barrier()
; #define PG8_SCHED __builtin_amdgcn_sched_barrier(0)
; template <class Map, class Epi>
; DI void gemm_phase(LAS unsigned char* lds, const Map& MP, const Epi& E, const int nM, const int nN, const int K, const int lda, const int ldb) {
;     ...
;             PG8_WAIT_V(6); PG8_BAR; PG8_MMA(1, 1, At, B1); PG8_BAR;
;             PG8_LDB(B0, 1, 0); PG8_SCHED; PG8_LDA(At, 1, 0); PG8_STAGE(PG8_SA(0, 1), a2 + hstepA, voffA);
;             PG8_WAIT_L(8); PG8_BAR; PG8_WAIT_L(0); PG8_MMA(0, 0, At, B0); PG8_BAR; PG8_SCHED;
;             PG8_LDB(B1, 1, 1); PG8_STAGE(PG8_SB(1, 0), b3, voffB);
;             PG8_BAR; PG8_WAIT_L(0); PG8_MMA(0, 1, At, B1); PG8_BAR;
;             PG8_LDA(At, 1, 1); PG8_STAGE(PG8_SA(1, 0), a3, voffA);
;             PG8_BAR; PG8_WAIT_L(0); PG8_MMA(1, 0, At, B0); PG8_BAR; PG8_SCHED;
	v_mfma_f32_16x16x32_bf16 v[52:55], v[202:205], v[168:171], v[52:55]
	v_mfma_f32_16x16x32_bf16 v[48:51], v[210:213], v[168:171], v[48:51]
	s_add_i32 s49, 0, 0x18000
	v_add_u32_e32 v164, s49, v148
	ds_read_b128 v[152:155], v164
	v_mfma_f32_16x16x32_bf16 v[36:39], v[202:205], v[176:179], v[36:39]
	v_mfma_f32_16x16x32_bf16 v[32:35], v[210:213], v[176:179], v[32:35]
	ds_read_b128 v[156:159], v164 offset:1024
	v_mfma_f32_16x16x32_bf16 v[20:23], v[202:205], v[184:187], v[20:23]
	v_mfma_f32_16x16x32_bf16 v[16:19], v[210:213], v[184:187], v[16:19]
	ds_read_b128 v[160:163], v164 offset:2048
	v_mfma_f32_16x16x32_bf16 v[4:7], v[202:205], v[192:195], v[4:7]
	v_mfma_f32_16x16x32_bf16 v[0:3], v[210:213], v[192:195], v[0:3]
	ds_read_b128 v[164:167], v164 offset:3072
	v_mfma_f32_16x16x32_bf16 v[52:55], v[206:209], v[172:175], v[52:55]
	v_mfma_f32_16x16x32_bf16 v[48:51], v[214:217], v[172:175], v[48:51]
	v_mfma_f32_16x16x32_bf16 v[36:39], v[206:209], v[180:183], v[36:39]
	v_mfma_f32_16x16x32_bf16 v[32:35], v[214:217], v[180:183], v[32:35]
	v_mfma_f32_16x16x32_bf16 v[20:23], v[206:209], v[188:191], v[20:23]
	v_mfma_f32_16x16x32_bf16 v[16:19], v[214:217], v[188:191], v[16:19]
	v_mfma_f32_16x16x32_bf16 v[4:7], v[206:209], v[198:201], v[4:7]
	v_mfma_f32_16x16x32_bf16 v[0:3], v[214:217], v[198:201], v[0:3]
	s_barrier
	s_setprio 0
	s_add_u32 s14, s14, 0x80000
	s_addc_u32 s15, s15, 0
	s_mov_b32 m0, s25
	ds_read_b128 v[168:171], v150 offset:32768
	ds_read_b128 v[172:175], v150 offset:33792
	ds_read_b128 v[176:179], v150 offset:34816
	ds_read_b128 v[180:183], v150 offset:35840
	ds_read_b128 v[184:187], v150 offset:36864
	ds_read_b128 v[188:191], v150 offset:37888
	ds_read_b128 v[192:195], v150 offset:38912
	ds_read_b128 v[198:201], v150 offset:39936
	global_load_lds_dwordx4 v134, s[14:15]
	s_mov_b32 m0, s26
	s_nop 0
	global_load_lds_dwordx4 v130, s[14:15]
	s_waitcnt lgkmcnt(7)
	s_setprio 1
	s_barrier
	v_mfma_f32_16x16x32_bf16 v[124:127], v[152:155], v[168:171], v[124:127]
	v_mfma_f32_16x16x32_bf16 v[120:123], v[160:163], v[168:171], v[120:123]
	s_waitcnt lgkmcnt(5)
	v_mfma_f32_16x16x32_bf16 v[108:111], v[152:155], v[176:179], v[108:111]
	v_mfma_f32_16x16x32_bf16 v[104:107], v[160:163], v[176:179], v[104:107]
	s_waitcnt lgkmcnt(3)
	v_mfma_f32_16x16x32_bf16 v[92:95], v[152:155], v[184:187], v[92:95]
	v_mfma_f32_16x16x32_bf16 v[88:91], v[160:163], v[184:187], v[88:91]
	s_waitcnt lgkmcnt(1)
	v_mfma_f32_16x16x32_bf16 v[76:79], v[152:155], v[192:195], v[76:79]
	v_mfma_f32_16x16x32_bf16 v[72:75], v[160:163], v[192:195], v[72:75]
	v_mfma_f32_16x16x32_bf16 v[124:127], v[156:159], v[172:175], v[124:127]
	v_mfma_f32_16x16x32_bf16 v[120:123], v[164:167], v[172:175], v[120:123]
	v_mfma_f32_16x16x32_bf16 v[108:111], v[156:159], v[180:183], v[108:111]
	v_mfma_f32_16x16x32_bf16 v[104:107], v[164:167], v[180:183], v[104:107]
	v_mfma_f32_16x16x32_bf16 v[92:95], v[156:159], v[188:191], v[92:95]
	v_mfma_f32_16x16x32_bf16 v[88:91], v[164:167], v[188:191], v[88:91]
	s_waitcnt lgkmcnt(0)
	v_mfma_f32_16x16x32_bf16 v[76:79], v[156:159], v[198:201], v[76:79]
	v_mfma_f32_16x16x32_bf16 v[72:75], v[164:167], v[198:201], v[72:75]
	s_barrier
	s_setprio 0
	s_add_i32 s14, 0, 0x1c000
	s_add_i32 s15, s49, s22
	v_add_u32_e32 v196, s14, v148
	v_lshl_add_u64 v[144:145], v[144:145], 0, s[42:43]
	s_mov_b32 m0, s15
	ds_read_b128 v[202:205], v196
	ds_read_b128 v[206:209], v196 offset:1024
	ds_read_b128 v[210:213], v196 offset:2048
	ds_read_b128 v[214:217], v196 offset:3072
	global_load_lds_dwordx4 v[144:145], off
	v_lshl_add_u64 v[144:145], v[218:219], 0, s[42:43]
	s_add_i32 m0, s15, 0x2000
	s_nop 0
	global_load_lds_dwordx4 v[144:145], off
	s_waitcnt lgkmcnt(3)
	s_setprio 1
	s_barrier
	v_mfma_f32_16x16x32_bf16 v[116:119], v[202:205], v[168:171], v[116:119]
	s_waitcnt lgkmcnt(1)
	v_mfma_f32_16x16x32_bf16 v[112:115], v[210:213], v[168:171], v[112:115]
	v_mfma_f32_16x16x32_bf16 v[100:103], v[202:205], v[176:179], v[100:103]
	v_mfma_f32_16x16x32_bf16 v[96:99], v[210:213], v[176:179], v[96:99]
	v_mfma_f32_16x16x32_bf16 v[84:87], v[202:205], v[184:187], v[84:87]
	v_mfma_f32_16x16x32_bf16 v[80:83], v[210:213], v[184:187], v[80:83]
	v_mfma_f32_16x16x32_bf16 v[68:71], v[202:205], v[192:195], v[68:71]
	v_mfma_f32_16x16x32_bf16 v[64:67], v[210:213], v[192:195], v[64:67]
	v_mfma_f32_16x16x32_bf16 v[116:119], v[206:209], v[172:175], v[116:119]
	s_mov_b32 m0, s30
	s_waitcnt lgkmcnt(0)
	v_mfma_f32_16x16x32_bf16 v[112:115], v[214:217], v[172:175], v[112:115]
	v_lshl_add_u64 v[144:145], v[220:221], 0, s[42:43]
	v_mfma_f32_16x16x32_bf16 v[100:103], v[206:209], v[180:183], v[100:103]
	v_mfma_f32_16x16x32_bf16 v[96:99], v[214:217], v[180:183], v[96:99]
	v_mfma_f32_16x16x32_bf16 v[84:87], v[206:209], v[188:191], v[84:87]
	v_mfma_f32_16x16x32_bf16 v[80:83], v[214:217], v[188:191], v[80:83]
	v_mfma_f32_16x16x32_bf16 v[68:71], v[206:209], v[198:201], v[68:71]
	v_mfma_f32_16x16x32_bf16 v[64:67], v[214:217], v[198:201], v[64:67]
	s_barrier
	s_setprio 0
	ds_read_b128 v[168:171], v150 offset:49152
	ds_read_b128 v[172:175], v150 offset:50176
	ds_read_b128 v[176:179], v150 offset:51200
	ds_read_b128 v[180:183], v150 offset:52224
	ds_read_b128 v[184:187], v150 offset:53248
	ds_read_b128 v[188:191], v150 offset:54272
	ds_read_b128 v[192:195], v150 offset:55296
	ds_read_b128 v[198:201], v150 offset:56320
	global_load_lds_dwordx4 v[144:145], off
	v_lshl_add_u64 v[144:145], v[222:223], 0, s[42:43]
	s_mov_b32 m0, s31
	s_nop 0
	global_load_lds_dwordx4 v[144:145], off
	s_waitcnt vmcnt(10) lgkmcnt(7)
	s_setprio 1
	s_barrier
; DI unsigned pack2(float a, float b) { f32x2 v = {a, b}; hwbf16x2 r = __builtin_convertvector(v, hwbf16x2); return __builtin_bit_cast(unsigned, r); }
; DI float bflo(unsigned w) { return __uint_as_float(w << 16); }
; DI float bfhi(unsigned w) { return __uint_as_float(w & 0xffff0000u); }
; #define PG8_WAIT_V(n) asm volatile("s_waitcnt vmcnt(" #n ")" ::: "memory")
; #define PG8_BAR __builtin_amdgcn_s_barrier()
;     DI void operator()(const f32x4 (&acc)[2][2][4][2], const Unit& u, int wr, int wc, int fr, int fq) const {
;     ...
;         for (int ai = 0; ai < 2; ++ai)
; #pragma unroll
;             for (int m = 0; m < 4; ++m) { const size_t ro = (size_t)(row0 + ai * HALF + m * 16) * D + col0;
; #pragma unroll
;                 for (int bj = 0; bj < 2; ++bj) {
;                     f32x4 x0, x1;
;                     if constexpr (IB) { const u32x4 w = *(const u32x4*)((const bf16_t*)Xin + ro + bj * HALF);
;                         x0 = (f32x4){bflo(w[0]), bfhi(w[0]), bflo(w[1]), bfhi(w[1])}; x1 = (f32x4){bflo(w[2]), bfhi(w[2]), bflo(w[3]), bfhi(w[3])}; }
;                     else { x0 = *(const f32x4*)((const float*)Xin + ro + bj * HALF); x1 = *(const f32x4*)((const float*)Xin + ro + bj * HALF + 4); }
;                     x0 += acc[ai][bj][m][0] * sc[bj][0]; x1 += acc[ai][bj][m][1] * sc[bj][1];
;                     if constexpr (OB) { u32x4 o; o[0] = pack2(x0[0], x0[1]); o[1] = pack2(x0[2], x0[3]); o[2] = pack2(x1[0], x1[1]); o[3] = pack2(x1[2], x1[3]);
;                         *(u32x4*)((bf16_t*)Xout + ro + bj * HALF) = o; }
;                     else { *(f32x4*)((float*)Xout + ro + bj * HALF) = x0; *(f32x4*)((float*)Xout + ro + bj * HALF + 4) = x1; } } }
; template <class Map, class Epi>
; DI void gemm_phase(LAS unsigned char* lds, const Map& MP, const Epi& E, const int nM, const int nN, const int K, const int lda, const int ldb) {
;     ...
;             PG8_WAIT_L(8); PG8_BAR; PG8_WAIT_L(0); PG8_MMA(0, 0, At, B0); PG8_BAR; PG8_SCHED;
;             PG8_LDB(B1, 1, 1); PG8_STAGE(PG8_SB(1, 0), b3, voffB);
;             PG8_BAR; PG8_WAIT_L(0); PG8_MMA(0, 1, At, B1); PG8_BAR;
;             PG8_LDA(At, 1, 1); PG8_STAGE(PG8_SA(1, 0), a3, voffA);
;             PG8_BAR; PG8_WAIT_L(0); PG8_MMA(1, 0, At, B0); PG8_BAR; PG8_SCHED;
;             PG8_STAGE(PG8_SB(1, 1), b3 + hstepB, voffB);
;             PG8_WAIT_V(6); PG8_BAR; PG8_MMA(1, 1, At, B1); PG8_BAR;
	v_mfma_f32_16x16x32_bf16 v[60:63], v[152:155], v[168:171], v[60:63]
	v_mfma_f32_16x16x32_bf16 v[56:59], v[160:163], v[168:171], v[56:59]
	s_waitcnt lgkmcnt(5)
	v_mfma_f32_16x16x32_bf16 v[44:47], v[152:155], v[176:179], v[44:47]
	v_mfma_f32_16x16x32_bf16 v[40:43], v[160:163], v[176:179], v[40:43]
	s_waitcnt lgkmcnt(3)
	v_mfma_f32_16x16x32_bf16 v[28:31], v[152:155], v[184:187], v[28:31]
	v_mfma_f32_16x16x32_bf16 v[24:27], v[160:163], v[184:187], v[24:27]
	s_waitcnt lgkmcnt(1)
	v_mfma_f32_16x16x32_bf16 v[12:15], v[152:155], v[192:195], v[12:15]
	v_mfma_f32_16x16x32_bf16 v[8:11], v[160:163], v[192:195], v[8:11]
	v_mfma_f32_16x16x32_bf16 v[60:63], v[156:159], v[172:175], v[60:63]
	v_mfma_f32_16x16x32_bf16 v[56:59], v[164:167], v[172:175], v[56:59]
	v_mfma_f32_16x16x32_bf16 v[44:47], v[156:159], v[180:183], v[44:47]
	v_mfma_f32_16x16x32_bf16 v[40:43], v[164:167], v[180:183], v[40:43]
	v_mfma_f32_16x16x32_bf16 v[28:31], v[156:159], v[188:191], v[28:31]
	v_mfma_f32_16x16x32_bf16 v[24:27], v[164:167], v[188:191], v[24:27]
	s_waitcnt lgkmcnt(0)
	v_mfma_f32_16x16x32_bf16 v[12:15], v[156:159], v[198:201], v[12:15]
	v_mfma_f32_16x16x32_bf16 v[8:11], v[164:167], v[198:201], v[8:11]
	s_barrier
	s_setprio 0
	s_add_u32 s12, s12, 0x80080
	s_addc_u32 s13, s13, 0
	s_add_i32 s14, s14, s22
	s_mov_b32 m0, s14
	s_nop 0
	global_load_lds_dwordx4 v132, s[12:13]
	s_add_i32 m0, s14, 0x2000
	s_nop 0
	global_load_lds_dwordx4 v128, s[12:13]
	s_waitcnt vmcnt(6)
	s_setprio 1
	s_barrier
	v_mfma_f32_16x16x32_bf16 v[52:55], v[202:205], v[168:171], v[52:55]
	v_mfma_f32_16x16x32_bf16 v[48:51], v[210:213], v[168:171], v[48:51]
	ds_read_b128 v[152:155], v149
	v_mfma_f32_16x16x32_bf16 v[36:39], v[202:205], v[176:179], v[36:39]
	v_mfma_f32_16x16x32_bf16 v[32:35], v[210:213], v[176:179], v[32:35]
	ds_read_b128 v[156:159], v149 offset:1024
	v_mfma_f32_16x16x32_bf16 v[20:23], v[202:205], v[184:187], v[20:23]
	v_mfma_f32_16x16x32_bf16 v[16:19], v[210:213], v[184:187], v[16:19]
	ds_read_b128 v[160:163], v149 offset:2048
	v_mfma_f32_16x16x32_bf16 v[4:7], v[202:205], v[192:195], v[4:7]
	v_mfma_f32_16x16x32_bf16 v[0:3], v[210:213], v[192:195], v[0:3]
	ds_read_b128 v[164:167], v149 offset:3072
	v_mfma_f32_16x16x32_bf16 v[52:55], v[206:209], v[172:175], v[52:55]
	s_add_i32 s3, s3, 2
	v_mfma_f32_16x16x32_bf16 v[48:51], v[214:217], v[172:175], v[48:51]
	s_add_u32 s47, s47, 0x100
	s_addc_u32 s48, s48, 0
	v_mfma_f32_16x16x32_bf16 v[36:39], v[206:209], v[180:183], v[36:39]
	s_add_u32 s10, s10, 0x100
	s_addc_u32 s11, s11, 0
	v_mfma_f32_16x16x32_bf16 v[32:35], v[214:217], v[180:183], v[32:35]
	s_cmp_gt_u32 s3, 29
	v_mfma_f32_16x16x32_bf16 v[20:23], v[206:209], v[188:191], v[20:23]
	v_mfma_f32_16x16x32_bf16 v[16:19], v[214:217], v[188:191], v[16:19]
	v_mfma_f32_16x16x32_bf16 v[4:7], v[206:209], v[198:201], v[4:7]
	v_mfma_f32_16x16x32_bf16 v[0:3], v[214:217], v[198:201], v[0:3]
	s_barrier
	s_setprio 0
	s_cbranch_scc0 .LBB1_1764
	s_waitcnt lgkmcnt(0)
	v_mov_b32_e32 v152, v147
	v_mov_b32_e32 v144, v146
	s_lshl_b32 s2, s2, 8
	s_or_b32 s2, s2, s29
	v_lshl_add_u32 v144, v144, 3, s2
	s_lshl_b32 s2, s8, 8
	s_add_i32 s2, s2, s28
	v_add_u32_e32 v152, s2, v152
	v_ashrrev_i32_e32 v153, 31, v152
	v_lshlrev_b64 v[152:153], 12, v[152:153]
	v_ashrrev_i32_e32 v145, 31, v144
	v_lshl_add_u64 v[152:153], s[4:5], 0, v[152:153]
	v_lshl_add_u64 v[144:145], v[144:145], 1, v[152:153]
	global_load_dwordx4 v[160:163], v[144:145], off
	global_load_dwordx4 v[164:167], v[144:145], off offset:256
	s_mov_b64 s[98:99], 0x10000
	v_lshl_add_u64 v[154:155], v[144:145], 0, s[98:99]
	global_load_dwordx4 v[168:171], v[154:155], off
	global_load_dwordx4 v[172:175], v[154:155], off offset:256
	s_mov_b64 s[98:99], 0x20000
	v_lshl_add_u64 v[154:155], v[144:145], 0, s[98:99]
	global_load_dwordx4 v[176:179], v[154:155], off
	global_load_dwordx4 v[180:183], v[154:155], off offset:256
	s_mov_b64 s[98:99], 0x30000
	v_lshl_add_u64 v[154:155], v[144:145], 0, s[98:99]
	global_load_dwordx4 v[184:187], v[154:155], off
	global_load_dwordx4 v[188:191], v[154:155], off offset:256
	s_mov_b64 s[98:99], 0x80000
	v_lshl_add_u64 v[154:155], v[144:145], 0, s[98:99]
	global_load_dwordx4 v[192:195], v[154:155], off
	global_load_dwordx4 v[198:201], v[154:155], off offset:256
	s_mov_b64 s[98:99], 0x90000
	v_lshl_add_u64 v[154:155], v[144:145], 0, s[98:99]
	global_load_dwordx4 v[202:205], v[154:155], off
	global_load_dwordx4 v[206:209], v[154:155], off offset:256
	s_mov_b64 s[98:99], 0xa0000
	v_lshl_add_u64 v[154:155], v[144:145], 0, s[98:99]
	global_load_dwordx4 v[210:213], v[154:155], off
	global_load_dwordx4 v[214:217], v[154:155], off offset:256
	s_mov_b64 s[98:99], 0xb0000
	v_lshl_add_u64 v[154:155], v[144:145], 0, s[98:99]
	global_load_dwordx4 v[248:251], v[154:155], off
	global_load_dwordx4 v[252:255], v[154:155], off offset:256
	s_waitcnt vmcnt(15)
	s_nop 1
	v_mov_b32_e32 v152, v160
	v_mov_b32_e32 v153, v161
	v_mov_b32_e32 v154, v162
	v_mov_b32_e32 v155, v163
	s_mov_b64 s[2:3], 0x10000
	s_mov_b32 s8, s46
	s_mov_b64 s[10:11], s[6:7]
	s_mov_b64 s[12:13], s[52:53]
	s_waitcnt lgkmcnt(0)
	v_lshlrev_b32_e32 v156, 16, v152
	v_and_b32_e32 v157, 0xffff0000, v152
	v_lshlrev_b32_e32 v152, 16, v153
	v_and_b32_e32 v153, 0xffff0000, v153
	v_lshlrev_b32_e32 v158, 16, v154
	v_and_b32_e32 v159, 0xffff0000, v154
	v_lshlrev_b32_e32 v154, 16, v155
	v_and_b32_e32 v155, 0xffff0000, v155
	v_pk_add_f32 v[126:127], v[126:127], v[152:153]
	v_pk_add_f32 v[124:125], v[124:125], v[156:157]
	v_pk_add_f32 v[152:153], v[122:123], v[154:155]
	v_pk_add_f32 v[122:123], v[120:121], v[158:159]
	v_cvt_pk_bf16_f32 v120, v124, v125
	v_cvt_pk_bf16_f32 v121, v126, v127
	v_cvt_pk_bf16_f32 v122, v122, v123
	v_cvt_pk_bf16_f32 v123, v152, v153
	global_store_dwordx4 v[144:145], v[120:123], off
	s_waitcnt vmcnt(15)
; DI unsigned pack2(float a, float b) { f32x2 v = {a, b}; hwbf16x2 r = __builtin_convertvector(v, hwbf16x2); return __builtin_bit_cast(unsigned, r); }
; DI float bflo(unsigned w) { return __uint_as_float(w << 16); }
; DI float bfhi(unsigned w) { return __uint_as_float(w & 0xffff0000u); }
;     DI void operator()(const f32x4 (&acc)[2][2][4][2], const Unit& u, int wr, int wc, int fr, int fq) const {
;     ...
;         for (int ai = 0; ai < 2; ++ai)
; #pragma unroll
;             for (int m = 0; m < 4; ++m) { const size_t ro = (size_t)(row0 + ai * HALF + m * 16) * D + col0;
; #pragma unroll
;                 for (int bj = 0; bj < 2; ++bj) {
;                     f32x4 x0, x1;
;                     if constexpr (IB) { const u32x4 w = *(const u32x4*)((const bf16_t*)Xin + ro + bj * HALF);
;                         x0 = (f32x4){bflo(w[0]), bfhi(w[0]), bflo(w[1]), bfhi(w[1])}; x1 = (f32x4){bflo(w[2]), bfhi(w[2]), bflo(w[3]), bfhi(w[3])}; }
;                     else { x0 = *(const f32x4*)((const float*)Xin + ro + bj * HALF); x1 = *(const f32x4*)((const float*)Xin + ro + bj * HALF + 4); }
;                     x0 += acc[ai][bj][m][0] * sc[bj][0]; x1 += acc[ai][bj][m][1] * sc[bj][1];
;                     if constexpr (OB) { u32x4 o; o[0] = pack2(x0[0], x0[1]); o[1] = pack2(x0[2], x0[3]); o[2] = pack2(x1[0], x1[1]); o[3] = pack2(x1[2], x1[3]);
;                         *(u32x4*)((bf16_t*)Xout + ro + bj * HALF) = o; }
;                     else { *(f32x4*)((float*)Xout + ro + bj * HALF) = x0; *(f32x4*)((float*)Xout + ro + bj * HALF + 4) = x1; } } }
	s_nop 1
	v_mov_b32_e32 v120, v164
	v_mov_b32_e32 v121, v165
	v_mov_b32_e32 v122, v166
	v_mov_b32_e32 v123, v167
	s_waitcnt lgkmcnt(0)
	v_lshlrev_b32_e32 v124, 16, v120
	v_and_b32_e32 v125, 0xffff0000, v120
	v_lshlrev_b32_e32 v120, 16, v121
	v_and_b32_e32 v121, 0xffff0000, v121
	v_lshlrev_b32_e32 v126, 16, v122
	v_and_b32_e32 v127, 0xffff0000, v122
	v_lshlrev_b32_e32 v122, 16, v123
	v_and_b32_e32 v123, 0xffff0000, v123
	v_pk_add_f32 v[116:117], v[116:117], v[124:125]
	v_pk_add_f32 v[118:119], v[118:119], v[120:121]
	v_pk_add_f32 v[120:121], v[114:115], v[122:123]
	v_pk_add_f32 v[114:115], v[112:113], v[126:127]
	v_cvt_pk_bf16_f32 v112, v116, v117
	v_lshl_add_u64 v[116:117], v[144:145], 0, s[2:3]
	s_mov_b32 s2, 0x10000
	v_cvt_pk_bf16_f32 v113, v118, v119
	v_add_co_u32_e32 v118, vcc, s2, v144
	v_cvt_pk_bf16_f32 v114, v114, v115
	v_cvt_pk_bf16_f32 v115, v120, v121
	v_addc_co_u32_e32 v119, vcc, 0, v145, vcc
	global_store_dwordx4 v[144:145], v[112:115], off offset:256
	s_waitcnt vmcnt(15)
	s_nop 1
	v_mov_b32_e32 v112, v168
	v_mov_b32_e32 v113, v169
	v_mov_b32_e32 v114, v170
	v_mov_b32_e32 v115, v171
	s_mov_b64 s[2:3], 0x20000
	s_waitcnt lgkmcnt(0)
	v_lshlrev_b32_e32 v120, 16, v112
	v_and_b32_e32 v121, 0xffff0000, v112
	v_lshlrev_b32_e32 v112, 16, v113
	v_and_b32_e32 v113, 0xffff0000, v113
	v_lshlrev_b32_e32 v122, 16, v114
	v_and_b32_e32 v123, 0xffff0000, v114
	v_lshlrev_b32_e32 v114, 16, v115
	v_and_b32_e32 v115, 0xffff0000, v115
	v_pk_add_f32 v[110:111], v[110:111], v[112:113]
	v_pk_add_f32 v[108:109], v[108:109], v[120:121]
	v_pk_add_f32 v[112:113], v[106:107], v[114:115]
	v_pk_add_f32 v[106:107], v[104:105], v[122:123]
	v_cvt_pk_bf16_f32 v104, v108, v109
	v_cvt_pk_bf16_f32 v105, v110, v111
	v_cvt_pk_bf16_f32 v106, v106, v107
	v_cvt_pk_bf16_f32 v107, v112, v113
	global_store_dwordx4 v[118:119], v[104:107], off
	s_waitcnt vmcnt(15)
	s_nop 1
	v_mov_b32_e32 v104, v172
	v_mov_b32_e32 v105, v173
	v_mov_b32_e32 v106, v174
	v_mov_b32_e32 v107, v175
	s_waitcnt lgkmcnt(0)
	v_lshlrev_b32_e32 v108, 16, v104
	v_and_b32_e32 v109, 0xffff0000, v104
	v_lshlrev_b32_e32 v104, 16, v105
	v_and_b32_e32 v105, 0xffff0000, v105
	v_lshlrev_b32_e32 v110, 16, v106
	v_and_b32_e32 v111, 0xffff0000, v106
	v_lshlrev_b32_e32 v106, 16, v107
	v_and_b32_e32 v107, 0xffff0000, v107
	v_pk_add_f32 v[100:101], v[100:101], v[108:109]
	v_pk_add_f32 v[102:103], v[102:103], v[104:105]
	v_pk_add_f32 v[104:105], v[98:99], v[106:107]
	v_pk_add_f32 v[98:99], v[96:97], v[110:111]
	v_cvt_pk_bf16_f32 v96, v100, v101
	v_lshl_add_u64 v[100:101], v[144:145], 0, s[2:3]
	s_mov_b32 s2, 0x20000
	v_cvt_pk_bf16_f32 v97, v102, v103
	v_add_co_u32_e32 v102, vcc, s2, v144
	v_cvt_pk_bf16_f32 v98, v98, v99
	v_cvt_pk_bf16_f32 v99, v104, v105
	v_addc_co_u32_e32 v103, vcc, 0, v145, vcc
	global_store_dwordx4 v[116:117], v[96:99], off offset:256
	s_waitcnt vmcnt(15)
	s_nop 1
	v_mov_b32_e32 v96, v176
	v_mov_b32_e32 v97, v177
	v_mov_b32_e32 v98, v178
	v_mov_b32_e32 v99, v179
	s_mov_b64 s[2:3], 0x30000
	s_waitcnt lgkmcnt(0)
	v_lshlrev_b32_e32 v104, 16, v96
	v_and_b32_e32 v105, 0xffff0000, v96
	v_lshlrev_b32_e32 v96, 16, v97
	v_and_b32_e32 v97, 0xffff0000, v97
	v_lshlrev_b32_e32 v106, 16, v98
	v_and_b32_e32 v107, 0xffff0000, v98
	v_lshlrev_b32_e32 v98, 16, v99
	v_and_b32_e32 v99, 0xffff0000, v99
	v_pk_add_f32 v[94:95], v[94:95], v[96:97]
	v_pk_add_f32 v[92:93], v[92:93], v[104:105]
	v_pk_add_f32 v[96:97], v[90:91], v[98:99]
	v_pk_add_f32 v[90:91], v[88:89], v[106:107]
	v_cvt_pk_bf16_f32 v88, v92, v93
	v_cvt_pk_bf16_f32 v89, v94, v95
	v_cvt_pk_bf16_f32 v90, v90, v91
	v_cvt_pk_bf16_f32 v91, v96, v97
	global_store_dwordx4 v[102:103], v[88:91], off
	s_waitcnt vmcnt(15)
	s_nop 1
	v_mov_b32_e32 v88, v180
	v_mov_b32_e32 v89, v181
	v_mov_b32_e32 v90, v182
	v_mov_b32_e32 v91, v183
	s_waitcnt lgkmcnt(0)
	v_lshlrev_b32_e32 v92, 16, v88
	v_and_b32_e32 v93, 0xffff0000, v88
	v_lshlrev_b32_e32 v88, 16, v89
	v_and_b32_e32 v89, 0xffff0000, v89
	v_lshlrev_b32_e32 v94, 16, v90
	v_and_b32_e32 v95, 0xffff0000, v90
	v_lshlrev_b32_e32 v90, 16, v91
	v_and_b32_e32 v91, 0xffff0000, v91
	v_pk_add_f32 v[86:87], v[86:87], v[88:89]
	v_pk_add_f32 v[84:85], v[84:85], v[92:93]
	v_pk_add_f32 v[88:89], v[82:83], v[90:91]
	v_pk_add_f32 v[82:83], v[80:81], v[94:95]
	v_cvt_pk_bf16_f32 v80, v84, v85
	v_cvt_pk_bf16_f32 v81, v86, v87
	v_cvt_pk_bf16_f32 v82, v82, v83
	v_cvt_pk_bf16_f32 v83, v88, v89
	global_store_dwordx4 v[100:101], v[80:83], off offset:256
	s_nop 1
	v_lshl_add_u64 v[80:81], v[144:145], 0, s[2:3]
	s_mov_b32 s2, 0x30000
	v_add_co_u32_e32 v86, vcc, s2, v144
	s_mov_b64 s[2:3], 0x80000
	s_nop 0
	v_addc_co_u32_e32 v87, vcc, 0, v145, vcc
	s_waitcnt vmcnt(15)
	s_nop 1
	v_mov_b32_e32 v82, v184
	v_mov_b32_e32 v83, v185
	v_mov_b32_e32 v84, v186
	v_mov_b32_e32 v85, v187
	s_waitcnt lgkmcnt(0)
	v_lshlrev_b32_e32 v88, 16, v82
	v_and_b32_e32 v89, 0xffff0000, v82
	v_lshlrev_b32_e32 v82, 16, v83
	v_and_b32_e32 v83, 0xffff0000, v83
	v_lshlrev_b32_e32 v90, 16, v84
	v_and_b32_e32 v91, 0xffff0000, v84
	v_lshlrev_b32_e32 v84, 16, v85
	v_and_b32_e32 v85, 0xffff0000, v85
	v_pk_add_f32 v[78:79], v[78:79], v[82:83]
	v_pk_add_f32 v[76:77], v[76:77], v[88:89]
	v_pk_add_f32 v[82:83], v[74:75], v[84:85]
	v_pk_add_f32 v[74:75], v[72:73], v[90:91]
	v_cvt_pk_bf16_f32 v72, v76, v77
	v_cvt_pk_bf16_f32 v73, v78, v79
	v_cvt_pk_bf16_f32 v74, v74, v75
	v_cvt_pk_bf16_f32 v75, v82, v83
	global_store_dwordx4 v[86:87], v[72:75], off
	s_waitcnt vmcnt(15)
	s_nop 1
	v_mov_b32_e32 v72, v188
	v_mov_b32_e32 v73, v189
	v_mov_b32_e32 v74, v190
	v_mov_b32_e32 v75, v191
	s_waitcnt lgkmcnt(0)
; DI unsigned pack2(float a, float b) { f32x2 v = {a, b}; hwbf16x2 r = __builtin_convertvector(v, hwbf16x2); return __builtin_bit_cast(unsigned, r); }
; DI float bflo(unsigned w) { return __uint_as_float(w << 16); }
; DI float bfhi(unsigned w) { return __uint_as_float(w & 0xffff0000u); }
;     DI void operator()(const f32x4 (&acc)[2][2][4][2], const Unit& u, int wr, int wc, int fr, int fq) const {
;     ...
;         for (int ai = 0; ai < 2; ++ai)
; #pragma unroll
;             for (int m = 0; m < 4; ++m) { const size_t ro = (size_t)(row0 + ai * HALF + m * 16) * D + col0;
; #pragma unroll
;                 for (int bj = 0; bj < 2; ++bj) {
;                     f32x4 x0, x1;
;                     if constexpr (IB) { const u32x4 w = *(const u32x4*)((const bf16_t*)Xin + ro + bj * HALF);
;                         x0 = (f32x4){bflo(w[0]), bfhi(w[0]), bflo(w[1]), bfhi(w[1])}; x1 = (f32x4){bflo(w[2]), bfhi(w[2]), bflo(w[3]), bfhi(w[3])}; }
;                     else { x0 = *(const f32x4*)((const float*)Xin + ro + bj * HALF); x1 = *(const f32x4*)((const float*)Xin + ro + bj * HALF + 4); }
;                     x0 += acc[ai][bj][m][0] * sc[bj][0]; x1 += acc[ai][bj][m][1] * sc[bj][1];
;                     if constexpr (OB) { u32x4 o; o[0] = pack2(x0[0], x0[1]); o[1] = pack2(x0[2], x0[3]); o[2] = pack2(x1[0], x1[1]); o[3] = pack2(x1[2], x1[3]);
;                         *(u32x4*)((bf16_t*)Xout + ro + bj * HALF) = o; }
;                     else { *(f32x4*)((float*)Xout + ro + bj * HALF) = x0; *(f32x4*)((float*)Xout + ro + bj * HALF + 4) = x1; } } }
	v_lshlrev_b32_e32 v76, 16, v72
	v_and_b32_e32 v77, 0xffff0000, v72
	v_lshlrev_b32_e32 v72, 16, v73
	v_and_b32_e32 v73, 0xffff0000, v73
	v_lshlrev_b32_e32 v78, 16, v74
	v_and_b32_e32 v79, 0xffff0000, v74
	v_lshlrev_b32_e32 v74, 16, v75
	v_and_b32_e32 v75, 0xffff0000, v75
	v_pk_add_f32 v[70:71], v[70:71], v[72:73]
	v_pk_add_f32 v[68:69], v[68:69], v[76:77]
	v_pk_add_f32 v[72:73], v[66:67], v[74:75]
	v_pk_add_f32 v[66:67], v[64:65], v[78:79]
	v_cvt_pk_bf16_f32 v64, v68, v69
	v_cvt_pk_bf16_f32 v65, v70, v71
	v_cvt_pk_bf16_f32 v66, v66, v67
	v_cvt_pk_bf16_f32 v67, v72, v73
	global_store_dwordx4 v[80:81], v[64:67], off offset:256
	s_nop 1
	v_lshl_add_u64 v[64:65], v[144:145], 0, s[2:3]
	s_mov_b32 s2, 0x80000
	v_add_co_u32_e32 v70, vcc, s2, v144
	s_mov_b64 s[2:3], 0x90000
	s_nop 0
	v_addc_co_u32_e32 v71, vcc, 0, v145, vcc
	s_waitcnt vmcnt(15)
	s_nop 1
	v_mov_b32_e32 v66, v192
	v_mov_b32_e32 v67, v193
	v_mov_b32_e32 v68, v194
	v_mov_b32_e32 v69, v195
	s_waitcnt lgkmcnt(0)
	v_lshlrev_b32_e32 v72, 16, v66
	v_and_b32_e32 v73, 0xffff0000, v66
	v_lshlrev_b32_e32 v66, 16, v67
	v_and_b32_e32 v67, 0xffff0000, v67
	v_lshlrev_b32_e32 v74, 16, v68
	v_and_b32_e32 v75, 0xffff0000, v68
	v_lshlrev_b32_e32 v68, 16, v69
	v_and_b32_e32 v69, 0xffff0000, v69
	v_pk_add_f32 v[62:63], v[62:63], v[66:67]
	v_pk_add_f32 v[60:61], v[60:61], v[72:73]
	v_pk_add_f32 v[66:67], v[58:59], v[68:69]
	v_pk_add_f32 v[58:59], v[56:57], v[74:75]
	v_cvt_pk_bf16_f32 v56, v60, v61
	v_cvt_pk_bf16_f32 v57, v62, v63
	v_cvt_pk_bf16_f32 v58, v58, v59
	v_cvt_pk_bf16_f32 v59, v66, v67
	global_store_dwordx4 v[70:71], v[56:59], off
	s_waitcnt vmcnt(15)
	s_nop 1
	v_mov_b32_e32 v56, v198
	v_mov_b32_e32 v57, v199
	v_mov_b32_e32 v58, v200
	v_mov_b32_e32 v59, v201
	s_waitcnt lgkmcnt(0)
	v_lshlrev_b32_e32 v60, 16, v56
	v_and_b32_e32 v61, 0xffff0000, v56
	v_lshlrev_b32_e32 v56, 16, v57
	v_and_b32_e32 v57, 0xffff0000, v57
	v_lshlrev_b32_e32 v62, 16, v58
	v_and_b32_e32 v63, 0xffff0000, v58
	v_lshlrev_b32_e32 v58, 16, v59
	v_and_b32_e32 v59, 0xffff0000, v59
	v_pk_add_f32 v[54:55], v[54:55], v[56:57]
	v_pk_add_f32 v[52:53], v[52:53], v[60:61]
	v_pk_add_f32 v[56:57], v[50:51], v[58:59]
	v_pk_add_f32 v[50:51], v[48:49], v[62:63]
	v_cvt_pk_bf16_f32 v48, v52, v53
	v_cvt_pk_bf16_f32 v49, v54, v55
	v_cvt_pk_bf16_f32 v50, v50, v51
	v_cvt_pk_bf16_f32 v51, v56, v57
	global_store_dwordx4 v[64:65], v[48:51], off offset:256
	s_nop 1
	v_lshl_add_u64 v[48:49], v[144:145], 0, s[2:3]
	s_mov_b32 s2, 0x90000
	v_add_co_u32_e32 v54, vcc, s2, v144
	s_mov_b64 s[2:3], 0xa0000
	s_nop 0
	v_addc_co_u32_e32 v55, vcc, 0, v145, vcc
	s_waitcnt vmcnt(15)
	s_nop 1
	v_mov_b32_e32 v50, v202
	v_mov_b32_e32 v51, v203
	v_mov_b32_e32 v52, v204
	v_mov_b32_e32 v53, v205
	s_waitcnt lgkmcnt(0)
	v_lshlrev_b32_e32 v56, 16, v50
	v_and_b32_e32 v57, 0xffff0000, v50
	v_lshlrev_b32_e32 v50, 16, v51
	v_and_b32_e32 v51, 0xffff0000, v51
	v_lshlrev_b32_e32 v58, 16, v52
	v_and_b32_e32 v59, 0xffff0000, v52
	v_lshlrev_b32_e32 v52, 16, v53
	v_and_b32_e32 v53, 0xffff0000, v53
	v_pk_add_f32 v[46:47], v[46:47], v[50:51]
	v_pk_add_f32 v[44:45], v[44:45], v[56:57]
	v_pk_add_f32 v[50:51], v[42:43], v[52:53]
	v_pk_add_f32 v[42:43], v[40:41], v[58:59]
	v_cvt_pk_bf16_f32 v40, v44, v45
	v_cvt_pk_bf16_f32 v41, v46, v47
	v_cvt_pk_bf16_f32 v42, v42, v43
	v_cvt_pk_bf16_f32 v43, v50, v51
	global_store_dwordx4 v[54:55], v[40:43], off
	s_waitcnt vmcnt(15)
	s_nop 1
	v_mov_b32_e32 v40, v206
	v_mov_b32_e32 v41, v207
	v_mov_b32_e32 v42, v208
	v_mov_b32_e32 v43, v209
	s_waitcnt lgkmcnt(0)
; DI unsigned pack2(float a, float b) { f32x2 v = {a, b}; hwbf16x2 r = __builtin_convertvector(v, hwbf16x2); return __builtin_bit_cast(unsigned, r); }
; DI float bflo(unsigned w) { return __uint_as_float(w << 16); }
; DI float bfhi(unsigned w) { return __uint_as_float(w & 0xffff0000u); }
; #define PG8_WAIT_V(n) asm volatile("s_waitcnt vmcnt(" #n ")" ::: "memory")
; #define PG8_BAR __builtin_amdgcn_s_barrier()
;     DI void operator()(const f32x4 (&acc)[2][2][4][2], const Unit& u, int wr, int wc, int fr, int fq) const {
;     ...
;             for (int m = 0; m < 4; ++m) { const size_t ro = (size_t)(row0 + ai * HALF + m * 16) * D + col0;
; #pragma unroll
;                 for (int bj = 0; bj < 2; ++bj) {
;                     f32x4 x0, x1;
;                     if constexpr (IB) { const u32x4 w = *(const u32x4*)((const bf16_t*)Xin + ro + bj * HALF);
;                         x0 = (f32x4){bflo(w[0]), bfhi(w[0]), bflo(w[1]), bfhi(w[1])}; x1 = (f32x4){bflo(w[2]), bfhi(w[2]), bflo(w[3]), bfhi(w[3])}; }
;                     else { x0 = *(const f32x4*)((const float*)Xin + ro + bj * HALF); x1 = *(const f32x4*)((const float*)Xin + ro + bj * HALF + 4); }
;                     x0 += acc[ai][bj][m][0] * sc[bj][0]; x1 += acc[ai][bj][m][1] * sc[bj][1];
;                     if constexpr (OB) { u32x4 o; o[0] = pack2(x0[0], x0[1]); o[1] = pack2(x0[2], x0[3]); o[2] = pack2(x1[0], x1[1]); o[3] = pack2(x1[2], x1[3]);
;                         *(u32x4*)((bf16_t*)Xout + ro + bj * HALF) = o; }
;                     else { *(f32x4*)((float*)Xout + ro + bj * HALF) = x0; *(f32x4*)((float*)Xout + ro + bj * HALF + 4) = x1; } } }
; template <class Map, class Epi>
; DI void gemm_phase(LAS unsigned char* lds, const Map& MP, const Epi& E, const int nM, const int nN, const int K, const int lda, const int ldb) {
;     ...
;         cur = nxt; cA = nA; cB = nB; ++ui;
;     }
;     PG8_WAIT_V(0);
;     if (wr == 0) PG8_BAR;
;     PG8_BAR;
	v_lshlrev_b32_e32 v44, 16, v40
	v_and_b32_e32 v45, 0xffff0000, v40
	v_lshlrev_b32_e32 v40, 16, v41
	v_and_b32_e32 v41, 0xffff0000, v41
	v_lshlrev_b32_e32 v46, 16, v42
	v_and_b32_e32 v47, 0xffff0000, v42
	v_lshlrev_b32_e32 v42, 16, v43
	v_and_b32_e32 v43, 0xffff0000, v43
	v_pk_add_f32 v[38:39], v[38:39], v[40:41]
	v_pk_add_f32 v[36:37], v[36:37], v[44:45]
	v_pk_add_f32 v[40:41], v[34:35], v[42:43]
	v_pk_add_f32 v[34:35], v[32:33], v[46:47]
	v_cvt_pk_bf16_f32 v32, v36, v37
	v_cvt_pk_bf16_f32 v33, v38, v39
	v_cvt_pk_bf16_f32 v34, v34, v35
	v_cvt_pk_bf16_f32 v35, v40, v41
	global_store_dwordx4 v[48:49], v[32:35], off offset:256
	s_nop 1
	v_lshl_add_u64 v[32:33], v[144:145], 0, s[2:3]
	s_mov_b32 s2, 0xa0000
	v_add_co_u32_e32 v38, vcc, s2, v144
	s_mov_b64 s[2:3], 0xb0000
	s_nop 0
	v_addc_co_u32_e32 v39, vcc, 0, v145, vcc
	s_waitcnt vmcnt(15)
	s_nop 1
	v_mov_b32_e32 v34, v210
	v_mov_b32_e32 v35, v211
	v_mov_b32_e32 v36, v212
	v_mov_b32_e32 v37, v213
	s_waitcnt lgkmcnt(0)
	v_lshlrev_b32_e32 v40, 16, v34
	v_and_b32_e32 v41, 0xffff0000, v34
	v_lshlrev_b32_e32 v34, 16, v35
	v_and_b32_e32 v35, 0xffff0000, v35
	v_lshlrev_b32_e32 v42, 16, v36
	v_and_b32_e32 v43, 0xffff0000, v36
	v_lshlrev_b32_e32 v36, 16, v37
	v_and_b32_e32 v37, 0xffff0000, v37
	v_pk_add_f32 v[30:31], v[30:31], v[34:35]
	v_pk_add_f32 v[28:29], v[28:29], v[40:41]
	v_pk_add_f32 v[34:35], v[26:27], v[36:37]
	v_pk_add_f32 v[26:27], v[24:25], v[42:43]
	v_cvt_pk_bf16_f32 v24, v28, v29
	v_cvt_pk_bf16_f32 v25, v30, v31
	v_cvt_pk_bf16_f32 v26, v26, v27
	v_cvt_pk_bf16_f32 v27, v34, v35
	global_store_dwordx4 v[38:39], v[24:27], off
	s_waitcnt vmcnt(15)
	s_nop 1
	v_mov_b32_e32 v24, v214
	v_mov_b32_e32 v25, v215
	v_mov_b32_e32 v26, v216
	v_mov_b32_e32 v27, v217
	s_waitcnt lgkmcnt(0)
	v_lshlrev_b32_e32 v28, 16, v24
	v_and_b32_e32 v29, 0xffff0000, v24
	v_lshlrev_b32_e32 v24, 16, v25
	v_and_b32_e32 v25, 0xffff0000, v25
	v_lshlrev_b32_e32 v30, 16, v26
	v_and_b32_e32 v31, 0xffff0000, v26
	v_lshlrev_b32_e32 v26, 16, v27
	v_and_b32_e32 v27, 0xffff0000, v27
	v_pk_add_f32 v[22:23], v[22:23], v[24:25]
	v_pk_add_f32 v[20:21], v[20:21], v[28:29]
	v_pk_add_f32 v[24:25], v[18:19], v[26:27]
	v_pk_add_f32 v[18:19], v[16:17], v[30:31]
	v_cvt_pk_bf16_f32 v16, v20, v21
	v_cvt_pk_bf16_f32 v17, v22, v23
	v_cvt_pk_bf16_f32 v18, v18, v19
	v_cvt_pk_bf16_f32 v19, v24, v25
	global_store_dwordx4 v[32:33], v[16:19], off offset:256
	s_nop 1
	v_lshl_add_u64 v[16:17], v[144:145], 0, s[2:3]
	s_mov_b32 s2, 0xb0000
	v_add_co_u32_e32 v22, vcc, s2, v144
	s_mov_b32 s2, s44
	s_nop 0
	v_addc_co_u32_e32 v23, vcc, 0, v145, vcc
	s_waitcnt vmcnt(15)
	s_nop 1
	v_mov_b32_e32 v18, v248
	v_mov_b32_e32 v19, v249
	v_mov_b32_e32 v20, v250
	v_mov_b32_e32 v21, v251
	s_and_b64 vcc, exec, s[40:41]
	s_waitcnt lgkmcnt(0)
	v_lshlrev_b32_e32 v24, 16, v18
	v_and_b32_e32 v25, 0xffff0000, v18
	v_lshlrev_b32_e32 v18, 16, v19
	v_and_b32_e32 v19, 0xffff0000, v19
	v_lshlrev_b32_e32 v26, 16, v20
	v_and_b32_e32 v27, 0xffff0000, v20
	v_lshlrev_b32_e32 v20, 16, v21
	v_and_b32_e32 v21, 0xffff0000, v21
	v_pk_add_f32 v[14:15], v[14:15], v[18:19]
	v_pk_add_f32 v[12:13], v[12:13], v[24:25]
	v_pk_add_f32 v[18:19], v[10:11], v[20:21]
	v_pk_add_f32 v[10:11], v[8:9], v[26:27]
	v_cvt_pk_bf16_f32 v8, v12, v13
	v_cvt_pk_bf16_f32 v9, v14, v15
	v_cvt_pk_bf16_f32 v10, v10, v11
	v_cvt_pk_bf16_f32 v11, v18, v19
	global_store_dwordx4 v[22:23], v[8:11], off
	s_waitcnt vmcnt(15)
	s_nop 1
	v_mov_b32_e32 v8, v252
	v_mov_b32_e32 v9, v253
	v_mov_b32_e32 v10, v254
	v_mov_b32_e32 v11, v255
	s_waitcnt lgkmcnt(0)
	v_lshlrev_b32_e32 v12, 16, v8
	v_and_b32_e32 v13, 0xffff0000, v8
	v_lshlrev_b32_e32 v8, 16, v9
	v_and_b32_e32 v9, 0xffff0000, v9
	v_lshlrev_b32_e32 v14, 16, v10
	v_and_b32_e32 v15, 0xffff0000, v10
	v_lshlrev_b32_e32 v10, 16, v11
	v_and_b32_e32 v11, 0xffff0000, v11
	v_pk_add_f32 v[6:7], v[6:7], v[8:9]
	v_pk_add_f32 v[4:5], v[4:5], v[12:13]
	v_pk_add_f32 v[8:9], v[2:3], v[10:11]
	v_pk_add_f32 v[2:3], v[0:1], v[14:15]
	v_cvt_pk_bf16_f32 v0, v4, v5
	v_cvt_pk_bf16_f32 v1, v6, v7
	v_cvt_pk_bf16_f32 v2, v2, v3
	v_cvt_pk_bf16_f32 v3, v8, v9
	global_store_dwordx4 v[16:17], v[0:3], off offset:256
	s_cbranch_vccz .LBB1_1761
	s_waitcnt vmcnt(0)
	s_cmpk_gt_u32 s17, 0xff
	s_cbranch_scc1 .LBB1_1768
	s_barrier

; #define PG8_STAGE(bufoff, gbase, voff) do { _Pragma("unroll") for (int _i = 0; _i < 2; ++_i) \
;         __builtin_amdgcn_global_load_lds((const unsigned*)((const char*)(gbase) + (voff)[_i]), (LAS unsigned*)(lds + (bufoff) + ldsw + _i * 8192), 16, 0, 0); } while (0)
; #define PG8_LDA(dst, b, h) do { _Pragma("unroll") for (int m = 0; m < 4; ++m) _Pragma("unroll") for (int k = 0; k < 2; ++k) dst[m][k] = *(const LAS bf16x8*)(lds + PG8_SA(b, h) + aoff + m * 2048 + k * 1024); } while (0)
; #define PG8_LDB(dst, b, h) do { _Pragma("unroll") for (int n = 0; n < 2; ++n) _Pragma("unroll") for (int k = 0; k < 2; ++k) dst[n][k] = *(const LAS bf16x8*)(lds + PG8_SB(b, h) + boff + n * 2048 + k * 1024); } while (0)
; #define PG8_MMA(ai, bj, At, Bt) do { __builtin_amdgcn_s_setprio(1); _Pragma("unroll") for (int m = 0; m < 4; ++m) _Pragma("unroll") for (int n = 0; n < 2; ++n) _Pragma("unroll") for (int k = 0; k < 2; ++k) \
;         acc[ai][bj][m][n] = __builtin_amdgcn_mfma_f32_16x16x32_bf16(Bt[n][k], At[m][k], acc[ai][bj][m][n], 0, 0, 0); __builtin_amdgcn_s_setprio(0); } while (0)
; #define PG8_WAIT_V(n) asm volatile("s_waitcnt vmcnt(" #n ")" ::: "memory")
; #define PG8_WAIT_L(n) asm volatile("s_waitcnt lgkmcnt(" #n ")" ::: "memory")
; #define PG8_BAR __builtin_amdgcn_s_barrier()
; #define PG8_SCHED __builtin_amdgcn_sched_barrier(0)
; template <class Map, class Epi>
; DI void gemm_phase(LAS unsigned char* lds, const Map& MP, const Epi& E, const int nM, const int nN, const int K, const int lda, const int ldb) {
;     ...
;             PG8_LDB(B0, 0, 0); PG8_SCHED; PG8_LDA(At, 0, 0); PG8_STAGE(PG8_SA(1, 1), a1 + hstepA, voffA);
;             PG8_WAIT_L(8); PG8_BAR; PG8_WAIT_L(0); PG8_MMA(0, 0, At, B0); PG8_BAR; PG8_SCHED;
;             PG8_LDB(B1, 0, 1); PG8_STAGE(PG8_SB(0, 0), b2, voffB);
;             PG8_BAR; PG8_WAIT_L(0); PG8_MMA(0, 1, At, B1); PG8_BAR;
;             PG8_LDA(At, 0, 1); PG8_STAGE(PG8_SA(0, 0), a2, voffA);
;             PG8_BAR; PG8_WAIT_L(0); PG8_MMA(1, 0, At, B0); PG8_BAR; PG8_SCHED;
;             PG8_STAGE(PG8_SB(0, 1), b2 + hstepB, voffB);
;             PG8_WAIT_V(6); PG8_BAR; PG8_MMA(1, 1, At, B1); PG8_BAR;
.LBB1_1908:
	s_add_u32 s28, s42, 0xfff80080
	s_addc_u32 s29, s43, -1
	s_cmp_eq_u32 s3, 28
	s_cselect_b32 s47, s23, s29
	s_cselect_b32 s46, s58, s28
	s_cselect_b32 s29, s21, vcc_hi
	s_cselect_b32 s28, s59, vcc_lo
	s_add_i32 m0, s38, 0xc000
	ds_read_b128 v[96:99], v190
	ds_read_b128 v[100:103], v190 offset:1024
	ds_read_b128 v[108:111], v190 offset:2048
	ds_read_b128 v[112:115], v190 offset:3072
	ds_read_b128 v[160:163], v190 offset:4096
	ds_read_b128 v[164:167], v190 offset:5120
	ds_read_b128 v[198:201], v190 offset:6144
	ds_read_b128 v[202:205], v190 offset:7168
	global_load_lds_dwordx4 v178, s[42:43]
	s_add_i32 m0, s38, 0xe000
	s_nop 0
	global_load_lds_dwordx4 v176, s[42:43]
	s_waitcnt lgkmcnt(7)
	s_setprio 1
	s_barrier
	v_mfma_f32_16x16x32_bf16 v[148:151], v[80:83], v[96:99], v[148:151]
	v_mfma_f32_16x16x32_bf16 v[144:147], v[88:91], v[96:99], v[144:147]
	s_waitcnt lgkmcnt(5)
	v_mfma_f32_16x16x32_bf16 v[136:139], v[80:83], v[108:111], v[136:139]
	v_mfma_f32_16x16x32_bf16 v[128:131], v[88:91], v[108:111], v[128:131]
	s_waitcnt lgkmcnt(3)
	v_mfma_f32_16x16x32_bf16 v[120:123], v[80:83], v[160:163], v[120:123]
	v_mfma_f32_16x16x32_bf16 v[104:107], v[88:91], v[160:163], v[104:107]
	s_waitcnt lgkmcnt(1)
	v_mfma_f32_16x16x32_bf16 v[76:79], v[80:83], v[198:201], v[76:79]
	v_mfma_f32_16x16x32_bf16 v[72:75], v[88:91], v[198:201], v[72:75]
	v_mfma_f32_16x16x32_bf16 v[148:151], v[84:87], v[100:103], v[148:151]
	v_mfma_f32_16x16x32_bf16 v[144:147], v[92:95], v[100:103], v[144:147]
	v_mfma_f32_16x16x32_bf16 v[136:139], v[84:87], v[112:115], v[136:139]
	v_mfma_f32_16x16x32_bf16 v[128:131], v[92:95], v[112:115], v[128:131]
	v_mfma_f32_16x16x32_bf16 v[120:123], v[84:87], v[164:167], v[120:123]
	v_mfma_f32_16x16x32_bf16 v[104:107], v[92:95], v[164:167], v[104:107]
	s_waitcnt lgkmcnt(0)
	v_mfma_f32_16x16x32_bf16 v[76:79], v[84:87], v[202:205], v[76:79]
	v_mfma_f32_16x16x32_bf16 v[72:75], v[92:95], v[202:205], v[72:75]
	s_barrier
	s_setprio 0
	s_add_i32 s68, s2, s54
	v_lshl_add_u64 v[184:185], s[28:29], 0, v[172:173]
	s_mov_b32 m0, s68
	ds_read_b128 v[206:209], v191
	ds_read_b128 v[210:213], v191 offset:1024
	ds_read_b128 v[214:217], v191 offset:2048
	ds_read_b128 v[218:221], v191 offset:3072
	global_load_lds_dwordx4 v[184:185], off
	v_lshl_add_u64 v[194:195], s[28:29], 0, v[168:169]
	s_add_i32 m0, s68, 0x2000
	s_nop 0
	global_load_lds_dwordx4 v[194:195], off
	s_waitcnt lgkmcnt(3)
	s_setprio 1
	s_barrier
	v_mfma_f32_16x16x32_bf16 v[156:159], v[206:209], v[96:99], v[156:159]
	s_waitcnt lgkmcnt(1)
	v_mfma_f32_16x16x32_bf16 v[96:99], v[214:217], v[96:99], v[152:155]
	v_mfma_f32_16x16x32_bf16 v[156:159], v[210:213], v[100:103], v[156:159]
	s_waitcnt lgkmcnt(0)
	v_mfma_f32_16x16x32_bf16 v[96:99], v[218:221], v[100:103], v[96:99]
	v_mfma_f32_16x16x32_bf16 v[100:103], v[206:209], v[108:111], v[140:143]
	v_mfma_f32_16x16x32_bf16 v[108:111], v[214:217], v[108:111], v[132:135]
	v_mfma_f32_16x16x32_bf16 v[116:119], v[214:217], v[160:163], v[116:119]
	v_mfma_f32_16x16x32_bf16 v[68:71], v[206:209], v[198:201], v[68:71]
	v_mfma_f32_16x16x32_bf16 v[64:67], v[214:217], v[198:201], v[64:67]
	s_mov_b32 m0, s38
	v_mfma_f32_16x16x32_bf16 v[100:103], v[210:213], v[112:115], v[100:103]
	v_lshl_add_u64 v[226:227], s[46:47], 0, v[174:175]
	v_mfma_f32_16x16x32_bf16 v[108:111], v[218:221], v[112:115], v[108:111]
	v_mfma_f32_16x16x32_bf16 v[112:115], v[206:209], v[160:163], v[124:127]
	v_mfma_f32_16x16x32_bf16 v[116:119], v[218:221], v[164:167], v[116:119]
	v_mfma_f32_16x16x32_bf16 v[68:71], v[210:213], v[202:205], v[68:71]
	v_mfma_f32_16x16x32_bf16 v[64:67], v[218:221], v[202:205], v[64:67]
	v_mfma_f32_16x16x32_bf16 v[112:115], v[210:213], v[164:167], v[112:115]
	s_barrier
	s_setprio 0
	ds_read_b128 v[124:127], v190 offset:16384
	ds_read_b128 v[132:135], v190 offset:17408
	ds_read_b128 v[140:143], v190 offset:18432
	ds_read_b128 v[152:155], v190 offset:19456
	ds_read_b128 v[160:163], v190 offset:20480
	ds_read_b128 v[164:167], v190 offset:21504
	ds_read_b128 v[198:201], v190 offset:22528
	ds_read_b128 v[202:205], v190 offset:23552
	global_load_lds_dwordx4 v[226:227], off
	v_lshl_add_u64 v[234:235], s[46:47], 0, v[170:171]
	s_mov_b32 m0, s39
	s_nop 0
	global_load_lds_dwordx4 v[234:235], off
	s_waitcnt vmcnt(10) lgkmcnt(7)
	s_setprio 1
	s_barrier
	v_mfma_f32_16x16x32_bf16 v[60:63], v[80:83], v[124:127], v[60:63]
	v_mfma_f32_16x16x32_bf16 v[48:51], v[88:91], v[124:127], v[48:51]
	s_waitcnt lgkmcnt(5)
	v_mfma_f32_16x16x32_bf16 v[40:43], v[80:83], v[140:143], v[40:43]
	v_mfma_f32_16x16x32_bf16 v[32:35], v[88:91], v[140:143], v[32:35]
	s_waitcnt lgkmcnt(3)
	v_mfma_f32_16x16x32_bf16 v[24:27], v[80:83], v[160:163], v[24:27]
	v_mfma_f32_16x16x32_bf16 v[16:19], v[88:91], v[160:163], v[16:19]
	s_waitcnt lgkmcnt(1)
	v_mfma_f32_16x16x32_bf16 v[12:15], v[80:83], v[198:201], v[12:15]
	v_mfma_f32_16x16x32_bf16 v[8:11], v[88:91], v[198:201], v[8:11]
	v_mfma_f32_16x16x32_bf16 v[60:63], v[84:87], v[132:135], v[60:63]
	v_mfma_f32_16x16x32_bf16 v[48:51], v[92:95], v[132:135], v[48:51]
	v_mfma_f32_16x16x32_bf16 v[40:43], v[84:87], v[152:155], v[40:43]
	v_mfma_f32_16x16x32_bf16 v[32:35], v[92:95], v[152:155], v[32:35]
	v_mfma_f32_16x16x32_bf16 v[24:27], v[84:87], v[164:167], v[24:27]
	v_mfma_f32_16x16x32_bf16 v[16:19], v[92:95], v[164:167], v[16:19]
	s_waitcnt lgkmcnt(0)
	v_mfma_f32_16x16x32_bf16 v[12:15], v[84:87], v[202:205], v[12:15]
	v_mfma_f32_16x16x32_bf16 v[8:11], v[92:95], v[202:205], v[8:11]
	s_barrier
	s_setprio 0
	s_add_u32 s68, s28, 0x80000
	s_addc_u32 s69, s29, 0
	s_add_i32 s70, s31, s54
	s_mov_b32 m0, s70
	s_nop 0
	global_load_lds_dwordx4 v172, s[68:69]
	s_add_i32 m0, s70, 0x2000
	s_nop 0
	global_load_lds_dwordx4 v168, s[68:69]
	s_waitcnt vmcnt(6)
	s_setprio 1
	s_barrier
; #define PG8_STAGE(bufoff, gbase, voff) do { _Pragma("unroll") for (int _i = 0; _i < 2; ++_i) \
;         __builtin_amdgcn_global_load_lds((const unsigned*)((const char*)(gbase) + (voff)[_i]), (LAS unsigned*)(lds + (bufoff) + ldsw + _i * 8192), 16, 0, 0); } while (0)
; #define PG8_LDA(dst, b, h) do { _Pragma("unroll") for (int m = 0; m < 4; ++m) _Pragma("unroll") for (int k = 0; k < 2; ++k) dst[m][k] = *(const LAS bf16x8*)(lds + PG8_SA(b, h) + aoff + m * 2048 + k * 1024); } while (0)
; #define PG8_LDB(dst, b, h) do { _Pragma("unroll") for (int n = 0; n < 2; ++n) _Pragma("unroll") for (int k = 0; k < 2; ++k) dst[n][k] = *(const LAS bf16x8*)(lds + PG8_SB(b, h) + boff + n * 2048 + k * 1024); } while (0)
; #define PG8_MMA(ai, bj, At, Bt) do { __builtin_amdgcn_s_setprio(1); _Pragma("unroll") for (int m = 0; m < 4; ++m) _Pragma("unroll") for (int n = 0; n < 2; ++n) _Pragma("unroll") for (int k = 0; k < 2; ++k) \
;         acc[ai][bj][m][n] = __builtin_amdgcn_mfma_f32_16x16x32_bf16(Bt[n][k], At[m][k], acc[ai][bj][m][n], 0, 0, 0); __builtin_amdgcn_s_setprio(0); } while (0)
; #define PG8_WAIT_V(n) asm volatile("s_waitcnt vmcnt(" #n ")" ::: "memory")
; #define PG8_WAIT_L(n) asm volatile("s_waitcnt lgkmcnt(" #n ")" ::: "memory")
; #define PG8_BAR __builtin_amdgcn_s_barrier()
; #define PG8_SCHED __builtin_amdgcn_sched_barrier(0)
; template <class Map, class Epi>
; DI void gemm_phase(LAS unsigned char* lds, const Map& MP, const Epi& E, const int nM, const int nN, const int K, const int lda, const int ldb) {
;     ...
;             PG8_WAIT_V(6); PG8_BAR; PG8_MMA(1, 1, At, B1); PG8_BAR;
;             PG8_LDB(B0, 1, 0); PG8_SCHED; PG8_LDA(At, 1, 0); PG8_STAGE(PG8_SA(0, 1), a2 + hstepA, voffA);
;             PG8_WAIT_L(8); PG8_BAR; PG8_WAIT_L(0); PG8_MMA(0, 0, At, B0); PG8_BAR; PG8_SCHED;
;             PG8_LDB(B1, 1, 1); PG8_STAGE(PG8_SB(1, 0), b3, voffB);
;             PG8_BAR; PG8_WAIT_L(0); PG8_MMA(0, 1, At, B1); PG8_BAR;
;             PG8_LDA(At, 1, 1); PG8_STAGE(PG8_SA(1, 0), a3, voffA);
;             PG8_BAR; PG8_WAIT_L(0); PG8_MMA(1, 0, At, B0); PG8_BAR; PG8_SCHED;
	v_mfma_f32_16x16x32_bf16 v[56:59], v[206:209], v[124:127], v[56:59]
	v_mfma_f32_16x16x32_bf16 v[52:55], v[214:217], v[124:127], v[52:55]
	s_add_i32 s68, 0, 0x18000
	v_add_u32_e32 v92, s68, v188
	ds_read_b128 v[80:83], v92
	v_mfma_f32_16x16x32_bf16 v[44:47], v[206:209], v[140:143], v[44:47]
	v_mfma_f32_16x16x32_bf16 v[36:39], v[214:217], v[140:143], v[36:39]
	ds_read_b128 v[84:87], v92 offset:1024
	v_mfma_f32_16x16x32_bf16 v[28:31], v[206:209], v[160:163], v[28:31]
	v_mfma_f32_16x16x32_bf16 v[20:23], v[214:217], v[160:163], v[20:23]
	ds_read_b128 v[88:91], v92 offset:2048
	v_mfma_f32_16x16x32_bf16 v[4:7], v[206:209], v[198:201], v[4:7]
	v_mfma_f32_16x16x32_bf16 v[0:3], v[214:217], v[198:201], v[0:3]
	ds_read_b128 v[92:95], v92 offset:3072
	v_mfma_f32_16x16x32_bf16 v[56:59], v[210:213], v[132:135], v[56:59]
	v_mfma_f32_16x16x32_bf16 v[52:55], v[218:221], v[132:135], v[52:55]
	v_mfma_f32_16x16x32_bf16 v[44:47], v[210:213], v[152:155], v[44:47]
	v_mfma_f32_16x16x32_bf16 v[36:39], v[218:221], v[152:155], v[36:39]
	v_mfma_f32_16x16x32_bf16 v[28:31], v[210:213], v[164:167], v[28:31]
	v_mfma_f32_16x16x32_bf16 v[20:23], v[218:221], v[164:167], v[20:23]
	v_mfma_f32_16x16x32_bf16 v[4:7], v[210:213], v[202:205], v[4:7]
	v_mfma_f32_16x16x32_bf16 v[0:3], v[218:221], v[202:205], v[0:3]
	s_barrier
	s_setprio 0
	s_add_u32 s46, s46, 0x80000
	s_addc_u32 s47, s47, 0
	s_mov_b32 m0, s56
	ds_read_b128 v[124:127], v190 offset:32768
	ds_read_b128 v[132:135], v190 offset:33792
	ds_read_b128 v[160:163], v190 offset:34816
	ds_read_b128 v[164:167], v190 offset:35840
	ds_read_b128 v[198:201], v190 offset:36864
	ds_read_b128 v[202:205], v190 offset:37888
	ds_read_b128 v[206:209], v190 offset:38912
	ds_read_b128 v[210:213], v190 offset:39936
	global_load_lds_dwordx4 v174, s[46:47]
	s_mov_b32 m0, s57
	s_nop 0
	global_load_lds_dwordx4 v170, s[46:47]
	s_waitcnt lgkmcnt(7)
	s_setprio 1
	s_barrier
	v_mfma_f32_16x16x32_bf16 v[140:143], v[80:83], v[124:127], v[148:151]
	s_waitcnt lgkmcnt(6)
	v_mfma_f32_16x16x32_bf16 v[148:151], v[84:87], v[132:135], v[140:143]
	v_mfma_f32_16x16x32_bf16 v[140:143], v[88:91], v[124:127], v[144:147]
	s_waitcnt lgkmcnt(5)
	v_mfma_f32_16x16x32_bf16 v[136:139], v[80:83], v[160:163], v[136:139]
	v_mfma_f32_16x16x32_bf16 v[128:131], v[88:91], v[160:163], v[128:131]
	s_waitcnt lgkmcnt(3)
	v_mfma_f32_16x16x32_bf16 v[120:123], v[80:83], v[198:201], v[120:123]
	v_mfma_f32_16x16x32_bf16 v[104:107], v[88:91], v[198:201], v[104:107]
	s_waitcnt lgkmcnt(1)
	v_mfma_f32_16x16x32_bf16 v[76:79], v[80:83], v[206:209], v[76:79]
	v_mfma_f32_16x16x32_bf16 v[72:75], v[88:91], v[206:209], v[72:75]
	v_mfma_f32_16x16x32_bf16 v[144:147], v[92:95], v[132:135], v[140:143]
	v_mfma_f32_16x16x32_bf16 v[136:139], v[84:87], v[164:167], v[136:139]
	v_mfma_f32_16x16x32_bf16 v[128:131], v[92:95], v[164:167], v[128:131]
	v_mfma_f32_16x16x32_bf16 v[120:123], v[84:87], v[202:205], v[120:123]
	v_mfma_f32_16x16x32_bf16 v[104:107], v[92:95], v[202:205], v[104:107]
	s_waitcnt lgkmcnt(0)
	v_mfma_f32_16x16x32_bf16 v[76:79], v[84:87], v[210:213], v[76:79]
	v_mfma_f32_16x16x32_bf16 v[72:75], v[92:95], v[210:213], v[72:75]
	s_barrier
	s_setprio 0
	s_add_i32 s46, 0, 0x1c000
	v_add_u32_e32 v140, s46, v188
	s_add_i32 s47, s68, s54
	ds_read_b128 v[214:217], v140
	ds_read_b128 v[218:221], v140 offset:1024
	ds_read_b128 v[222:225], v140 offset:2048
	ds_read_b128 v[230:233], v140 offset:3072
	v_lshl_add_u64 v[140:141], v[184:185], 0, s[14:15]
	s_mov_b32 m0, s47
	s_nop 0
	global_load_lds_dwordx4 v[140:141], off
	v_lshl_add_u64 v[140:141], v[194:195], 0, s[14:15]
	s_add_i32 m0, s47, 0x2000
	s_nop 0
	global_load_lds_dwordx4 v[140:141], off
	s_waitcnt lgkmcnt(1)
	s_setprio 1
	s_barrier
	v_mfma_f32_16x16x32_bf16 v[96:99], v[222:225], v[124:127], v[96:99]
	v_mfma_f32_16x16x32_bf16 v[140:143], v[214:217], v[124:127], v[156:159]
	s_waitcnt lgkmcnt(0)
	v_mfma_f32_16x16x32_bf16 v[152:155], v[230:233], v[132:135], v[96:99]
	v_mfma_f32_16x16x32_bf16 v[96:99], v[214:217], v[160:163], v[100:103]
	v_mfma_f32_16x16x32_bf16 v[156:159], v[218:221], v[132:135], v[140:143]
	v_mfma_f32_16x16x32_bf16 v[140:143], v[218:221], v[164:167], v[96:99]
	v_mfma_f32_16x16x32_bf16 v[96:99], v[222:225], v[160:163], v[108:111]
	v_mfma_f32_16x16x32_bf16 v[132:135], v[230:233], v[164:167], v[96:99]
	v_mfma_f32_16x16x32_bf16 v[96:99], v[214:217], v[198:201], v[112:115]
	s_mov_b32 m0, s63
	v_mfma_f32_16x16x32_bf16 v[124:127], v[218:221], v[202:205], v[96:99]
	v_lshl_add_u64 v[184:185], v[226:227], 0, s[14:15]
	v_mfma_f32_16x16x32_bf16 v[96:99], v[222:225], v[198:201], v[116:119]
	v_mfma_f32_16x16x32_bf16 v[68:71], v[214:217], v[206:209], v[68:71]
	v_mfma_f32_16x16x32_bf16 v[64:67], v[222:225], v[206:209], v[64:67]
	v_mfma_f32_16x16x32_bf16 v[116:119], v[230:233], v[202:205], v[96:99]
	v_mfma_f32_16x16x32_bf16 v[68:71], v[218:221], v[210:213], v[68:71]
	v_mfma_f32_16x16x32_bf16 v[64:67], v[230:233], v[210:213], v[64:67]
	s_barrier
	s_setprio 0
	ds_read_b128 v[96:99], v190 offset:49152
	ds_read_b128 v[100:103], v190 offset:50176
	ds_read_b128 v[108:111], v190 offset:51200
	ds_read_b128 v[112:115], v190 offset:52224
	ds_read_b128 v[160:163], v190 offset:53248
	ds_read_b128 v[164:167], v190 offset:54272
	ds_read_b128 v[198:201], v190 offset:55296
	ds_read_b128 v[202:205], v190 offset:56320
	global_load_lds_dwordx4 v[184:185], off
	v_lshl_add_u64 v[184:185], v[234:235], 0, s[14:15]
	s_mov_b32 m0, s66
	s_nop 0
	global_load_lds_dwordx4 v[184:185], off
	s_waitcnt vmcnt(10) lgkmcnt(7)
	s_setprio 1
	s_barrier
; #define PG8_STAGE(bufoff, gbase, voff) do { _Pragma("unroll") for (int _i = 0; _i < 2; ++_i) \
;         __builtin_amdgcn_global_load_lds((const unsigned*)((const char*)(gbase) + (voff)[_i]), (LAS unsigned*)(lds + (bufoff) + ldsw + _i * 8192), 16, 0, 0); } while (0)
; #define PG8_MMA(ai, bj, At, Bt) do { __builtin_amdgcn_s_setprio(1); _Pragma("unroll") for (int m = 0; m < 4; ++m) _Pragma("unroll") for (int n = 0; n < 2; ++n) _Pragma("unroll") for (int k = 0; k < 2; ++k) \
;         acc[ai][bj][m][n] = __builtin_amdgcn_mfma_f32_16x16x32_bf16(Bt[n][k], At[m][k], acc[ai][bj][m][n], 0, 0, 0); __builtin_amdgcn_s_setprio(0); } while (0)
; #define PG8_WAIT_V(n) asm volatile("s_waitcnt vmcnt(" #n ")" ::: "memory")
; #define PG8_WAIT_L(n) asm volatile("s_waitcnt lgkmcnt(" #n ")" ::: "memory")
; #define PG8_BAR __builtin_amdgcn_s_barrier()
; #define PG8_SCHED __builtin_amdgcn_sched_barrier(0)
; template <class Map, class Epi>
; DI void gemm_phase(LAS unsigned char* lds, const Map& MP, const Epi& E, const int nM, const int nN, const int K, const int lda, const int ldb) {
;     ...
;             PG8_BAR; PG8_WAIT_L(0); PG8_MMA(1, 0, At, B0); PG8_BAR; PG8_SCHED;
;             PG8_STAGE(PG8_SB(1, 1), b3 + hstepB, voffB);
;             PG8_WAIT_V(6); PG8_BAR; PG8_MMA(1, 1, At, B1); PG8_BAR;
;         }
	v_mfma_f32_16x16x32_bf16 v[60:63], v[80:83], v[96:99], v[60:63]
	v_mfma_f32_16x16x32_bf16 v[48:51], v[88:91], v[96:99], v[48:51]
	s_waitcnt lgkmcnt(5)
	v_mfma_f32_16x16x32_bf16 v[40:43], v[80:83], v[108:111], v[40:43]
	v_mfma_f32_16x16x32_bf16 v[32:35], v[88:91], v[108:111], v[32:35]
	s_waitcnt lgkmcnt(3)
	v_mfma_f32_16x16x32_bf16 v[24:27], v[80:83], v[160:163], v[24:27]
	v_mfma_f32_16x16x32_bf16 v[16:19], v[88:91], v[160:163], v[16:19]
	s_waitcnt lgkmcnt(1)
	v_mfma_f32_16x16x32_bf16 v[12:15], v[80:83], v[198:201], v[12:15]
	v_mfma_f32_16x16x32_bf16 v[8:11], v[88:91], v[198:201], v[8:11]
	v_mfma_f32_16x16x32_bf16 v[60:63], v[84:87], v[100:103], v[60:63]
	v_mfma_f32_16x16x32_bf16 v[48:51], v[92:95], v[100:103], v[48:51]
	v_mfma_f32_16x16x32_bf16 v[40:43], v[84:87], v[112:115], v[40:43]
	v_mfma_f32_16x16x32_bf16 v[32:35], v[92:95], v[112:115], v[32:35]
	v_mfma_f32_16x16x32_bf16 v[24:27], v[84:87], v[164:167], v[24:27]
	v_mfma_f32_16x16x32_bf16 v[16:19], v[92:95], v[164:167], v[16:19]
	s_waitcnt lgkmcnt(0)
	v_mfma_f32_16x16x32_bf16 v[12:15], v[84:87], v[202:205], v[12:15]
	v_mfma_f32_16x16x32_bf16 v[8:11], v[92:95], v[202:205], v[8:11]
	s_barrier
	s_setprio 0
	s_add_u32 s28, s28, 0x80080
	s_addc_u32 s29, s29, 0
	s_add_i32 s46, s46, s54
	s_mov_b32 m0, s46
	s_nop 0
	global_load_lds_dwordx4 v172, s[28:29]
	s_add_i32 m0, s46, 0x2000
	s_nop 0
	global_load_lds_dwordx4 v168, s[28:29]
	s_waitcnt vmcnt(6)
	s_setprio 1
	s_barrier
	v_mfma_f32_16x16x32_bf16 v[56:59], v[214:217], v[96:99], v[56:59]
	v_mfma_f32_16x16x32_bf16 v[52:55], v[222:225], v[96:99], v[52:55]
	ds_read_b128 v[80:83], v189
	v_mfma_f32_16x16x32_bf16 v[44:47], v[214:217], v[108:111], v[44:47]
	v_mfma_f32_16x16x32_bf16 v[36:39], v[222:225], v[108:111], v[36:39]
	ds_read_b128 v[84:87], v189 offset:1024
	v_mfma_f32_16x16x32_bf16 v[28:31], v[214:217], v[160:163], v[28:31]
	v_mfma_f32_16x16x32_bf16 v[20:23], v[222:225], v[160:163], v[20:23]
	ds_read_b128 v[88:91], v189 offset:2048
	v_mfma_f32_16x16x32_bf16 v[4:7], v[214:217], v[198:201], v[4:7]
	v_mfma_f32_16x16x32_bf16 v[0:3], v[222:225], v[198:201], v[0:3]
	ds_read_b128 v[92:95], v189 offset:3072
	v_mfma_f32_16x16x32_bf16 v[56:59], v[218:221], v[100:103], v[56:59]
	s_add_i32 s3, s3, 2
	v_mfma_f32_16x16x32_bf16 v[52:55], v[230:233], v[100:103], v[52:55]
	s_add_u32 vcc_lo, vcc_lo, 0x100
	s_addc_u32 vcc_hi, vcc_hi, 0
	v_mfma_f32_16x16x32_bf16 v[44:47], v[218:221], v[112:115], v[44:47]
	s_add_u32 s42, s42, 0x100
	s_addc_u32 s43, s43, 0
	v_mfma_f32_16x16x32_bf16 v[36:39], v[230:233], v[112:115], v[36:39]
	s_cmp_gt_u32 s3, 29
	v_mfma_f32_16x16x32_bf16 v[28:31], v[218:221], v[164:167], v[28:31]
	v_mfma_f32_16x16x32_bf16 v[20:23], v[230:233], v[164:167], v[20:23]
	v_mfma_f32_16x16x32_bf16 v[4:7], v[218:221], v[202:205], v[4:7]
	v_mfma_f32_16x16x32_bf16 v[0:3], v[230:233], v[202:205], v[0:3]
	s_barrier
	s_setprio 0
	s_cbranch_scc0 .LBB1_1908
; DI float silu_mul(float g, float v) { return g * v * __builtin_amdgcn_rcpf(1.0f + __builtin_amdgcn_exp2f(-LOG2E * g)); }
;     DI void operator()(const f32x4 (&acc)[2][2][4][2], const Unit& u, int wr, int wc, int fr, int fq) const {
;         const int row0 = u.pm * BM + wr * 64 + fr, ch0 = u.pn * 128 + wc * 32 + 8 * fq;
;         f32x4 w0[2], w1[2], w2[2], bb[2];
; #pragma unroll
;         for (int n = 0; n < 2; ++n) { w0[n] = *(const f32x4*)(cw + ch0 + 4 * n); w1[n] = *(const f32x4*)(cw + DFF + ch0 + 4 * n); w2[n] = *(const f32x4*)(cw + 2 * DFF + ch0 + 4 * n); bb[n] = *(const f32x4*)(cb + ch0 + 4 * n); }
; #pragma unroll
;         for (int ai = 0; ai < 2; ++ai)
; #pragma unroll
;             for (int m = 0; m < 4; ++m) {
;                 const bool efirst = (m == 0) && (fr == 0), elast = (m == 3) && (fr == 15);
;                 const int row = row0 + ai * HALF + m * 16;
;                 f32x4 gc[2];
; #pragma unroll
;                 for (int n = 0; n < 2; ++n) {
;                     const f32x4 g = acc[ai][0][m][n];
;                     const f32x4 gprev = acc[ai][0][m > 0 ? m - 1 : 0][n], gnext = acc[ai][0][m < 3 ? m + 1 : 3][n];
;                     f32x4 up, dn;
; #pragma unroll
;                     for (int e = 0; e < 4; ++e) {
;                         const float pu = (m > 0 && fr == 15) ? gprev[e] : g[e];
;                         const float pd = (m < 3 && fr == 0) ? gnext[e] : g[e];
;                         up[e] = dpp_ror1(pu); dn[e] = dpp_ror15(pd);
;                     }
;                     if (efirst) up = (f32x4){0.f, 0.f, 0.f, 0.f};
;                     if (elast) dn = (f32x4){0.f, 0.f, 0.f, 0.f};
;                     gc[n] = w0[n] * up + w1[n] * g + w2[n] * dn + bb[n];
;                 }
;                 if (efirst || elast) {
;                     const size_t eo = (size_t)((row >> 6) * 2 + (elast ? 1 : 0)) * DFF + ch0;
; #pragma unroll
;                     for (int n = 0; n < 2; ++n) { *(f32x4*)(EP + eo + 4 * n) = gc[n]; *(f32x4*)(ER + eo + 4 * n) = acc[ai][0][m][n]; *(f32x4*)(EV + eo + 4 * n) = acc[ai][1][m][n]; }
;                 } else {
;                     const f32x4 v0 = acc[ai][1][m][0], v1 = acc[ai][1][m][1];
;                     u32x4 o;
;                     o[0] = pack2(silu_mul(gc[0][0], v0[0]), silu_mul(gc[0][1], v0[1])); o[1] = pack2(silu_mul(gc[0][2], v0[2]), silu_mul(gc[0][3], v0[3]));
	s_waitcnt lgkmcnt(0)
	s_lshl_b32 s21, s45, 7
	v_mov_b32_e32 v194, v186
	v_mov_b32_e32 v80, v187
	s_or_b32 s21, s21, s62
	v_mov_b32_e32 v160, 0
	v_lshl_add_u32 v184, v80, 3, s21
	v_ashrrev_i32_e32 v185, 31, v184
	v_lshlrev_b64 v[80:81], 2, v[184:185]
	v_lshl_add_u64 v[84:85], s[4:5], 0, v[80:81]
	v_lshl_add_u64 v[88:89], s[16:17], 0, v[80:81]
	v_lshl_add_u64 v[92:93], s[18:19], 0, v[80:81]
	v_lshl_add_u64 v[112:113], s[6:7], 0, v[80:81]
	global_load_dwordx4 v[80:83], v[84:85], off offset:16
	global_load_dwordx4 v[96:99], v[84:85], off
	s_nop 0
	global_load_dwordx4 v[84:87], v[88:89], off offset:16
	global_load_dwordx4 v[100:103], v[88:89], off
	s_nop 0
	global_load_dwordx4 v[88:91], v[92:93], off offset:16
	global_load_dwordx4 v[108:111], v[92:93], off
	s_nop 0
	global_load_dwordx4 v[92:95], v[112:113], off offset:16
	s_nop 0
	global_load_dwordx4 v[112:115], v[112:113], off
	v_cmp_eq_u32_e32 vcc, 0, v194
	v_mov_b32_e32 v164, 0
	v_mov_b32_e32 v195, 0
	v_cndmask_b32_e32 v161, v148, v136, vcc
	v_cndmask_b32_e32 v162, v149, v137, vcc
	v_cndmask_b32_e32 v163, v150, v138, vcc
	v_mov_b32_dpp v160, v161 row_ror:15 row_mask:0xf bank_mask:0xf
	v_mov_b32_e32 v161, 0
	v_mov_b32_e32 v166, 0
	v_mov_b32_e32 v167, 0
	v_mov_b32_dpp v161, v162 row_ror:15 row_mask:0xf bank_mask:0xf
	v_mov_b32_e32 v162, 0
	v_mov_b32_dpp v164, v150 row_ror:1 row_mask:0xf bank_mask:0xf
	v_cndmask_b32_e32 v165, v151, v139, vcc
	v_mov_b32_dpp v162, v163 row_ror:15 row_mask:0xf bank_mask:0xf
	v_mov_b32_dpp v195, v151 row_ror:1 row_mask:0xf bank_mask:0xf
	v_mov_b32_e32 v163, 0
	v_mov_b32_dpp v166, v148 row_ror:1 row_mask:0xf bank_mask:0xf
	v_mov_b32_dpp v167, v149 row_ror:1 row_mask:0xf bank_mask:0xf
	v_mov_b32_dpp v163, v165 row_ror:15 row_mask:0xf bank_mask:0xf
	v_cndmask_b32_e64 v165, v195, 0, vcc
	v_cndmask_b32_e64 v164, v164, 0, vcc
	v_cndmask_b32_e64 v167, v167, 0, vcc
	v_cndmask_b32_e64 v166, v166, 0, vcc
	v_mov_b32_e32 v195, 0
	v_mov_b32_e32 v196, 0
	v_mov_b32_e32 v198, 0
	v_mov_b32_e32 v200, 0
	v_mov_b32_dpp v195, v144 row_ror:1 row_mask:0xf bank_mask:0xf
	v_mov_b32_dpp v196, v145 row_ror:1 row_mask:0xf bank_mask:0xf
	v_mov_b32_dpp v198, v146 row_ror:1 row_mask:0xf bank_mask:0xf
	v_cndmask_b32_e32 v199, v147, v131, vcc
	v_mov_b32_dpp v200, v147 row_ror:1 row_mask:0xf bank_mask:0xf
	v_cndmask_b32_e64 v198, v198, 0, vcc
	v_cndmask_b32_e64 v201, v196, 0, vcc
	s_lshl_b32 s3, s44, 8
	s_add_i32 s3, s3, s49
	v_add_u32_e32 v193, s3, v194
	v_cmp_ne_u32_e64 s[46:47], 0, v194
	s_waitcnt vmcnt(0)
	v_pk_mul_f32 v[164:165], v[98:99], v[164:165]
	v_pk_mul_f32 v[166:167], v[96:97], v[166:167]
	v_pk_fma_f32 v[164:165], v[150:151], v[102:103], v[164:165]
	v_pk_fma_f32 v[166:167], v[148:149], v[100:101], v[166:167]
	v_pk_fma_f32 v[162:163], v[110:111], v[162:163], v[164:165]
	v_cndmask_b32_e32 v165, v144, v128, vcc
	v_mov_b32_e32 v164, 0
	v_pk_fma_f32 v[160:161], v[108:109], v[160:161], v[166:167]
	v_cndmask_b32_e32 v166, v145, v129, vcc
	v_mov_b32_dpp v164, v165 row_ror:15 row_mask:0xf bank_mask:0xf
	v_mov_b32_e32 v165, 0
	v_cndmask_b32_e32 v167, v146, v130, vcc
	v_pk_add_f32 v[162:163], v[114:115], v[162:163]
	v_mov_b32_dpp v165, v166 row_ror:15 row_mask:0xf bank_mask:0xf
	v_mov_b32_e32 v166, 0
	v_pk_add_f32 v[160:161], v[112:113], v[160:161]
	s_nop 0
	v_mov_b32_dpp v166, v167 row_ror:15 row_mask:0xf bank_mask:0xf
	v_mov_b32_e32 v167, 0
	s_nop 1
	v_mov_b32_dpp v167, v199 row_ror:15 row_mask:0xf bank_mask:0xf
	v_cndmask_b32_e64 v199, v200, 0, vcc
	v_cndmask_b32_e64 v200, v195, 0, vcc
	v_pk_mul_f32 v[200:201], v[80:81], v[200:201]
	v_pk_mul_f32 v[198:199], v[82:83], v[198:199]
	v_pk_fma_f32 v[200:201], v[144:145], v[84:85], v[200:201]
	v_pk_fma_f32 v[198:199], v[146:147], v[86:87], v[198:199]
	v_pk_fma_f32 v[164:165], v[88:89], v[164:165], v[200:201]
	v_pk_fma_f32 v[166:167], v[90:91], v[166:167], v[198:199]
	v_pk_add_f32 v[164:165], v[92:93], v[164:165]
	v_pk_add_f32 v[166:167], v[94:95], v[166:167]
	s_and_saveexec_b64 s[28:29], s[46:47]
	s_xor_b64 s[28:29], exec, s[28:29]
	s_cbranch_execz .LBB1_1911
	v_mul_f32_e32 v195, 0xbfb8aa3b, v160
	v_exp_f32_e32 v195, v195
	v_mul_f32_e32 v196, 0xbfb8aa3b, v161
	v_exp_f32_e32 v196, v196
	v_pk_mul_f32 v[160:161], v[156:157], v[160:161]
	v_add_f32_e32 v195, 1.0, v195
	v_rcp_f32_e32 v198, v195
	v_add_f32_e32 v196, 1.0, v196
	v_mul_f32_e32 v195, 0xbfb8aa3b, v162
	v_rcp_f32_e32 v199, v196
	v_exp_f32_e32 v195, v195
	v_mul_f32_e32 v196, 0xbfb8aa3b, v163
	v_exp_f32_e32 v196, v196
	v_pk_mul_f32 v[160:161], v[160:161], v[198:199]
	v_add_f32_e32 v195, 1.0, v195
	v_rcp_f32_e32 v200, v195
	v_add_f32_e32 v195, 1.0, v196
	v_rcp_f32_e32 v201, v195
	v_cvt_pk_bf16_f32 v160, v160, v161
	v_mul_f32_e32 v161, 0xbfb8aa3b, v164
	v_exp_f32_e32 v195, v161
	v_mul_f32_e32 v161, 0xbfb8aa3b, v165
	v_exp_f32_e32 v196, v161
	v_pk_mul_f32 v[162:163], v[158:159], v[162:163]
	v_pk_mul_f32 v[164:165], v[152:153], v[164:165]
	v_pk_mul_f32 v[162:163], v[162:163], v[200:201]
	s_nop 0
	v_cvt_pk_bf16_f32 v161, v162, v163
	v_add_f32_e32 v162, 1.0, v195
	v_mul_f32_e32 v195, 0xbfb8aa3b, v166
	v_add_f32_e32 v163, 1.0, v196
	v_exp_f32_e32 v195, v195
	v_mul_f32_e32 v196, 0xbfb8aa3b, v167
	v_exp_f32_e32 v196, v196
	v_rcp_f32_e32 v162, v162
	v_add_f32_e32 v195, 1.0, v195
	v_rcp_f32_e32 v198, v195
	v_add_f32_e32 v195, 1.0, v196
	v_rcp_f32_e32 v163, v163
	v_rcp_f32_e32 v199, v195
	v_pk_mul_f32 v[166:167], v[154:155], v[166:167]
	v_pk_mul_f32 v[162:163], v[164:165], v[162:163]
	v_pk_mul_f32 v[164:165], v[166:167], v[198:199]
	v_cvt_pk_bf16_f32 v162, v162, v163
	v_cvt_pk_bf16_f32 v163, v164, v165
	v_mov_b64_e32 v[164:165], s[52:53]
	v_mad_i64_i32 v[164:165], s[42:43], v193, s60, v[164:165]
	v_lshl_add_u64 v[164:165], v[184:185], 1, v[164:165]
	global_store_dwordx4 v[164:165], v[160:163], off

; #define PG8_STAGE(bufoff, gbase, voff) do { _Pragma("unroll") for (int _i = 0; _i < 2; ++_i) \
;         __builtin_amdgcn_global_load_lds((const unsigned*)((const char*)(gbase) + (voff)[_i]), (LAS unsigned*)(lds + (bufoff) + ldsw + _i * 8192), 16, 0, 0); } while (0)
; #define PG8_LDA(dst, b, h) do { _Pragma("unroll") for (int m = 0; m < 4; ++m) _Pragma("unroll") for (int k = 0; k < 2; ++k) dst[m][k] = *(const LAS bf16x8*)(lds + PG8_SA(b, h) + aoff + m * 2048 + k * 1024); } while (0)
; #define PG8_LDB(dst, b, h) do { _Pragma("unroll") for (int n = 0; n < 2; ++n) _Pragma("unroll") for (int k = 0; k < 2; ++k) dst[n][k] = *(const LAS bf16x8*)(lds + PG8_SB(b, h) + boff + n * 2048 + k * 1024); } while (0)
; #define PG8_MMA(ai, bj, At, Bt) do { __builtin_amdgcn_s_setprio(1); _Pragma("unroll") for (int m = 0; m < 4; ++m) _Pragma("unroll") for (int n = 0; n < 2; ++n) _Pragma("unroll") for (int k = 0; k < 2; ++k) \
;         acc[ai][bj][m][n] = __builtin_amdgcn_mfma_f32_16x16x32_bf16(Bt[n][k], At[m][k], acc[ai][bj][m][n], 0, 0, 0); __builtin_amdgcn_s_setprio(0); } while (0)
; #define PG8_WAIT_V(n) asm volatile("s_waitcnt vmcnt(" #n ")" ::: "memory")
; #define PG8_WAIT_L(n) asm volatile("s_waitcnt lgkmcnt(" #n ")" ::: "memory")
; #define PG8_BAR __builtin_amdgcn_s_barrier()
; #define PG8_SCHED __builtin_amdgcn_sched_barrier(0)
; template <class Map, class Epi>
; DI void gemm_phase(LAS unsigned char* lds, const Map& MP, const Epi& E, const int nM, const int nN, const int K, const int lda, const int ldb) {
;     ...
;             PG8_LDB(B0, 0, 0); PG8_SCHED; PG8_LDA(At, 0, 0); PG8_STAGE(PG8_SA(1, 1), a1 + hstepA, voffA);
;             PG8_WAIT_L(8); PG8_BAR; PG8_WAIT_L(0); PG8_MMA(0, 0, At, B0); PG8_BAR; PG8_SCHED;
;             PG8_LDB(B1, 0, 1); PG8_STAGE(PG8_SB(0, 0), b2, voffB);
;             PG8_BAR; PG8_WAIT_L(0); PG8_MMA(0, 1, At, B1); PG8_BAR;
;             PG8_LDA(At, 0, 1); PG8_STAGE(PG8_SA(0, 0), a2, voffA);
;             PG8_BAR; PG8_WAIT_L(0); PG8_MMA(1, 0, At, B0); PG8_BAR; PG8_SCHED;
;             PG8_STAGE(PG8_SB(0, 1), b2 + hstepB, voffB);
;             PG8_WAIT_V(6); PG8_BAR; PG8_MMA(1, 1, At, B1); PG8_BAR;
.LBB1_2078:
	s_add_u32 s10, s8, 0x100
	s_addc_u32 s11, s9, 0
	s_cmpk_eq_i32 s3, 0x54
	s_cselect_b32 s15, s43, s11
	s_cselect_b32 s14, s42, s10
	s_cselect_b32 s13, s7, s44
	s_cselect_b32 s12, s6, s39
	s_add_i32 m0, s24, 0xc000
	ds_read_b128 v[168:171], v150
	ds_read_b128 v[172:175], v150 offset:1024
	ds_read_b128 v[176:179], v150 offset:2048
	ds_read_b128 v[180:183], v150 offset:3072
	ds_read_b128 v[184:187], v150 offset:4096
	ds_read_b128 v[188:191], v150 offset:5120
	ds_read_b128 v[192:195], v150 offset:6144
	ds_read_b128 v[198:201], v150 offset:7168
	global_load_lds_dwordx4 v138, s[8:9]
	s_add_i32 m0, s24, 0xe000
	s_nop 0
	global_load_lds_dwordx4 v136, s[8:9]
	s_waitcnt lgkmcnt(7)
	s_setprio 1
	s_barrier
	v_mfma_f32_16x16x32_bf16 v[124:127], v[152:155], v[168:171], v[124:127]
	v_mfma_f32_16x16x32_bf16 v[120:123], v[160:163], v[168:171], v[120:123]
	s_waitcnt lgkmcnt(5)
	v_mfma_f32_16x16x32_bf16 v[108:111], v[152:155], v[176:179], v[108:111]
	v_mfma_f32_16x16x32_bf16 v[104:107], v[160:163], v[176:179], v[104:107]
	s_waitcnt lgkmcnt(3)
	v_mfma_f32_16x16x32_bf16 v[92:95], v[152:155], v[184:187], v[92:95]
	v_mfma_f32_16x16x32_bf16 v[88:91], v[160:163], v[184:187], v[88:91]
	s_waitcnt lgkmcnt(1)
	v_mfma_f32_16x16x32_bf16 v[76:79], v[152:155], v[192:195], v[76:79]
	v_mfma_f32_16x16x32_bf16 v[72:75], v[160:163], v[192:195], v[72:75]
	v_mfma_f32_16x16x32_bf16 v[124:127], v[156:159], v[172:175], v[124:127]
	v_mfma_f32_16x16x32_bf16 v[120:123], v[164:167], v[172:175], v[120:123]
	v_mfma_f32_16x16x32_bf16 v[108:111], v[156:159], v[180:183], v[108:111]
	v_mfma_f32_16x16x32_bf16 v[104:107], v[164:167], v[180:183], v[104:107]
	v_mfma_f32_16x16x32_bf16 v[92:95], v[156:159], v[188:191], v[92:95]
	v_mfma_f32_16x16x32_bf16 v[88:91], v[164:167], v[188:191], v[88:91]
	s_waitcnt lgkmcnt(0)
	v_mfma_f32_16x16x32_bf16 v[76:79], v[156:159], v[198:201], v[76:79]
	v_mfma_f32_16x16x32_bf16 v[72:75], v[164:167], v[198:201], v[72:75]
	s_barrier
	s_setprio 0
	s_add_i32 s8, s35, s22
	v_lshl_add_u64 v[144:145], s[12:13], 0, v[132:133]
	s_mov_b32 m0, s8
	ds_read_b128 v[202:205], v151
	ds_read_b128 v[206:209], v151 offset:1024
	ds_read_b128 v[210:213], v151 offset:2048
	ds_read_b128 v[214:217], v151 offset:3072
	global_load_lds_dwordx4 v[144:145], off
	v_lshl_add_u64 v[218:219], s[12:13], 0, v[128:129]
	s_add_i32 m0, s8, 0x2000
	s_nop 0
	global_load_lds_dwordx4 v[218:219], off
	s_waitcnt lgkmcnt(3)
	s_setprio 1
	s_barrier
	v_mfma_f32_16x16x32_bf16 v[116:119], v[202:205], v[168:171], v[116:119]
	s_waitcnt lgkmcnt(1)
	v_mfma_f32_16x16x32_bf16 v[112:115], v[210:213], v[168:171], v[112:115]
	v_mfma_f32_16x16x32_bf16 v[100:103], v[202:205], v[176:179], v[100:103]
	v_mfma_f32_16x16x32_bf16 v[96:99], v[210:213], v[176:179], v[96:99]
	v_mfma_f32_16x16x32_bf16 v[84:87], v[202:205], v[184:187], v[84:87]
	v_mfma_f32_16x16x32_bf16 v[80:83], v[210:213], v[184:187], v[80:83]
	v_mfma_f32_16x16x32_bf16 v[68:71], v[202:205], v[192:195], v[68:71]
	v_mfma_f32_16x16x32_bf16 v[64:67], v[210:213], v[192:195], v[64:67]
	v_mfma_f32_16x16x32_bf16 v[116:119], v[206:209], v[172:175], v[116:119]
	s_mov_b32 m0, s24
	s_waitcnt lgkmcnt(0)
	v_mfma_f32_16x16x32_bf16 v[112:115], v[214:217], v[172:175], v[112:115]
	v_lshl_add_u64 v[220:221], s[14:15], 0, v[134:135]
	v_mfma_f32_16x16x32_bf16 v[100:103], v[206:209], v[180:183], v[100:103]
	v_mfma_f32_16x16x32_bf16 v[96:99], v[214:217], v[180:183], v[96:99]
	v_mfma_f32_16x16x32_bf16 v[84:87], v[206:209], v[188:191], v[84:87]
	v_mfma_f32_16x16x32_bf16 v[80:83], v[214:217], v[188:191], v[80:83]
	v_mfma_f32_16x16x32_bf16 v[68:71], v[206:209], v[198:201], v[68:71]
	v_mfma_f32_16x16x32_bf16 v[64:67], v[214:217], v[198:201], v[64:67]
	s_barrier
	s_setprio 0
	ds_read_b128 v[168:171], v150 offset:16384
	ds_read_b128 v[172:175], v150 offset:17408
	ds_read_b128 v[176:179], v150 offset:18432
	ds_read_b128 v[180:183], v150 offset:19456
	ds_read_b128 v[184:187], v150 offset:20480
	ds_read_b128 v[188:191], v150 offset:21504
	ds_read_b128 v[192:195], v150 offset:22528
	ds_read_b128 v[198:201], v150 offset:23552
	global_load_lds_dwordx4 v[220:221], off
	v_lshl_add_u64 v[222:223], s[14:15], 0, v[130:131]
	s_mov_b32 m0, s25
	s_nop 0
	global_load_lds_dwordx4 v[222:223], off
	s_waitcnt vmcnt(10) lgkmcnt(7)
	s_setprio 1
	s_barrier
	v_mfma_f32_16x16x32_bf16 v[60:63], v[152:155], v[168:171], v[60:63]
	v_mfma_f32_16x16x32_bf16 v[56:59], v[160:163], v[168:171], v[56:59]
	s_waitcnt lgkmcnt(5)
	v_mfma_f32_16x16x32_bf16 v[44:47], v[152:155], v[176:179], v[44:47]
	v_mfma_f32_16x16x32_bf16 v[40:43], v[160:163], v[176:179], v[40:43]
	s_waitcnt lgkmcnt(3)
	v_mfma_f32_16x16x32_bf16 v[28:31], v[152:155], v[184:187], v[28:31]
	v_mfma_f32_16x16x32_bf16 v[24:27], v[160:163], v[184:187], v[24:27]
	s_waitcnt lgkmcnt(1)
	v_mfma_f32_16x16x32_bf16 v[12:15], v[152:155], v[192:195], v[12:15]
	v_mfma_f32_16x16x32_bf16 v[8:11], v[160:163], v[192:195], v[8:11]
	v_mfma_f32_16x16x32_bf16 v[60:63], v[156:159], v[172:175], v[60:63]
	v_mfma_f32_16x16x32_bf16 v[56:59], v[164:167], v[172:175], v[56:59]
	v_mfma_f32_16x16x32_bf16 v[44:47], v[156:159], v[180:183], v[44:47]
	v_mfma_f32_16x16x32_bf16 v[40:43], v[164:167], v[180:183], v[40:43]
	v_mfma_f32_16x16x32_bf16 v[28:31], v[156:159], v[188:191], v[28:31]
	v_mfma_f32_16x16x32_bf16 v[24:27], v[164:167], v[188:191], v[24:27]
	s_waitcnt lgkmcnt(0)
	v_mfma_f32_16x16x32_bf16 v[12:15], v[156:159], v[198:201], v[12:15]
	v_mfma_f32_16x16x32_bf16 v[8:11], v[164:167], v[198:201], v[8:11]
	s_barrier
	s_setprio 0
	s_add_u32 s8, s12, 0x160000
	s_addc_u32 s9, s13, 0
	s_add_i32 s45, s36, s22
	s_mov_b32 m0, s45
	s_nop 0
	global_load_lds_dwordx4 v132, s[8:9]
	s_add_i32 m0, s45, 0x2000
	s_nop 0
	global_load_lds_dwordx4 v128, s[8:9]
	s_waitcnt vmcnt(6)
	s_setprio 1
	s_barrier
; #define PG8_STAGE(bufoff, gbase, voff) do { _Pragma("unroll") for (int _i = 0; _i < 2; ++_i) \
;         __builtin_amdgcn_global_load_lds((const unsigned*)((const char*)(gbase) + (voff)[_i]), (LAS unsigned*)(lds + (bufoff) + ldsw + _i * 8192), 16, 0, 0); } while (0)
; #define PG8_LDA(dst, b, h) do { _Pragma("unroll") for (int m = 0; m < 4; ++m) _Pragma("unroll") for (int k = 0; k < 2; ++k) dst[m][k] = *(const LAS bf16x8*)(lds + PG8_SA(b, h) + aoff + m * 2048 + k * 1024); } while (0)
; #define PG8_LDB(dst, b, h) do { _Pragma("unroll") for (int n = 0; n < 2; ++n) _Pragma("unroll") for (int k = 0; k < 2; ++k) dst[n][k] = *(const LAS bf16x8*)(lds + PG8_SB(b, h) + boff + n * 2048 + k * 1024); } while (0)
; #define PG8_MMA(ai, bj, At, Bt) do { __builtin_amdgcn_s_setprio(1); _Pragma("unroll") for (int m = 0; m < 4; ++m) _Pragma("unroll") for (int n = 0; n < 2; ++n) _Pragma("unroll") for (int k = 0; k < 2; ++k) \
;         acc[ai][bj][m][n] = __builtin_amdgcn_mfma_f32_16x16x32_bf16(Bt[n][k], At[m][k], acc[ai][bj][m][n], 0, 0, 0); __builtin_amdgcn_s_setprio(0); } while (0)
; #define PG8_WAIT_V(n) asm volatile("s_waitcnt vmcnt(" #n ")" ::: "memory")
; #define PG8_WAIT_L(n) asm volatile("s_waitcnt lgkmcnt(" #n ")" ::: "memory")
; #define PG8_BAR __builtin_amdgcn_s_barrier()
; #define PG8_SCHED __builtin_amdgcn_sched_barrier(0)
; template <class Map, class Epi>
; DI void gemm_phase(LAS unsigned char* lds, const Map& MP, const Epi& E, const int nM, const int nN, const int K, const int lda, const int ldb) {
;     ...
;             PG8_WAIT_V(6); PG8_BAR; PG8_MMA(1, 1, At, B1); PG8_BAR;
;             PG8_LDB(B0, 1, 0); PG8_SCHED; PG8_LDA(At, 1, 0); PG8_STAGE(PG8_SA(0, 1), a2 + hstepA, voffA);
;             PG8_WAIT_L(8); PG8_BAR; PG8_WAIT_L(0); PG8_MMA(0, 0, At, B0); PG8_BAR; PG8_SCHED;
;             PG8_LDB(B1, 1, 1); PG8_STAGE(PG8_SB(1, 0), b3, voffB);
;             PG8_BAR; PG8_WAIT_L(0); PG8_MMA(0, 1, At, B1); PG8_BAR;
;             PG8_LDA(At, 1, 1); PG8_STAGE(PG8_SA(1, 0), a3, voffA);
;             PG8_BAR; PG8_WAIT_L(0); PG8_MMA(1, 0, At, B0); PG8_BAR; PG8_SCHED;
	v_mfma_f32_16x16x32_bf16 v[52:55], v[202:205], v[168:171], v[52:55]
	v_mfma_f32_16x16x32_bf16 v[48:51], v[210:213], v[168:171], v[48:51]
	s_add_i32 s45, 0, 0x18000
	v_add_u32_e32 v164, s45, v148
	ds_read_b128 v[152:155], v164
	v_mfma_f32_16x16x32_bf16 v[36:39], v[202:205], v[176:179], v[36:39]
	v_mfma_f32_16x16x32_bf16 v[32:35], v[210:213], v[176:179], v[32:35]
	ds_read_b128 v[156:159], v164 offset:1024
	v_mfma_f32_16x16x32_bf16 v[20:23], v[202:205], v[184:187], v[20:23]
	v_mfma_f32_16x16x32_bf16 v[16:19], v[210:213], v[184:187], v[16:19]
	ds_read_b128 v[160:163], v164 offset:2048
	v_mfma_f32_16x16x32_bf16 v[4:7], v[202:205], v[192:195], v[4:7]
	v_mfma_f32_16x16x32_bf16 v[0:3], v[210:213], v[192:195], v[0:3]
	ds_read_b128 v[164:167], v164 offset:3072
	v_mfma_f32_16x16x32_bf16 v[52:55], v[206:209], v[172:175], v[52:55]
	v_mfma_f32_16x16x32_bf16 v[48:51], v[214:217], v[172:175], v[48:51]
	v_mfma_f32_16x16x32_bf16 v[36:39], v[206:209], v[180:183], v[36:39]
	v_mfma_f32_16x16x32_bf16 v[32:35], v[214:217], v[180:183], v[32:35]
	v_mfma_f32_16x16x32_bf16 v[20:23], v[206:209], v[188:191], v[20:23]
	v_mfma_f32_16x16x32_bf16 v[16:19], v[214:217], v[188:191], v[16:19]
	v_mfma_f32_16x16x32_bf16 v[4:7], v[206:209], v[198:201], v[4:7]
	v_mfma_f32_16x16x32_bf16 v[0:3], v[214:217], v[198:201], v[0:3]
	s_barrier
	s_setprio 0
	s_add_u32 s8, s14, 0x160000
	s_addc_u32 s9, s15, 0
	s_mov_b32 m0, s26
	ds_read_b128 v[168:171], v150 offset:32768
	ds_read_b128 v[172:175], v150 offset:33792
	ds_read_b128 v[176:179], v150 offset:34816
	ds_read_b128 v[180:183], v150 offset:35840
	ds_read_b128 v[184:187], v150 offset:36864
	ds_read_b128 v[188:191], v150 offset:37888
	ds_read_b128 v[192:195], v150 offset:38912
	ds_read_b128 v[198:201], v150 offset:39936
	global_load_lds_dwordx4 v134, s[8:9]
	s_mov_b32 m0, s27
	s_nop 0
	global_load_lds_dwordx4 v130, s[8:9]
	s_waitcnt lgkmcnt(7)
	s_setprio 1
	s_barrier
	v_mfma_f32_16x16x32_bf16 v[124:127], v[152:155], v[168:171], v[124:127]
	v_mfma_f32_16x16x32_bf16 v[120:123], v[160:163], v[168:171], v[120:123]
	s_waitcnt lgkmcnt(5)
	v_mfma_f32_16x16x32_bf16 v[108:111], v[152:155], v[176:179], v[108:111]
	v_mfma_f32_16x16x32_bf16 v[104:107], v[160:163], v[176:179], v[104:107]
	s_waitcnt lgkmcnt(3)
	v_mfma_f32_16x16x32_bf16 v[92:95], v[152:155], v[184:187], v[92:95]
	v_mfma_f32_16x16x32_bf16 v[88:91], v[160:163], v[184:187], v[88:91]
	s_waitcnt lgkmcnt(1)
	v_mfma_f32_16x16x32_bf16 v[76:79], v[152:155], v[192:195], v[76:79]
	v_mfma_f32_16x16x32_bf16 v[72:75], v[160:163], v[192:195], v[72:75]
	v_mfma_f32_16x16x32_bf16 v[124:127], v[156:159], v[172:175], v[124:127]
	v_mfma_f32_16x16x32_bf16 v[120:123], v[164:167], v[172:175], v[120:123]
	v_mfma_f32_16x16x32_bf16 v[108:111], v[156:159], v[180:183], v[108:111]
	v_mfma_f32_16x16x32_bf16 v[104:107], v[164:167], v[180:183], v[104:107]
	v_mfma_f32_16x16x32_bf16 v[92:95], v[156:159], v[188:191], v[92:95]
	v_mfma_f32_16x16x32_bf16 v[88:91], v[164:167], v[188:191], v[88:91]
	s_waitcnt lgkmcnt(0)
	v_mfma_f32_16x16x32_bf16 v[76:79], v[156:159], v[198:201], v[76:79]
	v_mfma_f32_16x16x32_bf16 v[72:75], v[164:167], v[198:201], v[72:75]
	s_barrier
	s_setprio 0
	s_add_i32 s14, 0, 0x1c000
	s_add_i32 s8, s45, s22
	v_add_u32_e32 v196, s14, v148
	v_lshl_add_u64 v[144:145], v[144:145], 0, s[46:47]
	s_mov_b32 m0, s8
	ds_read_b128 v[202:205], v196
	ds_read_b128 v[206:209], v196 offset:1024
	ds_read_b128 v[210:213], v196 offset:2048
	ds_read_b128 v[214:217], v196 offset:3072
	global_load_lds_dwordx4 v[144:145], off
	v_lshl_add_u64 v[144:145], v[218:219], 0, s[46:47]
	s_add_i32 m0, s8, 0x2000
	s_nop 0
	global_load_lds_dwordx4 v[144:145], off
	s_waitcnt lgkmcnt(3)
	s_setprio 1
	s_barrier
	v_mfma_f32_16x16x32_bf16 v[116:119], v[202:205], v[168:171], v[116:119]
	s_waitcnt lgkmcnt(1)
	v_mfma_f32_16x16x32_bf16 v[112:115], v[210:213], v[168:171], v[112:115]
	v_mfma_f32_16x16x32_bf16 v[100:103], v[202:205], v[176:179], v[100:103]
	v_mfma_f32_16x16x32_bf16 v[96:99], v[210:213], v[176:179], v[96:99]
	v_mfma_f32_16x16x32_bf16 v[84:87], v[202:205], v[184:187], v[84:87]
	v_mfma_f32_16x16x32_bf16 v[80:83], v[210:213], v[184:187], v[80:83]
	v_mfma_f32_16x16x32_bf16 v[68:71], v[202:205], v[192:195], v[68:71]
	v_mfma_f32_16x16x32_bf16 v[64:67], v[210:213], v[192:195], v[64:67]
	v_mfma_f32_16x16x32_bf16 v[116:119], v[206:209], v[172:175], v[116:119]
	s_mov_b32 m0, s30
	s_waitcnt lgkmcnt(0)
	v_mfma_f32_16x16x32_bf16 v[112:115], v[214:217], v[172:175], v[112:115]
	v_lshl_add_u64 v[144:145], v[220:221], 0, s[46:47]
	v_mfma_f32_16x16x32_bf16 v[100:103], v[206:209], v[180:183], v[100:103]
	v_mfma_f32_16x16x32_bf16 v[96:99], v[214:217], v[180:183], v[96:99]
	v_mfma_f32_16x16x32_bf16 v[84:87], v[206:209], v[188:191], v[84:87]
	v_mfma_f32_16x16x32_bf16 v[80:83], v[214:217], v[188:191], v[80:83]
	v_mfma_f32_16x16x32_bf16 v[68:71], v[206:209], v[198:201], v[68:71]
	v_mfma_f32_16x16x32_bf16 v[64:67], v[214:217], v[198:201], v[64:67]
	s_barrier
	s_setprio 0
	ds_read_b128 v[168:171], v150 offset:49152
	ds_read_b128 v[172:175], v150 offset:50176
	ds_read_b128 v[176:179], v150 offset:51200
	ds_read_b128 v[180:183], v150 offset:52224
	ds_read_b128 v[184:187], v150 offset:53248
	ds_read_b128 v[188:191], v150 offset:54272
	ds_read_b128 v[192:195], v150 offset:55296
	ds_read_b128 v[198:201], v150 offset:56320
	global_load_lds_dwordx4 v[144:145], off
	v_lshl_add_u64 v[144:145], v[222:223], 0, s[46:47]
	s_mov_b32 m0, s31
	s_nop 0
	global_load_lds_dwordx4 v[144:145], off
	s_waitcnt vmcnt(10) lgkmcnt(7)
	s_setprio 1
	s_barrier
; DI float bflo(unsigned w) { return __uint_as_float(w << 16); }
; DI float bfhi(unsigned w) { return __uint_as_float(w & 0xffff0000u); }
;     DI void operator()(const f32x4 (&acc)[2][2][4][2], const Unit& u, int wr, int wc, int fr, int fq) const {
;     ...
;             for (int m = 0; m < 4; ++m) { const size_t ro = (size_t)(row0 + ai * HALF + m * 16) * D + col0;
; #pragma unroll
;                 for (int bj = 0; bj < 2; ++bj) {
;                     f32x4 x0, x1;
;                     if constexpr (IB) { const u32x4 w = *(const u32x4*)((const bf16_t*)Xin + ro + bj * HALF);
;                         x0 = (f32x4){bflo(w[0]), bfhi(w[0]), bflo(w[1]), bfhi(w[1])}; x1 = (f32x4){bflo(w[2]), bfhi(w[2]), bflo(w[3]), bfhi(w[3])}; }
;                     else { x0 = *(const f32x4*)((const float*)Xin + ro + bj * HALF); x1 = *(const f32x4*)((const float*)Xin + ro + bj * HALF + 4); }
;                     x0 += acc[ai][bj][m][0] * sc[bj][0]; x1 += acc[ai][bj][m][1] * sc[bj][1];
; template <class Map, class Epi>
; DI void gemm_phase(LAS unsigned char* lds, const Map& MP, const Epi& E, const int nM, const int nN, const int K, const int lda, const int ldb) {
;     ...
;             PG8_LDB(B0, 0, 0); PG8_SCHED; PG8_LDA(At, 0, 0); PG8_STAGE(PG8_SA(1, 1), a1 + hstepA, voffA);
;             PG8_WAIT_L(8); PG8_BAR; PG8_WAIT_L(0); PG8_MMA(0, 0, At, B0); PG8_BAR; PG8_SCHED;
;             PG8_LDB(B1, 0, 1); PG8_STAGE(PG8_SB(0, 0), b2, voffB);
;             PG8_BAR; PG8_WAIT_L(0); PG8_MMA(0, 1, At, B1); PG8_BAR;
;             PG8_LDA(At, 0, 1); PG8_STAGE(PG8_SA(0, 0), a2, voffA);
;             PG8_BAR; PG8_WAIT_L(0); PG8_MMA(1, 0, At, B0); PG8_BAR; PG8_SCHED;
;             PG8_STAGE(PG8_SB(0, 1), b2 + hstepB, voffB);
;             PG8_WAIT_V(6); PG8_BAR; PG8_MMA(1, 1, At, B1); PG8_BAR;
;             PG8_LDB(B0, 1, 0); PG8_SCHED; PG8_LDA(At, 1, 0); PG8_STAGE(PG8_SA(0, 1), a2 + hstepA, voffA);
;             PG8_WAIT_L(8); PG8_BAR; PG8_WAIT_L(0); PG8_MMA(0, 0, At, B0); PG8_BAR; PG8_SCHED;
;             PG8_LDB(B1, 1, 1); PG8_STAGE(PG8_SB(1, 0), b3, voffB);
;             PG8_BAR; PG8_WAIT_L(0); PG8_MMA(0, 1, At, B1); PG8_BAR;
;             PG8_LDA(At, 1, 1); PG8_STAGE(PG8_SA(1, 0), a3, voffA);
;             PG8_BAR; PG8_WAIT_L(0); PG8_MMA(1, 0, At, B0); PG8_BAR; PG8_SCHED;
;             PG8_STAGE(PG8_SB(1, 1), b3 + hstepB, voffB);
;             PG8_WAIT_V(6); PG8_BAR; PG8_MMA(1, 1, At, B1); PG8_BAR;
	v_mfma_f32_16x16x32_bf16 v[60:63], v[152:155], v[168:171], v[60:63]
	v_mfma_f32_16x16x32_bf16 v[56:59], v[160:163], v[168:171], v[56:59]
	s_waitcnt lgkmcnt(5)
	v_mfma_f32_16x16x32_bf16 v[44:47], v[152:155], v[176:179], v[44:47]
	v_mfma_f32_16x16x32_bf16 v[40:43], v[160:163], v[176:179], v[40:43]
	s_waitcnt lgkmcnt(3)
	v_mfma_f32_16x16x32_bf16 v[28:31], v[152:155], v[184:187], v[28:31]
	v_mfma_f32_16x16x32_bf16 v[24:27], v[160:163], v[184:187], v[24:27]
	s_waitcnt lgkmcnt(1)
	v_mfma_f32_16x16x32_bf16 v[12:15], v[152:155], v[192:195], v[12:15]
	v_mfma_f32_16x16x32_bf16 v[8:11], v[160:163], v[192:195], v[8:11]
	v_mfma_f32_16x16x32_bf16 v[60:63], v[156:159], v[172:175], v[60:63]
	v_mfma_f32_16x16x32_bf16 v[56:59], v[164:167], v[172:175], v[56:59]
	v_mfma_f32_16x16x32_bf16 v[44:47], v[156:159], v[180:183], v[44:47]
	v_mfma_f32_16x16x32_bf16 v[40:43], v[164:167], v[180:183], v[40:43]
	v_mfma_f32_16x16x32_bf16 v[28:31], v[156:159], v[188:191], v[28:31]
	v_mfma_f32_16x16x32_bf16 v[24:27], v[164:167], v[188:191], v[24:27]
	s_waitcnt lgkmcnt(0)
	v_mfma_f32_16x16x32_bf16 v[12:15], v[156:159], v[198:201], v[12:15]
	v_mfma_f32_16x16x32_bf16 v[8:11], v[164:167], v[198:201], v[8:11]
	s_barrier
	s_setprio 0
	s_add_u32 s8, s12, 0x160080
	s_addc_u32 s9, s13, 0
	s_add_i32 s12, s14, s22
	s_mov_b32 m0, s12
	s_nop 0
	global_load_lds_dwordx4 v132, s[8:9]
	s_add_i32 m0, s12, 0x2000
	s_nop 0
	global_load_lds_dwordx4 v128, s[8:9]
	s_waitcnt vmcnt(6)
	s_setprio 1
	s_barrier
	v_mfma_f32_16x16x32_bf16 v[52:55], v[202:205], v[168:171], v[52:55]
	v_mfma_f32_16x16x32_bf16 v[48:51], v[210:213], v[168:171], v[48:51]
	ds_read_b128 v[152:155], v149
	v_mfma_f32_16x16x32_bf16 v[36:39], v[202:205], v[176:179], v[36:39]
	v_mfma_f32_16x16x32_bf16 v[32:35], v[210:213], v[176:179], v[32:35]
	ds_read_b128 v[156:159], v149 offset:1024
	v_mfma_f32_16x16x32_bf16 v[20:23], v[202:205], v[184:187], v[20:23]
	v_mfma_f32_16x16x32_bf16 v[16:19], v[210:213], v[184:187], v[16:19]
	ds_read_b128 v[160:163], v149 offset:2048
	v_mfma_f32_16x16x32_bf16 v[4:7], v[202:205], v[192:195], v[4:7]
	v_mfma_f32_16x16x32_bf16 v[0:3], v[210:213], v[192:195], v[0:3]
	ds_read_b128 v[164:167], v149 offset:3072
	v_mfma_f32_16x16x32_bf16 v[52:55], v[206:209], v[172:175], v[52:55]
	s_add_i32 s3, s3, 2
	v_mfma_f32_16x16x32_bf16 v[48:51], v[214:217], v[172:175], v[48:51]
	s_add_u32 s39, s39, 0x100
	s_addc_u32 s44, s44, 0
	v_mfma_f32_16x16x32_bf16 v[36:39], v[206:209], v[180:183], v[36:39]
	s_cmpk_gt_u32 s3, 0x55
	v_mfma_f32_16x16x32_bf16 v[32:35], v[214:217], v[180:183], v[32:35]
	s_mov_b64 s[8:9], s[10:11]
	v_mfma_f32_16x16x32_bf16 v[20:23], v[206:209], v[188:191], v[20:23]
	v_mfma_f32_16x16x32_bf16 v[16:19], v[214:217], v[188:191], v[16:19]
	v_mfma_f32_16x16x32_bf16 v[4:7], v[206:209], v[198:201], v[4:7]
	v_mfma_f32_16x16x32_bf16 v[0:3], v[214:217], v[198:201], v[0:3]
	s_barrier
	s_setprio 0
	s_cbranch_scc0 .LBB1_2078
	s_waitcnt lgkmcnt(0)
	v_mov_b32_e32 v152, v147
	v_mov_b32_e32 v144, v146
	s_lshl_b32 s2, s2, 8
	s_add_i32 s2, s2, s29
	s_lshl_b32 s3, s38, 8
	v_add_u32_e32 v152, s2, v152
	s_or_b32 s3, s3, s52
	v_ashrrev_i32_e32 v153, 31, v152
	v_lshl_add_u32 v144, v144, 3, s3
	v_lshlrev_b64 v[152:153], 12, v[152:153]
	v_ashrrev_i32_e32 v145, 31, v144
	v_lshl_add_u64 v[152:153], s[4:5], 0, v[152:153]
	v_lshl_add_u64 v[144:145], v[144:145], 1, v[152:153]
	global_load_dwordx4 v[160:163], v[144:145], off
	global_load_dwordx4 v[164:167], v[144:145], off offset:256
	s_mov_b64 s[98:99], 0x10000
	v_lshl_add_u64 v[154:155], v[144:145], 0, s[98:99]
	global_load_dwordx4 v[168:171], v[154:155], off
	global_load_dwordx4 v[172:175], v[154:155], off offset:256
	s_mov_b64 s[98:99], 0x20000
	v_lshl_add_u64 v[154:155], v[144:145], 0, s[98:99]
	global_load_dwordx4 v[176:179], v[154:155], off
	global_load_dwordx4 v[180:183], v[154:155], off offset:256
	s_mov_b64 s[98:99], 0x30000
	v_lshl_add_u64 v[154:155], v[144:145], 0, s[98:99]
	global_load_dwordx4 v[184:187], v[154:155], off
	global_load_dwordx4 v[188:191], v[154:155], off offset:256
	s_mov_b64 s[98:99], 0x80000
	v_lshl_add_u64 v[154:155], v[144:145], 0, s[98:99]
	global_load_dwordx4 v[192:195], v[154:155], off
	global_load_dwordx4 v[198:201], v[154:155], off offset:256
	s_mov_b64 s[98:99], 0x90000
	v_lshl_add_u64 v[154:155], v[144:145], 0, s[98:99]
	global_load_dwordx4 v[202:205], v[154:155], off
	global_load_dwordx4 v[206:209], v[154:155], off offset:256
	s_mov_b64 s[98:99], 0xa0000
	v_lshl_add_u64 v[154:155], v[144:145], 0, s[98:99]
	global_load_dwordx4 v[210:213], v[154:155], off
	global_load_dwordx4 v[214:217], v[154:155], off offset:256
	s_mov_b64 s[98:99], 0xb0000
	v_lshl_add_u64 v[154:155], v[144:145], 0, s[98:99]
	global_load_dwordx4 v[248:251], v[154:155], off
	global_load_dwordx4 v[252:255], v[154:155], off offset:256
	s_waitcnt vmcnt(15)
	s_nop 1
	v_mov_b32_e32 v152, v160
	v_mov_b32_e32 v153, v161
	v_mov_b32_e32 v154, v162
	v_mov_b32_e32 v155, v163
	s_mov_b64 s[2:3], 0x10000
	s_mov_b32 s38, s37
	s_mov_b64 s[10:11], s[6:7]
	s_mov_b64 s[8:9], s[42:43]
	s_waitcnt lgkmcnt(0)
	v_lshlrev_b32_e32 v156, 16, v152
	v_and_b32_e32 v157, 0xffff0000, v152
	v_lshlrev_b32_e32 v152, 16, v153
	v_and_b32_e32 v153, 0xffff0000, v153
	v_lshlrev_b32_e32 v158, 16, v154
	v_and_b32_e32 v159, 0xffff0000, v154
	v_lshlrev_b32_e32 v154, 16, v155
	v_and_b32_e32 v155, 0xffff0000, v155
	v_pk_add_f32 v[126:127], v[126:127], v[152:153]
	v_pk_add_f32 v[124:125], v[124:125], v[156:157]
	v_pk_add_f32 v[152:153], v[122:123], v[154:155]
	v_pk_add_f32 v[122:123], v[120:121], v[158:159]
	v_cvt_pk_bf16_f32 v120, v124, v125
	v_cvt_pk_bf16_f32 v121, v126, v127
	v_cvt_pk_bf16_f32 v122, v122, v123
	v_cvt_pk_bf16_f32 v123, v152, v153
	global_store_dwordx4 v[144:145], v[120:123], off
	s_waitcnt vmcnt(15)
; DI unsigned pack2(float a, float b) { f32x2 v = {a, b}; hwbf16x2 r = __builtin_convertvector(v, hwbf16x2); return __builtin_bit_cast(unsigned, r); }
; DI float bflo(unsigned w) { return __uint_as_float(w << 16); }
; DI float bfhi(unsigned w) { return __uint_as_float(w & 0xffff0000u); }
;     DI void operator()(const f32x4 (&acc)[2][2][4][2], const Unit& u, int wr, int wc, int fr, int fq) const {
;     ...
;             for (int m = 0; m < 4; ++m) { const size_t ro = (size_t)(row0 + ai * HALF + m * 16) * D + col0;
; #pragma unroll
;                 for (int bj = 0; bj < 2; ++bj) {
;                     f32x4 x0, x1;
;                     if constexpr (IB) { const u32x4 w = *(const u32x4*)((const bf16_t*)Xin + ro + bj * HALF);
;                         x0 = (f32x4){bflo(w[0]), bfhi(w[0]), bflo(w[1]), bfhi(w[1])}; x1 = (f32x4){bflo(w[2]), bfhi(w[2]), bflo(w[3]), bfhi(w[3])}; }
;                     else { x0 = *(const f32x4*)((const float*)Xin + ro + bj * HALF); x1 = *(const f32x4*)((const float*)Xin + ro + bj * HALF + 4); }
;                     x0 += acc[ai][bj][m][0] * sc[bj][0]; x1 += acc[ai][bj][m][1] * sc[bj][1];
;                     if constexpr (OB) { u32x4 o; o[0] = pack2(x0[0], x0[1]); o[1] = pack2(x0[2], x0[3]); o[2] = pack2(x1[0], x1[1]); o[3] = pack2(x1[2], x1[3]);
;                         *(u32x4*)((bf16_t*)Xout + ro + bj * HALF) = o; }
;                     else { *(f32x4*)((float*)Xout + ro + bj * HALF) = x0; *(f32x4*)((float*)Xout + ro + bj * HALF + 4) = x1; } } }
	s_nop 1
	v_mov_b32_e32 v120, v164
	v_mov_b32_e32 v121, v165
	v_mov_b32_e32 v122, v166
	v_mov_b32_e32 v123, v167
	s_waitcnt lgkmcnt(0)
	v_lshlrev_b32_e32 v124, 16, v120
	v_and_b32_e32 v125, 0xffff0000, v120
	v_lshlrev_b32_e32 v120, 16, v121
	v_and_b32_e32 v121, 0xffff0000, v121
	v_lshlrev_b32_e32 v126, 16, v122
	v_and_b32_e32 v127, 0xffff0000, v122
	v_lshlrev_b32_e32 v122, 16, v123
	v_and_b32_e32 v123, 0xffff0000, v123
	v_pk_add_f32 v[116:117], v[116:117], v[124:125]
	v_pk_add_f32 v[118:119], v[118:119], v[120:121]
	v_pk_add_f32 v[120:121], v[114:115], v[122:123]
	v_pk_add_f32 v[114:115], v[112:113], v[126:127]
	v_cvt_pk_bf16_f32 v112, v116, v117
	v_lshl_add_u64 v[116:117], v[144:145], 0, s[2:3]
	s_mov_b32 s2, 0x10000
	v_cvt_pk_bf16_f32 v113, v118, v119
	v_add_co_u32_e32 v118, vcc, s2, v144
	v_cvt_pk_bf16_f32 v114, v114, v115
	v_cvt_pk_bf16_f32 v115, v120, v121
	v_addc_co_u32_e32 v119, vcc, 0, v145, vcc
	global_store_dwordx4 v[144:145], v[112:115], off offset:256
	s_waitcnt vmcnt(15)
	s_nop 1
	v_mov_b32_e32 v112, v168
	v_mov_b32_e32 v113, v169
	v_mov_b32_e32 v114, v170
	v_mov_b32_e32 v115, v171
	s_mov_b64 s[2:3], 0x20000
	s_waitcnt lgkmcnt(0)
	v_lshlrev_b32_e32 v120, 16, v112
	v_and_b32_e32 v121, 0xffff0000, v112
	v_lshlrev_b32_e32 v112, 16, v113
	v_and_b32_e32 v113, 0xffff0000, v113
	v_lshlrev_b32_e32 v122, 16, v114
	v_and_b32_e32 v123, 0xffff0000, v114
	v_lshlrev_b32_e32 v114, 16, v115
	v_and_b32_e32 v115, 0xffff0000, v115
	v_pk_add_f32 v[110:111], v[110:111], v[112:113]
	v_pk_add_f32 v[108:109], v[108:109], v[120:121]
	v_pk_add_f32 v[112:113], v[106:107], v[114:115]
	v_pk_add_f32 v[106:107], v[104:105], v[122:123]
	v_cvt_pk_bf16_f32 v104, v108, v109
	v_cvt_pk_bf16_f32 v105, v110, v111
	v_cvt_pk_bf16_f32 v106, v106, v107
	v_cvt_pk_bf16_f32 v107, v112, v113
	global_store_dwordx4 v[118:119], v[104:107], off
	s_waitcnt vmcnt(15)
	s_nop 1
	v_mov_b32_e32 v104, v172
	v_mov_b32_e32 v105, v173
	v_mov_b32_e32 v106, v174
	v_mov_b32_e32 v107, v175
	s_waitcnt lgkmcnt(0)
	v_lshlrev_b32_e32 v108, 16, v104
	v_and_b32_e32 v109, 0xffff0000, v104
	v_lshlrev_b32_e32 v104, 16, v105
	v_and_b32_e32 v105, 0xffff0000, v105
	v_lshlrev_b32_e32 v110, 16, v106
	v_and_b32_e32 v111, 0xffff0000, v106
	v_lshlrev_b32_e32 v106, 16, v107
	v_and_b32_e32 v107, 0xffff0000, v107
	v_pk_add_f32 v[100:101], v[100:101], v[108:109]
	v_pk_add_f32 v[102:103], v[102:103], v[104:105]
	v_pk_add_f32 v[104:105], v[98:99], v[106:107]
	v_pk_add_f32 v[98:99], v[96:97], v[110:111]
	v_cvt_pk_bf16_f32 v96, v100, v101
	v_lshl_add_u64 v[100:101], v[144:145], 0, s[2:3]
	s_mov_b32 s2, 0x20000
	v_cvt_pk_bf16_f32 v97, v102, v103
	v_add_co_u32_e32 v102, vcc, s2, v144
	v_cvt_pk_bf16_f32 v98, v98, v99
	v_cvt_pk_bf16_f32 v99, v104, v105
	v_addc_co_u32_e32 v103, vcc, 0, v145, vcc
	global_store_dwordx4 v[116:117], v[96:99], off offset:256
	s_waitcnt vmcnt(15)
	s_nop 1
	v_mov_b32_e32 v96, v176
	v_mov_b32_e32 v97, v177
	v_mov_b32_e32 v98, v178
	v_mov_b32_e32 v99, v179
	s_mov_b64 s[2:3], 0x30000
	s_waitcnt lgkmcnt(0)
	v_lshlrev_b32_e32 v104, 16, v96
	v_and_b32_e32 v105, 0xffff0000, v96
	v_lshlrev_b32_e32 v96, 16, v97
	v_and_b32_e32 v97, 0xffff0000, v97
	v_lshlrev_b32_e32 v106, 16, v98
	v_and_b32_e32 v107, 0xffff0000, v98
	v_lshlrev_b32_e32 v98, 16, v99
	v_and_b32_e32 v99, 0xffff0000, v99
	v_pk_add_f32 v[94:95], v[94:95], v[96:97]
	v_pk_add_f32 v[92:93], v[92:93], v[104:105]
	v_pk_add_f32 v[96:97], v[90:91], v[98:99]
	v_pk_add_f32 v[90:91], v[88:89], v[106:107]
	v_cvt_pk_bf16_f32 v88, v92, v93
	v_cvt_pk_bf16_f32 v89, v94, v95
	v_cvt_pk_bf16_f32 v90, v90, v91
	v_cvt_pk_bf16_f32 v91, v96, v97
	global_store_dwordx4 v[102:103], v[88:91], off
	s_waitcnt vmcnt(15)
	s_nop 1
	v_mov_b32_e32 v88, v180
	v_mov_b32_e32 v89, v181
	v_mov_b32_e32 v90, v182
	v_mov_b32_e32 v91, v183
	s_waitcnt lgkmcnt(0)
	v_lshlrev_b32_e32 v92, 16, v88
	v_and_b32_e32 v93, 0xffff0000, v88
	v_lshlrev_b32_e32 v88, 16, v89
	v_and_b32_e32 v89, 0xffff0000, v89
	v_lshlrev_b32_e32 v94, 16, v90
	v_and_b32_e32 v95, 0xffff0000, v90
	v_lshlrev_b32_e32 v90, 16, v91
	v_and_b32_e32 v91, 0xffff0000, v91
	v_pk_add_f32 v[86:87], v[86:87], v[88:89]
	v_pk_add_f32 v[84:85], v[84:85], v[92:93]
	v_pk_add_f32 v[88:89], v[82:83], v[90:91]
	v_pk_add_f32 v[82:83], v[80:81], v[94:95]
	v_cvt_pk_bf16_f32 v80, v84, v85
	v_cvt_pk_bf16_f32 v81, v86, v87
	v_cvt_pk_bf16_f32 v82, v82, v83
	v_cvt_pk_bf16_f32 v83, v88, v89
	global_store_dwordx4 v[100:101], v[80:83], off offset:256
	s_nop 1
	v_lshl_add_u64 v[80:81], v[144:145], 0, s[2:3]
	s_mov_b32 s2, 0x30000
	v_add_co_u32_e32 v86, vcc, s2, v144
	s_mov_b64 s[2:3], 0x80000
	s_nop 0
	v_addc_co_u32_e32 v87, vcc, 0, v145, vcc
	s_waitcnt vmcnt(15)
	s_nop 1
	v_mov_b32_e32 v82, v184
	v_mov_b32_e32 v83, v185
	v_mov_b32_e32 v84, v186
	v_mov_b32_e32 v85, v187
	s_waitcnt lgkmcnt(0)
	v_lshlrev_b32_e32 v88, 16, v82
	v_and_b32_e32 v89, 0xffff0000, v82
	v_lshlrev_b32_e32 v82, 16, v83
	v_and_b32_e32 v83, 0xffff0000, v83
	v_lshlrev_b32_e32 v90, 16, v84
	v_and_b32_e32 v91, 0xffff0000, v84
	v_lshlrev_b32_e32 v84, 16, v85
	v_and_b32_e32 v85, 0xffff0000, v85
	v_pk_add_f32 v[78:79], v[78:79], v[82:83]
	v_pk_add_f32 v[76:77], v[76:77], v[88:89]
	v_pk_add_f32 v[82:83], v[74:75], v[84:85]
	v_pk_add_f32 v[74:75], v[72:73], v[90:91]
	v_cvt_pk_bf16_f32 v72, v76, v77
	v_cvt_pk_bf16_f32 v73, v78, v79
	v_cvt_pk_bf16_f32 v74, v74, v75
	v_cvt_pk_bf16_f32 v75, v82, v83
	global_store_dwordx4 v[86:87], v[72:75], off
	s_waitcnt vmcnt(15)
	s_nop 1
	v_mov_b32_e32 v72, v188
	v_mov_b32_e32 v73, v189
	v_mov_b32_e32 v74, v190
	v_mov_b32_e32 v75, v191
	s_waitcnt lgkmcnt(0)
; DI unsigned pack2(float a, float b) { f32x2 v = {a, b}; hwbf16x2 r = __builtin_convertvector(v, hwbf16x2); return __builtin_bit_cast(unsigned, r); }
; DI float bflo(unsigned w) { return __uint_as_float(w << 16); }
; DI float bfhi(unsigned w) { return __uint_as_float(w & 0xffff0000u); }
;     DI void operator()(const f32x4 (&acc)[2][2][4][2], const Unit& u, int wr, int wc, int fr, int fq) const {
;     ...
;             for (int m = 0; m < 4; ++m) { const size_t ro = (size_t)(row0 + ai * HALF + m * 16) * D + col0;
; #pragma unroll
;                 for (int bj = 0; bj < 2; ++bj) {
;                     f32x4 x0, x1;
;                     if constexpr (IB) { const u32x4 w = *(const u32x4*)((const bf16_t*)Xin + ro + bj * HALF);
;                         x0 = (f32x4){bflo(w[0]), bfhi(w[0]), bflo(w[1]), bfhi(w[1])}; x1 = (f32x4){bflo(w[2]), bfhi(w[2]), bflo(w[3]), bfhi(w[3])}; }
;                     else { x0 = *(const f32x4*)((const float*)Xin + ro + bj * HALF); x1 = *(const f32x4*)((const float*)Xin + ro + bj * HALF + 4); }
;                     x0 += acc[ai][bj][m][0] * sc[bj][0]; x1 += acc[ai][bj][m][1] * sc[bj][1];
;                     if constexpr (OB) { u32x4 o; o[0] = pack2(x0[0], x0[1]); o[1] = pack2(x0[2], x0[3]); o[2] = pack2(x1[0], x1[1]); o[3] = pack2(x1[2], x1[3]);
;                         *(u32x4*)((bf16_t*)Xout + ro + bj * HALF) = o; }
;                     else { *(f32x4*)((float*)Xout + ro + bj * HALF) = x0; *(f32x4*)((float*)Xout + ro + bj * HALF + 4) = x1; } } }
	v_lshlrev_b32_e32 v76, 16, v72
	v_and_b32_e32 v77, 0xffff0000, v72
	v_lshlrev_b32_e32 v72, 16, v73
	v_and_b32_e32 v73, 0xffff0000, v73
	v_lshlrev_b32_e32 v78, 16, v74
	v_and_b32_e32 v79, 0xffff0000, v74
	v_lshlrev_b32_e32 v74, 16, v75
	v_and_b32_e32 v75, 0xffff0000, v75
	v_pk_add_f32 v[70:71], v[70:71], v[72:73]
	v_pk_add_f32 v[68:69], v[68:69], v[76:77]
	v_pk_add_f32 v[72:73], v[66:67], v[74:75]
	v_pk_add_f32 v[66:67], v[64:65], v[78:79]
	v_cvt_pk_bf16_f32 v64, v68, v69
	v_cvt_pk_bf16_f32 v65, v70, v71
	v_cvt_pk_bf16_f32 v66, v66, v67
	v_cvt_pk_bf16_f32 v67, v72, v73
	global_store_dwordx4 v[80:81], v[64:67], off offset:256
	s_nop 1
	v_lshl_add_u64 v[64:65], v[144:145], 0, s[2:3]
	s_mov_b32 s2, 0x80000
	v_add_co_u32_e32 v70, vcc, s2, v144
	s_mov_b64 s[2:3], 0x90000
	s_nop 0
	v_addc_co_u32_e32 v71, vcc, 0, v145, vcc
	s_waitcnt vmcnt(15)
	s_nop 1
	v_mov_b32_e32 v66, v192
	v_mov_b32_e32 v67, v193
	v_mov_b32_e32 v68, v194
	v_mov_b32_e32 v69, v195
	s_waitcnt lgkmcnt(0)
	v_lshlrev_b32_e32 v72, 16, v66
	v_and_b32_e32 v73, 0xffff0000, v66
	v_lshlrev_b32_e32 v66, 16, v67
	v_and_b32_e32 v67, 0xffff0000, v67
	v_lshlrev_b32_e32 v74, 16, v68
	v_and_b32_e32 v75, 0xffff0000, v68
	v_lshlrev_b32_e32 v68, 16, v69
	v_and_b32_e32 v69, 0xffff0000, v69
	v_pk_add_f32 v[62:63], v[62:63], v[66:67]
	v_pk_add_f32 v[60:61], v[60:61], v[72:73]
	v_pk_add_f32 v[66:67], v[58:59], v[68:69]
	v_pk_add_f32 v[58:59], v[56:57], v[74:75]
	v_cvt_pk_bf16_f32 v56, v60, v61
	v_cvt_pk_bf16_f32 v57, v62, v63
	v_cvt_pk_bf16_f32 v58, v58, v59
	v_cvt_pk_bf16_f32 v59, v66, v67
	global_store_dwordx4 v[70:71], v[56:59], off
	s_waitcnt vmcnt(15)
	s_nop 1
	v_mov_b32_e32 v56, v198
	v_mov_b32_e32 v57, v199
	v_mov_b32_e32 v58, v200
	v_mov_b32_e32 v59, v201
	s_waitcnt lgkmcnt(0)
	v_lshlrev_b32_e32 v60, 16, v56
	v_and_b32_e32 v61, 0xffff0000, v56
	v_lshlrev_b32_e32 v56, 16, v57
	v_and_b32_e32 v57, 0xffff0000, v57
	v_lshlrev_b32_e32 v62, 16, v58
	v_and_b32_e32 v63, 0xffff0000, v58
	v_lshlrev_b32_e32 v58, 16, v59
	v_and_b32_e32 v59, 0xffff0000, v59
	v_pk_add_f32 v[54:55], v[54:55], v[56:57]
	v_pk_add_f32 v[52:53], v[52:53], v[60:61]
	v_pk_add_f32 v[56:57], v[50:51], v[58:59]
	v_pk_add_f32 v[50:51], v[48:49], v[62:63]
	v_cvt_pk_bf16_f32 v48, v52, v53
	v_cvt_pk_bf16_f32 v49, v54, v55
	v_cvt_pk_bf16_f32 v50, v50, v51
	v_cvt_pk_bf16_f32 v51, v56, v57
	global_store_dwordx4 v[64:65], v[48:51], off offset:256
	s_nop 1
	v_lshl_add_u64 v[48:49], v[144:145], 0, s[2:3]
	s_mov_b32 s2, 0x90000
	v_add_co_u32_e32 v54, vcc, s2, v144
	s_mov_b64 s[2:3], 0xa0000
	s_nop 0
	v_addc_co_u32_e32 v55, vcc, 0, v145, vcc
	s_waitcnt vmcnt(15)
	s_nop 1
	v_mov_b32_e32 v50, v202
	v_mov_b32_e32 v51, v203
	v_mov_b32_e32 v52, v204
	v_mov_b32_e32 v53, v205
	s_waitcnt lgkmcnt(0)
	v_lshlrev_b32_e32 v56, 16, v50
	v_and_b32_e32 v57, 0xffff0000, v50
	v_lshlrev_b32_e32 v50, 16, v51
	v_and_b32_e32 v51, 0xffff0000, v51
	v_lshlrev_b32_e32 v58, 16, v52
	v_and_b32_e32 v59, 0xffff0000, v52
	v_lshlrev_b32_e32 v52, 16, v53
	v_and_b32_e32 v53, 0xffff0000, v53
	v_pk_add_f32 v[46:47], v[46:47], v[50:51]
	v_pk_add_f32 v[44:45], v[44:45], v[56:57]
	v_pk_add_f32 v[50:51], v[42:43], v[52:53]
	v_pk_add_f32 v[42:43], v[40:41], v[58:59]
	v_cvt_pk_bf16_f32 v40, v44, v45
	v_cvt_pk_bf16_f32 v41, v46, v47
	v_cvt_pk_bf16_f32 v42, v42, v43
	v_cvt_pk_bf16_f32 v43, v50, v51
	global_store_dwordx4 v[54:55], v[40:43], off
	s_waitcnt vmcnt(15)
	s_nop 1
	v_mov_b32_e32 v40, v206
	v_mov_b32_e32 v41, v207
	v_mov_b32_e32 v42, v208
	v_mov_b32_e32 v43, v209
	s_waitcnt lgkmcnt(0)
; DI unsigned pack2(float a, float b) { f32x2 v = {a, b}; hwbf16x2 r = __builtin_convertvector(v, hwbf16x2); return __builtin_bit_cast(unsigned, r); }
; DI float bflo(unsigned w) { return __uint_as_float(w << 16); }
; DI float bfhi(unsigned w) { return __uint_as_float(w & 0xffff0000u); }
;     DI const char* a(const Unit& u) const { return (const char*)(A + (size_t)u.pm * BM * lda); }
;     DI const char* a(const Unit& u) const { return (const char*)(A + (size_t)u.pm * BM * 2048 + (u.pn >> 1) * 512); }
; #define PG8_BAR __builtin_amdgcn_s_barrier()
;     DI void operator()(const f32x4 (&acc)[2][2][4][2], const Unit& u, int wr, int wc, int fr, int fq) const {
;     ...
;             for (int m = 0; m < 4; ++m) { const size_t ro = (size_t)(row0 + ai * HALF + m * 16) * D + col0;
; #pragma unroll
;                 for (int bj = 0; bj < 2; ++bj) {
;                     f32x4 x0, x1;
;                     if constexpr (IB) { const u32x4 w = *(const u32x4*)((const bf16_t*)Xin + ro + bj * HALF);
;                         x0 = (f32x4){bflo(w[0]), bfhi(w[0]), bflo(w[1]), bfhi(w[1])}; x1 = (f32x4){bflo(w[2]), bfhi(w[2]), bflo(w[3]), bfhi(w[3])}; }
;                     else { x0 = *(const f32x4*)((const float*)Xin + ro + bj * HALF); x1 = *(const f32x4*)((const float*)Xin + ro + bj * HALF + 4); }
;                     x0 += acc[ai][bj][m][0] * sc[bj][0]; x1 += acc[ai][bj][m][1] * sc[bj][1];
;                     if constexpr (OB) { u32x4 o; o[0] = pack2(x0[0], x0[1]); o[1] = pack2(x0[2], x0[3]); o[2] = pack2(x1[0], x1[1]); o[3] = pack2(x1[2], x1[3]);
;                         *(u32x4*)((bf16_t*)Xout + ro + bj * HALF) = o; }
;                     else { *(f32x4*)((float*)Xout + ro + bj * HALF) = x0; *(f32x4*)((float*)Xout + ro + bj * HALF + 4) = x1; } } }
; template <class Map, class Epi>
; DI void gemm_phase(LAS unsigned char* lds, const Map& MP, const Epi& E, const int nM, const int nN, const int K, const int lda, const int ldb) {
;     ...
;         if (!has_next) break;
; #pragma unroll
;         for (int a = 0; a < 2; ++a)
; #pragma unroll
;             for (int b = 0; b < 2; ++b)
; #pragma unroll
;                 for (int m = 0; m < 4; ++m)
; #pragma unroll
;                     for (int n = 0; n < 2; ++n) acc[a][b][m][n] = (f32x4){0.f, 0.f, 0.f, 0.f};
;         cur = nxt; cA = nA; cB = nB; ++ui;
;     }
;     PG8_WAIT_V(0);
;     if (wr == 0) PG8_BAR;
;     PG8_BAR;
	v_lshlrev_b32_e32 v44, 16, v40
	v_and_b32_e32 v45, 0xffff0000, v40
	v_lshlrev_b32_e32 v40, 16, v41
	v_and_b32_e32 v41, 0xffff0000, v41
	v_lshlrev_b32_e32 v46, 16, v42
	v_and_b32_e32 v47, 0xffff0000, v42
	v_lshlrev_b32_e32 v42, 16, v43
	v_and_b32_e32 v43, 0xffff0000, v43
	v_pk_add_f32 v[38:39], v[38:39], v[40:41]
	v_pk_add_f32 v[36:37], v[36:37], v[44:45]
	v_pk_add_f32 v[40:41], v[34:35], v[42:43]
	v_pk_add_f32 v[34:35], v[32:33], v[46:47]
	v_cvt_pk_bf16_f32 v32, v36, v37
	v_cvt_pk_bf16_f32 v33, v38, v39
	v_cvt_pk_bf16_f32 v34, v34, v35
	v_cvt_pk_bf16_f32 v35, v40, v41
	global_store_dwordx4 v[48:49], v[32:35], off offset:256
	s_nop 1
	v_lshl_add_u64 v[32:33], v[144:145], 0, s[2:3]
	s_mov_b32 s2, 0xa0000
	v_add_co_u32_e32 v38, vcc, s2, v144
	s_mov_b64 s[2:3], 0xb0000
	s_nop 0
	v_addc_co_u32_e32 v39, vcc, 0, v145, vcc
	s_waitcnt vmcnt(15)
	s_nop 1
	v_mov_b32_e32 v34, v210
	v_mov_b32_e32 v35, v211
	v_mov_b32_e32 v36, v212
	v_mov_b32_e32 v37, v213
	s_waitcnt lgkmcnt(0)
	v_lshlrev_b32_e32 v40, 16, v34
	v_and_b32_e32 v41, 0xffff0000, v34
	v_lshlrev_b32_e32 v34, 16, v35
	v_and_b32_e32 v35, 0xffff0000, v35
	v_lshlrev_b32_e32 v42, 16, v36
	v_and_b32_e32 v43, 0xffff0000, v36
	v_lshlrev_b32_e32 v36, 16, v37
	v_and_b32_e32 v37, 0xffff0000, v37
	v_pk_add_f32 v[30:31], v[30:31], v[34:35]
	v_pk_add_f32 v[28:29], v[28:29], v[40:41]
	v_pk_add_f32 v[34:35], v[26:27], v[36:37]
	v_pk_add_f32 v[26:27], v[24:25], v[42:43]
	v_cvt_pk_bf16_f32 v24, v28, v29
	v_cvt_pk_bf16_f32 v25, v30, v31
	v_cvt_pk_bf16_f32 v26, v26, v27
	v_cvt_pk_bf16_f32 v27, v34, v35
	global_store_dwordx4 v[38:39], v[24:27], off
	s_waitcnt vmcnt(15)
	s_nop 1
	v_mov_b32_e32 v24, v214
	v_mov_b32_e32 v25, v215
	v_mov_b32_e32 v26, v216
	v_mov_b32_e32 v27, v217
	s_waitcnt lgkmcnt(0)
	v_lshlrev_b32_e32 v28, 16, v24
	v_and_b32_e32 v29, 0xffff0000, v24
	v_lshlrev_b32_e32 v24, 16, v25
	v_and_b32_e32 v25, 0xffff0000, v25
	v_lshlrev_b32_e32 v30, 16, v26
	v_and_b32_e32 v31, 0xffff0000, v26
	v_lshlrev_b32_e32 v26, 16, v27
	v_and_b32_e32 v27, 0xffff0000, v27
	v_pk_add_f32 v[22:23], v[22:23], v[24:25]
	v_pk_add_f32 v[20:21], v[20:21], v[28:29]
	v_pk_add_f32 v[24:25], v[18:19], v[26:27]
	v_pk_add_f32 v[18:19], v[16:17], v[30:31]
	v_cvt_pk_bf16_f32 v16, v20, v21
	v_cvt_pk_bf16_f32 v17, v22, v23
	v_cvt_pk_bf16_f32 v18, v18, v19
	v_cvt_pk_bf16_f32 v19, v24, v25
	global_store_dwordx4 v[32:33], v[16:19], off offset:256
	s_nop 1
	v_lshl_add_u64 v[16:17], v[144:145], 0, s[2:3]
	s_mov_b32 s2, 0xb0000
	v_add_co_u32_e32 v22, vcc, s2, v144
	s_mov_b32 s2, s53
	s_nop 0
	v_addc_co_u32_e32 v23, vcc, 0, v145, vcc
	s_waitcnt vmcnt(15)
	s_nop 1
	v_mov_b32_e32 v18, v248
	v_mov_b32_e32 v19, v249
	v_mov_b32_e32 v20, v250
	v_mov_b32_e32 v21, v251
	s_and_b64 vcc, exec, s[40:41]
	s_waitcnt lgkmcnt(0)
	v_lshlrev_b32_e32 v24, 16, v18
	v_and_b32_e32 v25, 0xffff0000, v18
	v_lshlrev_b32_e32 v18, 16, v19
	v_and_b32_e32 v19, 0xffff0000, v19
	v_lshlrev_b32_e32 v26, 16, v20
	v_and_b32_e32 v27, 0xffff0000, v20
	v_lshlrev_b32_e32 v20, 16, v21
	v_and_b32_e32 v21, 0xffff0000, v21
	v_pk_add_f32 v[14:15], v[14:15], v[18:19]
	v_pk_add_f32 v[12:13], v[12:13], v[24:25]
	v_pk_add_f32 v[18:19], v[10:11], v[20:21]
	v_pk_add_f32 v[10:11], v[8:9], v[26:27]
	v_cvt_pk_bf16_f32 v8, v12, v13
	v_cvt_pk_bf16_f32 v9, v14, v15
	v_cvt_pk_bf16_f32 v10, v10, v11
	v_cvt_pk_bf16_f32 v11, v18, v19
	global_store_dwordx4 v[22:23], v[8:11], off
	s_waitcnt vmcnt(15)
	s_nop 1
	v_mov_b32_e32 v8, v252
	v_mov_b32_e32 v9, v253
	v_mov_b32_e32 v10, v254
	v_mov_b32_e32 v11, v255
	s_waitcnt lgkmcnt(0)
	v_lshlrev_b32_e32 v12, 16, v8
	v_and_b32_e32 v13, 0xffff0000, v8
	v_lshlrev_b32_e32 v8, 16, v9
	v_and_b32_e32 v9, 0xffff0000, v9
	v_lshlrev_b32_e32 v14, 16, v10
	v_and_b32_e32 v15, 0xffff0000, v10
	v_lshlrev_b32_e32 v10, 16, v11
	v_and_b32_e32 v11, 0xffff0000, v11
	v_pk_add_f32 v[6:7], v[6:7], v[8:9]
	v_pk_add_f32 v[4:5], v[4:5], v[12:13]
	v_pk_add_f32 v[8:9], v[2:3], v[10:11]
	v_pk_add_f32 v[2:3], v[0:1], v[14:15]
	v_cvt_pk_bf16_f32 v0, v4, v5
	v_cvt_pk_bf16_f32 v1, v6, v7
	v_cvt_pk_bf16_f32 v2, v2, v3
	v_cvt_pk_bf16_f32 v3, v8, v9
	global_store_dwordx4 v[16:17], v[0:3], off offset:256
	s_cbranch_vccz .LBB1_2071
	s_waitcnt vmcnt(0)
	s_cmpk_gt_u32 s17, 0xff
	s_cbranch_scc1 .LBB1_2082
	s_barrier

; #define PG8_STAGE(bufoff, gbase, voff) do { _Pragma("unroll") for (int _i = 0; _i < 2; ++_i) \
;         __builtin_amdgcn_global_load_lds((const unsigned*)((const char*)(gbase) + (voff)[_i]), (LAS unsigned*)(lds + (bufoff) + ldsw + _i * 8192), 16, 0, 0); } while (0)
; #define PG8_LDA(dst, b, h) do { _Pragma("unroll") for (int m = 0; m < 4; ++m) _Pragma("unroll") for (int k = 0; k < 2; ++k) dst[m][k] = *(const LAS bf16x8*)(lds + PG8_SA(b, h) + aoff + m * 2048 + k * 1024); } while (0)
; #define PG8_LDB(dst, b, h) do { _Pragma("unroll") for (int n = 0; n < 2; ++n) _Pragma("unroll") for (int k = 0; k < 2; ++k) dst[n][k] = *(const LAS bf16x8*)(lds + PG8_SB(b, h) + boff + n * 2048 + k * 1024); } while (0)
; #define PG8_WAIT_V(n) asm volatile("s_waitcnt vmcnt(" #n ")" ::: "memory")
; #define PG8_WAIT_L(n) asm volatile("s_waitcnt lgkmcnt(" #n ")" ::: "memory")
; #define PG8_BAR __builtin_amdgcn_s_barrier()
; #define PG8_SCHED __builtin_amdgcn_sched_barrier(0)
; template <class Map, class Epi>
; DI void gemm_phase(LAS unsigned char* lds, const Map& MP, const Epi& E, const int nM, const int nN, const int K, const int lda, const int ldb) {
;     ...
;             PG8_LDB(B0, 0, 0); PG8_SCHED; PG8_LDA(At, 0, 0); PG8_STAGE(PG8_SA(1, 1), a1 + hstepA, voffA);
;             PG8_WAIT_L(8); PG8_BAR; PG8_WAIT_L(0); PG8_MMA(0, 0, At, B0); PG8_BAR; PG8_SCHED;
;             PG8_LDB(B1, 0, 1); PG8_STAGE(PG8_SB(0, 0), b2, voffB);
;             PG8_BAR; PG8_WAIT_L(0); PG8_MMA(0, 1, At, B1); PG8_BAR;
;             PG8_LDA(At, 0, 1); PG8_STAGE(PG8_SA(0, 0), a2, voffA);
;             PG8_BAR; PG8_WAIT_L(0); PG8_MMA(1, 0, At, B0); PG8_BAR; PG8_SCHED;
;             PG8_STAGE(PG8_SB(0, 1), b2 + hstepB, voffB);
;             PG8_WAIT_V(6); PG8_BAR; PG8_MMA(1, 1, At, B1); PG8_BAR;
;             PG8_LDB(B0, 1, 0); PG8_SCHED; PG8_LDA(At, 1, 0); PG8_STAGE(PG8_SA(0, 1), a2 + hstepA, voffA);
;             PG8_WAIT_L(8); PG8_BAR; PG8_WAIT_L(0); PG8_MMA(0, 0, At, B0); PG8_BAR; PG8_SCHED;
;             PG8_LDB(B1, 1, 1); PG8_STAGE(PG8_SB(1, 0), b3, voffB);
;             PG8_BAR; PG8_WAIT_L(0); PG8_MMA(0, 1, At, B1); PG8_BAR;
;             PG8_LDA(At, 1, 1); PG8_STAGE(PG8_SA(1, 0), a3, voffA);
;             PG8_BAR; PG8_WAIT_L(0); PG8_MMA(1, 0, At, B0); PG8_BAR; PG8_SCHED;
;             PG8_STAGE(PG8_SB(1, 1), b3 + hstepB, voffB);
;             PG8_WAIT_V(6); PG8_BAR; PG8_MMA(1, 1, At, B1); PG8_BAR;
.LBB1_2339:
	s_add_u32 s12, s10, 0xfff80080
	s_addc_u32 s13, s11, -1
	s_cmp_eq_u32 s3, 4
	s_cselect_b32 s15, s38, s13
	s_cselect_b32 s14, s39, s12
	s_cselect_b32 s13, s48, s56
	s_cselect_b32 s12, s49, s53
	s_add_i32 m0, s9, 0xc000
	ds_read_b128 v[168:171], v166
	ds_read_b128 v[172:175], v166 offset:1024
	ds_read_b128 v[176:179], v166 offset:2048
	ds_read_b128 v[180:183], v166 offset:3072
	ds_read_b128 v[184:187], v166 offset:4096
	ds_read_b128 v[188:191], v166 offset:5120
	ds_read_b128 v[192:195], v166 offset:6144
	ds_read_b128 v[198:201], v166 offset:7168
	global_load_lds_dwordx4 v154, s[10:11]
	s_add_i32 m0, s9, 0xe000
	s_nop 0
	global_load_lds_dwordx4 v152, s[10:11]
	s_waitcnt lgkmcnt(7)
	s_setprio 1
	s_barrier
	v_mfma_f32_16x16x32_bf16 v[140:143], v[40:43], v[168:171], v[140:143]
	v_mfma_f32_16x16x32_bf16 v[136:139], v[56:59], v[168:171], v[136:139]
	s_waitcnt lgkmcnt(5)
	v_mfma_f32_16x16x32_bf16 v[124:127], v[40:43], v[176:179], v[124:127]
	v_mfma_f32_16x16x32_bf16 v[120:123], v[56:59], v[176:179], v[120:123]
	s_waitcnt lgkmcnt(3)
	v_mfma_f32_16x16x32_bf16 v[108:111], v[40:43], v[184:187], v[108:111]
	v_mfma_f32_16x16x32_bf16 v[104:107], v[56:59], v[184:187], v[104:107]
	s_waitcnt lgkmcnt(1)
	v_mfma_f32_16x16x32_bf16 v[92:95], v[40:43], v[192:195], v[92:95]
	v_mfma_f32_16x16x32_bf16 v[88:91], v[56:59], v[192:195], v[88:91]
	v_mfma_f32_16x16x32_bf16 v[140:143], v[44:47], v[172:175], v[140:143]
	v_mfma_f32_16x16x32_bf16 v[136:139], v[60:63], v[172:175], v[136:139]
	v_mfma_f32_16x16x32_bf16 v[124:127], v[44:47], v[180:183], v[124:127]
	v_mfma_f32_16x16x32_bf16 v[120:123], v[60:63], v[180:183], v[120:123]
	v_mfma_f32_16x16x32_bf16 v[108:111], v[44:47], v[188:191], v[108:111]
	v_mfma_f32_16x16x32_bf16 v[104:107], v[60:63], v[188:191], v[104:107]
	s_waitcnt lgkmcnt(0)
	v_mfma_f32_16x16x32_bf16 v[92:95], v[44:47], v[198:201], v[92:95]
	v_mfma_f32_16x16x32_bf16 v[88:91], v[60:63], v[198:201], v[88:91]
	s_barrier
	s_setprio 0
	s_add_i32 s57, s35, s22
	v_lshl_add_u64 v[160:161], s[12:13], 0, v[148:149]
	s_mov_b32 m0, s57
	ds_read_b128 v[202:205], v167
	ds_read_b128 v[206:209], v167 offset:1024
	ds_read_b128 v[210:213], v167 offset:2048
	ds_read_b128 v[214:217], v167 offset:3072
	global_load_lds_dwordx4 v[160:161], off
	v_lshl_add_u64 v[218:219], s[12:13], 0, v[144:145]
	s_add_i32 m0, s57, 0x2000
	s_nop 0
	global_load_lds_dwordx4 v[218:219], off
	s_waitcnt lgkmcnt(3)
	s_setprio 1
	s_barrier
	v_mfma_f32_16x16x32_bf16 v[132:135], v[202:205], v[168:171], v[132:135]
	s_waitcnt lgkmcnt(1)
	v_mfma_f32_16x16x32_bf16 v[128:131], v[210:213], v[168:171], v[128:131]
	v_mfma_f32_16x16x32_bf16 v[116:119], v[202:205], v[176:179], v[116:119]
	v_mfma_f32_16x16x32_bf16 v[112:115], v[210:213], v[176:179], v[112:115]
	v_mfma_f32_16x16x32_bf16 v[100:103], v[202:205], v[184:187], v[100:103]
	v_mfma_f32_16x16x32_bf16 v[96:99], v[210:213], v[184:187], v[96:99]
	v_mfma_f32_16x16x32_bf16 v[84:87], v[202:205], v[192:195], v[84:87]
	v_mfma_f32_16x16x32_bf16 v[80:83], v[210:213], v[192:195], v[80:83]
	v_mfma_f32_16x16x32_bf16 v[132:135], v[206:209], v[172:175], v[132:135]
	s_mov_b32 m0, s9
	s_waitcnt lgkmcnt(0)
	v_mfma_f32_16x16x32_bf16 v[128:131], v[214:217], v[172:175], v[128:131]
	v_lshl_add_u64 v[220:221], s[14:15], 0, v[150:151]
	v_mfma_f32_16x16x32_bf16 v[116:119], v[206:209], v[180:183], v[116:119]
	v_mfma_f32_16x16x32_bf16 v[112:115], v[214:217], v[180:183], v[112:115]
	v_mfma_f32_16x16x32_bf16 v[100:103], v[206:209], v[188:191], v[100:103]
	v_mfma_f32_16x16x32_bf16 v[96:99], v[214:217], v[188:191], v[96:99]
	v_mfma_f32_16x16x32_bf16 v[84:87], v[206:209], v[198:201], v[84:87]
	v_mfma_f32_16x16x32_bf16 v[80:83], v[214:217], v[198:201], v[80:83]
	s_barrier
	s_setprio 0
	ds_read_b128 v[168:171], v166 offset:16384
	ds_read_b128 v[172:175], v166 offset:17408
	ds_read_b128 v[176:179], v166 offset:18432
	ds_read_b128 v[180:183], v166 offset:19456
	ds_read_b128 v[184:187], v166 offset:20480
	ds_read_b128 v[188:191], v166 offset:21504
	ds_read_b128 v[192:195], v166 offset:22528
	ds_read_b128 v[198:201], v166 offset:23552
	global_load_lds_dwordx4 v[220:221], off
	v_lshl_add_u64 v[222:223], s[14:15], 0, v[146:147]
	s_mov_b32 m0, s24
	s_nop 0
	global_load_lds_dwordx4 v[222:223], off
	s_waitcnt vmcnt(10) lgkmcnt(7)
	s_setprio 1
	s_barrier
	v_mfma_f32_16x16x32_bf16 v[76:79], v[40:43], v[168:171], v[76:79]
	v_mfma_f32_16x16x32_bf16 v[72:75], v[56:59], v[168:171], v[72:75]
	s_waitcnt lgkmcnt(5)
	v_mfma_f32_16x16x32_bf16 v[52:55], v[40:43], v[176:179], v[52:55]
	v_mfma_f32_16x16x32_bf16 v[48:51], v[56:59], v[176:179], v[48:51]
	s_waitcnt lgkmcnt(3)
	v_mfma_f32_16x16x32_bf16 v[28:31], v[40:43], v[184:187], v[28:31]
	v_mfma_f32_16x16x32_bf16 v[24:27], v[56:59], v[184:187], v[24:27]
	s_waitcnt lgkmcnt(1)
	v_mfma_f32_16x16x32_bf16 v[12:15], v[40:43], v[192:195], v[12:15]
	v_mfma_f32_16x16x32_bf16 v[8:11], v[56:59], v[192:195], v[8:11]
	v_mfma_f32_16x16x32_bf16 v[76:79], v[44:47], v[172:175], v[76:79]
	v_mfma_f32_16x16x32_bf16 v[72:75], v[60:63], v[172:175], v[72:75]
	v_mfma_f32_16x16x32_bf16 v[52:55], v[44:47], v[180:183], v[52:55]
	v_mfma_f32_16x16x32_bf16 v[48:51], v[60:63], v[180:183], v[48:51]
	v_mfma_f32_16x16x32_bf16 v[28:31], v[44:47], v[188:191], v[28:31]
	v_mfma_f32_16x16x32_bf16 v[24:27], v[60:63], v[188:191], v[24:27]
	s_waitcnt lgkmcnt(0)
	v_mfma_f32_16x16x32_bf16 v[12:15], v[44:47], v[198:201], v[12:15]
	v_mfma_f32_16x16x32_bf16 v[8:11], v[60:63], v[198:201], v[8:11]
	s_barrier
	s_setprio 0
	s_add_u32 s58, s12, 0x20000
	s_addc_u32 s59, s13, 0
	s_add_i32 s57, s36, s22
	s_mov_b32 m0, s57
	s_nop 0
	global_load_lds_dwordx4 v148, s[58:59]
	s_add_i32 m0, s57, 0x2000
	s_nop 0
	global_load_lds_dwordx4 v144, s[58:59]
	s_waitcnt vmcnt(6)
	s_setprio 1
	s_barrier
; #define PG8_STAGE(bufoff, gbase, voff) do { _Pragma("unroll") for (int _i = 0; _i < 2; ++_i) \
;         __builtin_amdgcn_global_load_lds((const unsigned*)((const char*)(gbase) + (voff)[_i]), (LAS unsigned*)(lds + (bufoff) + ldsw + _i * 8192), 16, 0, 0); } while (0)
; #define PG8_LDA(dst, b, h) do { _Pragma("unroll") for (int m = 0; m < 4; ++m) _Pragma("unroll") for (int k = 0; k < 2; ++k) dst[m][k] = *(const LAS bf16x8*)(lds + PG8_SA(b, h) + aoff + m * 2048 + k * 1024); } while (0)
; #define PG8_LDB(dst, b, h) do { _Pragma("unroll") for (int n = 0; n < 2; ++n) _Pragma("unroll") for (int k = 0; k < 2; ++k) dst[n][k] = *(const LAS bf16x8*)(lds + PG8_SB(b, h) + boff + n * 2048 + k * 1024); } while (0)
; #define PG8_WAIT_V(n) asm volatile("s_waitcnt vmcnt(" #n ")" ::: "memory")
; #define PG8_WAIT_L(n) asm volatile("s_waitcnt lgkmcnt(" #n ")" ::: "memory")
; #define PG8_BAR __builtin_amdgcn_s_barrier()
; #define PG8_SCHED __builtin_amdgcn_sched_barrier(0)
; template <class Map, class Epi>
; DI void gemm_phase(LAS unsigned char* lds, const Map& MP, const Epi& E, const int nM, const int nN, const int K, const int lda, const int ldb) {
;     ...
;             PG8_LDB(B0, 0, 0); PG8_SCHED; PG8_LDA(At, 0, 0); PG8_STAGE(PG8_SA(1, 1), a1 + hstepA, voffA);
;             PG8_WAIT_L(8); PG8_BAR; PG8_WAIT_L(0); PG8_MMA(0, 0, At, B0); PG8_BAR; PG8_SCHED;
;             PG8_LDB(B1, 0, 1); PG8_STAGE(PG8_SB(0, 0), b2, voffB);
;             PG8_BAR; PG8_WAIT_L(0); PG8_MMA(0, 1, At, B1); PG8_BAR;
;             PG8_LDA(At, 0, 1); PG8_STAGE(PG8_SA(0, 0), a2, voffA);
;             PG8_BAR; PG8_WAIT_L(0); PG8_MMA(1, 0, At, B0); PG8_BAR; PG8_SCHED;
;             PG8_STAGE(PG8_SB(0, 1), b2 + hstepB, voffB);
;             PG8_WAIT_V(6); PG8_BAR; PG8_MMA(1, 1, At, B1); PG8_BAR;
;             PG8_LDB(B0, 1, 0); PG8_SCHED; PG8_LDA(At, 1, 0); PG8_STAGE(PG8_SA(0, 1), a2 + hstepA, voffA);
;             PG8_WAIT_L(8); PG8_BAR; PG8_WAIT_L(0); PG8_MMA(0, 0, At, B0); PG8_BAR; PG8_SCHED;
;             PG8_LDB(B1, 1, 1); PG8_STAGE(PG8_SB(1, 0), b3, voffB);
;             PG8_BAR; PG8_WAIT_L(0); PG8_MMA(0, 1, At, B1); PG8_BAR;
;             PG8_LDA(At, 1, 1); PG8_STAGE(PG8_SA(1, 0), a3, voffA);
;             PG8_BAR; PG8_WAIT_L(0); PG8_MMA(1, 0, At, B0); PG8_BAR; PG8_SCHED;
;             PG8_STAGE(PG8_SB(1, 1), b3 + hstepB, voffB);
;             PG8_WAIT_V(6); PG8_BAR; PG8_MMA(1, 1, At, B1); PG8_BAR;
	v_mfma_f32_16x16x32_bf16 v[36:39], v[202:205], v[176:179], v[36:39]
	v_mfma_f32_16x16x32_bf16 v[32:35], v[210:213], v[176:179], v[32:35]
	v_mfma_f32_16x16x32_bf16 v[20:23], v[202:205], v[184:187], v[20:23]
	v_mfma_f32_16x16x32_bf16 v[16:19], v[210:213], v[184:187], v[16:19]
	v_mfma_f32_16x16x32_bf16 v[4:7], v[202:205], v[192:195], v[4:7]
	v_mfma_f32_16x16x32_bf16 v[0:3], v[210:213], v[192:195], v[0:3]
	v_mfma_f32_16x16x32_bf16 v[40:43], v[202:205], v[168:171], v[68:71]
	s_add_i32 s57, 0, 0x18000
	v_add_u32_e32 v68, s57, v164
	ds_read_b128 v[56:59], v68
	ds_read_b128 v[60:63], v68 offset:1024
	v_mfma_f32_16x16x32_bf16 v[44:47], v[210:213], v[168:171], v[64:67]
	ds_read_b128 v[64:67], v68 offset:2048
	ds_read_b128 v[68:71], v68 offset:3072
	v_mfma_f32_16x16x32_bf16 v[36:39], v[206:209], v[180:183], v[36:39]
	v_mfma_f32_16x16x32_bf16 v[32:35], v[214:217], v[180:183], v[32:35]
	v_mfma_f32_16x16x32_bf16 v[20:23], v[206:209], v[188:191], v[20:23]
	v_mfma_f32_16x16x32_bf16 v[16:19], v[214:217], v[188:191], v[16:19]
	v_mfma_f32_16x16x32_bf16 v[4:7], v[206:209], v[198:201], v[4:7]
	v_mfma_f32_16x16x32_bf16 v[0:3], v[214:217], v[198:201], v[0:3]
	v_mfma_f32_16x16x32_bf16 v[40:43], v[206:209], v[172:175], v[40:43]
	v_mfma_f32_16x16x32_bf16 v[44:47], v[214:217], v[172:175], v[44:47]
	s_barrier
	s_setprio 0
	s_add_u32 s14, s14, 0x80000
	s_addc_u32 s15, s15, 0
	s_mov_b32 m0, s25
	ds_read_b128 v[168:171], v166 offset:32768
	ds_read_b128 v[172:175], v166 offset:33792
	ds_read_b128 v[176:179], v166 offset:34816
	ds_read_b128 v[180:183], v166 offset:35840
	ds_read_b128 v[184:187], v166 offset:36864
	ds_read_b128 v[188:191], v166 offset:37888
	ds_read_b128 v[192:195], v166 offset:38912
	ds_read_b128 v[198:201], v166 offset:39936
	global_load_lds_dwordx4 v150, s[14:15]
	s_mov_b32 m0, s26
	s_nop 0
	global_load_lds_dwordx4 v146, s[14:15]
	s_waitcnt lgkmcnt(7)
	s_setprio 1
	s_barrier
	v_mfma_f32_16x16x32_bf16 v[140:143], v[56:59], v[168:171], v[140:143]
	v_mfma_f32_16x16x32_bf16 v[136:139], v[64:67], v[168:171], v[136:139]
	s_waitcnt lgkmcnt(5)
	v_mfma_f32_16x16x32_bf16 v[124:127], v[56:59], v[176:179], v[124:127]
	v_mfma_f32_16x16x32_bf16 v[120:123], v[64:67], v[176:179], v[120:123]
	s_waitcnt lgkmcnt(3)
	v_mfma_f32_16x16x32_bf16 v[108:111], v[56:59], v[184:187], v[108:111]
	v_mfma_f32_16x16x32_bf16 v[104:107], v[64:67], v[184:187], v[104:107]
	s_waitcnt lgkmcnt(1)
	v_mfma_f32_16x16x32_bf16 v[92:95], v[56:59], v[192:195], v[92:95]
	v_mfma_f32_16x16x32_bf16 v[88:91], v[64:67], v[192:195], v[88:91]
	v_mfma_f32_16x16x32_bf16 v[140:143], v[60:63], v[172:175], v[140:143]
	v_mfma_f32_16x16x32_bf16 v[136:139], v[68:71], v[172:175], v[136:139]
	v_mfma_f32_16x16x32_bf16 v[124:127], v[60:63], v[180:183], v[124:127]
	v_mfma_f32_16x16x32_bf16 v[120:123], v[68:71], v[180:183], v[120:123]
	v_mfma_f32_16x16x32_bf16 v[108:111], v[60:63], v[188:191], v[108:111]
	v_mfma_f32_16x16x32_bf16 v[104:107], v[68:71], v[188:191], v[104:107]
	s_waitcnt lgkmcnt(0)
	v_mfma_f32_16x16x32_bf16 v[92:95], v[60:63], v[198:201], v[92:95]
	v_mfma_f32_16x16x32_bf16 v[88:91], v[68:71], v[198:201], v[88:91]
	s_barrier
	s_setprio 0
	s_add_i32 s14, 0, 0x1c000
	s_add_i32 s15, s57, s22
	v_add_u32_e32 v196, s14, v164
	v_lshl_add_u64 v[160:161], v[160:161], 0, s[46:47]
	s_mov_b32 m0, s15
	ds_read_b128 v[202:205], v196
	ds_read_b128 v[206:209], v196 offset:1024
	ds_read_b128 v[210:213], v196 offset:2048
	ds_read_b128 v[214:217], v196 offset:3072
	global_load_lds_dwordx4 v[160:161], off
	v_lshl_add_u64 v[160:161], v[218:219], 0, s[46:47]
	s_add_i32 m0, s15, 0x2000
	s_nop 0
	global_load_lds_dwordx4 v[160:161], off
	s_waitcnt lgkmcnt(3)
	s_setprio 1
	s_barrier
	v_mfma_f32_16x16x32_bf16 v[132:135], v[202:205], v[168:171], v[132:135]
	s_waitcnt lgkmcnt(1)
	v_mfma_f32_16x16x32_bf16 v[128:131], v[210:213], v[168:171], v[128:131]
	v_mfma_f32_16x16x32_bf16 v[116:119], v[202:205], v[176:179], v[116:119]
	v_mfma_f32_16x16x32_bf16 v[112:115], v[210:213], v[176:179], v[112:115]
	v_mfma_f32_16x16x32_bf16 v[100:103], v[202:205], v[184:187], v[100:103]
	v_mfma_f32_16x16x32_bf16 v[96:99], v[210:213], v[184:187], v[96:99]
	v_mfma_f32_16x16x32_bf16 v[84:87], v[202:205], v[192:195], v[84:87]
	v_mfma_f32_16x16x32_bf16 v[80:83], v[210:213], v[192:195], v[80:83]
	v_mfma_f32_16x16x32_bf16 v[132:135], v[206:209], v[172:175], v[132:135]
	s_mov_b32 m0, s30
	s_waitcnt lgkmcnt(0)
	v_mfma_f32_16x16x32_bf16 v[128:131], v[214:217], v[172:175], v[128:131]
	v_lshl_add_u64 v[160:161], v[220:221], 0, s[46:47]
	v_mfma_f32_16x16x32_bf16 v[116:119], v[206:209], v[180:183], v[116:119]
	v_mfma_f32_16x16x32_bf16 v[112:115], v[214:217], v[180:183], v[112:115]
	v_mfma_f32_16x16x32_bf16 v[100:103], v[206:209], v[188:191], v[100:103]
	v_mfma_f32_16x16x32_bf16 v[96:99], v[214:217], v[188:191], v[96:99]
	v_mfma_f32_16x16x32_bf16 v[84:87], v[206:209], v[198:201], v[84:87]
	v_mfma_f32_16x16x32_bf16 v[80:83], v[214:217], v[198:201], v[80:83]
	s_barrier
	s_setprio 0
	ds_read_b128 v[168:171], v166 offset:49152
	ds_read_b128 v[172:175], v166 offset:50176
	ds_read_b128 v[176:179], v166 offset:51200
	ds_read_b128 v[180:183], v166 offset:52224
	ds_read_b128 v[184:187], v166 offset:53248
	ds_read_b128 v[188:191], v166 offset:54272
	ds_read_b128 v[192:195], v166 offset:55296
	ds_read_b128 v[198:201], v166 offset:56320
	global_load_lds_dwordx4 v[160:161], off
	v_lshl_add_u64 v[160:161], v[222:223], 0, s[46:47]
	s_mov_b32 m0, s31
	s_nop 0
	global_load_lds_dwordx4 v[160:161], off
	s_waitcnt vmcnt(10) lgkmcnt(7)
	s_setprio 1
	s_barrier
; #define PG8_WAIT_V(n) asm volatile("s_waitcnt vmcnt(" #n ")" ::: "memory")
; #define PG8_BAR __builtin_amdgcn_s_barrier()
;     DI void operator()(const f32x4 (&acc)[2][2][4][2], const Unit& u, int wr, int wc, int fr, int fq) const {
;         const int row0 = u.pm * BM + wr * 64 + fr, col0 = u.pn * BM + wc * 32 + 8 * fq;
;         f32x4 sc[2][2];
; #pragma unroll
;         for (int bj = 0; bj < 2; ++bj)
; #pragma unroll
;             for (int n = 0; n < 2; ++n) sc[bj][n] = scale ? *(const f32x4*)(scale + col0 + bj * HALF + 4 * n) : (f32x4){1.f, 1.f, 1.f, 1.f};
; #pragma unroll
;         for (int ai = 0; ai < 2; ++ai)
; #pragma unroll
;             for (int m = 0; m < 4; ++m) { const size_t ro = (size_t)(row0 + ai * HALF + m * 16) * D + col0;
; #pragma unroll
;                 for (int bj = 0; bj < 2; ++bj) {
;                     f32x4 x0, x1;
;                     if constexpr (IB) { const u32x4 w = *(const u32x4*)((const bf16_t*)Xin + ro + bj * HALF);
; template <class Map, class Epi>
; DI void gemm_phase(LAS unsigned char* lds, const Map& MP, const Epi& E, const int nM, const int nN, const int K, const int lda, const int ldb) {
;     ...
;             PG8_LDB(B0, 0, 0); PG8_SCHED; PG8_LDA(At, 0, 0); PG8_STAGE(PG8_SA(1, 1), a1 + hstepA, voffA);
;             PG8_WAIT_L(8); PG8_BAR; PG8_WAIT_L(0); PG8_MMA(0, 0, At, B0); PG8_BAR; PG8_SCHED;
;             PG8_LDB(B1, 0, 1); PG8_STAGE(PG8_SB(0, 0), b2, voffB);
;             PG8_BAR; PG8_WAIT_L(0); PG8_MMA(0, 1, At, B1); PG8_BAR;
;             PG8_LDA(At, 0, 1); PG8_STAGE(PG8_SA(0, 0), a2, voffA);
;             PG8_BAR; PG8_WAIT_L(0); PG8_MMA(1, 0, At, B0); PG8_BAR; PG8_SCHED;
;             PG8_STAGE(PG8_SB(0, 1), b2 + hstepB, voffB);
;             PG8_WAIT_V(6); PG8_BAR; PG8_MMA(1, 1, At, B1); PG8_BAR;
;             PG8_LDB(B0, 1, 0); PG8_SCHED; PG8_LDA(At, 1, 0); PG8_STAGE(PG8_SA(0, 1), a2 + hstepA, voffA);
;             PG8_WAIT_L(8); PG8_BAR; PG8_WAIT_L(0); PG8_MMA(0, 0, At, B0); PG8_BAR; PG8_SCHED;
;             PG8_LDB(B1, 1, 1); PG8_STAGE(PG8_SB(1, 0), b3, voffB);
;             PG8_BAR; PG8_WAIT_L(0); PG8_MMA(0, 1, At, B1); PG8_BAR;
;             PG8_LDA(At, 1, 1); PG8_STAGE(PG8_SA(1, 0), a3, voffA);
;             PG8_BAR; PG8_WAIT_L(0); PG8_MMA(1, 0, At, B0); PG8_BAR; PG8_SCHED;
;             PG8_STAGE(PG8_SB(1, 1), b3 + hstepB, voffB);
;             PG8_WAIT_V(6); PG8_BAR; PG8_MMA(1, 1, At, B1); PG8_BAR;
	v_mfma_f32_16x16x32_bf16 v[76:79], v[56:59], v[168:171], v[76:79]
	v_mfma_f32_16x16x32_bf16 v[72:75], v[64:67], v[168:171], v[72:75]
	s_waitcnt lgkmcnt(5)
	v_mfma_f32_16x16x32_bf16 v[52:55], v[56:59], v[176:179], v[52:55]
	v_mfma_f32_16x16x32_bf16 v[48:51], v[64:67], v[176:179], v[48:51]
	s_waitcnt lgkmcnt(3)
	v_mfma_f32_16x16x32_bf16 v[28:31], v[56:59], v[184:187], v[28:31]
	v_mfma_f32_16x16x32_bf16 v[24:27], v[64:67], v[184:187], v[24:27]
	s_waitcnt lgkmcnt(1)
	v_mfma_f32_16x16x32_bf16 v[12:15], v[56:59], v[192:195], v[12:15]
	v_mfma_f32_16x16x32_bf16 v[8:11], v[64:67], v[192:195], v[8:11]
	v_mfma_f32_16x16x32_bf16 v[76:79], v[60:63], v[172:175], v[76:79]
	v_mfma_f32_16x16x32_bf16 v[72:75], v[68:71], v[172:175], v[72:75]
	v_mfma_f32_16x16x32_bf16 v[52:55], v[60:63], v[180:183], v[52:55]
	v_mfma_f32_16x16x32_bf16 v[48:51], v[68:71], v[180:183], v[48:51]
	v_mfma_f32_16x16x32_bf16 v[28:31], v[60:63], v[188:191], v[28:31]
	v_mfma_f32_16x16x32_bf16 v[24:27], v[68:71], v[188:191], v[24:27]
	s_waitcnt lgkmcnt(0)
	v_mfma_f32_16x16x32_bf16 v[12:15], v[60:63], v[198:201], v[12:15]
	v_mfma_f32_16x16x32_bf16 v[8:11], v[68:71], v[198:201], v[8:11]
	s_barrier
	s_setprio 0
	s_add_u32 s12, s12, 0x20080
	s_addc_u32 s13, s13, 0
	s_add_i32 s14, s14, s22
	s_mov_b32 m0, s14
	s_nop 0
	global_load_lds_dwordx4 v148, s[12:13]
	s_add_i32 m0, s14, 0x2000
	s_nop 0
	global_load_lds_dwordx4 v144, s[12:13]
	s_waitcnt vmcnt(6)
	s_setprio 1
	s_barrier
	v_mfma_f32_16x16x32_bf16 v[40:43], v[202:205], v[168:171], v[40:43]
	v_mfma_f32_16x16x32_bf16 v[68:71], v[206:209], v[172:175], v[40:43]
	v_mfma_f32_16x16x32_bf16 v[40:43], v[210:213], v[168:171], v[44:47]
	v_mfma_f32_16x16x32_bf16 v[36:39], v[202:205], v[176:179], v[36:39]
	v_mfma_f32_16x16x32_bf16 v[32:35], v[210:213], v[176:179], v[32:35]
	v_mfma_f32_16x16x32_bf16 v[20:23], v[202:205], v[184:187], v[20:23]
	v_mfma_f32_16x16x32_bf16 v[16:19], v[210:213], v[184:187], v[16:19]
	v_mfma_f32_16x16x32_bf16 v[4:7], v[202:205], v[192:195], v[4:7]
	v_mfma_f32_16x16x32_bf16 v[0:3], v[210:213], v[192:195], v[0:3]
	s_add_i32 s3, s3, 2
	v_mfma_f32_16x16x32_bf16 v[64:67], v[214:217], v[172:175], v[40:43]
	s_add_u32 s53, s53, 0x100
	s_addc_u32 s56, s56, 0
	ds_read_b128 v[40:43], v165
	ds_read_b128 v[44:47], v165 offset:1024
	ds_read_b128 v[56:59], v165 offset:2048
	ds_read_b128 v[60:63], v165 offset:3072
	v_mfma_f32_16x16x32_bf16 v[36:39], v[206:209], v[180:183], v[36:39]
	s_add_u32 s10, s10, 0x100
	s_addc_u32 s11, s11, 0
	v_mfma_f32_16x16x32_bf16 v[32:35], v[214:217], v[180:183], v[32:35]
	s_cmp_gt_u32 s3, 5
	v_mfma_f32_16x16x32_bf16 v[20:23], v[206:209], v[188:191], v[20:23]
	v_mfma_f32_16x16x32_bf16 v[16:19], v[214:217], v[188:191], v[16:19]
	v_mfma_f32_16x16x32_bf16 v[4:7], v[206:209], v[198:201], v[4:7]
	v_mfma_f32_16x16x32_bf16 v[0:3], v[214:217], v[198:201], v[0:3]
	s_barrier
	s_setprio 0
	s_cbranch_scc0 .LBB1_2339
	s_waitcnt lgkmcnt(0)
	s_lshl_b32 s2, s2, 8
	v_mov_b32_e32 v40, v163
	v_mov_b32_e32 v168, v162
	s_or_b32 s2, s2, s29
	s_and_b64 vcc, exec, s[40:41]
	v_lshl_add_u32 v160, v40, 3, s2
	s_lshl_b32 s2, s8, 8
	s_add_i32 s2, s2, s28
	v_add_u32_e32 v168, s2, v168
	v_ashrrev_i32_e32 v169, 31, v168
	v_ashrrev_i32_e32 v161, 31, v160
	v_lshlrev_b64 v[168:169], 11, v[168:169]
	v_lshl_add_u64 v[44:45], v[160:161], 2, s[44:45]
	v_lshl_add_u64 v[160:161], v[168:169], 0, v[160:161]
	v_lshlrev_b64 v[160:161], 1, v[160:161]
	v_lshl_add_u64 v[172:173], s[4:5], 0, v[160:161]
	global_load_dwordx4 v[56:59], v[44:45], off offset:16
	global_load_dwordx4 v[60:63], v[44:45], off
	global_load_dwordx4 v[40:43], v[44:45], off offset:528
	s_nop 0
	global_load_dwordx4 v[44:47], v[44:45], off offset:512
	s_mov_b64 s[2:3], 0x10000
	global_load_dwordx4 v[178:181], v[172:173], off
	global_load_dwordx4 v[182:185], v[172:173], off offset:256
	s_mov_b64 s[98:99], 0x10000
	v_lshl_add_u64 v[170:171], v[172:173], 0, s[98:99]
	global_load_dwordx4 v[186:189], v[170:171], off
	global_load_dwordx4 v[190:193], v[170:171], off offset:256
	s_mov_b64 s[98:99], 0x20000
	v_lshl_add_u64 v[170:171], v[172:173], 0, s[98:99]
	global_load_dwordx4 v[198:201], v[170:171], off
	global_load_dwordx4 v[202:205], v[170:171], off offset:256
	s_mov_b64 s[98:99], 0x30000
	v_lshl_add_u64 v[170:171], v[172:173], 0, s[98:99]
	global_load_dwordx4 v[206:209], v[170:171], off
	global_load_dwordx4 v[210:213], v[170:171], off offset:256
	s_mov_b64 s[98:99], 0x80000
	v_lshl_add_u64 v[170:171], v[172:173], 0, s[98:99]
	global_load_dwordx4 v[214:217], v[170:171], off
	global_load_dwordx4 v[248:251], v[170:171], off offset:256
	s_mov_b64 s[98:99], 0x90000
	v_lshl_add_u64 v[170:171], v[172:173], 0, s[98:99]
	global_load_dwordx4 v[252:255], v[170:171], off
	s_waitcnt vmcnt(10)
	s_nop 1
	v_mov_b32_e32 v168, v178
	v_mov_b32_e32 v169, v179
	v_mov_b32_e32 v170, v180
	v_mov_b32_e32 v171, v181
	s_mov_b32 s8, s52
	s_mov_b64 s[10:11], s[54:55]
	s_mov_b64 s[12:13], s[6:7]
	s_waitcnt lgkmcnt(0)
	v_lshlrev_b32_e32 v174, 16, v168
	v_and_b32_e32 v175, 0xffff0000, v168
	v_lshlrev_b32_e32 v168, 16, v169
	v_and_b32_e32 v169, 0xffff0000, v169
	v_lshlrev_b32_e32 v176, 16, v170
	v_and_b32_e32 v177, 0xffff0000, v170
	v_lshlrev_b32_e32 v170, 16, v171
	v_and_b32_e32 v171, 0xffff0000, v171
	v_pk_fma_f32 v[142:143], v[142:143], v[62:63], v[168:169]
	v_pk_fma_f32 v[140:141], v[140:141], v[60:61], v[174:175]
	v_pk_fma_f32 v[168:169], v[138:139], v[58:59], v[170:171]
	v_pk_fma_f32 v[138:139], v[136:137], v[56:57], v[176:177]
	v_cvt_pk_bf16_f32 v136, v140, v141
	v_cvt_pk_bf16_f32 v137, v142, v143
	v_cvt_pk_bf16_f32 v138, v138, v139
	v_cvt_pk_bf16_f32 v139, v168, v169
	v_lshl_add_u64 v[140:141], s[42:43], 0, v[160:161]
	global_store_dwordx4 v[140:141], v[136:139], off
	s_waitcnt vmcnt(10)
; DI unsigned pack2(float a, float b) { f32x2 v = {a, b}; hwbf16x2 r = __builtin_convertvector(v, hwbf16x2); return __builtin_bit_cast(unsigned, r); }
; DI float bflo(unsigned w) { return __uint_as_float(w << 16); }
; DI float bfhi(unsigned w) { return __uint_as_float(w & 0xffff0000u); }
;     DI void operator()(const f32x4 (&acc)[2][2][4][2], const Unit& u, int wr, int wc, int fr, int fq) const {
;         const int row0 = u.pm * BM + wr * 64 + fr, col0 = u.pn * BM + wc * 32 + 8 * fq;
;         f32x4 sc[2][2];
; #pragma unroll
;         for (int bj = 0; bj < 2; ++bj)
; #pragma unroll
;             for (int n = 0; n < 2; ++n) sc[bj][n] = scale ? *(const f32x4*)(scale + col0 + bj * HALF + 4 * n) : (f32x4){1.f, 1.f, 1.f, 1.f};
; #pragma unroll
;         for (int ai = 0; ai < 2; ++ai)
; #pragma unroll
;             for (int m = 0; m < 4; ++m) { const size_t ro = (size_t)(row0 + ai * HALF + m * 16) * D + col0;
; #pragma unroll
;                 for (int bj = 0; bj < 2; ++bj) {
;                     f32x4 x0, x1;
;                     if constexpr (IB) { const u32x4 w = *(const u32x4*)((const bf16_t*)Xin + ro + bj * HALF);
;                         x0 = (f32x4){bflo(w[0]), bfhi(w[0]), bflo(w[1]), bfhi(w[1])}; x1 = (f32x4){bflo(w[2]), bfhi(w[2]), bflo(w[3]), bfhi(w[3])}; }
;                     else { x0 = *(const f32x4*)((const float*)Xin + ro + bj * HALF); x1 = *(const f32x4*)((const float*)Xin + ro + bj * HALF + 4); }
;                     x0 += acc[ai][bj][m][0] * sc[bj][0]; x1 += acc[ai][bj][m][1] * sc[bj][1];
;                     if constexpr (OB) { u32x4 o; o[0] = pack2(x0[0], x0[1]); o[1] = pack2(x0[2], x0[3]); o[2] = pack2(x1[0], x1[1]); o[3] = pack2(x1[2], x1[3]);
;                         *(u32x4*)((bf16_t*)Xout + ro + bj * HALF) = o; }
;                     else { *(f32x4*)((float*)Xout + ro + bj * HALF) = x0; *(f32x4*)((float*)Xout + ro + bj * HALF + 4) = x1; } } }
	s_nop 1
	v_mov_b32_e32 v136, v182
	v_mov_b32_e32 v137, v183
	v_mov_b32_e32 v138, v184
	v_mov_b32_e32 v139, v185
	s_waitcnt lgkmcnt(0)
	v_lshlrev_b32_e32 v142, 16, v136
	v_and_b32_e32 v143, 0xffff0000, v136
	v_lshlrev_b32_e32 v136, 16, v137
	v_and_b32_e32 v137, 0xffff0000, v137
	v_lshlrev_b32_e32 v168, 16, v138
	v_and_b32_e32 v169, 0xffff0000, v138
	v_lshlrev_b32_e32 v138, 16, v139
	v_and_b32_e32 v139, 0xffff0000, v139
	v_pk_fma_f32 v[134:135], v[134:135], v[46:47], v[136:137]
	v_pk_fma_f32 v[132:133], v[132:133], v[44:45], v[142:143]
	v_pk_fma_f32 v[136:137], v[130:131], v[42:43], v[138:139]
	v_pk_fma_f32 v[130:131], v[128:129], v[40:41], v[168:169]
	v_cvt_pk_bf16_f32 v128, v132, v133
	v_cvt_pk_bf16_f32 v129, v134, v135
	v_cvt_pk_bf16_f32 v130, v130, v131
	v_cvt_pk_bf16_f32 v131, v136, v137
	v_lshl_add_u64 v[132:133], v[160:161], 0, s[2:3]
	global_store_dwordx4 v[140:141], v[128:131], off offset:256
	v_lshl_add_u64 v[134:135], s[4:5], 0, v[132:133]
	s_waitcnt vmcnt(10)
	s_nop 1
	v_mov_b32_e32 v128, v186
	v_mov_b32_e32 v129, v187
	v_mov_b32_e32 v130, v188
	v_mov_b32_e32 v131, v189
	s_mov_b64 s[2:3], 0x20000
	s_waitcnt lgkmcnt(0)
	v_lshlrev_b32_e32 v136, 16, v128
	v_and_b32_e32 v137, 0xffff0000, v128
	v_lshlrev_b32_e32 v128, 16, v129
	v_and_b32_e32 v129, 0xffff0000, v129
	v_lshlrev_b32_e32 v138, 16, v130
	v_and_b32_e32 v139, 0xffff0000, v130
	v_lshlrev_b32_e32 v130, 16, v131
	v_and_b32_e32 v131, 0xffff0000, v131
	v_pk_fma_f32 v[126:127], v[126:127], v[62:63], v[128:129]
	v_pk_fma_f32 v[124:125], v[124:125], v[60:61], v[136:137]
	v_pk_fma_f32 v[128:129], v[122:123], v[58:59], v[130:131]
	v_pk_fma_f32 v[122:123], v[120:121], v[56:57], v[138:139]
	v_cvt_pk_bf16_f32 v120, v124, v125
	v_cvt_pk_bf16_f32 v121, v126, v127
	v_cvt_pk_bf16_f32 v122, v122, v123
	v_cvt_pk_bf16_f32 v123, v128, v129
	v_lshl_add_u64 v[124:125], s[42:43], 0, v[132:133]
	global_store_dwordx4 v[124:125], v[120:123], off
	s_waitcnt vmcnt(10)
	s_nop 1
	v_mov_b32_e32 v120, v190
	v_mov_b32_e32 v121, v191
	v_mov_b32_e32 v122, v192
	v_mov_b32_e32 v123, v193
	s_waitcnt lgkmcnt(0)
	v_lshlrev_b32_e32 v126, 16, v120
	v_and_b32_e32 v127, 0xffff0000, v120
	v_lshlrev_b32_e32 v120, 16, v121
	v_and_b32_e32 v121, 0xffff0000, v121
	v_lshlrev_b32_e32 v128, 16, v122
	v_and_b32_e32 v129, 0xffff0000, v122
	v_lshlrev_b32_e32 v122, 16, v123
	v_and_b32_e32 v123, 0xffff0000, v123
	v_pk_fma_f32 v[118:119], v[118:119], v[46:47], v[120:121]
	v_pk_fma_f32 v[116:117], v[116:117], v[44:45], v[126:127]
	v_pk_fma_f32 v[120:121], v[114:115], v[42:43], v[122:123]
	v_pk_fma_f32 v[114:115], v[112:113], v[40:41], v[128:129]
	v_cvt_pk_bf16_f32 v112, v116, v117
	v_cvt_pk_bf16_f32 v113, v118, v119
	v_cvt_pk_bf16_f32 v114, v114, v115
	v_cvt_pk_bf16_f32 v115, v120, v121
	v_lshl_add_u64 v[116:117], v[160:161], 0, s[2:3]
	global_store_dwordx4 v[124:125], v[112:115], off offset:256
	v_lshl_add_u64 v[118:119], s[4:5], 0, v[116:117]
	s_waitcnt vmcnt(10)
	s_nop 1
	v_mov_b32_e32 v112, v198
	v_mov_b32_e32 v113, v199
	v_mov_b32_e32 v114, v200
	v_mov_b32_e32 v115, v201
	s_mov_b64 s[2:3], 0x30000
	s_waitcnt lgkmcnt(0)
	v_lshlrev_b32_e32 v120, 16, v112
	v_and_b32_e32 v121, 0xffff0000, v112
	v_lshlrev_b32_e32 v112, 16, v113
	v_and_b32_e32 v113, 0xffff0000, v113
	v_lshlrev_b32_e32 v122, 16, v114
	v_and_b32_e32 v123, 0xffff0000, v114
	v_lshlrev_b32_e32 v114, 16, v115
	v_and_b32_e32 v115, 0xffff0000, v115
	v_pk_fma_f32 v[110:111], v[110:111], v[62:63], v[112:113]
	v_pk_fma_f32 v[108:109], v[108:109], v[60:61], v[120:121]
	v_pk_fma_f32 v[112:113], v[106:107], v[58:59], v[114:115]
	v_pk_fma_f32 v[106:107], v[104:105], v[56:57], v[122:123]
	v_cvt_pk_bf16_f32 v104, v108, v109
	v_cvt_pk_bf16_f32 v105, v110, v111
	v_cvt_pk_bf16_f32 v106, v106, v107
	v_cvt_pk_bf16_f32 v107, v112, v113
	v_lshl_add_u64 v[108:109], s[42:43], 0, v[116:117]
	global_store_dwordx4 v[108:109], v[104:107], off
	s_waitcnt vmcnt(10)
	s_nop 1
	v_mov_b32_e32 v104, v202
	v_mov_b32_e32 v105, v203
	v_mov_b32_e32 v106, v204
	v_mov_b32_e32 v107, v205
	s_waitcnt lgkmcnt(0)
	v_lshlrev_b32_e32 v110, 16, v104
	v_and_b32_e32 v111, 0xffff0000, v104
	v_lshlrev_b32_e32 v104, 16, v105
	v_and_b32_e32 v105, 0xffff0000, v105
	v_lshlrev_b32_e32 v112, 16, v106
	v_and_b32_e32 v113, 0xffff0000, v106
	v_lshlrev_b32_e32 v106, 16, v107
	v_and_b32_e32 v107, 0xffff0000, v107
	v_pk_fma_f32 v[102:103], v[102:103], v[46:47], v[104:105]
	v_pk_fma_f32 v[100:101], v[100:101], v[44:45], v[110:111]
	v_pk_fma_f32 v[104:105], v[98:99], v[42:43], v[106:107]
	v_pk_fma_f32 v[98:99], v[96:97], v[40:41], v[112:113]
	v_cvt_pk_bf16_f32 v96, v100, v101
	v_cvt_pk_bf16_f32 v97, v102, v103
	v_cvt_pk_bf16_f32 v98, v98, v99
	v_cvt_pk_bf16_f32 v99, v104, v105
	v_lshl_add_u64 v[100:101], v[160:161], 0, s[2:3]
	global_store_dwordx4 v[108:109], v[96:99], off offset:256
	v_lshl_add_u64 v[102:103], s[4:5], 0, v[100:101]
	s_waitcnt vmcnt(10)
	s_nop 1
	v_mov_b32_e32 v96, v206
	v_mov_b32_e32 v97, v207
	v_mov_b32_e32 v98, v208
	v_mov_b32_e32 v99, v209
	s_mov_b64 s[2:3], 0x80000
	s_waitcnt lgkmcnt(0)
	v_lshlrev_b32_e32 v104, 16, v96
	v_and_b32_e32 v105, 0xffff0000, v96
	v_lshlrev_b32_e32 v96, 16, v97
	v_and_b32_e32 v97, 0xffff0000, v97
	v_lshlrev_b32_e32 v106, 16, v98
	v_and_b32_e32 v107, 0xffff0000, v98
	v_lshlrev_b32_e32 v98, 16, v99
	v_and_b32_e32 v99, 0xffff0000, v99
	v_pk_fma_f32 v[94:95], v[94:95], v[62:63], v[96:97]
	v_pk_fma_f32 v[92:93], v[92:93], v[60:61], v[104:105]
	v_pk_fma_f32 v[96:97], v[90:91], v[58:59], v[98:99]
	v_pk_fma_f32 v[90:91], v[88:89], v[56:57], v[106:107]
	v_cvt_pk_bf16_f32 v88, v92, v93
	v_cvt_pk_bf16_f32 v89, v94, v95
	v_cvt_pk_bf16_f32 v90, v90, v91
	v_cvt_pk_bf16_f32 v91, v96, v97
	v_lshl_add_u64 v[92:93], s[42:43], 0, v[100:101]
	global_store_dwordx4 v[92:93], v[88:91], off
	s_waitcnt vmcnt(10)
; DI unsigned pack2(float a, float b) { f32x2 v = {a, b}; hwbf16x2 r = __builtin_convertvector(v, hwbf16x2); return __builtin_bit_cast(unsigned, r); }
; DI float bflo(unsigned w) { return __uint_as_float(w << 16); }
; DI float bfhi(unsigned w) { return __uint_as_float(w & 0xffff0000u); }
;     DI void operator()(const f32x4 (&acc)[2][2][4][2], const Unit& u, int wr, int wc, int fr, int fq) const {
;         const int row0 = u.pm * BM + wr * 64 + fr, col0 = u.pn * BM + wc * 32 + 8 * fq;
;         f32x4 sc[2][2];
; #pragma unroll
;         for (int bj = 0; bj < 2; ++bj)
; #pragma unroll
;             for (int n = 0; n < 2; ++n) sc[bj][n] = scale ? *(const f32x4*)(scale + col0 + bj * HALF + 4 * n) : (f32x4){1.f, 1.f, 1.f, 1.f};
; #pragma unroll
;         for (int ai = 0; ai < 2; ++ai)
; #pragma unroll
;             for (int m = 0; m < 4; ++m) { const size_t ro = (size_t)(row0 + ai * HALF + m * 16) * D + col0;
; #pragma unroll
;                 for (int bj = 0; bj < 2; ++bj) {
;                     f32x4 x0, x1;
;                     if constexpr (IB) { const u32x4 w = *(const u32x4*)((const bf16_t*)Xin + ro + bj * HALF);
;                         x0 = (f32x4){bflo(w[0]), bfhi(w[0]), bflo(w[1]), bfhi(w[1])}; x1 = (f32x4){bflo(w[2]), bfhi(w[2]), bflo(w[3]), bfhi(w[3])}; }
;                     else { x0 = *(const f32x4*)((const float*)Xin + ro + bj * HALF); x1 = *(const f32x4*)((const float*)Xin + ro + bj * HALF + 4); }
;                     x0 += acc[ai][bj][m][0] * sc[bj][0]; x1 += acc[ai][bj][m][1] * sc[bj][1];
;                     if constexpr (OB) { u32x4 o; o[0] = pack2(x0[0], x0[1]); o[1] = pack2(x0[2], x0[3]); o[2] = pack2(x1[0], x1[1]); o[3] = pack2(x1[2], x1[3]);
;                         *(u32x4*)((bf16_t*)Xout + ro + bj * HALF) = o; }
;                     else { *(f32x4*)((float*)Xout + ro + bj * HALF) = x0; *(f32x4*)((float*)Xout + ro + bj * HALF + 4) = x1; } } }
	s_nop 1
	v_mov_b32_e32 v88, v210
	v_mov_b32_e32 v89, v211
	v_mov_b32_e32 v90, v212
	v_mov_b32_e32 v91, v213
	s_waitcnt lgkmcnt(0)
	v_lshlrev_b32_e32 v94, 16, v88
	v_and_b32_e32 v95, 0xffff0000, v88
	v_lshlrev_b32_e32 v88, 16, v89
	v_and_b32_e32 v89, 0xffff0000, v89
	v_lshlrev_b32_e32 v96, 16, v90
	v_and_b32_e32 v97, 0xffff0000, v90
	v_lshlrev_b32_e32 v90, 16, v91
	v_and_b32_e32 v91, 0xffff0000, v91
	v_pk_fma_f32 v[86:87], v[86:87], v[46:47], v[88:89]
	v_pk_fma_f32 v[84:85], v[84:85], v[44:45], v[94:95]
	v_pk_fma_f32 v[88:89], v[82:83], v[42:43], v[90:91]
	v_pk_fma_f32 v[82:83], v[80:81], v[40:41], v[96:97]
	v_cvt_pk_bf16_f32 v80, v84, v85
	v_cvt_pk_bf16_f32 v81, v86, v87
	v_cvt_pk_bf16_f32 v82, v82, v83
	v_cvt_pk_bf16_f32 v83, v88, v89
	v_lshl_add_u64 v[84:85], v[160:161], 0, s[2:3]
	global_store_dwordx4 v[92:93], v[80:83], off offset:256
	v_lshl_add_u64 v[86:87], s[4:5], 0, v[84:85]
	s_waitcnt vmcnt(10)
	s_nop 1
	v_mov_b32_e32 v80, v214
	v_mov_b32_e32 v81, v215
	v_mov_b32_e32 v82, v216
	v_mov_b32_e32 v83, v217
	s_mov_b64 s[2:3], 0x90000
	s_waitcnt lgkmcnt(0)
	v_lshlrev_b32_e32 v88, 16, v80
	v_and_b32_e32 v89, 0xffff0000, v80
	v_lshlrev_b32_e32 v80, 16, v81
	v_and_b32_e32 v81, 0xffff0000, v81
	v_lshlrev_b32_e32 v90, 16, v82
	v_and_b32_e32 v91, 0xffff0000, v82
	v_lshlrev_b32_e32 v82, 16, v83
	v_and_b32_e32 v83, 0xffff0000, v83
	v_pk_fma_f32 v[78:79], v[78:79], v[62:63], v[80:81]
	v_pk_fma_f32 v[76:77], v[76:77], v[60:61], v[88:89]
	v_pk_fma_f32 v[80:81], v[74:75], v[58:59], v[82:83]
	v_pk_fma_f32 v[74:75], v[72:73], v[56:57], v[90:91]
	v_cvt_pk_bf16_f32 v72, v76, v77
	v_cvt_pk_bf16_f32 v73, v78, v79
	v_cvt_pk_bf16_f32 v74, v74, v75
	v_cvt_pk_bf16_f32 v75, v80, v81
	v_lshl_add_u64 v[76:77], s[42:43], 0, v[84:85]
	global_store_dwordx4 v[76:77], v[72:75], off
	s_waitcnt vmcnt(10)
	s_nop 1
	v_mov_b32_e32 v72, v248
	v_mov_b32_e32 v73, v249
	v_mov_b32_e32 v74, v250
	v_mov_b32_e32 v75, v251
	s_waitcnt lgkmcnt(0)
	v_lshlrev_b32_e32 v78, 16, v72
	v_and_b32_e32 v79, 0xffff0000, v72
	v_lshlrev_b32_e32 v72, 16, v73
	v_and_b32_e32 v73, 0xffff0000, v73
	v_lshlrev_b32_e32 v80, 16, v74
	v_and_b32_e32 v81, 0xffff0000, v74
	v_lshlrev_b32_e32 v74, 16, v75
	v_and_b32_e32 v75, 0xffff0000, v75
	v_pk_fma_f32 v[70:71], v[70:71], v[46:47], v[72:73]
	v_pk_fma_f32 v[68:69], v[68:69], v[44:45], v[78:79]
	v_pk_fma_f32 v[72:73], v[66:67], v[42:43], v[74:75]
	v_pk_fma_f32 v[66:67], v[64:65], v[40:41], v[80:81]
	v_cvt_pk_bf16_f32 v64, v68, v69
	v_cvt_pk_bf16_f32 v65, v70, v71
	v_cvt_pk_bf16_f32 v66, v66, v67
	v_cvt_pk_bf16_f32 v67, v72, v73
	v_lshl_add_u64 v[68:69], v[160:161], 0, s[2:3]
	global_store_dwordx4 v[76:77], v[64:67], off offset:256
	v_lshl_add_u64 v[70:71], s[4:5], 0, v[68:69]
	s_waitcnt vmcnt(10)
	s_nop 1
	v_mov_b32_e32 v64, v252
	v_mov_b32_e32 v65, v253
	v_mov_b32_e32 v66, v254
	v_mov_b32_e32 v67, v255
	s_mov_b64 s[2:3], 0xa0000
	s_waitcnt lgkmcnt(0)
	v_lshlrev_b32_e32 v72, 16, v64
	v_and_b32_e32 v73, 0xffff0000, v64
	v_lshlrev_b32_e32 v64, 16, v65
	v_and_b32_e32 v65, 0xffff0000, v65
	v_lshlrev_b32_e32 v74, 16, v66
	v_and_b32_e32 v75, 0xffff0000, v66
	v_lshlrev_b32_e32 v66, 16, v67
	v_and_b32_e32 v67, 0xffff0000, v67
	v_pk_fma_f32 v[54:55], v[54:55], v[62:63], v[64:65]
	v_pk_fma_f32 v[52:53], v[52:53], v[60:61], v[72:73]
	v_pk_fma_f32 v[64:65], v[50:51], v[58:59], v[66:67]
	v_pk_fma_f32 v[50:51], v[48:49], v[56:57], v[74:75]
	v_cvt_pk_bf16_f32 v48, v52, v53
	v_cvt_pk_bf16_f32 v49, v54, v55
	v_cvt_pk_bf16_f32 v50, v50, v51
	v_cvt_pk_bf16_f32 v51, v64, v65
	v_lshl_add_u64 v[52:53], s[42:43], 0, v[68:69]
	global_store_dwordx4 v[52:53], v[48:51], off
	global_load_dwordx4 v[48:51], v[70:71], off offset:256
	s_waitcnt vmcnt(0) lgkmcnt(0)
; DI unsigned pack2(float a, float b) { f32x2 v = {a, b}; hwbf16x2 r = __builtin_convertvector(v, hwbf16x2); return __builtin_bit_cast(unsigned, r); }
;     DI void operator()(const f32x4 (&acc)[2][2][4][2], const Unit& u, int wr, int wc, int fr, int fq) const {
;         const int row0 = u.pm * BM + wr * 64 + fr, col0 = u.pn * BM + wc * 32 + 8 * fq;
;         f32x4 sc[2][2];
; #pragma unroll
;         for (int bj = 0; bj < 2; ++bj)
; #pragma unroll
;             for (int n = 0; n < 2; ++n) sc[bj][n] = scale ? *(const f32x4*)(scale + col0 + bj * HALF + 4 * n) : (f32x4){1.f, 1.f, 1.f, 1.f};
; #pragma unroll
;         for (int ai = 0; ai < 2; ++ai)
; #pragma unroll
;             for (int m = 0; m < 4; ++m) { const size_t ro = (size_t)(row0 + ai * HALF + m * 16) * D + col0;
; #pragma unroll
;                 for (int bj = 0; bj < 2; ++bj) {
;                     f32x4 x0, x1;
;                     if constexpr (IB) { const u32x4 w = *(const u32x4*)((const bf16_t*)Xin + ro + bj * HALF);
;                         x0 = (f32x4){bflo(w[0]), bfhi(w[0]), bflo(w[1]), bfhi(w[1])}; x1 = (f32x4){bflo(w[2]), bfhi(w[2]), bflo(w[3]), bfhi(w[3])}; }
;                     else { x0 = *(const f32x4*)((const float*)Xin + ro + bj * HALF); x1 = *(const f32x4*)((const float*)Xin + ro + bj * HALF + 4); }
;                     x0 += acc[ai][bj][m][0] * sc[bj][0]; x1 += acc[ai][bj][m][1] * sc[bj][1];
;                     if constexpr (OB) { u32x4 o; o[0] = pack2(x0[0], x0[1]); o[1] = pack2(x0[2], x0[3]); o[2] = pack2(x1[0], x1[1]); o[3] = pack2(x1[2], x1[3]);
;                         *(u32x4*)((bf16_t*)Xout + ro + bj * HALF) = o; }
;                     else { *(f32x4*)((float*)Xout + ro + bj * HALF) = x0; *(f32x4*)((float*)Xout + ro + bj * HALF + 4) = x1; } } }
; template <class Map, class Epi>
; DI void gemm_phase(LAS unsigned char* lds, const Map& MP, const Epi& E, const int nM, const int nN, const int K, const int lda, const int ldb) {
;     ...
;         if (!has_next) break;
; #pragma unroll
;         for (int a = 0; a < 2; ++a)
; #pragma unroll
;             for (int b = 0; b < 2; ++b)
; #pragma unroll
;                 for (int m = 0; m < 4; ++m)
; #pragma unroll
;                     for (int n = 0; n < 2; ++n) acc[a][b][m][n] = (f32x4){0.f, 0.f, 0.f, 0.f};
;         cur = nxt; cA = nA; cB = nB; ++ui;
;     }
;     PG8_WAIT_V(0);
;     if (wr == 0) PG8_BAR;
;     PG8_BAR;
	v_lshlrev_b32_e32 v54, 16, v48
	v_and_b32_e32 v55, 0xffff0000, v48
	v_lshlrev_b32_e32 v48, 16, v49
	v_and_b32_e32 v49, 0xffff0000, v49
	v_lshlrev_b32_e32 v64, 16, v50
	v_and_b32_e32 v65, 0xffff0000, v50
	v_lshlrev_b32_e32 v50, 16, v51
	v_and_b32_e32 v51, 0xffff0000, v51
	v_pk_fma_f32 v[38:39], v[38:39], v[46:47], v[48:49]
	v_pk_fma_f32 v[36:37], v[36:37], v[44:45], v[54:55]
	v_pk_fma_f32 v[48:49], v[34:35], v[42:43], v[50:51]
	v_pk_fma_f32 v[34:35], v[32:33], v[40:41], v[64:65]
	v_cvt_pk_bf16_f32 v32, v36, v37
	v_cvt_pk_bf16_f32 v33, v38, v39
	v_cvt_pk_bf16_f32 v34, v34, v35
	v_cvt_pk_bf16_f32 v35, v48, v49
	v_lshl_add_u64 v[36:37], v[160:161], 0, s[2:3]
	global_store_dwordx4 v[52:53], v[32:35], off offset:256
	v_lshl_add_u64 v[38:39], s[4:5], 0, v[36:37]
	global_load_dwordx4 v[32:35], v[38:39], off
	s_mov_b64 s[2:3], 0xb0000
	s_waitcnt vmcnt(0) lgkmcnt(0)
	v_lshlrev_b32_e32 v48, 16, v32
	v_and_b32_e32 v49, 0xffff0000, v32
	v_lshlrev_b32_e32 v32, 16, v33
	v_and_b32_e32 v33, 0xffff0000, v33
	v_lshlrev_b32_e32 v50, 16, v34
	v_and_b32_e32 v51, 0xffff0000, v34
	v_lshlrev_b32_e32 v34, 16, v35
	v_and_b32_e32 v35, 0xffff0000, v35
	v_pk_fma_f32 v[30:31], v[30:31], v[62:63], v[32:33]
	v_pk_fma_f32 v[28:29], v[28:29], v[60:61], v[48:49]
	v_pk_fma_f32 v[32:33], v[26:27], v[58:59], v[34:35]
	v_pk_fma_f32 v[26:27], v[24:25], v[56:57], v[50:51]
	v_cvt_pk_bf16_f32 v24, v28, v29
	v_cvt_pk_bf16_f32 v25, v30, v31
	v_cvt_pk_bf16_f32 v26, v26, v27
	v_cvt_pk_bf16_f32 v27, v32, v33
	v_lshl_add_u64 v[28:29], s[42:43], 0, v[36:37]
	global_store_dwordx4 v[28:29], v[24:27], off
	global_load_dwordx4 v[24:27], v[38:39], off offset:256
	s_waitcnt vmcnt(0) lgkmcnt(0)
	v_lshlrev_b32_e32 v30, 16, v24
	v_and_b32_e32 v31, 0xffff0000, v24
	v_lshlrev_b32_e32 v24, 16, v25
	v_and_b32_e32 v25, 0xffff0000, v25
	v_lshlrev_b32_e32 v32, 16, v26
	v_and_b32_e32 v33, 0xffff0000, v26
	v_lshlrev_b32_e32 v26, 16, v27
	v_and_b32_e32 v27, 0xffff0000, v27
	v_pk_fma_f32 v[22:23], v[22:23], v[46:47], v[24:25]
	v_pk_fma_f32 v[20:21], v[20:21], v[44:45], v[30:31]
	v_pk_fma_f32 v[24:25], v[18:19], v[42:43], v[26:27]
	v_pk_fma_f32 v[18:19], v[16:17], v[40:41], v[32:33]
	v_cvt_pk_bf16_f32 v16, v20, v21
	v_cvt_pk_bf16_f32 v17, v22, v23
	v_cvt_pk_bf16_f32 v18, v18, v19
	v_cvt_pk_bf16_f32 v19, v24, v25
	v_lshl_add_u64 v[20:21], v[160:161], 0, s[2:3]
	global_store_dwordx4 v[28:29], v[16:19], off offset:256
	v_lshl_add_u64 v[22:23], s[4:5], 0, v[20:21]
	global_load_dwordx4 v[16:19], v[22:23], off
	s_mov_b32 s2, s37
	s_waitcnt vmcnt(0) lgkmcnt(0)
	v_lshlrev_b32_e32 v24, 16, v16
	v_and_b32_e32 v25, 0xffff0000, v16
	v_lshlrev_b32_e32 v16, 16, v17
	v_and_b32_e32 v17, 0xffff0000, v17
	v_lshlrev_b32_e32 v26, 16, v18
	v_and_b32_e32 v27, 0xffff0000, v18
	v_lshlrev_b32_e32 v18, 16, v19
	v_and_b32_e32 v19, 0xffff0000, v19
	v_pk_fma_f32 v[14:15], v[14:15], v[62:63], v[16:17]
	v_pk_fma_f32 v[12:13], v[12:13], v[60:61], v[24:25]
	v_pk_fma_f32 v[16:17], v[10:11], v[58:59], v[18:19]
	v_pk_fma_f32 v[10:11], v[8:9], v[56:57], v[26:27]
	v_cvt_pk_bf16_f32 v8, v12, v13
	v_cvt_pk_bf16_f32 v9, v14, v15
	v_cvt_pk_bf16_f32 v10, v10, v11
	v_cvt_pk_bf16_f32 v11, v16, v17
	v_lshl_add_u64 v[12:13], s[42:43], 0, v[20:21]
	global_store_dwordx4 v[12:13], v[8:11], off
	global_load_dwordx4 v[8:11], v[22:23], off offset:256
	s_waitcnt vmcnt(0) lgkmcnt(0)
	v_lshlrev_b32_e32 v14, 16, v8
	v_and_b32_e32 v15, 0xffff0000, v8
	v_lshlrev_b32_e32 v8, 16, v9
	v_and_b32_e32 v9, 0xffff0000, v9
	v_lshlrev_b32_e32 v16, 16, v10
	v_and_b32_e32 v17, 0xffff0000, v10
	v_lshlrev_b32_e32 v10, 16, v11
	v_and_b32_e32 v11, 0xffff0000, v11
	v_pk_fma_f32 v[6:7], v[6:7], v[46:47], v[8:9]
	v_pk_fma_f32 v[4:5], v[4:5], v[44:45], v[14:15]
	v_pk_fma_f32 v[8:9], v[2:3], v[42:43], v[10:11]
	v_pk_fma_f32 v[2:3], v[0:1], v[40:41], v[16:17]
	v_cvt_pk_bf16_f32 v0, v4, v5
	v_cvt_pk_bf16_f32 v1, v6, v7
	v_cvt_pk_bf16_f32 v2, v2, v3
	v_cvt_pk_bf16_f32 v3, v8, v9
	global_store_dwordx4 v[12:13], v[0:3], off offset:256
	s_cbranch_vccz .LBB1_2336
	s_waitcnt vmcnt(0)
	s_cmpk_gt_u32 s17, 0xff
	s_cbranch_scc1 .LBB1_2343
	s_barrier

; #define PG8_STAGE(bufoff, gbase, voff) do { _Pragma("unroll") for (int _i = 0; _i < 2; ++_i) \
;         __builtin_amdgcn_global_load_lds((const unsigned*)((const char*)(gbase) + (voff)[_i]), (LAS unsigned*)(lds + (bufoff) + ldsw + _i * 8192), 16, 0, 0); } while (0)
; #define PG8_LDA(dst, b, h) do { _Pragma("unroll") for (int m = 0; m < 4; ++m) _Pragma("unroll") for (int k = 0; k < 2; ++k) dst[m][k] = *(const LAS bf16x8*)(lds + PG8_SA(b, h) + aoff + m * 2048 + k * 1024); } while (0)
; #define PG8_LDB(dst, b, h) do { _Pragma("unroll") for (int n = 0; n < 2; ++n) _Pragma("unroll") for (int k = 0; k < 2; ++k) dst[n][k] = *(const LAS bf16x8*)(lds + PG8_SB(b, h) + boff + n * 2048 + k * 1024); } while (0)
; #define PG8_WAIT_V(n) asm volatile("s_waitcnt vmcnt(" #n ")" ::: "memory")
; #define PG8_WAIT_L(n) asm volatile("s_waitcnt lgkmcnt(" #n ")" ::: "memory")
; #define PG8_BAR __builtin_amdgcn_s_barrier()
; #define PG8_SCHED __builtin_amdgcn_sched_barrier(0)
; template <class Map, class Epi>
; DI void gemm_phase(LAS unsigned char* lds, const Map& MP, const Epi& E, const int nM, const int nN, const int K, const int lda, const int ldb) {
;     ...
;             PG8_LDB(B0, 0, 0); PG8_SCHED; PG8_LDA(At, 0, 0); PG8_STAGE(PG8_SA(1, 1), a1 + hstepA, voffA);
;             PG8_WAIT_L(8); PG8_BAR; PG8_WAIT_L(0); PG8_MMA(0, 0, At, B0); PG8_BAR; PG8_SCHED;
;             PG8_LDB(B1, 0, 1); PG8_STAGE(PG8_SB(0, 0), b2, voffB);
;             PG8_BAR; PG8_WAIT_L(0); PG8_MMA(0, 1, At, B1); PG8_BAR;
;             PG8_LDA(At, 0, 1); PG8_STAGE(PG8_SA(0, 0), a2, voffA);
;             PG8_BAR; PG8_WAIT_L(0); PG8_MMA(1, 0, At, B0); PG8_BAR; PG8_SCHED;
;             PG8_STAGE(PG8_SB(0, 1), b2 + hstepB, voffB);
;             PG8_WAIT_V(6); PG8_BAR; PG8_MMA(1, 1, At, B1); PG8_BAR;
;             PG8_LDB(B0, 1, 0); PG8_SCHED; PG8_LDA(At, 1, 0); PG8_STAGE(PG8_SA(0, 1), a2 + hstepA, voffA);
;             PG8_WAIT_L(8); PG8_BAR; PG8_WAIT_L(0); PG8_MMA(0, 0, At, B0); PG8_BAR; PG8_SCHED;
;             PG8_LDB(B1, 1, 1); PG8_STAGE(PG8_SB(1, 0), b3, voffB);
;             PG8_BAR; PG8_WAIT_L(0); PG8_MMA(0, 1, At, B1); PG8_BAR;
;             PG8_LDA(At, 1, 1); PG8_STAGE(PG8_SA(1, 0), a3, voffA);
;             PG8_BAR; PG8_WAIT_L(0); PG8_MMA(1, 0, At, B0); PG8_BAR; PG8_SCHED;
;             PG8_STAGE(PG8_SB(1, 1), b3 + hstepB, voffB);
;             PG8_WAIT_V(6); PG8_BAR; PG8_MMA(1, 1, At, B1); PG8_BAR;
.LBB1_2483:
	s_add_u32 s28, s42, 0xfff80080
	s_addc_u32 s29, s43, -1
	s_cmp_eq_u32 s3, 28
	s_cselect_b32 s47, s23, s29
	s_cselect_b32 s46, s58, s28
	s_cselect_b32 s29, s21, vcc_hi
	s_cselect_b32 s28, s59, vcc_lo
	s_add_i32 m0, s38, 0xc000
	ds_read_b128 v[96:99], v190
	ds_read_b128 v[100:103], v190 offset:1024
	ds_read_b128 v[108:111], v190 offset:2048
	ds_read_b128 v[112:115], v190 offset:3072
	ds_read_b128 v[160:163], v190 offset:4096
	ds_read_b128 v[164:167], v190 offset:5120
	ds_read_b128 v[198:201], v190 offset:6144
	ds_read_b128 v[202:205], v190 offset:7168
	global_load_lds_dwordx4 v178, s[42:43]
	s_add_i32 m0, s38, 0xe000
	s_nop 0
	global_load_lds_dwordx4 v176, s[42:43]
	s_waitcnt lgkmcnt(7)
	s_setprio 1
	s_barrier
	v_mfma_f32_16x16x32_bf16 v[148:151], v[80:83], v[96:99], v[148:151]
	v_mfma_f32_16x16x32_bf16 v[144:147], v[88:91], v[96:99], v[144:147]
	s_waitcnt lgkmcnt(5)
	v_mfma_f32_16x16x32_bf16 v[136:139], v[80:83], v[108:111], v[136:139]
	v_mfma_f32_16x16x32_bf16 v[128:131], v[88:91], v[108:111], v[128:131]
	s_waitcnt lgkmcnt(3)
	v_mfma_f32_16x16x32_bf16 v[120:123], v[80:83], v[160:163], v[120:123]
	v_mfma_f32_16x16x32_bf16 v[104:107], v[88:91], v[160:163], v[104:107]
	s_waitcnt lgkmcnt(1)
	v_mfma_f32_16x16x32_bf16 v[76:79], v[80:83], v[198:201], v[76:79]
	v_mfma_f32_16x16x32_bf16 v[72:75], v[88:91], v[198:201], v[72:75]
	v_mfma_f32_16x16x32_bf16 v[148:151], v[84:87], v[100:103], v[148:151]
	v_mfma_f32_16x16x32_bf16 v[144:147], v[92:95], v[100:103], v[144:147]
	v_mfma_f32_16x16x32_bf16 v[136:139], v[84:87], v[112:115], v[136:139]
	v_mfma_f32_16x16x32_bf16 v[128:131], v[92:95], v[112:115], v[128:131]
	v_mfma_f32_16x16x32_bf16 v[120:123], v[84:87], v[164:167], v[120:123]
	v_mfma_f32_16x16x32_bf16 v[104:107], v[92:95], v[164:167], v[104:107]
	s_waitcnt lgkmcnt(0)
	v_mfma_f32_16x16x32_bf16 v[76:79], v[84:87], v[202:205], v[76:79]
	v_mfma_f32_16x16x32_bf16 v[72:75], v[92:95], v[202:205], v[72:75]
	s_barrier
	s_setprio 0
	s_add_i32 s68, s2, s37
	v_lshl_add_u64 v[184:185], s[28:29], 0, v[172:173]
	s_mov_b32 m0, s68
	ds_read_b128 v[206:209], v191
	ds_read_b128 v[210:213], v191 offset:1024
	ds_read_b128 v[214:217], v191 offset:2048
	ds_read_b128 v[218:221], v191 offset:3072
	global_load_lds_dwordx4 v[184:185], off
	v_lshl_add_u64 v[194:195], s[28:29], 0, v[168:169]
	s_add_i32 m0, s68, 0x2000
	s_nop 0
	global_load_lds_dwordx4 v[194:195], off
	s_waitcnt lgkmcnt(3)
	s_setprio 1
	s_barrier
	v_mfma_f32_16x16x32_bf16 v[156:159], v[206:209], v[96:99], v[156:159]
	s_waitcnt lgkmcnt(1)
	v_mfma_f32_16x16x32_bf16 v[96:99], v[214:217], v[96:99], v[152:155]
	v_mfma_f32_16x16x32_bf16 v[156:159], v[210:213], v[100:103], v[156:159]
	s_waitcnt lgkmcnt(0)
	v_mfma_f32_16x16x32_bf16 v[96:99], v[218:221], v[100:103], v[96:99]
	v_mfma_f32_16x16x32_bf16 v[100:103], v[206:209], v[108:111], v[140:143]
	v_mfma_f32_16x16x32_bf16 v[108:111], v[214:217], v[108:111], v[132:135]
	v_mfma_f32_16x16x32_bf16 v[116:119], v[214:217], v[160:163], v[116:119]
	v_mfma_f32_16x16x32_bf16 v[68:71], v[206:209], v[198:201], v[68:71]
	v_mfma_f32_16x16x32_bf16 v[64:67], v[214:217], v[198:201], v[64:67]
	s_mov_b32 m0, s38
	v_mfma_f32_16x16x32_bf16 v[100:103], v[210:213], v[112:115], v[100:103]
	v_lshl_add_u64 v[230:231], s[46:47], 0, v[174:175]
	v_mfma_f32_16x16x32_bf16 v[108:111], v[218:221], v[112:115], v[108:111]
	v_mfma_f32_16x16x32_bf16 v[112:115], v[206:209], v[160:163], v[124:127]
	v_mfma_f32_16x16x32_bf16 v[116:119], v[218:221], v[164:167], v[116:119]
	v_mfma_f32_16x16x32_bf16 v[68:71], v[210:213], v[202:205], v[68:71]
	v_mfma_f32_16x16x32_bf16 v[64:67], v[218:221], v[202:205], v[64:67]
	v_mfma_f32_16x16x32_bf16 v[112:115], v[210:213], v[164:167], v[112:115]
	s_barrier
	s_setprio 0
	ds_read_b128 v[124:127], v190 offset:16384
	ds_read_b128 v[132:135], v190 offset:17408
	ds_read_b128 v[140:143], v190 offset:18432
	ds_read_b128 v[152:155], v190 offset:19456
	ds_read_b128 v[160:163], v190 offset:20480
	ds_read_b128 v[164:167], v190 offset:21504
	ds_read_b128 v[198:201], v190 offset:22528
	ds_read_b128 v[202:205], v190 offset:23552
	global_load_lds_dwordx4 v[230:231], off
	v_lshl_add_u64 v[232:233], s[46:47], 0, v[170:171]
	s_mov_b32 m0, s39
	s_nop 0
	global_load_lds_dwordx4 v[232:233], off
	s_waitcnt vmcnt(10) lgkmcnt(7)
	s_setprio 1
	s_barrier
	v_mfma_f32_16x16x32_bf16 v[60:63], v[80:83], v[124:127], v[60:63]
	v_mfma_f32_16x16x32_bf16 v[48:51], v[88:91], v[124:127], v[48:51]
	s_waitcnt lgkmcnt(5)
	v_mfma_f32_16x16x32_bf16 v[40:43], v[80:83], v[140:143], v[40:43]
	v_mfma_f32_16x16x32_bf16 v[32:35], v[88:91], v[140:143], v[32:35]
	s_waitcnt lgkmcnt(3)
	v_mfma_f32_16x16x32_bf16 v[24:27], v[80:83], v[160:163], v[24:27]
	v_mfma_f32_16x16x32_bf16 v[16:19], v[88:91], v[160:163], v[16:19]
	s_waitcnt lgkmcnt(1)
	v_mfma_f32_16x16x32_bf16 v[12:15], v[80:83], v[198:201], v[12:15]
	v_mfma_f32_16x16x32_bf16 v[8:11], v[88:91], v[198:201], v[8:11]
	v_mfma_f32_16x16x32_bf16 v[60:63], v[84:87], v[132:135], v[60:63]
	v_mfma_f32_16x16x32_bf16 v[48:51], v[92:95], v[132:135], v[48:51]
	v_mfma_f32_16x16x32_bf16 v[40:43], v[84:87], v[152:155], v[40:43]
	v_mfma_f32_16x16x32_bf16 v[32:35], v[92:95], v[152:155], v[32:35]
	v_mfma_f32_16x16x32_bf16 v[24:27], v[84:87], v[164:167], v[24:27]
	v_mfma_f32_16x16x32_bf16 v[16:19], v[92:95], v[164:167], v[16:19]
	s_waitcnt lgkmcnt(0)
	v_mfma_f32_16x16x32_bf16 v[12:15], v[84:87], v[202:205], v[12:15]
	v_mfma_f32_16x16x32_bf16 v[8:11], v[92:95], v[202:205], v[8:11]
	s_barrier
	s_setprio 0
	s_add_u32 s68, s28, 0x80000
	s_addc_u32 s69, s29, 0
	s_add_i32 s70, s67, s37
	s_mov_b32 m0, s70
	s_nop 0
	global_load_lds_dwordx4 v172, s[68:69]
	s_add_i32 m0, s70, 0x2000
	s_nop 0
	global_load_lds_dwordx4 v168, s[68:69]
	s_waitcnt vmcnt(6)
	s_setprio 1
	s_barrier
; #define PG8_STAGE(bufoff, gbase, voff) do { _Pragma("unroll") for (int _i = 0; _i < 2; ++_i) \
;         __builtin_amdgcn_global_load_lds((const unsigned*)((const char*)(gbase) + (voff)[_i]), (LAS unsigned*)(lds + (bufoff) + ldsw + _i * 8192), 16, 0, 0); } while (0)
; #define PG8_LDA(dst, b, h) do { _Pragma("unroll") for (int m = 0; m < 4; ++m) _Pragma("unroll") for (int k = 0; k < 2; ++k) dst[m][k] = *(const LAS bf16x8*)(lds + PG8_SA(b, h) + aoff + m * 2048 + k * 1024); } while (0)
; #define PG8_LDB(dst, b, h) do { _Pragma("unroll") for (int n = 0; n < 2; ++n) _Pragma("unroll") for (int k = 0; k < 2; ++k) dst[n][k] = *(const LAS bf16x8*)(lds + PG8_SB(b, h) + boff + n * 2048 + k * 1024); } while (0)
; #define PG8_WAIT_V(n) asm volatile("s_waitcnt vmcnt(" #n ")" ::: "memory")
; #define PG8_WAIT_L(n) asm volatile("s_waitcnt lgkmcnt(" #n ")" ::: "memory")
; #define PG8_BAR __builtin_amdgcn_s_barrier()
; #define PG8_SCHED __builtin_amdgcn_sched_barrier(0)
; template <class Map, class Epi>
; DI void gemm_phase(LAS unsigned char* lds, const Map& MP, const Epi& E, const int nM, const int nN, const int K, const int lda, const int ldb) {
;     ...
;             PG8_LDB(B0, 0, 0); PG8_SCHED; PG8_LDA(At, 0, 0); PG8_STAGE(PG8_SA(1, 1), a1 + hstepA, voffA);
;             PG8_WAIT_L(8); PG8_BAR; PG8_WAIT_L(0); PG8_MMA(0, 0, At, B0); PG8_BAR; PG8_SCHED;
;             PG8_LDB(B1, 0, 1); PG8_STAGE(PG8_SB(0, 0), b2, voffB);
;             PG8_BAR; PG8_WAIT_L(0); PG8_MMA(0, 1, At, B1); PG8_BAR;
;             PG8_LDA(At, 0, 1); PG8_STAGE(PG8_SA(0, 0), a2, voffA);
;             PG8_BAR; PG8_WAIT_L(0); PG8_MMA(1, 0, At, B0); PG8_BAR; PG8_SCHED;
;             PG8_STAGE(PG8_SB(0, 1), b2 + hstepB, voffB);
;             PG8_WAIT_V(6); PG8_BAR; PG8_MMA(1, 1, At, B1); PG8_BAR;
;             PG8_LDB(B0, 1, 0); PG8_SCHED; PG8_LDA(At, 1, 0); PG8_STAGE(PG8_SA(0, 1), a2 + hstepA, voffA);
;             PG8_WAIT_L(8); PG8_BAR; PG8_WAIT_L(0); PG8_MMA(0, 0, At, B0); PG8_BAR; PG8_SCHED;
;             PG8_LDB(B1, 1, 1); PG8_STAGE(PG8_SB(1, 0), b3, voffB);
;             PG8_BAR; PG8_WAIT_L(0); PG8_MMA(0, 1, At, B1); PG8_BAR;
;             PG8_LDA(At, 1, 1); PG8_STAGE(PG8_SA(1, 0), a3, voffA);
;             PG8_BAR; PG8_WAIT_L(0); PG8_MMA(1, 0, At, B0); PG8_BAR; PG8_SCHED;
;             PG8_STAGE(PG8_SB(1, 1), b3 + hstepB, voffB);
;             PG8_WAIT_V(6); PG8_BAR; PG8_MMA(1, 1, At, B1); PG8_BAR;
	v_mfma_f32_16x16x32_bf16 v[56:59], v[206:209], v[124:127], v[56:59]
	v_mfma_f32_16x16x32_bf16 v[52:55], v[214:217], v[124:127], v[52:55]
	s_add_i32 s68, 0, 0x18000
	v_add_u32_e32 v92, s68, v188
	ds_read_b128 v[80:83], v92
	v_mfma_f32_16x16x32_bf16 v[44:47], v[206:209], v[140:143], v[44:47]
	v_mfma_f32_16x16x32_bf16 v[36:39], v[214:217], v[140:143], v[36:39]
	ds_read_b128 v[84:87], v92 offset:1024
	v_mfma_f32_16x16x32_bf16 v[28:31], v[206:209], v[160:163], v[28:31]
	v_mfma_f32_16x16x32_bf16 v[20:23], v[214:217], v[160:163], v[20:23]
	ds_read_b128 v[88:91], v92 offset:2048
	v_mfma_f32_16x16x32_bf16 v[4:7], v[206:209], v[198:201], v[4:7]
	v_mfma_f32_16x16x32_bf16 v[0:3], v[214:217], v[198:201], v[0:3]
	ds_read_b128 v[92:95], v92 offset:3072
	v_mfma_f32_16x16x32_bf16 v[56:59], v[210:213], v[132:135], v[56:59]
	v_mfma_f32_16x16x32_bf16 v[52:55], v[218:221], v[132:135], v[52:55]
	v_mfma_f32_16x16x32_bf16 v[44:47], v[210:213], v[152:155], v[44:47]
	v_mfma_f32_16x16x32_bf16 v[36:39], v[218:221], v[152:155], v[36:39]
	v_mfma_f32_16x16x32_bf16 v[28:31], v[210:213], v[164:167], v[28:31]
	v_mfma_f32_16x16x32_bf16 v[20:23], v[218:221], v[164:167], v[20:23]
	v_mfma_f32_16x16x32_bf16 v[4:7], v[210:213], v[202:205], v[4:7]
	v_mfma_f32_16x16x32_bf16 v[0:3], v[218:221], v[202:205], v[0:3]
	s_barrier
	s_setprio 0
	s_add_u32 s46, s46, 0x80000
	s_addc_u32 s47, s47, 0
	s_mov_b32 m0, s55
	ds_read_b128 v[124:127], v190 offset:32768
	ds_read_b128 v[132:135], v190 offset:33792
	ds_read_b128 v[160:163], v190 offset:34816
	ds_read_b128 v[164:167], v190 offset:35840
	ds_read_b128 v[198:201], v190 offset:36864
	ds_read_b128 v[202:205], v190 offset:37888
	ds_read_b128 v[206:209], v190 offset:38912
	ds_read_b128 v[210:213], v190 offset:39936
	global_load_lds_dwordx4 v174, s[46:47]
	s_mov_b32 m0, s56
	s_nop 0
	global_load_lds_dwordx4 v170, s[46:47]
	s_waitcnt lgkmcnt(7)
	s_setprio 1
	s_barrier
	v_mfma_f32_16x16x32_bf16 v[140:143], v[80:83], v[124:127], v[148:151]
	s_waitcnt lgkmcnt(6)
	v_mfma_f32_16x16x32_bf16 v[148:151], v[84:87], v[132:135], v[140:143]
	v_mfma_f32_16x16x32_bf16 v[140:143], v[88:91], v[124:127], v[144:147]
	s_waitcnt lgkmcnt(5)
	v_mfma_f32_16x16x32_bf16 v[136:139], v[80:83], v[160:163], v[136:139]
	v_mfma_f32_16x16x32_bf16 v[128:131], v[88:91], v[160:163], v[128:131]
	s_waitcnt lgkmcnt(3)
	v_mfma_f32_16x16x32_bf16 v[120:123], v[80:83], v[198:201], v[120:123]
	v_mfma_f32_16x16x32_bf16 v[104:107], v[88:91], v[198:201], v[104:107]
	s_waitcnt lgkmcnt(1)
	v_mfma_f32_16x16x32_bf16 v[76:79], v[80:83], v[206:209], v[76:79]
	v_mfma_f32_16x16x32_bf16 v[72:75], v[88:91], v[206:209], v[72:75]
	v_mfma_f32_16x16x32_bf16 v[144:147], v[92:95], v[132:135], v[140:143]
	v_mfma_f32_16x16x32_bf16 v[136:139], v[84:87], v[164:167], v[136:139]
	v_mfma_f32_16x16x32_bf16 v[128:131], v[92:95], v[164:167], v[128:131]
	v_mfma_f32_16x16x32_bf16 v[120:123], v[84:87], v[202:205], v[120:123]
	v_mfma_f32_16x16x32_bf16 v[104:107], v[92:95], v[202:205], v[104:107]
	s_waitcnt lgkmcnt(0)
	v_mfma_f32_16x16x32_bf16 v[76:79], v[84:87], v[210:213], v[76:79]
	v_mfma_f32_16x16x32_bf16 v[72:75], v[92:95], v[210:213], v[72:75]
	s_barrier
	s_setprio 0
	s_add_i32 s46, 0, 0x1c000
	v_add_u32_e32 v140, s46, v188
	s_add_i32 s47, s68, s37
	ds_read_b128 v[214:217], v140
	ds_read_b128 v[218:221], v140 offset:1024
	ds_read_b128 v[222:225], v140 offset:2048
	ds_read_b128 v[226:229], v140 offset:3072
	v_lshl_add_u64 v[140:141], v[184:185], 0, s[14:15]
	s_mov_b32 m0, s47
	s_nop 0
	global_load_lds_dwordx4 v[140:141], off
	v_lshl_add_u64 v[140:141], v[194:195], 0, s[14:15]
	s_add_i32 m0, s47, 0x2000
	s_nop 0
	global_load_lds_dwordx4 v[140:141], off
	s_waitcnt lgkmcnt(1)
	s_setprio 1
	s_barrier
	v_mfma_f32_16x16x32_bf16 v[96:99], v[222:225], v[124:127], v[96:99]
	v_mfma_f32_16x16x32_bf16 v[140:143], v[214:217], v[124:127], v[156:159]
	s_waitcnt lgkmcnt(0)
	v_mfma_f32_16x16x32_bf16 v[152:155], v[226:229], v[132:135], v[96:99]
	v_mfma_f32_16x16x32_bf16 v[96:99], v[214:217], v[160:163], v[100:103]
	v_mfma_f32_16x16x32_bf16 v[156:159], v[218:221], v[132:135], v[140:143]
	v_mfma_f32_16x16x32_bf16 v[140:143], v[218:221], v[164:167], v[96:99]
	v_mfma_f32_16x16x32_bf16 v[96:99], v[222:225], v[160:163], v[108:111]
	v_mfma_f32_16x16x32_bf16 v[132:135], v[226:229], v[164:167], v[96:99]
	v_mfma_f32_16x16x32_bf16 v[96:99], v[214:217], v[198:201], v[112:115]
	s_mov_b32 m0, s62
	v_mfma_f32_16x16x32_bf16 v[124:127], v[218:221], v[202:205], v[96:99]
	v_lshl_add_u64 v[184:185], v[230:231], 0, s[14:15]
	v_mfma_f32_16x16x32_bf16 v[96:99], v[222:225], v[198:201], v[116:119]
	v_mfma_f32_16x16x32_bf16 v[68:71], v[214:217], v[206:209], v[68:71]
	v_mfma_f32_16x16x32_bf16 v[64:67], v[222:225], v[206:209], v[64:67]
	v_mfma_f32_16x16x32_bf16 v[116:119], v[226:229], v[202:205], v[96:99]
	v_mfma_f32_16x16x32_bf16 v[68:71], v[218:221], v[210:213], v[68:71]
	v_mfma_f32_16x16x32_bf16 v[64:67], v[226:229], v[210:213], v[64:67]
	s_barrier
	s_setprio 0
	ds_read_b128 v[96:99], v190 offset:49152
	ds_read_b128 v[100:103], v190 offset:50176
	ds_read_b128 v[108:111], v190 offset:51200
	ds_read_b128 v[112:115], v190 offset:52224
	ds_read_b128 v[160:163], v190 offset:53248
	ds_read_b128 v[164:167], v190 offset:54272
	ds_read_b128 v[198:201], v190 offset:55296
	ds_read_b128 v[202:205], v190 offset:56320
	global_load_lds_dwordx4 v[184:185], off
	v_lshl_add_u64 v[184:185], v[232:233], 0, s[14:15]
	s_mov_b32 m0, s63
	s_nop 0
	global_load_lds_dwordx4 v[184:185], off
	s_waitcnt vmcnt(10) lgkmcnt(7)
	s_setprio 1
	s_barrier
; #define PG8_STAGE(bufoff, gbase, voff) do { _Pragma("unroll") for (int _i = 0; _i < 2; ++_i) \
;         __builtin_amdgcn_global_load_lds((const unsigned*)((const char*)(gbase) + (voff)[_i]), (LAS unsigned*)(lds + (bufoff) + ldsw + _i * 8192), 16, 0, 0); } while (0)
; #define PG8_LDA(dst, b, h) do { _Pragma("unroll") for (int m = 0; m < 4; ++m) _Pragma("unroll") for (int k = 0; k < 2; ++k) dst[m][k] = *(const LAS bf16x8*)(lds + PG8_SA(b, h) + aoff + m * 2048 + k * 1024); } while (0)
; #define PG8_LDB(dst, b, h) do { _Pragma("unroll") for (int n = 0; n < 2; ++n) _Pragma("unroll") for (int k = 0; k < 2; ++k) dst[n][k] = *(const LAS bf16x8*)(lds + PG8_SB(b, h) + boff + n * 2048 + k * 1024); } while (0)
; #define PG8_WAIT_V(n) asm volatile("s_waitcnt vmcnt(" #n ")" ::: "memory")
; #define PG8_WAIT_L(n) asm volatile("s_waitcnt lgkmcnt(" #n ")" ::: "memory")
; #define PG8_BAR __builtin_amdgcn_s_barrier()
; #define PG8_SCHED __builtin_amdgcn_sched_barrier(0)
; template <class Map, class Epi>
; DI void gemm_phase(LAS unsigned char* lds, const Map& MP, const Epi& E, const int nM, const int nN, const int K, const int lda, const int ldb) {
;     ...
;             PG8_LDB(B0, 0, 0); PG8_SCHED; PG8_LDA(At, 0, 0); PG8_STAGE(PG8_SA(1, 1), a1 + hstepA, voffA);
;             PG8_WAIT_L(8); PG8_BAR; PG8_WAIT_L(0); PG8_MMA(0, 0, At, B0); PG8_BAR; PG8_SCHED;
;             PG8_LDB(B1, 0, 1); PG8_STAGE(PG8_SB(0, 0), b2, voffB);
;             PG8_BAR; PG8_WAIT_L(0); PG8_MMA(0, 1, At, B1); PG8_BAR;
;             PG8_LDA(At, 0, 1); PG8_STAGE(PG8_SA(0, 0), a2, voffA);
;             PG8_BAR; PG8_WAIT_L(0); PG8_MMA(1, 0, At, B0); PG8_BAR; PG8_SCHED;
;             PG8_STAGE(PG8_SB(0, 1), b2 + hstepB, voffB);
;             PG8_WAIT_V(6); PG8_BAR; PG8_MMA(1, 1, At, B1); PG8_BAR;
;             PG8_LDB(B0, 1, 0); PG8_SCHED; PG8_LDA(At, 1, 0); PG8_STAGE(PG8_SA(0, 1), a2 + hstepA, voffA);
;             PG8_WAIT_L(8); PG8_BAR; PG8_WAIT_L(0); PG8_MMA(0, 0, At, B0); PG8_BAR; PG8_SCHED;
;             PG8_LDB(B1, 1, 1); PG8_STAGE(PG8_SB(1, 0), b3, voffB);
;             PG8_BAR; PG8_WAIT_L(0); PG8_MMA(0, 1, At, B1); PG8_BAR;
;             PG8_LDA(At, 1, 1); PG8_STAGE(PG8_SA(1, 0), a3, voffA);
;             PG8_BAR; PG8_WAIT_L(0); PG8_MMA(1, 0, At, B0); PG8_BAR; PG8_SCHED;
;             PG8_STAGE(PG8_SB(1, 1), b3 + hstepB, voffB);
;             PG8_WAIT_V(6); PG8_BAR; PG8_MMA(1, 1, At, B1); PG8_BAR;
	v_mfma_f32_16x16x32_bf16 v[60:63], v[80:83], v[96:99], v[60:63]
	v_mfma_f32_16x16x32_bf16 v[48:51], v[88:91], v[96:99], v[48:51]
	s_waitcnt lgkmcnt(5)
	v_mfma_f32_16x16x32_bf16 v[40:43], v[80:83], v[108:111], v[40:43]
	v_mfma_f32_16x16x32_bf16 v[32:35], v[88:91], v[108:111], v[32:35]
	s_waitcnt lgkmcnt(3)
	v_mfma_f32_16x16x32_bf16 v[24:27], v[80:83], v[160:163], v[24:27]
	v_mfma_f32_16x16x32_bf16 v[16:19], v[88:91], v[160:163], v[16:19]
	s_waitcnt lgkmcnt(1)
	v_mfma_f32_16x16x32_bf16 v[12:15], v[80:83], v[198:201], v[12:15]
	v_mfma_f32_16x16x32_bf16 v[8:11], v[88:91], v[198:201], v[8:11]
	v_mfma_f32_16x16x32_bf16 v[60:63], v[84:87], v[100:103], v[60:63]
	v_mfma_f32_16x16x32_bf16 v[48:51], v[92:95], v[100:103], v[48:51]
	v_mfma_f32_16x16x32_bf16 v[40:43], v[84:87], v[112:115], v[40:43]
	v_mfma_f32_16x16x32_bf16 v[32:35], v[92:95], v[112:115], v[32:35]
	v_mfma_f32_16x16x32_bf16 v[24:27], v[84:87], v[164:167], v[24:27]
	v_mfma_f32_16x16x32_bf16 v[16:19], v[92:95], v[164:167], v[16:19]
	s_waitcnt lgkmcnt(0)
	v_mfma_f32_16x16x32_bf16 v[12:15], v[84:87], v[202:205], v[12:15]
	v_mfma_f32_16x16x32_bf16 v[8:11], v[92:95], v[202:205], v[8:11]
	s_barrier
	s_setprio 0
	s_add_u32 s28, s28, 0x80080
	s_addc_u32 s29, s29, 0
	s_add_i32 s46, s46, s37
	s_mov_b32 m0, s46
	s_nop 0
	global_load_lds_dwordx4 v172, s[28:29]
	s_add_i32 m0, s46, 0x2000
	s_nop 0
	global_load_lds_dwordx4 v168, s[28:29]
	s_waitcnt vmcnt(6)
	s_setprio 1
	s_barrier
	v_mfma_f32_16x16x32_bf16 v[56:59], v[214:217], v[96:99], v[56:59]
	v_mfma_f32_16x16x32_bf16 v[52:55], v[222:225], v[96:99], v[52:55]
	ds_read_b128 v[80:83], v189
	v_mfma_f32_16x16x32_bf16 v[44:47], v[214:217], v[108:111], v[44:47]
	v_mfma_f32_16x16x32_bf16 v[36:39], v[222:225], v[108:111], v[36:39]
	ds_read_b128 v[84:87], v189 offset:1024
	v_mfma_f32_16x16x32_bf16 v[28:31], v[214:217], v[160:163], v[28:31]
	v_mfma_f32_16x16x32_bf16 v[20:23], v[222:225], v[160:163], v[20:23]
	ds_read_b128 v[88:91], v189 offset:2048
	v_mfma_f32_16x16x32_bf16 v[4:7], v[214:217], v[198:201], v[4:7]
	v_mfma_f32_16x16x32_bf16 v[0:3], v[222:225], v[198:201], v[0:3]
	ds_read_b128 v[92:95], v189 offset:3072
	v_mfma_f32_16x16x32_bf16 v[56:59], v[218:221], v[100:103], v[56:59]
	s_add_i32 s3, s3, 2
	v_mfma_f32_16x16x32_bf16 v[52:55], v[226:229], v[100:103], v[52:55]
	s_add_u32 vcc_lo, vcc_lo, 0x100
	s_addc_u32 vcc_hi, vcc_hi, 0
	v_mfma_f32_16x16x32_bf16 v[44:47], v[218:221], v[112:115], v[44:47]
	s_add_u32 s42, s42, 0x100
	s_addc_u32 s43, s43, 0
	v_mfma_f32_16x16x32_bf16 v[36:39], v[226:229], v[112:115], v[36:39]
	s_cmp_gt_u32 s3, 29
	v_mfma_f32_16x16x32_bf16 v[28:31], v[218:221], v[164:167], v[28:31]
	v_mfma_f32_16x16x32_bf16 v[20:23], v[226:229], v[164:167], v[20:23]
	v_mfma_f32_16x16x32_bf16 v[4:7], v[218:221], v[202:205], v[4:7]
	v_mfma_f32_16x16x32_bf16 v[0:3], v[226:229], v[202:205], v[0:3]
	s_barrier
	s_setprio 0
	s_cbranch_scc0 .LBB1_2483
; DI float silu_mul(float g, float v) { return g * v * __builtin_amdgcn_rcpf(1.0f + __builtin_amdgcn_exp2f(-LOG2E * g)); }
;     DI void operator()(const f32x4 (&acc)[2][2][4][2], const Unit& u, int wr, int wc, int fr, int fq) const {
;         const int row0 = u.pm * BM + wr * 64 + fr, ch0 = u.pn * 128 + wc * 32 + 8 * fq;
;         f32x4 w0[2], w1[2], w2[2], bb[2];
; #pragma unroll
;         for (int n = 0; n < 2; ++n) { w0[n] = *(const f32x4*)(cw + ch0 + 4 * n); w1[n] = *(const f32x4*)(cw + DFF + ch0 + 4 * n); w2[n] = *(const f32x4*)(cw + 2 * DFF + ch0 + 4 * n); bb[n] = *(const f32x4*)(cb + ch0 + 4 * n); }
; #pragma unroll
;         for (int ai = 0; ai < 2; ++ai)
; #pragma unroll
;             for (int m = 0; m < 4; ++m) {
;                 const bool efirst = (m == 0) && (fr == 0), elast = (m == 3) && (fr == 15);
;                 const int row = row0 + ai * HALF + m * 16;
;                 f32x4 gc[2];
; #pragma unroll
;                 for (int n = 0; n < 2; ++n) {
;                     const f32x4 g = acc[ai][0][m][n];
;                     const f32x4 gprev = acc[ai][0][m > 0 ? m - 1 : 0][n], gnext = acc[ai][0][m < 3 ? m + 1 : 3][n];
;                     f32x4 up, dn;
; #pragma unroll
;                     for (int e = 0; e < 4; ++e) {
;                         const float pu = (m > 0 && fr == 15) ? gprev[e] : g[e];
;                         const float pd = (m < 3 && fr == 0) ? gnext[e] : g[e];
;                         up[e] = dpp_ror1(pu); dn[e] = dpp_ror15(pd);
;                     }
;                     if (efirst) up = (f32x4){0.f, 0.f, 0.f, 0.f};
;                     if (elast) dn = (f32x4){0.f, 0.f, 0.f, 0.f};
;                     gc[n] = w0[n] * up + w1[n] * g + w2[n] * dn + bb[n];
;                 }
;                 if (efirst || elast) {
;                     const size_t eo = (size_t)((row >> 6) * 2 + (elast ? 1 : 0)) * DFF + ch0;
; #pragma unroll
;                     for (int n = 0; n < 2; ++n) { *(f32x4*)(EP + eo + 4 * n) = gc[n]; *(f32x4*)(ER + eo + 4 * n) = acc[ai][0][m][n]; *(f32x4*)(EV + eo + 4 * n) = acc[ai][1][m][n]; }
;                 } else {
;                     const f32x4 v0 = acc[ai][1][m][0], v1 = acc[ai][1][m][1];
;                     u32x4 o;
;                     o[0] = pack2(silu_mul(gc[0][0], v0[0]), silu_mul(gc[0][1], v0[1])); o[1] = pack2(silu_mul(gc[0][2], v0[2]), silu_mul(gc[0][3], v0[3]));
	s_waitcnt lgkmcnt(0)
	s_lshl_b32 s21, s45, 7
	v_mov_b32_e32 v80, v187
	v_mov_b32_e32 v194, v186
	s_or_b32 s21, s21, s57
	v_mov_b32_e32 v160, 0
	v_lshl_add_u32 v184, v80, 3, s21
	v_ashrrev_i32_e32 v185, 31, v184
	v_lshlrev_b64 v[80:81], 2, v[184:185]
	v_lshl_add_u64 v[84:85], s[4:5], 0, v[80:81]
	v_lshl_add_u64 v[88:89], s[16:17], 0, v[80:81]
	v_lshl_add_u64 v[92:93], s[18:19], 0, v[80:81]
	v_lshl_add_u64 v[112:113], s[6:7], 0, v[80:81]
	global_load_dwordx4 v[80:83], v[84:85], off offset:16
	global_load_dwordx4 v[96:99], v[84:85], off
	s_nop 0
	global_load_dwordx4 v[84:87], v[88:89], off offset:16
	global_load_dwordx4 v[100:103], v[88:89], off
	s_nop 0
	global_load_dwordx4 v[88:91], v[92:93], off offset:16
	global_load_dwordx4 v[108:111], v[92:93], off
	s_nop 0
	global_load_dwordx4 v[92:95], v[112:113], off offset:16
	s_nop 0
	global_load_dwordx4 v[112:115], v[112:113], off
	v_cmp_eq_u32_e32 vcc, 0, v194
	v_mov_b32_e32 v164, 0
	v_mov_b32_e32 v195, 0
	v_cndmask_b32_e32 v161, v148, v136, vcc
	v_cndmask_b32_e32 v162, v149, v137, vcc
	v_cndmask_b32_e32 v163, v150, v138, vcc
	v_mov_b32_dpp v160, v161 row_ror:15 row_mask:0xf bank_mask:0xf
	v_mov_b32_e32 v161, 0
	v_mov_b32_e32 v166, 0
	v_mov_b32_e32 v167, 0
	v_mov_b32_dpp v161, v162 row_ror:15 row_mask:0xf bank_mask:0xf
	v_mov_b32_e32 v162, 0
	v_mov_b32_dpp v164, v150 row_ror:1 row_mask:0xf bank_mask:0xf
	v_cndmask_b32_e32 v165, v151, v139, vcc
	v_mov_b32_dpp v162, v163 row_ror:15 row_mask:0xf bank_mask:0xf
	v_mov_b32_dpp v195, v151 row_ror:1 row_mask:0xf bank_mask:0xf
	v_mov_b32_e32 v163, 0
	v_mov_b32_dpp v166, v148 row_ror:1 row_mask:0xf bank_mask:0xf
	v_mov_b32_dpp v167, v149 row_ror:1 row_mask:0xf bank_mask:0xf
	v_mov_b32_dpp v163, v165 row_ror:15 row_mask:0xf bank_mask:0xf
	v_cndmask_b32_e64 v165, v195, 0, vcc
	v_cndmask_b32_e64 v164, v164, 0, vcc
	v_cndmask_b32_e64 v167, v167, 0, vcc
	v_cndmask_b32_e64 v166, v166, 0, vcc
	v_mov_b32_e32 v195, 0
	v_mov_b32_e32 v196, 0
	v_mov_b32_e32 v198, 0
	v_mov_b32_e32 v200, 0
	v_mov_b32_dpp v195, v144 row_ror:1 row_mask:0xf bank_mask:0xf
	v_mov_b32_dpp v196, v145 row_ror:1 row_mask:0xf bank_mask:0xf
	v_mov_b32_dpp v198, v146 row_ror:1 row_mask:0xf bank_mask:0xf
	v_cndmask_b32_e32 v199, v147, v131, vcc
	v_mov_b32_dpp v200, v147 row_ror:1 row_mask:0xf bank_mask:0xf
	v_cndmask_b32_e64 v198, v198, 0, vcc
	v_cndmask_b32_e64 v201, v196, 0, vcc
	s_lshl_b32 s3, s44, 8
	s_add_i32 s3, s3, s49
	v_add_u32_e32 v193, s3, v194
	v_cmp_ne_u32_e64 s[46:47], 0, v194
	s_waitcnt vmcnt(0)
	v_pk_mul_f32 v[164:165], v[98:99], v[164:165]
	v_pk_mul_f32 v[166:167], v[96:97], v[166:167]
	v_pk_fma_f32 v[164:165], v[150:151], v[102:103], v[164:165]
	v_pk_fma_f32 v[166:167], v[148:149], v[100:101], v[166:167]
	v_pk_fma_f32 v[162:163], v[110:111], v[162:163], v[164:165]
	v_cndmask_b32_e32 v165, v144, v128, vcc
	v_mov_b32_e32 v164, 0
	v_pk_fma_f32 v[160:161], v[108:109], v[160:161], v[166:167]
	v_cndmask_b32_e32 v166, v145, v129, vcc
	v_mov_b32_dpp v164, v165 row_ror:15 row_mask:0xf bank_mask:0xf
	v_mov_b32_e32 v165, 0
	v_cndmask_b32_e32 v167, v146, v130, vcc
	v_pk_add_f32 v[162:163], v[114:115], v[162:163]
	v_mov_b32_dpp v165, v166 row_ror:15 row_mask:0xf bank_mask:0xf
	v_mov_b32_e32 v166, 0
	v_pk_add_f32 v[160:161], v[112:113], v[160:161]
	s_nop 0
	v_mov_b32_dpp v166, v167 row_ror:15 row_mask:0xf bank_mask:0xf
	v_mov_b32_e32 v167, 0
	s_nop 1
	v_mov_b32_dpp v167, v199 row_ror:15 row_mask:0xf bank_mask:0xf
	v_cndmask_b32_e64 v199, v200, 0, vcc
	v_cndmask_b32_e64 v200, v195, 0, vcc
	v_pk_mul_f32 v[200:201], v[80:81], v[200:201]
	v_pk_mul_f32 v[198:199], v[82:83], v[198:199]
	v_pk_fma_f32 v[200:201], v[144:145], v[84:85], v[200:201]
	v_pk_fma_f32 v[198:199], v[146:147], v[86:87], v[198:199]
	v_pk_fma_f32 v[164:165], v[88:89], v[164:165], v[200:201]
	v_pk_fma_f32 v[166:167], v[90:91], v[166:167], v[198:199]
	v_pk_add_f32 v[164:165], v[92:93], v[164:165]
	v_pk_add_f32 v[166:167], v[94:95], v[166:167]
	s_and_saveexec_b64 s[28:29], s[46:47]
	s_xor_b64 s[28:29], exec, s[28:29]
	s_cbranch_execz .LBB1_2486
	v_mul_f32_e32 v195, 0xbfb8aa3b, v160
	v_exp_f32_e32 v195, v195
	v_mul_f32_e32 v196, 0xbfb8aa3b, v161
	v_exp_f32_e32 v196, v196
	v_pk_mul_f32 v[160:161], v[156:157], v[160:161]
	v_add_f32_e32 v195, 1.0, v195
	v_rcp_f32_e32 v198, v195
	v_add_f32_e32 v196, 1.0, v196
	v_mul_f32_e32 v195, 0xbfb8aa3b, v162
	v_rcp_f32_e32 v199, v196
	v_exp_f32_e32 v195, v195
	v_mul_f32_e32 v196, 0xbfb8aa3b, v163
	v_exp_f32_e32 v196, v196
	v_pk_mul_f32 v[160:161], v[160:161], v[198:199]
	v_add_f32_e32 v195, 1.0, v195
	v_rcp_f32_e32 v200, v195
	v_add_f32_e32 v195, 1.0, v196
	v_rcp_f32_e32 v201, v195
	v_cvt_pk_bf16_f32 v160, v160, v161
	v_mul_f32_e32 v161, 0xbfb8aa3b, v164
	v_exp_f32_e32 v195, v161
	v_mul_f32_e32 v161, 0xbfb8aa3b, v165
	v_exp_f32_e32 v196, v161
	v_pk_mul_f32 v[162:163], v[158:159], v[162:163]
	v_pk_mul_f32 v[164:165], v[152:153], v[164:165]
	v_pk_mul_f32 v[162:163], v[162:163], v[200:201]
	s_nop 0
	v_cvt_pk_bf16_f32 v161, v162, v163
	v_add_f32_e32 v162, 1.0, v195
	v_mul_f32_e32 v195, 0xbfb8aa3b, v166
	v_add_f32_e32 v163, 1.0, v196
	v_exp_f32_e32 v195, v195
	v_mul_f32_e32 v196, 0xbfb8aa3b, v167
	v_exp_f32_e32 v196, v196
	v_rcp_f32_e32 v162, v162
	v_add_f32_e32 v195, 1.0, v195
	v_rcp_f32_e32 v198, v195
	v_add_f32_e32 v195, 1.0, v196
	v_rcp_f32_e32 v163, v163
	v_rcp_f32_e32 v199, v195
	v_pk_mul_f32 v[166:167], v[154:155], v[166:167]
	v_pk_mul_f32 v[162:163], v[164:165], v[162:163]
	v_pk_mul_f32 v[164:165], v[166:167], v[198:199]
	v_cvt_pk_bf16_f32 v162, v162, v163
	v_cvt_pk_bf16_f32 v163, v164, v165
	v_mov_b64_e32 v[164:165], s[52:53]
	v_mad_i64_i32 v[164:165], s[42:43], v193, s60, v[164:165]
	v_lshl_add_u64 v[164:165], v[184:185], 1, v[164:165]
	global_store_dwordx4 v[164:165], v[160:163], off

; #define PG8_STAGE(bufoff, gbase, voff) do { _Pragma("unroll") for (int _i = 0; _i < 2; ++_i) \
;         __builtin_amdgcn_global_load_lds((const unsigned*)((const char*)(gbase) + (voff)[_i]), (LAS unsigned*)(lds + (bufoff) + ldsw + _i * 8192), 16, 0, 0); } while (0)
; #define PG8_LDA(dst, b, h) do { _Pragma("unroll") for (int m = 0; m < 4; ++m) _Pragma("unroll") for (int k = 0; k < 2; ++k) dst[m][k] = *(const LAS bf16x8*)(lds + PG8_SA(b, h) + aoff + m * 2048 + k * 1024); } while (0)
; #define PG8_LDB(dst, b, h) do { _Pragma("unroll") for (int n = 0; n < 2; ++n) _Pragma("unroll") for (int k = 0; k < 2; ++k) dst[n][k] = *(const LAS bf16x8*)(lds + PG8_SB(b, h) + boff + n * 2048 + k * 1024); } while (0)
; #define PG8_WAIT_V(n) asm volatile("s_waitcnt vmcnt(" #n ")" ::: "memory")
; #define PG8_WAIT_L(n) asm volatile("s_waitcnt lgkmcnt(" #n ")" ::: "memory")
; #define PG8_BAR __builtin_amdgcn_s_barrier()
; #define PG8_SCHED __builtin_amdgcn_sched_barrier(0)
; template <class Map, class Epi>
; DI void gemm_phase(LAS unsigned char* lds, const Map& MP, const Epi& E, const int nM, const int nN, const int K, const int lda, const int ldb) {
;     ...
;             PG8_LDB(B0, 0, 0); PG8_SCHED; PG8_LDA(At, 0, 0); PG8_STAGE(PG8_SA(1, 1), a1 + hstepA, voffA);
;             PG8_WAIT_L(8); PG8_BAR; PG8_WAIT_L(0); PG8_MMA(0, 0, At, B0); PG8_BAR; PG8_SCHED;
;             PG8_LDB(B1, 0, 1); PG8_STAGE(PG8_SB(0, 0), b2, voffB);
;             PG8_BAR; PG8_WAIT_L(0); PG8_MMA(0, 1, At, B1); PG8_BAR;
;             PG8_LDA(At, 0, 1); PG8_STAGE(PG8_SA(0, 0), a2, voffA);
;             PG8_BAR; PG8_WAIT_L(0); PG8_MMA(1, 0, At, B0); PG8_BAR; PG8_SCHED;
;             PG8_STAGE(PG8_SB(0, 1), b2 + hstepB, voffB);
;             PG8_WAIT_V(6); PG8_BAR; PG8_MMA(1, 1, At, B1); PG8_BAR;
;             PG8_LDB(B0, 1, 0); PG8_SCHED; PG8_LDA(At, 1, 0); PG8_STAGE(PG8_SA(0, 1), a2 + hstepA, voffA);
;             PG8_WAIT_L(8); PG8_BAR; PG8_WAIT_L(0); PG8_MMA(0, 0, At, B0); PG8_BAR; PG8_SCHED;
;             PG8_LDB(B1, 1, 1); PG8_STAGE(PG8_SB(1, 0), b3, voffB);
;             PG8_BAR; PG8_WAIT_L(0); PG8_MMA(0, 1, At, B1); PG8_BAR;
;             PG8_LDA(At, 1, 1); PG8_STAGE(PG8_SA(1, 0), a3, voffA);
;             PG8_BAR; PG8_WAIT_L(0); PG8_MMA(1, 0, At, B0); PG8_BAR; PG8_SCHED;
;             PG8_STAGE(PG8_SB(1, 1), b3 + hstepB, voffB);
;             PG8_WAIT_V(6); PG8_BAR; PG8_MMA(1, 1, At, B1); PG8_BAR;
.LBB1_2653:
	s_add_u32 s10, s8, 0x100
	s_addc_u32 s11, s9, 0
	s_cmpk_eq_i32 s48, 0x54
	s_cselect_b32 s15, s43, s11
	s_cselect_b32 s14, s42, s10
	s_cselect_b32 s13, s45, s39
	s_cselect_b32 s12, s44, s38
	s_add_i32 m0, s22, 0xc000
	ds_read_b128 v[168:171], v150
	ds_read_b128 v[172:175], v150 offset:1024
	ds_read_b128 v[176:179], v150 offset:2048
	ds_read_b128 v[180:183], v150 offset:3072
	ds_read_b128 v[184:187], v150 offset:4096
	ds_read_b128 v[188:191], v150 offset:5120
	ds_read_b128 v[192:195], v150 offset:6144
	ds_read_b128 v[196:199], v150 offset:7168
	global_load_lds_dwordx4 v138, s[8:9]
	s_add_i32 m0, s22, 0xe000
	s_nop 0
	global_load_lds_dwordx4 v136, s[8:9]
	s_waitcnt lgkmcnt(7)
	s_setprio 1
	s_barrier
	v_mfma_f32_16x16x32_bf16 v[124:127], v[152:155], v[168:171], v[124:127]
	v_mfma_f32_16x16x32_bf16 v[120:123], v[160:163], v[168:171], v[120:123]
	s_waitcnt lgkmcnt(5)
	v_mfma_f32_16x16x32_bf16 v[108:111], v[152:155], v[176:179], v[108:111]
	v_mfma_f32_16x16x32_bf16 v[104:107], v[160:163], v[176:179], v[104:107]
	s_waitcnt lgkmcnt(3)
	v_mfma_f32_16x16x32_bf16 v[92:95], v[152:155], v[184:187], v[92:95]
	v_mfma_f32_16x16x32_bf16 v[88:91], v[160:163], v[184:187], v[88:91]
	s_waitcnt lgkmcnt(1)
	v_mfma_f32_16x16x32_bf16 v[76:79], v[152:155], v[192:195], v[76:79]
	v_mfma_f32_16x16x32_bf16 v[72:75], v[160:163], v[192:195], v[72:75]
	v_mfma_f32_16x16x32_bf16 v[124:127], v[156:159], v[172:175], v[124:127]
	v_mfma_f32_16x16x32_bf16 v[120:123], v[164:167], v[172:175], v[120:123]
	v_mfma_f32_16x16x32_bf16 v[108:111], v[156:159], v[180:183], v[108:111]
	v_mfma_f32_16x16x32_bf16 v[104:107], v[164:167], v[180:183], v[104:107]
	v_mfma_f32_16x16x32_bf16 v[92:95], v[156:159], v[188:191], v[92:95]
	v_mfma_f32_16x16x32_bf16 v[88:91], v[164:167], v[188:191], v[88:91]
	s_waitcnt lgkmcnt(0)
	v_mfma_f32_16x16x32_bf16 v[76:79], v[156:159], v[196:199], v[76:79]
	v_mfma_f32_16x16x32_bf16 v[72:75], v[164:167], v[196:199], v[72:75]
	s_barrier
	s_setprio 0
	s_add_i32 s8, s33, s20
	v_lshl_add_u64 v[144:145], s[12:13], 0, v[132:133]
	s_mov_b32 m0, s8
	ds_read_b128 v[200:203], v151
	ds_read_b128 v[204:207], v151 offset:1024
	ds_read_b128 v[208:211], v151 offset:2048
	ds_read_b128 v[212:215], v151 offset:3072
	global_load_lds_dwordx4 v[144:145], off
	v_lshl_add_u64 v[216:217], s[12:13], 0, v[128:129]
	s_add_i32 m0, s8, 0x2000
	s_nop 0
	global_load_lds_dwordx4 v[216:217], off
	s_waitcnt lgkmcnt(3)
	s_setprio 1
	s_barrier
	v_mfma_f32_16x16x32_bf16 v[116:119], v[200:203], v[168:171], v[116:119]
	s_waitcnt lgkmcnt(1)
	v_mfma_f32_16x16x32_bf16 v[112:115], v[208:211], v[168:171], v[112:115]
	v_mfma_f32_16x16x32_bf16 v[100:103], v[200:203], v[176:179], v[100:103]
	v_mfma_f32_16x16x32_bf16 v[96:99], v[208:211], v[176:179], v[96:99]
	v_mfma_f32_16x16x32_bf16 v[84:87], v[200:203], v[184:187], v[84:87]
	v_mfma_f32_16x16x32_bf16 v[80:83], v[208:211], v[184:187], v[80:83]
	v_mfma_f32_16x16x32_bf16 v[68:71], v[200:203], v[192:195], v[68:71]
	v_mfma_f32_16x16x32_bf16 v[64:67], v[208:211], v[192:195], v[64:67]
	v_mfma_f32_16x16x32_bf16 v[116:119], v[204:207], v[172:175], v[116:119]
	s_mov_b32 m0, s22
	s_waitcnt lgkmcnt(0)
	v_mfma_f32_16x16x32_bf16 v[112:115], v[212:215], v[172:175], v[112:115]
	v_lshl_add_u64 v[218:219], s[14:15], 0, v[134:135]
	v_mfma_f32_16x16x32_bf16 v[100:103], v[204:207], v[180:183], v[100:103]
	v_mfma_f32_16x16x32_bf16 v[96:99], v[212:215], v[180:183], v[96:99]
	v_mfma_f32_16x16x32_bf16 v[84:87], v[204:207], v[188:191], v[84:87]
	v_mfma_f32_16x16x32_bf16 v[80:83], v[212:215], v[188:191], v[80:83]
	v_mfma_f32_16x16x32_bf16 v[68:71], v[204:207], v[196:199], v[68:71]
	v_mfma_f32_16x16x32_bf16 v[64:67], v[212:215], v[196:199], v[64:67]
	s_barrier
	s_setprio 0
	ds_read_b128 v[168:171], v150 offset:16384
	ds_read_b128 v[172:175], v150 offset:17408
	ds_read_b128 v[176:179], v150 offset:18432
	ds_read_b128 v[180:183], v150 offset:19456
	ds_read_b128 v[184:187], v150 offset:20480
	ds_read_b128 v[188:191], v150 offset:21504
	ds_read_b128 v[192:195], v150 offset:22528
	ds_read_b128 v[196:199], v150 offset:23552
	global_load_lds_dwordx4 v[218:219], off
	v_lshl_add_u64 v[220:221], s[14:15], 0, v[130:131]
	s_mov_b32 m0, s23
	s_nop 0
	global_load_lds_dwordx4 v[220:221], off
	s_waitcnt vmcnt(10) lgkmcnt(7)
	s_setprio 1
	s_barrier
	v_mfma_f32_16x16x32_bf16 v[60:63], v[152:155], v[168:171], v[60:63]
	v_mfma_f32_16x16x32_bf16 v[56:59], v[160:163], v[168:171], v[56:59]
	s_waitcnt lgkmcnt(5)
	v_mfma_f32_16x16x32_bf16 v[44:47], v[152:155], v[176:179], v[44:47]
	v_mfma_f32_16x16x32_bf16 v[40:43], v[160:163], v[176:179], v[40:43]
	s_waitcnt lgkmcnt(3)
	v_mfma_f32_16x16x32_bf16 v[28:31], v[152:155], v[184:187], v[28:31]
	v_mfma_f32_16x16x32_bf16 v[24:27], v[160:163], v[184:187], v[24:27]
	s_waitcnt lgkmcnt(1)
	v_mfma_f32_16x16x32_bf16 v[12:15], v[152:155], v[192:195], v[12:15]
	v_mfma_f32_16x16x32_bf16 v[8:11], v[160:163], v[192:195], v[8:11]
	v_mfma_f32_16x16x32_bf16 v[60:63], v[156:159], v[172:175], v[60:63]
	v_mfma_f32_16x16x32_bf16 v[56:59], v[164:167], v[172:175], v[56:59]
	v_mfma_f32_16x16x32_bf16 v[44:47], v[156:159], v[180:183], v[44:47]
	v_mfma_f32_16x16x32_bf16 v[40:43], v[164:167], v[180:183], v[40:43]
	v_mfma_f32_16x16x32_bf16 v[28:31], v[156:159], v[188:191], v[28:31]
	v_mfma_f32_16x16x32_bf16 v[24:27], v[164:167], v[188:191], v[24:27]
	s_waitcnt lgkmcnt(0)
	v_mfma_f32_16x16x32_bf16 v[12:15], v[156:159], v[196:199], v[12:15]
	v_mfma_f32_16x16x32_bf16 v[8:11], v[164:167], v[196:199], v[8:11]
	s_barrier
	s_setprio 0
	s_add_u32 s8, s12, 0x160000
	s_addc_u32 s9, s13, 0
	s_add_i32 s49, s34, s20
	s_mov_b32 m0, s49
	s_nop 0
	global_load_lds_dwordx4 v132, s[8:9]
	s_add_i32 m0, s49, 0x2000
	s_nop 0
	global_load_lds_dwordx4 v128, s[8:9]
	s_waitcnt vmcnt(6)
	s_setprio 1
	s_barrier
; #define PG8_STAGE(bufoff, gbase, voff) do { _Pragma("unroll") for (int _i = 0; _i < 2; ++_i) \
;         __builtin_amdgcn_global_load_lds((const unsigned*)((const char*)(gbase) + (voff)[_i]), (LAS unsigned*)(lds + (bufoff) + ldsw + _i * 8192), 16, 0, 0); } while (0)
; #define PG8_LDA(dst, b, h) do { _Pragma("unroll") for (int m = 0; m < 4; ++m) _Pragma("unroll") for (int k = 0; k < 2; ++k) dst[m][k] = *(const LAS bf16x8*)(lds + PG8_SA(b, h) + aoff + m * 2048 + k * 1024); } while (0)
; #define PG8_LDB(dst, b, h) do { _Pragma("unroll") for (int n = 0; n < 2; ++n) _Pragma("unroll") for (int k = 0; k < 2; ++k) dst[n][k] = *(const LAS bf16x8*)(lds + PG8_SB(b, h) + boff + n * 2048 + k * 1024); } while (0)
; #define PG8_WAIT_V(n) asm volatile("s_waitcnt vmcnt(" #n ")" ::: "memory")
; #define PG8_WAIT_L(n) asm volatile("s_waitcnt lgkmcnt(" #n ")" ::: "memory")
; #define PG8_BAR __builtin_amdgcn_s_barrier()
; #define PG8_SCHED __builtin_amdgcn_sched_barrier(0)
; template <class Map, class Epi>
; DI void gemm_phase(LAS unsigned char* lds, const Map& MP, const Epi& E, const int nM, const int nN, const int K, const int lda, const int ldb) {
;     ...
;             PG8_LDB(B0, 0, 0); PG8_SCHED; PG8_LDA(At, 0, 0); PG8_STAGE(PG8_SA(1, 1), a1 + hstepA, voffA);
;             PG8_WAIT_L(8); PG8_BAR; PG8_WAIT_L(0); PG8_MMA(0, 0, At, B0); PG8_BAR; PG8_SCHED;
;             PG8_LDB(B1, 0, 1); PG8_STAGE(PG8_SB(0, 0), b2, voffB);
;             PG8_BAR; PG8_WAIT_L(0); PG8_MMA(0, 1, At, B1); PG8_BAR;
;             PG8_LDA(At, 0, 1); PG8_STAGE(PG8_SA(0, 0), a2, voffA);
;             PG8_BAR; PG8_WAIT_L(0); PG8_MMA(1, 0, At, B0); PG8_BAR; PG8_SCHED;
;             PG8_STAGE(PG8_SB(0, 1), b2 + hstepB, voffB);
;             PG8_WAIT_V(6); PG8_BAR; PG8_MMA(1, 1, At, B1); PG8_BAR;
;             PG8_LDB(B0, 1, 0); PG8_SCHED; PG8_LDA(At, 1, 0); PG8_STAGE(PG8_SA(0, 1), a2 + hstepA, voffA);
;             PG8_WAIT_L(8); PG8_BAR; PG8_WAIT_L(0); PG8_MMA(0, 0, At, B0); PG8_BAR; PG8_SCHED;
;             PG8_LDB(B1, 1, 1); PG8_STAGE(PG8_SB(1, 0), b3, voffB);
;             PG8_BAR; PG8_WAIT_L(0); PG8_MMA(0, 1, At, B1); PG8_BAR;
;             PG8_LDA(At, 1, 1); PG8_STAGE(PG8_SA(1, 0), a3, voffA);
;             PG8_BAR; PG8_WAIT_L(0); PG8_MMA(1, 0, At, B0); PG8_BAR; PG8_SCHED;
;             PG8_STAGE(PG8_SB(1, 1), b3 + hstepB, voffB);
;             PG8_WAIT_V(6); PG8_BAR; PG8_MMA(1, 1, At, B1); PG8_BAR;
	v_mfma_f32_16x16x32_bf16 v[52:55], v[200:203], v[168:171], v[52:55]
	v_mfma_f32_16x16x32_bf16 v[48:51], v[208:211], v[168:171], v[48:51]
	s_add_i32 s49, 0, 0x18000
	v_add_u32_e32 v164, s49, v148
	ds_read_b128 v[152:155], v164
	v_mfma_f32_16x16x32_bf16 v[36:39], v[200:203], v[176:179], v[36:39]
	v_mfma_f32_16x16x32_bf16 v[32:35], v[208:211], v[176:179], v[32:35]
	ds_read_b128 v[156:159], v164 offset:1024
	v_mfma_f32_16x16x32_bf16 v[20:23], v[200:203], v[184:187], v[20:23]
	v_mfma_f32_16x16x32_bf16 v[16:19], v[208:211], v[184:187], v[16:19]
	ds_read_b128 v[160:163], v164 offset:2048
	v_mfma_f32_16x16x32_bf16 v[4:7], v[200:203], v[192:195], v[4:7]
	v_mfma_f32_16x16x32_bf16 v[0:3], v[208:211], v[192:195], v[0:3]
	ds_read_b128 v[164:167], v164 offset:3072
	v_mfma_f32_16x16x32_bf16 v[52:55], v[204:207], v[172:175], v[52:55]
	v_mfma_f32_16x16x32_bf16 v[48:51], v[212:215], v[172:175], v[48:51]
	v_mfma_f32_16x16x32_bf16 v[36:39], v[204:207], v[180:183], v[36:39]
	v_mfma_f32_16x16x32_bf16 v[32:35], v[212:215], v[180:183], v[32:35]
	v_mfma_f32_16x16x32_bf16 v[20:23], v[204:207], v[188:191], v[20:23]
	v_mfma_f32_16x16x32_bf16 v[16:19], v[212:215], v[188:191], v[16:19]
	v_mfma_f32_16x16x32_bf16 v[4:7], v[204:207], v[196:199], v[4:7]
	v_mfma_f32_16x16x32_bf16 v[0:3], v[212:215], v[196:199], v[0:3]
	s_barrier
	s_setprio 0
	s_add_u32 s8, s14, 0x160000
	s_addc_u32 s9, s15, 0
	s_mov_b32 m0, s24
	ds_read_b128 v[168:171], v150 offset:32768
	ds_read_b128 v[172:175], v150 offset:33792
	ds_read_b128 v[176:179], v150 offset:34816
	ds_read_b128 v[180:183], v150 offset:35840
	ds_read_b128 v[184:187], v150 offset:36864
	ds_read_b128 v[188:191], v150 offset:37888
	ds_read_b128 v[192:195], v150 offset:38912
	ds_read_b128 v[196:199], v150 offset:39936
	global_load_lds_dwordx4 v134, s[8:9]
	s_mov_b32 m0, s25
	s_nop 0
	global_load_lds_dwordx4 v130, s[8:9]
	s_waitcnt lgkmcnt(7)
	s_setprio 1
	s_barrier
	v_mfma_f32_16x16x32_bf16 v[124:127], v[152:155], v[168:171], v[124:127]
	v_mfma_f32_16x16x32_bf16 v[120:123], v[160:163], v[168:171], v[120:123]
	s_waitcnt lgkmcnt(5)
	v_mfma_f32_16x16x32_bf16 v[108:111], v[152:155], v[176:179], v[108:111]
	v_mfma_f32_16x16x32_bf16 v[104:107], v[160:163], v[176:179], v[104:107]
	s_waitcnt lgkmcnt(3)
	v_mfma_f32_16x16x32_bf16 v[92:95], v[152:155], v[184:187], v[92:95]
	v_mfma_f32_16x16x32_bf16 v[88:91], v[160:163], v[184:187], v[88:91]
	s_waitcnt lgkmcnt(1)
	v_mfma_f32_16x16x32_bf16 v[76:79], v[152:155], v[192:195], v[76:79]
	v_mfma_f32_16x16x32_bf16 v[72:75], v[160:163], v[192:195], v[72:75]
	v_mfma_f32_16x16x32_bf16 v[124:127], v[156:159], v[172:175], v[124:127]
	v_mfma_f32_16x16x32_bf16 v[120:123], v[164:167], v[172:175], v[120:123]
	v_mfma_f32_16x16x32_bf16 v[108:111], v[156:159], v[180:183], v[108:111]
	v_mfma_f32_16x16x32_bf16 v[104:107], v[164:167], v[180:183], v[104:107]
	v_mfma_f32_16x16x32_bf16 v[92:95], v[156:159], v[188:191], v[92:95]
	v_mfma_f32_16x16x32_bf16 v[88:91], v[164:167], v[188:191], v[88:91]
	s_waitcnt lgkmcnt(0)
	v_mfma_f32_16x16x32_bf16 v[76:79], v[156:159], v[196:199], v[76:79]
	v_mfma_f32_16x16x32_bf16 v[72:75], v[164:167], v[196:199], v[72:75]
	s_barrier
	s_setprio 0
	s_add_i32 s14, 0, 0x1c000
	s_add_i32 s8, s49, s20
	v_add_u32_e32 v212, s14, v148
	v_lshl_add_u64 v[144:145], v[144:145], 0, s[46:47]
	s_mov_b32 m0, s8
	ds_read_b128 v[200:203], v212
	ds_read_b128 v[204:207], v212 offset:1024
	ds_read_b128 v[208:211], v212 offset:2048
	ds_read_b128 v[212:215], v212 offset:3072
	global_load_lds_dwordx4 v[144:145], off
	v_lshl_add_u64 v[144:145], v[216:217], 0, s[46:47]
	s_add_i32 m0, s8, 0x2000
	s_nop 0
	global_load_lds_dwordx4 v[144:145], off
	s_waitcnt lgkmcnt(3)
	s_setprio 1
	s_barrier
	v_mfma_f32_16x16x32_bf16 v[116:119], v[200:203], v[168:171], v[116:119]
	s_waitcnt lgkmcnt(1)
	v_mfma_f32_16x16x32_bf16 v[112:115], v[208:211], v[168:171], v[112:115]
	v_mfma_f32_16x16x32_bf16 v[100:103], v[200:203], v[176:179], v[100:103]
	v_mfma_f32_16x16x32_bf16 v[96:99], v[208:211], v[176:179], v[96:99]
	v_mfma_f32_16x16x32_bf16 v[84:87], v[200:203], v[184:187], v[84:87]
	v_mfma_f32_16x16x32_bf16 v[80:83], v[208:211], v[184:187], v[80:83]
	v_mfma_f32_16x16x32_bf16 v[68:71], v[200:203], v[192:195], v[68:71]
	v_mfma_f32_16x16x32_bf16 v[64:67], v[208:211], v[192:195], v[64:67]
	v_mfma_f32_16x16x32_bf16 v[116:119], v[204:207], v[172:175], v[116:119]
	s_mov_b32 m0, s29
	s_waitcnt lgkmcnt(0)
	v_mfma_f32_16x16x32_bf16 v[112:115], v[212:215], v[172:175], v[112:115]
	v_lshl_add_u64 v[144:145], v[218:219], 0, s[46:47]
	v_mfma_f32_16x16x32_bf16 v[100:103], v[204:207], v[180:183], v[100:103]
	v_mfma_f32_16x16x32_bf16 v[96:99], v[212:215], v[180:183], v[96:99]
	v_mfma_f32_16x16x32_bf16 v[84:87], v[204:207], v[188:191], v[84:87]
	v_mfma_f32_16x16x32_bf16 v[80:83], v[212:215], v[188:191], v[80:83]
	v_mfma_f32_16x16x32_bf16 v[68:71], v[204:207], v[196:199], v[68:71]
	v_mfma_f32_16x16x32_bf16 v[64:67], v[212:215], v[196:199], v[64:67]
	s_barrier
	s_setprio 0
	ds_read_b128 v[168:171], v150 offset:49152
	ds_read_b128 v[172:175], v150 offset:50176
	ds_read_b128 v[176:179], v150 offset:51200
	ds_read_b128 v[180:183], v150 offset:52224
	ds_read_b128 v[184:187], v150 offset:53248
	ds_read_b128 v[188:191], v150 offset:54272
	ds_read_b128 v[192:195], v150 offset:55296
	ds_read_b128 v[196:199], v150 offset:56320
	global_load_lds_dwordx4 v[144:145], off
	v_lshl_add_u64 v[144:145], v[220:221], 0, s[46:47]
	s_mov_b32 m0, s30
	s_nop 0
	global_load_lds_dwordx4 v[144:145], off
	s_waitcnt vmcnt(10) lgkmcnt(7)
	s_setprio 1
	s_barrier
; DI float bflo(unsigned w) { return __uint_as_float(w << 16); }
; DI float bfhi(unsigned w) { return __uint_as_float(w & 0xffff0000u); }
;     DI void operator()(const f32x4 (&acc)[2][2][4][2], const Unit& u, int wr, int wc, int fr, int fq) const {
;     ...
;             for (int m = 0; m < 4; ++m) { const size_t ro = (size_t)(row0 + ai * HALF + m * 16) * D + col0;
; #pragma unroll
;                 for (int bj = 0; bj < 2; ++bj) {
;                     f32x4 x0, x1;
;                     if constexpr (IB) { const u32x4 w = *(const u32x4*)((const bf16_t*)Xin + ro + bj * HALF);
;                         x0 = (f32x4){bflo(w[0]), bfhi(w[0]), bflo(w[1]), bfhi(w[1])}; x1 = (f32x4){bflo(w[2]), bfhi(w[2]), bflo(w[3]), bfhi(w[3])}; }
;                     else { x0 = *(const f32x4*)((const float*)Xin + ro + bj * HALF); x1 = *(const f32x4*)((const float*)Xin + ro + bj * HALF + 4); }
;                     x0 += acc[ai][bj][m][0] * sc[bj][0]; x1 += acc[ai][bj][m][1] * sc[bj][1];
; template <class Map, class Epi>
; DI void gemm_phase(LAS unsigned char* lds, const Map& MP, const Epi& E, const int nM, const int nN, const int K, const int lda, const int ldb) {
;     ...
;             PG8_LDB(B0, 0, 0); PG8_SCHED; PG8_LDA(At, 0, 0); PG8_STAGE(PG8_SA(1, 1), a1 + hstepA, voffA);
;             PG8_WAIT_L(8); PG8_BAR; PG8_WAIT_L(0); PG8_MMA(0, 0, At, B0); PG8_BAR; PG8_SCHED;
;             PG8_LDB(B1, 0, 1); PG8_STAGE(PG8_SB(0, 0), b2, voffB);
;             PG8_BAR; PG8_WAIT_L(0); PG8_MMA(0, 1, At, B1); PG8_BAR;
;             PG8_LDA(At, 0, 1); PG8_STAGE(PG8_SA(0, 0), a2, voffA);
;             PG8_BAR; PG8_WAIT_L(0); PG8_MMA(1, 0, At, B0); PG8_BAR; PG8_SCHED;
;             PG8_STAGE(PG8_SB(0, 1), b2 + hstepB, voffB);
;             PG8_WAIT_V(6); PG8_BAR; PG8_MMA(1, 1, At, B1); PG8_BAR;
;             PG8_LDB(B0, 1, 0); PG8_SCHED; PG8_LDA(At, 1, 0); PG8_STAGE(PG8_SA(0, 1), a2 + hstepA, voffA);
;             PG8_WAIT_L(8); PG8_BAR; PG8_WAIT_L(0); PG8_MMA(0, 0, At, B0); PG8_BAR; PG8_SCHED;
;             PG8_LDB(B1, 1, 1); PG8_STAGE(PG8_SB(1, 0), b3, voffB);
;             PG8_BAR; PG8_WAIT_L(0); PG8_MMA(0, 1, At, B1); PG8_BAR;
;             PG8_LDA(At, 1, 1); PG8_STAGE(PG8_SA(1, 0), a3, voffA);
;             PG8_BAR; PG8_WAIT_L(0); PG8_MMA(1, 0, At, B0); PG8_BAR; PG8_SCHED;
;             PG8_STAGE(PG8_SB(1, 1), b3 + hstepB, voffB);
;             PG8_WAIT_V(6); PG8_BAR; PG8_MMA(1, 1, At, B1); PG8_BAR;
	v_mfma_f32_16x16x32_bf16 v[60:63], v[152:155], v[168:171], v[60:63]
	v_mfma_f32_16x16x32_bf16 v[56:59], v[160:163], v[168:171], v[56:59]
	s_waitcnt lgkmcnt(5)
	v_mfma_f32_16x16x32_bf16 v[44:47], v[152:155], v[176:179], v[44:47]
	v_mfma_f32_16x16x32_bf16 v[40:43], v[160:163], v[176:179], v[40:43]
	s_waitcnt lgkmcnt(3)
	v_mfma_f32_16x16x32_bf16 v[28:31], v[152:155], v[184:187], v[28:31]
	v_mfma_f32_16x16x32_bf16 v[24:27], v[160:163], v[184:187], v[24:27]
	s_waitcnt lgkmcnt(1)
	v_mfma_f32_16x16x32_bf16 v[12:15], v[152:155], v[192:195], v[12:15]
	v_mfma_f32_16x16x32_bf16 v[8:11], v[160:163], v[192:195], v[8:11]
	v_mfma_f32_16x16x32_bf16 v[60:63], v[156:159], v[172:175], v[60:63]
	v_mfma_f32_16x16x32_bf16 v[56:59], v[164:167], v[172:175], v[56:59]
	v_mfma_f32_16x16x32_bf16 v[44:47], v[156:159], v[180:183], v[44:47]
	v_mfma_f32_16x16x32_bf16 v[40:43], v[164:167], v[180:183], v[40:43]
	v_mfma_f32_16x16x32_bf16 v[28:31], v[156:159], v[188:191], v[28:31]
	v_mfma_f32_16x16x32_bf16 v[24:27], v[164:167], v[188:191], v[24:27]
	s_waitcnt lgkmcnt(0)
	v_mfma_f32_16x16x32_bf16 v[12:15], v[156:159], v[196:199], v[12:15]
	v_mfma_f32_16x16x32_bf16 v[8:11], v[164:167], v[196:199], v[8:11]
	s_barrier
	s_setprio 0
	s_add_u32 s8, s12, 0x160080
	s_addc_u32 s9, s13, 0
	s_add_i32 s12, s14, s20
	s_mov_b32 m0, s12
	s_nop 0
	global_load_lds_dwordx4 v132, s[8:9]
	s_add_i32 m0, s12, 0x2000
	s_nop 0
	global_load_lds_dwordx4 v128, s[8:9]
	s_waitcnt vmcnt(6)
	s_setprio 1
	s_barrier
	v_mfma_f32_16x16x32_bf16 v[52:55], v[200:203], v[168:171], v[52:55]
	v_mfma_f32_16x16x32_bf16 v[48:51], v[208:211], v[168:171], v[48:51]
	ds_read_b128 v[152:155], v149
	v_mfma_f32_16x16x32_bf16 v[36:39], v[200:203], v[176:179], v[36:39]
	v_mfma_f32_16x16x32_bf16 v[32:35], v[208:211], v[176:179], v[32:35]
	ds_read_b128 v[156:159], v149 offset:1024
	v_mfma_f32_16x16x32_bf16 v[20:23], v[200:203], v[184:187], v[20:23]
	v_mfma_f32_16x16x32_bf16 v[16:19], v[208:211], v[184:187], v[16:19]
	ds_read_b128 v[160:163], v149 offset:2048
	v_mfma_f32_16x16x32_bf16 v[4:7], v[200:203], v[192:195], v[4:7]
	v_mfma_f32_16x16x32_bf16 v[0:3], v[208:211], v[192:195], v[0:3]
	ds_read_b128 v[164:167], v149 offset:3072
	v_mfma_f32_16x16x32_bf16 v[52:55], v[204:207], v[172:175], v[52:55]
	s_add_i32 s48, s48, 2
	v_mfma_f32_16x16x32_bf16 v[48:51], v[212:215], v[172:175], v[48:51]
	s_add_u32 s38, s38, 0x100
	s_addc_u32 s39, s39, 0
	v_mfma_f32_16x16x32_bf16 v[36:39], v[204:207], v[180:183], v[36:39]
	s_cmpk_gt_u32 s48, 0x55
	v_mfma_f32_16x16x32_bf16 v[32:35], v[212:215], v[180:183], v[32:35]
	s_mov_b64 s[8:9], s[10:11]
	v_mfma_f32_16x16x32_bf16 v[20:23], v[204:207], v[188:191], v[20:23]
	v_mfma_f32_16x16x32_bf16 v[16:19], v[212:215], v[188:191], v[16:19]
	v_mfma_f32_16x16x32_bf16 v[4:7], v[204:207], v[196:199], v[4:7]
	v_mfma_f32_16x16x32_bf16 v[0:3], v[212:215], v[196:199], v[0:3]
	s_barrier
	s_setprio 0
	s_cbranch_scc0 .LBB1_2653
	s_waitcnt lgkmcnt(0)
	v_mov_b32_e32 v144, v147
	v_mov_b32_e32 v152, v146
	s_lshl_b32 s2, s2, 8
	s_lshl_b32 s8, s37, 8
	s_add_i32 s2, s2, s27
	s_or_b32 s8, s8, s28
	v_add_u32_e32 v152, s2, v152
	v_lshl_add_u32 v144, v144, 3, s8
	v_ashrrev_i32_e32 v153, 31, v152
	v_ashrrev_i32_e32 v145, 31, v144
	v_lshlrev_b64 v[152:153], 11, v[152:153]
	v_lshl_add_u64 v[144:145], v[152:153], 0, v[144:145]
	v_lshl_add_u64 v[156:157], v[144:145], 1, s[6:7]
	global_load_dwordx4 v[162:165], v[156:157], off
	global_load_dwordx4 v[166:169], v[156:157], off offset:256
	s_mov_b64 s[98:99], 0x10000
	v_lshl_add_u64 v[154:155], v[156:157], 0, s[98:99]
	global_load_dwordx4 v[170:173], v[154:155], off
	global_load_dwordx4 v[174:177], v[154:155], off offset:256
	s_mov_b64 s[98:99], 0x20000
	v_lshl_add_u64 v[154:155], v[156:157], 0, s[98:99]
	global_load_dwordx4 v[178:181], v[154:155], off
	global_load_dwordx4 v[182:185], v[154:155], off offset:256
	s_mov_b64 s[98:99], 0x30000
	v_lshl_add_u64 v[154:155], v[156:157], 0, s[98:99]
	global_load_dwordx4 v[186:189], v[154:155], off
	global_load_dwordx4 v[190:193], v[154:155], off offset:256
	s_mov_b64 s[98:99], 0x80000
	v_lshl_add_u64 v[154:155], v[156:157], 0, s[98:99]
	global_load_dwordx4 v[194:197], v[154:155], off
	global_load_dwordx4 v[198:201], v[154:155], off offset:256
	s_mov_b64 s[98:99], 0x90000
	v_lshl_add_u64 v[154:155], v[156:157], 0, s[98:99]
	global_load_dwordx4 v[202:205], v[154:155], off
	global_load_dwordx4 v[206:209], v[154:155], off offset:256
	s_mov_b64 s[98:99], 0xa0000
	v_lshl_add_u64 v[154:155], v[156:157], 0, s[98:99]
	global_load_dwordx4 v[210:213], v[154:155], off
	global_load_dwordx4 v[248:251], v[154:155], off offset:256
	s_mov_b64 s[98:99], 0xb0000
	v_lshl_add_u64 v[154:155], v[156:157], 0, s[98:99]
	global_load_dwordx4 v[252:255], v[154:155], off
	s_waitcnt vmcnt(14)
	s_nop 1
	v_mov_b32_e32 v152, v162
	v_mov_b32_e32 v153, v163
	v_mov_b32_e32 v154, v164
	v_mov_b32_e32 v155, v165
	s_mov_b64 s[8:9], 0x8000
	s_and_b64 vcc, exec, s[40:41]
	s_mov_b32 s37, s35
	s_mov_b32 s2, s36
	s_mov_b64 s[10:11], s[44:45]
	s_waitcnt lgkmcnt(0)
	v_lshlrev_b32_e32 v158, 16, v152
	v_and_b32_e32 v159, 0xffff0000, v152
	v_lshlrev_b32_e32 v152, 16, v153
	v_and_b32_e32 v153, 0xffff0000, v153
	v_lshlrev_b32_e32 v160, 16, v154
	v_and_b32_e32 v161, 0xffff0000, v154
	v_lshlrev_b32_e32 v154, 16, v155
	v_and_b32_e32 v155, 0xffff0000, v155
	v_pk_add_f32 v[126:127], v[126:127], v[152:153]
	v_pk_add_f32 v[124:125], v[124:125], v[158:159]
	v_lshl_add_u64 v[152:153], v[144:145], 2, s[4:5]
	v_pk_add_f32 v[122:123], v[122:123], v[154:155]
	v_pk_add_f32 v[120:121], v[120:121], v[160:161]
	global_store_dwordx4 v[152:153], v[124:127], off
	global_store_dwordx4 v[152:153], v[120:123], off offset:16
	s_waitcnt vmcnt(15)
; DI unsigned pack2(float a, float b) { f32x2 v = {a, b}; hwbf16x2 r = __builtin_convertvector(v, hwbf16x2); return __builtin_bit_cast(unsigned, r); }
; DI float bflo(unsigned w) { return __uint_as_float(w << 16); }
; DI float bfhi(unsigned w) { return __uint_as_float(w & 0xffff0000u); }
;     DI void operator()(const f32x4 (&acc)[2][2][4][2], const Unit& u, int wr, int wc, int fr, int fq) const {
;     ...
;             for (int m = 0; m < 4; ++m) { const size_t ro = (size_t)(row0 + ai * HALF + m * 16) * D + col0;
; #pragma unroll
;                 for (int bj = 0; bj < 2; ++bj) {
;                     f32x4 x0, x1;
;                     if constexpr (IB) { const u32x4 w = *(const u32x4*)((const bf16_t*)Xin + ro + bj * HALF);
;                         x0 = (f32x4){bflo(w[0]), bfhi(w[0]), bflo(w[1]), bfhi(w[1])}; x1 = (f32x4){bflo(w[2]), bfhi(w[2]), bflo(w[3]), bfhi(w[3])}; }
;                     else { x0 = *(const f32x4*)((const float*)Xin + ro + bj * HALF); x1 = *(const f32x4*)((const float*)Xin + ro + bj * HALF + 4); }
;                     x0 += acc[ai][bj][m][0] * sc[bj][0]; x1 += acc[ai][bj][m][1] * sc[bj][1];
;                     if constexpr (OB) { u32x4 o; o[0] = pack2(x0[0], x0[1]); o[1] = pack2(x0[2], x0[3]); o[2] = pack2(x1[0], x1[1]); o[3] = pack2(x1[2], x1[3]);
;                         *(u32x4*)((bf16_t*)Xout + ro + bj * HALF) = o; }
;                     else { *(f32x4*)((float*)Xout + ro + bj * HALF) = x0; *(f32x4*)((float*)Xout + ro + bj * HALF + 4) = x1; } } }
	s_nop 1
	v_mov_b32_e32 v120, v166
	v_mov_b32_e32 v121, v167
	v_mov_b32_e32 v122, v168
	v_mov_b32_e32 v123, v169
	s_waitcnt lgkmcnt(0)
	v_lshlrev_b32_e32 v124, 16, v120
	v_and_b32_e32 v125, 0xffff0000, v120
	v_lshlrev_b32_e32 v120, 16, v121
	v_and_b32_e32 v121, 0xffff0000, v121
	v_lshlrev_b32_e32 v126, 16, v122
	v_and_b32_e32 v127, 0xffff0000, v122
	v_lshlrev_b32_e32 v122, 16, v123
	v_and_b32_e32 v123, 0xffff0000, v123
	v_pk_add_f32 v[118:119], v[118:119], v[120:121]
	v_pk_add_f32 v[116:117], v[116:117], v[124:125]
	v_pk_add_f32 v[114:115], v[114:115], v[122:123]
	v_pk_add_f32 v[112:113], v[112:113], v[126:127]
	global_store_dwordx4 v[152:153], v[116:119], off offset:512
	global_store_dwordx4 v[152:153], v[112:115], off offset:528
	s_nop 0
	v_lshl_add_u64 v[116:117], v[144:145], 0, s[8:9]
	v_lshl_add_u64 v[118:119], v[116:117], 1, s[6:7]
	s_waitcnt vmcnt(16)
	s_nop 1
	v_mov_b32_e32 v112, v170
	v_mov_b32_e32 v113, v171
	v_mov_b32_e32 v114, v172
	v_mov_b32_e32 v115, v173
	s_mov_b64 s[8:9], 0x10000
	s_waitcnt lgkmcnt(0)
	v_lshlrev_b32_e32 v120, 16, v112
	v_and_b32_e32 v121, 0xffff0000, v112
	v_lshlrev_b32_e32 v112, 16, v113
	v_and_b32_e32 v113, 0xffff0000, v113
	v_lshlrev_b32_e32 v122, 16, v114
	v_and_b32_e32 v123, 0xffff0000, v114
	v_lshlrev_b32_e32 v114, 16, v115
	v_and_b32_e32 v115, 0xffff0000, v115
	v_pk_add_f32 v[110:111], v[110:111], v[112:113]
	v_pk_add_f32 v[108:109], v[108:109], v[120:121]
	v_lshl_add_u64 v[112:113], v[116:117], 2, s[4:5]
	v_pk_add_f32 v[106:107], v[106:107], v[114:115]
	v_pk_add_f32 v[104:105], v[104:105], v[122:123]
	global_store_dwordx4 v[112:113], v[108:111], off
	global_store_dwordx4 v[112:113], v[104:107], off offset:16
	s_waitcnt vmcnt(17)
	s_nop 1
	v_mov_b32_e32 v104, v174
	v_mov_b32_e32 v105, v175
	v_mov_b32_e32 v106, v176
	v_mov_b32_e32 v107, v177
	s_waitcnt lgkmcnt(0)
	v_lshlrev_b32_e32 v108, 16, v104
	v_and_b32_e32 v109, 0xffff0000, v104
	v_lshlrev_b32_e32 v104, 16, v105
	v_and_b32_e32 v105, 0xffff0000, v105
	v_lshlrev_b32_e32 v110, 16, v106
	v_and_b32_e32 v111, 0xffff0000, v106
	v_lshlrev_b32_e32 v106, 16, v107
	v_and_b32_e32 v107, 0xffff0000, v107
	v_pk_add_f32 v[102:103], v[102:103], v[104:105]
	v_pk_add_f32 v[100:101], v[100:101], v[108:109]
	v_pk_add_f32 v[98:99], v[98:99], v[106:107]
	v_pk_add_f32 v[96:97], v[96:97], v[110:111]
	global_store_dwordx4 v[112:113], v[100:103], off offset:512
	global_store_dwordx4 v[112:113], v[96:99], off offset:528
	s_nop 0
	v_lshl_add_u64 v[100:101], v[144:145], 0, s[8:9]
	v_lshl_add_u64 v[102:103], v[100:101], 1, s[6:7]
	s_waitcnt vmcnt(18)
	s_nop 1
	v_mov_b32_e32 v96, v178
	v_mov_b32_e32 v97, v179
	v_mov_b32_e32 v98, v180
	v_mov_b32_e32 v99, v181
	s_mov_b64 s[8:9], 0x18000
	s_waitcnt lgkmcnt(0)
	v_lshlrev_b32_e32 v104, 16, v96
	v_and_b32_e32 v105, 0xffff0000, v96
	v_lshlrev_b32_e32 v96, 16, v97
	v_and_b32_e32 v97, 0xffff0000, v97
	v_lshlrev_b32_e32 v106, 16, v98
	v_and_b32_e32 v107, 0xffff0000, v98
	v_lshlrev_b32_e32 v98, 16, v99
	v_and_b32_e32 v99, 0xffff0000, v99
	v_pk_add_f32 v[94:95], v[94:95], v[96:97]
	v_pk_add_f32 v[92:93], v[92:93], v[104:105]
	v_lshl_add_u64 v[96:97], v[100:101], 2, s[4:5]
	v_pk_add_f32 v[90:91], v[90:91], v[98:99]
	v_pk_add_f32 v[88:89], v[88:89], v[106:107]
	global_store_dwordx4 v[96:97], v[92:95], off
	global_store_dwordx4 v[96:97], v[88:91], off offset:16
	s_waitcnt vmcnt(19)
	s_nop 1
	v_mov_b32_e32 v88, v182
	v_mov_b32_e32 v89, v183
	v_mov_b32_e32 v90, v184
	v_mov_b32_e32 v91, v185
	s_waitcnt lgkmcnt(0)
	v_lshlrev_b32_e32 v92, 16, v88
	v_and_b32_e32 v93, 0xffff0000, v88
	v_lshlrev_b32_e32 v88, 16, v89
	v_and_b32_e32 v89, 0xffff0000, v89
	v_lshlrev_b32_e32 v94, 16, v90
	v_and_b32_e32 v95, 0xffff0000, v90
	v_lshlrev_b32_e32 v90, 16, v91
	v_and_b32_e32 v91, 0xffff0000, v91
	v_pk_add_f32 v[86:87], v[86:87], v[88:89]
	v_pk_add_f32 v[84:85], v[84:85], v[92:93]
	v_pk_add_f32 v[82:83], v[82:83], v[90:91]
	v_pk_add_f32 v[80:81], v[80:81], v[94:95]
	global_store_dwordx4 v[96:97], v[84:87], off offset:512
	global_store_dwordx4 v[96:97], v[80:83], off offset:528
	s_nop 0
	v_lshl_add_u64 v[84:85], v[144:145], 0, s[8:9]
	v_lshl_add_u64 v[86:87], v[84:85], 1, s[6:7]
	s_waitcnt vmcnt(20)
	s_nop 1
	v_mov_b32_e32 v80, v186
	v_mov_b32_e32 v81, v187
	v_mov_b32_e32 v82, v188
	v_mov_b32_e32 v83, v189
	s_mov_b64 s[8:9], 0x40000
	s_waitcnt lgkmcnt(0)
	v_lshlrev_b32_e32 v88, 16, v80
	v_and_b32_e32 v89, 0xffff0000, v80
	v_lshlrev_b32_e32 v80, 16, v81
	v_and_b32_e32 v81, 0xffff0000, v81
	v_lshlrev_b32_e32 v90, 16, v82
	v_and_b32_e32 v91, 0xffff0000, v82
	v_lshlrev_b32_e32 v82, 16, v83
	v_and_b32_e32 v83, 0xffff0000, v83
	v_pk_add_f32 v[78:79], v[78:79], v[80:81]
	v_pk_add_f32 v[76:77], v[76:77], v[88:89]
	v_lshl_add_u64 v[80:81], v[84:85], 2, s[4:5]
	v_pk_add_f32 v[74:75], v[74:75], v[82:83]
	v_pk_add_f32 v[72:73], v[72:73], v[90:91]
	global_store_dwordx4 v[80:81], v[76:79], off
	global_store_dwordx4 v[80:81], v[72:75], off offset:16
	s_waitcnt vmcnt(21)
	s_nop 1
	v_mov_b32_e32 v72, v190
	v_mov_b32_e32 v73, v191
	v_mov_b32_e32 v74, v192
	v_mov_b32_e32 v75, v193
	s_waitcnt lgkmcnt(0)
	v_lshlrev_b32_e32 v76, 16, v72
	v_and_b32_e32 v77, 0xffff0000, v72
	v_lshlrev_b32_e32 v72, 16, v73
	v_and_b32_e32 v73, 0xffff0000, v73
	v_lshlrev_b32_e32 v78, 16, v74
	v_and_b32_e32 v79, 0xffff0000, v74
	v_lshlrev_b32_e32 v74, 16, v75
	v_and_b32_e32 v75, 0xffff0000, v75
	v_pk_add_f32 v[70:71], v[70:71], v[72:73]
	v_pk_add_f32 v[68:69], v[68:69], v[76:77]
	v_pk_add_f32 v[66:67], v[66:67], v[74:75]
	v_pk_add_f32 v[64:65], v[64:65], v[78:79]
	global_store_dwordx4 v[80:81], v[68:71], off offset:512
	global_store_dwordx4 v[80:81], v[64:67], off offset:528
	s_nop 0
	v_lshl_add_u64 v[68:69], v[144:145], 0, s[8:9]
	v_lshl_add_u64 v[70:71], v[68:69], 1, s[6:7]
	s_waitcnt vmcnt(22)
; DI unsigned pack2(float a, float b) { f32x2 v = {a, b}; hwbf16x2 r = __builtin_convertvector(v, hwbf16x2); return __builtin_bit_cast(unsigned, r); }
; DI float bflo(unsigned w) { return __uint_as_float(w << 16); }
; DI float bfhi(unsigned w) { return __uint_as_float(w & 0xffff0000u); }
;     DI const char* a(const Unit& u) const { return (const char*)(A + (size_t)u.pm * BM * lda); }
;     DI const char* a(const Unit& u) const { return (const char*)(A + (size_t)u.pm * BM * 2048 + (u.pn >> 1) * 512); }
; #define PG8_BAR __builtin_amdgcn_s_barrier()
;     DI void operator()(const f32x4 (&acc)[2][2][4][2], const Unit& u, int wr, int wc, int fr, int fq) const {
;     ...
;             for (int m = 0; m < 4; ++m) { const size_t ro = (size_t)(row0 + ai * HALF + m * 16) * D + col0;
; #pragma unroll
;                 for (int bj = 0; bj < 2; ++bj) {
;                     f32x4 x0, x1;
;                     if constexpr (IB) { const u32x4 w = *(const u32x4*)((const bf16_t*)Xin + ro + bj * HALF);
;                         x0 = (f32x4){bflo(w[0]), bfhi(w[0]), bflo(w[1]), bfhi(w[1])}; x1 = (f32x4){bflo(w[2]), bfhi(w[2]), bflo(w[3]), bfhi(w[3])}; }
;                     else { x0 = *(const f32x4*)((const float*)Xin + ro + bj * HALF); x1 = *(const f32x4*)((const float*)Xin + ro + bj * HALF + 4); }
;                     x0 += acc[ai][bj][m][0] * sc[bj][0]; x1 += acc[ai][bj][m][1] * sc[bj][1];
;                     if constexpr (OB) { u32x4 o; o[0] = pack2(x0[0], x0[1]); o[1] = pack2(x0[2], x0[3]); o[2] = pack2(x1[0], x1[1]); o[3] = pack2(x1[2], x1[3]);
;                         *(u32x4*)((bf16_t*)Xout + ro + bj * HALF) = o; }
;                     else { *(f32x4*)((float*)Xout + ro + bj * HALF) = x0; *(f32x4*)((float*)Xout + ro + bj * HALF + 4) = x1; } } }
; template <class Map, class Epi>
; DI void gemm_phase(LAS unsigned char* lds, const Map& MP, const Epi& E, const int nM, const int nN, const int K, const int lda, const int ldb) {
;     ...
;         if (!has_next) break;
; #pragma unroll
;         for (int a = 0; a < 2; ++a)
; #pragma unroll
;             for (int b = 0; b < 2; ++b)
; #pragma unroll
;                 for (int m = 0; m < 4; ++m)
; #pragma unroll
;                     for (int n = 0; n < 2; ++n) acc[a][b][m][n] = (f32x4){0.f, 0.f, 0.f, 0.f};
;         cur = nxt; cA = nA; cB = nB; ++ui;
;     }
;     PG8_WAIT_V(0);
;     if (wr == 0) PG8_BAR;
;     PG8_BAR;
	s_nop 1
	v_mov_b32_e32 v64, v194
	v_mov_b32_e32 v65, v195
	v_mov_b32_e32 v66, v196
	v_mov_b32_e32 v67, v197
	s_mov_b64 s[8:9], 0x48000
	s_waitcnt lgkmcnt(0)
	v_lshlrev_b32_e32 v72, 16, v64
	v_and_b32_e32 v73, 0xffff0000, v64
	v_lshlrev_b32_e32 v64, 16, v65
	v_and_b32_e32 v65, 0xffff0000, v65
	v_lshlrev_b32_e32 v74, 16, v66
	v_and_b32_e32 v75, 0xffff0000, v66
	v_lshlrev_b32_e32 v66, 16, v67
	v_and_b32_e32 v67, 0xffff0000, v67
	v_pk_add_f32 v[62:63], v[62:63], v[64:65]
	v_pk_add_f32 v[60:61], v[60:61], v[72:73]
	v_lshl_add_u64 v[64:65], v[68:69], 2, s[4:5]
	v_pk_add_f32 v[58:59], v[58:59], v[66:67]
	v_pk_add_f32 v[56:57], v[56:57], v[74:75]
	global_store_dwordx4 v[64:65], v[60:63], off
	global_store_dwordx4 v[64:65], v[56:59], off offset:16
	s_waitcnt vmcnt(23)
	s_nop 1
	v_mov_b32_e32 v56, v198
	v_mov_b32_e32 v57, v199
	v_mov_b32_e32 v58, v200
	v_mov_b32_e32 v59, v201
	s_waitcnt lgkmcnt(0)
	v_lshlrev_b32_e32 v60, 16, v56
	v_and_b32_e32 v61, 0xffff0000, v56
	v_lshlrev_b32_e32 v56, 16, v57
	v_and_b32_e32 v57, 0xffff0000, v57
	v_lshlrev_b32_e32 v62, 16, v58
	v_and_b32_e32 v63, 0xffff0000, v58
	v_lshlrev_b32_e32 v58, 16, v59
	v_and_b32_e32 v59, 0xffff0000, v59
	v_pk_add_f32 v[54:55], v[54:55], v[56:57]
	v_pk_add_f32 v[52:53], v[52:53], v[60:61]
	v_pk_add_f32 v[50:51], v[50:51], v[58:59]
	v_pk_add_f32 v[48:49], v[48:49], v[62:63]
	global_store_dwordx4 v[64:65], v[52:55], off offset:512
	global_store_dwordx4 v[64:65], v[48:51], off offset:528
	s_nop 0
	v_lshl_add_u64 v[52:53], v[144:145], 0, s[8:9]
	v_lshl_add_u64 v[54:55], v[52:53], 1, s[6:7]
	s_waitcnt vmcnt(24)
	s_nop 1
	v_mov_b32_e32 v48, v202
	v_mov_b32_e32 v49, v203
	v_mov_b32_e32 v50, v204
	v_mov_b32_e32 v51, v205
	s_mov_b64 s[8:9], 0x50000
	s_waitcnt lgkmcnt(0)
	v_lshlrev_b32_e32 v56, 16, v48
	v_and_b32_e32 v57, 0xffff0000, v48
	v_lshlrev_b32_e32 v48, 16, v49
	v_and_b32_e32 v49, 0xffff0000, v49
	v_lshlrev_b32_e32 v58, 16, v50
	v_and_b32_e32 v59, 0xffff0000, v50
	v_lshlrev_b32_e32 v50, 16, v51
	v_and_b32_e32 v51, 0xffff0000, v51
	v_pk_add_f32 v[46:47], v[46:47], v[48:49]
	v_pk_add_f32 v[44:45], v[44:45], v[56:57]
	v_lshl_add_u64 v[48:49], v[52:53], 2, s[4:5]
	v_pk_add_f32 v[42:43], v[42:43], v[50:51]
	v_pk_add_f32 v[40:41], v[40:41], v[58:59]
	global_store_dwordx4 v[48:49], v[44:47], off
	global_store_dwordx4 v[48:49], v[40:43], off offset:16
	s_waitcnt vmcnt(25)
	s_nop 1
	v_mov_b32_e32 v40, v206
	v_mov_b32_e32 v41, v207
	v_mov_b32_e32 v42, v208
	v_mov_b32_e32 v43, v209
	s_waitcnt lgkmcnt(0)
	v_lshlrev_b32_e32 v44, 16, v40
	v_and_b32_e32 v45, 0xffff0000, v40
	v_lshlrev_b32_e32 v40, 16, v41
	v_and_b32_e32 v41, 0xffff0000, v41
	v_lshlrev_b32_e32 v46, 16, v42
	v_and_b32_e32 v47, 0xffff0000, v42
	v_lshlrev_b32_e32 v42, 16, v43
	v_and_b32_e32 v43, 0xffff0000, v43
	v_pk_add_f32 v[38:39], v[38:39], v[40:41]
	v_pk_add_f32 v[36:37], v[36:37], v[44:45]
	v_pk_add_f32 v[34:35], v[34:35], v[42:43]
	v_pk_add_f32 v[32:33], v[32:33], v[46:47]
	global_store_dwordx4 v[48:49], v[36:39], off offset:512
	global_store_dwordx4 v[48:49], v[32:35], off offset:528
	s_nop 0
	v_lshl_add_u64 v[36:37], v[144:145], 0, s[8:9]
	v_lshl_add_u64 v[38:39], v[36:37], 1, s[6:7]
	s_waitcnt vmcnt(26)
	s_nop 1
	v_mov_b32_e32 v32, v210
	v_mov_b32_e32 v33, v211
	v_mov_b32_e32 v34, v212
	v_mov_b32_e32 v35, v213
	s_mov_b64 s[8:9], 0x58000
	s_waitcnt lgkmcnt(0)
	v_lshlrev_b32_e32 v40, 16, v32
	v_and_b32_e32 v41, 0xffff0000, v32
	v_lshlrev_b32_e32 v32, 16, v33
	v_and_b32_e32 v33, 0xffff0000, v33
	v_lshlrev_b32_e32 v42, 16, v34
	v_and_b32_e32 v43, 0xffff0000, v34
	v_lshlrev_b32_e32 v34, 16, v35
	v_and_b32_e32 v35, 0xffff0000, v35
	v_pk_add_f32 v[30:31], v[30:31], v[32:33]
	v_pk_add_f32 v[28:29], v[28:29], v[40:41]
	v_lshl_add_u64 v[32:33], v[36:37], 2, s[4:5]
	v_pk_add_f32 v[26:27], v[26:27], v[34:35]
	v_pk_add_f32 v[24:25], v[24:25], v[42:43]
	global_store_dwordx4 v[32:33], v[28:31], off
	global_store_dwordx4 v[32:33], v[24:27], off offset:16
	s_waitcnt vmcnt(27)
	s_nop 1
	v_mov_b32_e32 v24, v248
	v_mov_b32_e32 v25, v249
	v_mov_b32_e32 v26, v250
	v_mov_b32_e32 v27, v251
	s_waitcnt lgkmcnt(0)
	v_lshlrev_b32_e32 v28, 16, v24
	v_and_b32_e32 v29, 0xffff0000, v24
	v_lshlrev_b32_e32 v24, 16, v25
	v_and_b32_e32 v25, 0xffff0000, v25
	v_lshlrev_b32_e32 v30, 16, v26
	v_and_b32_e32 v31, 0xffff0000, v26
	v_lshlrev_b32_e32 v26, 16, v27
	v_and_b32_e32 v27, 0xffff0000, v27
	v_pk_add_f32 v[22:23], v[22:23], v[24:25]
	v_pk_add_f32 v[20:21], v[20:21], v[28:29]
	v_pk_add_f32 v[18:19], v[18:19], v[26:27]
	v_pk_add_f32 v[16:17], v[16:17], v[30:31]
	global_store_dwordx4 v[32:33], v[20:23], off offset:512
	global_store_dwordx4 v[32:33], v[16:19], off offset:528
	s_nop 0
	v_lshl_add_u64 v[20:21], v[144:145], 0, s[8:9]
	v_lshl_add_u64 v[22:23], v[20:21], 1, s[6:7]
	s_waitcnt vmcnt(28)
	s_nop 1
	v_mov_b32_e32 v16, v252
	v_mov_b32_e32 v17, v253
	v_mov_b32_e32 v18, v254
	v_mov_b32_e32 v19, v255
	s_mov_b64 s[8:9], s[42:43]
	s_waitcnt lgkmcnt(0)
	v_lshlrev_b32_e32 v24, 16, v16
	v_and_b32_e32 v25, 0xffff0000, v16
	v_lshlrev_b32_e32 v16, 16, v17
	v_and_b32_e32 v17, 0xffff0000, v17
	v_lshlrev_b32_e32 v26, 16, v18
	v_and_b32_e32 v27, 0xffff0000, v18
	v_lshlrev_b32_e32 v18, 16, v19
	v_and_b32_e32 v19, 0xffff0000, v19
	v_pk_add_f32 v[14:15], v[14:15], v[16:17]
	v_pk_add_f32 v[12:13], v[12:13], v[24:25]
	v_lshl_add_u64 v[16:17], v[20:21], 2, s[4:5]
	v_pk_add_f32 v[10:11], v[10:11], v[18:19]
	v_pk_add_f32 v[8:9], v[8:9], v[26:27]
	global_store_dwordx4 v[16:17], v[12:15], off
	global_store_dwordx4 v[16:17], v[8:11], off offset:16
	global_load_dwordx4 v[8:11], v[22:23], off offset:256
	s_waitcnt vmcnt(0) lgkmcnt(0)
	v_lshlrev_b32_e32 v12, 16, v8
	v_and_b32_e32 v13, 0xffff0000, v8
	v_lshlrev_b32_e32 v8, 16, v9
	v_and_b32_e32 v9, 0xffff0000, v9
	v_lshlrev_b32_e32 v14, 16, v10
	v_and_b32_e32 v15, 0xffff0000, v10
	v_lshlrev_b32_e32 v10, 16, v11
	v_and_b32_e32 v11, 0xffff0000, v11
	v_pk_add_f32 v[6:7], v[6:7], v[8:9]
	v_pk_add_f32 v[4:5], v[4:5], v[12:13]
	v_pk_add_f32 v[2:3], v[2:3], v[10:11]
	v_pk_add_f32 v[0:1], v[0:1], v[14:15]
	global_store_dwordx4 v[16:17], v[4:7], off offset:512
	global_store_dwordx4 v[16:17], v[0:3], off offset:528
	s_cbranch_vccz .LBB1_2646
	s_waitcnt vmcnt(0)
	s_cmpk_gt_u32 s3, 0xff
	s_cbranch_scc1 .LBB1_2657
	s_barrier
